# EpiRes: residual preloaded into accumulators (epilogue loads removed); EpiProj ss loads hoisted; make_ctx dead reads removed; hand solve
# speedup vs baseline: 1.0494x; 1.0494x over previous
.LBB0_21:
	s_cmp_lt_i32 s46, 1
	s_cselect_b64 s[4:5], -1, 0
	s_cmp_gt_i32 s46, 0
	s_cselect_b64 s[0:1], -1, 0
	s_cmp_lt_i32 s47, 1
	s_cselect_b64 s[2:3], -1, 0
	s_waitcnt lgkmcnt(0)
	s_lshl_b32 s68, s48, 3
	s_cmpk_eq_i32 s48, 0x100
	s_cselect_b64 s[6:7], -1, 0
	v_writelane_b32 v246, s6, 4
	s_cmpk_lg_i32 s48, 0x100
	s_nop 0
	v_writelane_b32 v246, s7, 5
	s_cselect_b64 s[6:7], -1, 0
	s_or_b64 s[0:1], s[0:1], s[2:3]
	v_writelane_b32 v246, s6, 6
	s_and_b64 vcc, exec, s[0:1]
	s_nop 0
	v_writelane_b32 v246, s7, 7
	s_cbranch_vccnz .LBB0_50
	v_readlane_b32 s0, v246, 4
	v_readlane_b32 s1, v246, 5
	s_movk_i32 s2, 0x1c20
	s_and_b64 s[0:1], s[0:1], exec
	s_cselect_b32 s43, s2, 0x7a40
	s_add_i32 s0, 0, 0x23000
	v_mov_b32_e32 v0, s0
	s_add_i32 s0, 0, 0x23004
	v_mov_b32_e32 v1, s0
	s_add_i32 s0, 0, 0x23008
	v_mov_b32_e32 v2, s0
	s_add_i32 s0, 0, 0x2300c
	v_mov_b32_e32 v3, s0
	s_add_i32 s0, 0, 0x23010
	v_mov_b32_e32 v4, s0
	ds_read_b32 v0, v0
	ds_read_b32 v1, v1
	ds_read_b32 v2, v2
	ds_read_b32 v3, v3
	ds_read_b32 v4, v4
	s_add_i32 s0, 0, 0x23014
	s_waitcnt lgkmcnt(0)
	s_add_i32 s0, 0, 0x23018
	s_waitcnt lgkmcnt(0)
	s_add_i32 s0, 0, 0x2301c
	s_waitcnt lgkmcnt(0)
	s_add_i32 s0, 0, 0x23020
	s_waitcnt lgkmcnt(0)
	s_add_i32 s0, 0, 0x23024
	s_waitcnt lgkmcnt(0)
	s_add_i32 s0, 0, 0x23028
	s_waitcnt lgkmcnt(0)
	s_add_i32 s0, 0, 0x2302c
	s_waitcnt lgkmcnt(0)
	s_add_i32 s0, 0, 0x23030
	s_waitcnt lgkmcnt(0)
	s_add_i32 s0, 0, 0x23034
	s_waitcnt lgkmcnt(0)
	s_add_i32 s0, 0, 0x23038
	s_waitcnt lgkmcnt(0)
	v_mov_b32_e32 v4, s0
	s_add_i32 s0, 0, 0x2303c
	v_readfirstlane_b32 s8, v0
	v_mov_b32_e32 v0, s0
	s_add_i32 s0, 0, 0x23040
	v_readfirstlane_b32 s9, v1
	v_mov_b32_e32 v1, s0
	s_add_i32 s0, 0, 0x23044
	v_readfirstlane_b32 s6, v2
	v_mov_b32_e32 v2, s0
	s_add_i32 s0, 0, 0x23048
	v_readfirstlane_b32 s7, v3
	v_mov_b32_e32 v3, s0
	ds_read_b32 v4, v4
	ds_read_b32 v0, v0
	ds_read_b32 v1, v1
	ds_read_b32 v2, v2
	ds_read_b32 v3, v3
	s_add_i32 s0, 0, 0x2304c
	s_waitcnt lgkmcnt(0)
	s_add_i32 s0, 0, 0x23050
	s_waitcnt lgkmcnt(0)
	s_add_i32 s0, 0, 0x23054
	s_waitcnt lgkmcnt(0)
	s_add_i32 s0, 0, 0x23058
	s_waitcnt lgkmcnt(0)
	s_add_i32 s0, 0, 0x2305c
	s_waitcnt lgkmcnt(0)
	s_add_i32 s0, 0, 0x23060
	s_waitcnt lgkmcnt(0)
	s_add_i32 s0, 0, 0x23064
	s_waitcnt lgkmcnt(0)
	s_add_i32 s0, 0, 0x23068
	s_waitcnt lgkmcnt(0)
	s_add_i32 s0, 0, 0x2306c
	s_waitcnt lgkmcnt(0)
	s_add_i32 s0, 0, 0x23070
	s_waitcnt lgkmcnt(0)
	s_add_i32 s0, 0, 0x23074
	s_waitcnt lgkmcnt(0)
	s_add_i32 s0, 0, 0x23078
	s_waitcnt lgkmcnt(0)
	s_add_i32 s0, 0, 0x2307c
	s_waitcnt lgkmcnt(0)
	s_add_i32 s0, 0, 0x23080
	s_waitcnt lgkmcnt(0)
	v_mov_b32_e32 v3, s0
	s_add_i32 s0, 0, 0x23084
	v_readfirstlane_b32 s10, v4
	v_mov_b32_e32 v4, s0
	s_add_i32 s0, 0, 0x23088
	v_readfirstlane_b32 s11, v0
	v_mov_b32_e32 v0, s0
	ds_read_b32 v3, v3
	ds_read_b32 v4, v4
	ds_read_b32 v0, v0
	s_add_i32 s0, 0, 0x2308c
	s_waitcnt lgkmcnt(0)
	s_add_i32 s0, 0, 0x23090
	s_waitcnt lgkmcnt(0)
	v_mov_b32_e32 v0, s0
	s_add_i32 s0, 0, 0x23094
	v_readfirstlane_b32 s14, v1
	v_mov_b32_e32 v1, s0
	s_add_i32 s0, 0, 0x23098
	v_readfirstlane_b32 s15, v2
	v_mov_b32_e32 v2, s0
	ds_read_b32 v0, v0
	ds_read_b32 v1, v1
	ds_read_b32 v2, v2
	s_add_i32 s0, 0, 0x2309c
	s_waitcnt lgkmcnt(0)
	s_add_i32 s0, 0, 0x230a0
	s_waitcnt lgkmcnt(0)
	s_add_i32 s0, 0, 0x230a4
	s_waitcnt lgkmcnt(0)
	s_add_i32 s0, 0, 0x230a8
	s_waitcnt lgkmcnt(0)
	v_mov_b32_e32 v2, s0
	s_add_i32 s0, 0, 0x230ac
	v_readfirstlane_b32 s16, v3
	v_mov_b32_e32 v3, s0
	s_add_i32 s0, 0, 0x230b0
	v_readfirstlane_b32 s17, v4
	v_mov_b32_e32 v4, s0
	ds_read_b32 v2, v2
	ds_read_b32 v3, v3
	ds_read_b32 v4, v4
	s_add_i32 s0, 0, 0x230b4
	s_waitcnt lgkmcnt(0)
	s_add_i32 s0, 0, 0x230b8
	s_waitcnt lgkmcnt(0)
	v_mov_b32_e32 v4, s0
	s_add_i32 s0, 0, 0x230bc
	v_readfirstlane_b32 s20, v0
	v_mov_b32_e32 v0, s0
	s_add_i32 s0, 0, 0x230c0
	v_readfirstlane_b32 s21, v1
	v_mov_b32_e32 v1, s0
	ds_read_b32 v4, v4
	ds_read_b32 v0, v0
	ds_read_b32 v1, v1
	s_add_i32 s0, 0, 0x230c4
	s_waitcnt lgkmcnt(0)
	s_add_i32 s0, 0, 0x230c8
	s_waitcnt lgkmcnt(0)
	s_add_i32 s0, 0, 0x230cc
	s_waitcnt lgkmcnt(0)
	s_add_i32 s0, 0, 0x230d0
	s_waitcnt lgkmcnt(0)
	v_mov_b32_e32 v1, s0
	s_add_i32 s0, 0, 0x230d4
	v_readfirstlane_b32 s50, v2
	v_mov_b32_e32 v2, s0
	s_add_i32 s0, 0, 0x230d8
	v_readfirstlane_b32 s51, v3
	v_mov_b32_e32 v3, s0
	ds_read_b32 v1, v1
	ds_read_b32 v2, v2
	ds_read_b32 v3, v3
	s_add_i32 s0, 0, 0x230dc
	s_waitcnt lgkmcnt(0)
	s_add_i32 s0, 0, 0x230e0
	s_waitcnt lgkmcnt(0)
	s_add_i32 s0, 0, 0x230e4
	s_waitcnt lgkmcnt(0)
	s_add_i32 s0, 0, 0x230e8
	s_waitcnt lgkmcnt(0)
	v_mov_b32_e32 v3, s0
	s_add_i32 s0, 0, 0x230ec
	v_readfirstlane_b32 s52, v4
	ds_read_b32 v3, v3
	v_mov_b32_e32 v4, s0
	ds_read_b32 v4, v4
	v_readfirstlane_b32 s22, v1
	v_mov_b32_e32 v1, v180
	v_readfirstlane_b32 s23, v2
	v_readlane_b32 s54, v246, 0
	v_ashrrev_i32_e32 v2, 6, v1
	s_waitcnt lgkmcnt(1)
	v_readfirstlane_b32 s12, v3
	s_waitcnt lgkmcnt(0)
	v_readfirstlane_b32 s13, v4
	v_lshl_add_u32 v32, s54, 3, v2
	s_add_u32 s18, s12, 0x100000
	v_and_b32_e32 v5, 63, v1
	v_cmp_lt_i32_e32 vcc, -1, v32
	v_cmp_gt_u32_e64 s[0:1], s43, v32
	s_mov_b32 s92, s68
	v_readfirstlane_b32 s53, v0
	s_addc_u32 s19, s13, 0
	s_and_b64 s[2:3], vcc, s[0:1]
	v_lshlrev_b32_e32 v4, 3, v5
	v_lshlrev_b32_e32 v34, 4, v5
	s_and_saveexec_b64 s[0:1], s[2:3]
	s_cbranch_execz .LBB0_41
	v_lshrrev_b32_e32 v7, 5, v5
	v_and_b32_e32 v0, 31, v1
	v_lshl_add_u32 v8, v2, 14, 0
	v_lshlrev_b32_e32 v6, 2, v0
	v_mul_u32_u24_e32 v9, 0x84, v7
	v_add3_u32 v22, v8, v6, v9
	v_lshrrev_b32_e32 v23, 3, v5
	v_and_b32_e32 v6, 56, v4
	v_mul_u32_u24_e32 v9, 0x84, v6
	v_lshlrev_b32_e32 v10, 2, v23
	v_add3_u32 v24, v8, v9, v10
	v_lshrrev_b16_e32 v8, 6, v1
	v_and_b32_e32 v8, 7, v8
	v_cmp_lt_u16_e32 vcc, 3, v8
	v_add_u16_e32 v9, -4, v8
	v_min_u16_e32 v12, v8, v9
	v_cndmask_b32_e64 v14, 0, 64, vcc
	v_or_b32_e32 v8, v14, v7
	v_or_b32_e32 v14, v14, v6
	s_add_u32 s24, s12, 0x3b00000
	v_lshlrev_b32_e32 v10, 5, v12
	v_lshlrev_b32_e32 v12, 9, v12
	v_lshlrev_b32_e32 v14, 1, v14
	s_movk_i32 s2, 0xc0
	s_addc_u32 s25, s13, 0
	v_and_b32_e32 v11, 48, v34
	v_and_or_b32 v15, v14, s2, v12
	s_add_u32 s26, s12, 0x4b00000
	v_or_b32_e32 v25, 8, v23
	v_bitop3_b32 v13, v23, 15, 24 bitop3:0xc8
	v_or_b32_e32 v14, v15, v11
	v_or_b32_e32 v15, 0x100, v15
	s_addc_u32 s27, s13, 0
	v_or_b32_e32 v12, v14, v23
	v_or_b32_e32 v14, v14, v25
	v_or3_b32 v16, v23, v11, v15
	v_or3_b32 v11, v11, v13, v15
	s_add_u32 s28, s12, 0x6b00000
	v_mov_b32_e32 v3, 0
	v_lshlrev_b32_e32 v12, 3, v12
	v_lshlrev_b32_e32 v14, 3, v14
	v_lshlrev_b32_e32 v16, 3, v16
	v_lshlrev_b32_e32 v18, 3, v11
	v_add_u32_e32 v28, 0xffff87c0, v32
	v_lshlrev_b32_e32 v2, 5, v2
	s_addc_u32 s29, s13, 0
	v_or_b32_e32 v26, 24, v23
	v_or_b32_e32 v27, 16, v23
	v_lshlrev_b32_e32 v8, 9, v8
	v_mov_b32_e32 v9, v3
	v_lshlrev_b32_e32 v29, 11, v28
	s_lshl_b32 s55, s48, 14
	v_lshl_add_u32 v30, s54, 8, v2
	s_lshl_b32 s56, s48, 8
	s_mov_b32 s57, 0x7c000
	v_lshlrev_b32_e32 v10, 2, v10
	s_movk_i32 s58, 0x4000
	s_mov_b32 s59, 0x8000
	s_mov_b32 s60, 0x7060302
	v_lshlrev_b32_e32 v12, 1, v12
	v_lshlrev_b32_e32 v14, 1, v14
	v_lshlrev_b32_e32 v16, 1, v16
	v_lshlrev_b32_e32 v18, 1, v18
	s_mov_b32 s61, 0xc000
	s_mov_b32 s62, 0x10000
	s_mov_b32 s63, 0x14000
	s_mov_b32 s64, 0x18000
	s_mov_b32 s65, 0x1c000
	s_mov_b32 s66, 0x20000
	s_mov_b32 s67, 0x24000
	s_mov_b32 s68, 0x28000
	s_mov_b32 s69, 0x2c000
	s_mov_b32 s70, 0x30000
	s_mov_b32 s71, 0x34000
	s_mov_b32 s72, 0x38000
	s_mov_b32 s73, 0x3c000
	s_mov_b32 s74, 0x40000
	s_mov_b32 s75, 0x44000
	s_mov_b32 s76, 0x48000
	s_mov_b32 s77, 0x4c000
	s_mov_b32 s78, 0x50000
	s_mov_b32 s79, 0x54000
	s_mov_b32 s80, 0x58000
	s_mov_b32 s81, 0x5c000
	s_mov_b32 s82, 0x60000
	s_mov_b32 s83, 0x64000
	s_mov_b32 s84, 0x68000
	s_mov_b32 s85, 0x6c000
	s_mov_b32 s86, 0x70000
	s_mov_b32 s87, 0x74000
	s_mov_b32 s88, 0x78000
	s_mov_b32 s89, 0x91a2b3c5
	v_mov_b32_e32 v31, 0x7c00000
	v_mov_b32_e32 v33, 0x7b00000
	s_movk_i32 s90, 0xe1
	s_movk_i32 s91, 0x7080
	s_mov_b64 s[30:31], 0
	s_branch .LBB0_25

.LBB0_104:
	s_lshr_b32 s0, s90, 1
	s_bitcmp1_b32 s90, 0
	s_cselect_b64 s[2:3], -1, 0
	v_writelane_b32 v244, s0, 12
	s_mov_b64 s[0:1], -1
	s_and_b64 vcc, exec, s[2:3]
	s_cbranch_vccz .LBB0_609
	s_cmp_lg_u32 s90, 1
	s_cselect_b64 s[18:19], -1, 0
	s_cmp_eq_u32 s90, 1
	s_cselect_b64 s[20:21], -1, 0
	s_and_b64 s[0:1], s[20:21], exec
	s_cselect_b32 s33, 7, 18
	s_cmp_le_i32 s46, s33
	s_cselect_b64 s[0:1], -1, 0
	s_cmp_lt_i32 s33, s47
	s_cselect_b64 s[2:3], -1, 0
	s_and_b64 s[0:1], s[0:1], s[2:3]
	v_readlane_b32 s2, v246, 4
	v_readlane_b32 s3, v246, 5
	s_and_b64 s[2:3], s[2:3], s[20:21]
	s_andn2_b64 vcc, exec, s[0:1]
	v_writelane_b32 v244, s2, 15
	s_nop 1
	v_writelane_b32 v244, s3, 16
	s_cbranch_vccnz .LBB0_146
	v_readlane_b32 s2, v246, 62
	v_readlane_b32 s22, v246, 0
	v_mov_b32_e32 v14, v180
	v_readlane_b32 s2, v246, 63
	s_waitcnt lgkmcnt(0)
	s_nop 0
	v_readlane_b32 s2, v245, 0
	s_waitcnt lgkmcnt(0)
	s_nop 0
	v_readlane_b32 s2, v245, 1
	s_waitcnt lgkmcnt(0)
	s_nop 0
	v_readlane_b32 s2, v245, 2
	s_waitcnt lgkmcnt(0)
	s_nop 0
	v_readlane_b32 s2, v245, 3
	s_waitcnt lgkmcnt(0)
	s_nop 0
	v_readlane_b32 s2, v245, 4
	s_waitcnt lgkmcnt(0)
	s_nop 0
	v_readlane_b32 s2, v245, 5
	s_waitcnt lgkmcnt(0)
	s_nop 0
	v_readlane_b32 s2, v245, 6
	s_waitcnt lgkmcnt(0)
	s_nop 0
	v_readlane_b32 s2, v245, 7
	s_waitcnt lgkmcnt(0)
	s_nop 0
	v_readlane_b32 s2, v245, 8
	s_waitcnt lgkmcnt(0)
	s_nop 0
	v_readlane_b32 s2, v245, 9
	s_waitcnt lgkmcnt(0)
	s_nop 0
	v_readlane_b32 s2, v245, 10
	s_waitcnt lgkmcnt(0)
	s_nop 0
	v_readlane_b32 s2, v245, 11
	s_waitcnt lgkmcnt(0)
	s_nop 0
	v_readlane_b32 s2, v245, 12
	s_waitcnt lgkmcnt(0)
	s_nop 0
	v_readlane_b32 s2, v245, 13
	s_waitcnt lgkmcnt(0)
	s_nop 0
	v_readlane_b32 s2, v245, 14
	s_waitcnt lgkmcnt(0)
	s_nop 0
	v_mov_b32_e32 v0, s2
	ds_read_b32 v0, v0
	v_readlane_b32 s2, v245, 15
	s_waitcnt lgkmcnt(0)
	v_readfirstlane_b32 s14, v0
	v_mov_b32_e32 v0, s2
	ds_read_b32 v0, v0
	v_readlane_b32 s2, v245, 16
	s_waitcnt lgkmcnt(0)
	v_readfirstlane_b32 s15, v0
	v_readlane_b32 s2, v245, 17
	s_waitcnt lgkmcnt(0)
	s_nop 0
	v_readlane_b32 s2, v245, 18
	s_waitcnt lgkmcnt(0)
	s_nop 0
	v_readlane_b32 s2, v245, 19
	s_waitcnt lgkmcnt(0)
	s_nop 0
	v_readlane_b32 s2, v245, 20
	s_waitcnt lgkmcnt(0)
	s_nop 0
	v_readlane_b32 s2, v245, 21
	s_waitcnt lgkmcnt(0)
	s_nop 0
	v_readlane_b32 s2, v245, 22
	s_waitcnt lgkmcnt(0)
	s_nop 0
	v_readlane_b32 s2, v245, 23
	s_waitcnt lgkmcnt(0)
	s_nop 0
	v_readlane_b32 s2, v245, 24
	s_waitcnt lgkmcnt(0)
	s_nop 0
	v_readlane_b32 s2, v245, 25
	s_waitcnt lgkmcnt(0)
	s_nop 0
	v_readlane_b32 s2, v245, 26
	s_waitcnt lgkmcnt(0)
	s_nop 0
	v_readlane_b32 s2, v245, 27
	s_waitcnt lgkmcnt(0)
	s_nop 0
	v_readlane_b32 s2, v245, 28
	s_waitcnt lgkmcnt(0)
	s_nop 0
	v_readlane_b32 s2, v245, 29
	s_waitcnt lgkmcnt(0)
	s_nop 0
	v_readlane_b32 s2, v245, 30
	s_waitcnt lgkmcnt(0)
	s_nop 0
	v_mov_b32_e32 v0, s2
	ds_read_b32 v0, v0
	v_readlane_b32 s2, v245, 31
	s_waitcnt lgkmcnt(0)
	v_readfirstlane_b32 s16, v0
	v_mov_b32_e32 v0, s2
	ds_read_b32 v0, v0
	v_readlane_b32 s2, v245, 32
	s_waitcnt lgkmcnt(0)
	v_readfirstlane_b32 s17, v0
	v_readlane_b32 s2, v245, 33
	s_waitcnt lgkmcnt(0)
	s_nop 0
	v_readlane_b32 s2, v245, 34
	s_waitcnt lgkmcnt(0)
	s_nop 0
	v_mov_b32_e32 v0, s2
	ds_read_b32 v0, v0
	v_readlane_b32 s2, v245, 35
	s_waitcnt lgkmcnt(0)
	v_readfirstlane_b32 s26, v0
	v_mov_b32_e32 v0, s2
	ds_read_b32 v0, v0
	v_readlane_b32 s2, v245, 36
	s_waitcnt lgkmcnt(0)
	v_readfirstlane_b32 s27, v0
	v_readlane_b32 s2, v245, 37
	s_waitcnt lgkmcnt(0)
	s_nop 0
	v_readlane_b32 s2, v245, 38
	s_waitcnt lgkmcnt(0)
	s_nop 0
	v_readlane_b32 s2, v245, 39
	s_waitcnt lgkmcnt(0)
	s_nop 0
	v_readlane_b32 s2, v245, 40
	s_waitcnt lgkmcnt(0)
	s_nop 0
	v_mov_b32_e32 v0, s2
	ds_read_b32 v0, v0
	v_readlane_b32 s2, v245, 41
	s_waitcnt lgkmcnt(0)
	v_readfirstlane_b32 s8, v0
	v_mov_b32_e32 v0, s2
	ds_read_b32 v0, v0
	v_readlane_b32 s2, v245, 42
	s_waitcnt lgkmcnt(0)
	v_readfirstlane_b32 s9, v0
	v_readlane_b32 s2, v245, 43
	s_waitcnt lgkmcnt(0)
	s_nop 0
	v_readlane_b32 s2, v245, 44
	s_waitcnt lgkmcnt(0)
	s_nop 0
	v_mov_b32_e32 v0, s2
	ds_read_b32 v0, v0
	v_readlane_b32 s2, v245, 45
	s_waitcnt lgkmcnt(0)
	v_readfirstlane_b32 s24, v0
	v_mov_b32_e32 v0, s2
	ds_read_b32 v0, v0
	v_readlane_b32 s2, v245, 46
	s_waitcnt lgkmcnt(0)
	v_readfirstlane_b32 s25, v0
	v_readlane_b32 s2, v245, 47
	s_waitcnt lgkmcnt(0)
	s_nop 0
	v_readlane_b32 s2, v245, 48
	s_waitcnt lgkmcnt(0)
	s_nop 0
	v_readlane_b32 s2, v245, 49
	s_waitcnt lgkmcnt(0)
	s_nop 0
	v_readlane_b32 s2, v245, 50
	s_waitcnt lgkmcnt(0)
	s_nop 0
	v_readlane_b32 s2, v245, 51
	s_waitcnt lgkmcnt(0)
	s_nop 0
	v_readlane_b32 s2, v245, 52
	s_waitcnt lgkmcnt(0)
	s_nop 0
	v_readlane_b32 s2, v245, 53
	s_waitcnt lgkmcnt(0)
	s_nop 0
	v_readlane_b32 s2, v245, 54
	s_waitcnt lgkmcnt(0)
	s_nop 0
	v_readlane_b32 s2, v245, 55
	s_waitcnt lgkmcnt(0)
	s_nop 0
	v_readlane_b32 s2, v245, 56
	s_waitcnt lgkmcnt(0)
	s_nop 0
	v_mov_b32_e32 v0, s2
	ds_read_b32 v0, v0
	v_readlane_b32 s2, v245, 57
	s_waitcnt lgkmcnt(0)
	v_readfirstlane_b32 s12, v0
	v_mov_b32_e32 v0, s2
	ds_read_b32 v0, v0
	s_add_u32 s28, s12, 0x4b00000
	s_waitcnt lgkmcnt(0)
	v_readfirstlane_b32 s13, v0
	s_addc_u32 s29, s13, 0
	v_readfirstlane_b32 s3, v14
	s_cmpk_gt_i32 s22, 0x23f
	s_cbranch_scc1 .LBB0_122
	v_lshlrev_b32_e32 v0, 4, v14
	v_add_u32_e32 v1, 0x2000, v0
	v_ashrrev_i32_e32 v2, 31, v1
	v_lshrrev_b32_e32 v2, 22, v2
	v_add_u32_e32 v2, v1, v2
	v_ashrrev_i32_e32 v8, 10, v2
	v_mul_i32_i24_e32 v2, 0x400, v8
	v_writelane_b32 v244, s26, 13
	v_sub_u32_e32 v1, v1, v2
	v_lshrrev_b32_e32 v2, 4, v1
	v_writelane_b32 v244, s27, 14
	v_writelane_b32 v244, s8, 17
	v_bitop3_b32 v1, v2, v1, 32 bitop3:0x6c
	v_ashrrev_i32_e32 v2, 31, v1
	v_writelane_b32 v244, s9, 18
	v_writelane_b32 v244, s24, 23
	v_lshrrev_b32_e32 v2, 26, v2
	v_add_u32_e32 v2, v1, v2
	v_writelane_b32 v244, s25, 24
	v_lshlrev_b32_e32 v3, 3, v8
	s_add_u32 s23, s12, 0xc500000
	v_readlane_b32 s2, v244, 12
	v_ashrrev_i32_e32 v9, 6, v2
	v_and_b32_e32 v3, -16, v3
	s_mov_b32 s27, s33
	s_addc_u32 s33, s13, 0
	s_lshl_b32 s2, s2, 24
	v_add_u32_e32 v3, v9, v3
	s_add_u32 s49, s28, s2
	v_and_b32_e32 v4, 3, v9
	s_mov_b32 s2, 0xfffe0
	v_lshrrev_b32_e32 v5, 2, v3
	v_lshlrev_b32_e32 v6, 1, v3
	v_and_b32_e32 v2, 0xc0, v2
	v_and_or_b32 v4, v3, s2, v4
	v_and_b32_e32 v5, 4, v5
	v_and_b32_e32 v6, 24, v6
	v_sub_u32_e32 v1, v1, v2
	v_or3_b32 v4, v4, v5, v6
	v_lshlrev_b32_e32 v5, 5, v8
	v_ashrrev_i16_sdwa v1, v147, sext(v1) dst_sel:DWORD dst_unused:UNUSED_PAD src0_sel:DWORD src1_sel:BYTE_0
	v_and_b32_e32 v5, 32, v5
	v_bfe_i32 v10, v1, 0, 16
	v_add_lshl_u32 v1, v5, v10, 1
	v_lshl_add_u32 v128, v4, 12, v1
	v_lshl_add_u32 v130, v3, 12, v1
	v_bfe_i32 v1, v14, 27, 1
	v_lshrrev_b32_e32 v1, 22, v1
	v_add_u32_e32 v1, v0, v1
	v_and_b32_e32 v1, 0xfffffc00, v1
	v_sub_u32_e32 v0, v0, v1
	v_lshrrev_b32_e32 v1, 4, v0
	v_ashrrev_i32_e32 v2, 31, v14
	v_bitop3_b32 v0, v1, v0, 32 bitop3:0x6c
	v_lshrrev_b32_e32 v2, 26, v2
	v_ashrrev_i32_e32 v1, 31, v0
	v_add_u32_e32 v2, v14, v2
	v_lshrrev_b32_e32 v1, 26, v1
	v_ashrrev_i32_e32 v12, 6, v2
	v_add_u32_e32 v1, v0, v1
	v_lshlrev_b32_e32 v2, 3, v12
	v_ashrrev_i32_e32 v11, 6, v1
	v_and_b32_e32 v2, -16, v2
	s_addc_u32 s51, s29, 0
	v_add_u32_e32 v2, v11, v2
	v_and_b32_e32 v3, 3, v11
	s_ashr_i32 s62, s22, 31
	v_and_or_b32 v3, v2, s2, v3
	s_lshr_b32 s2, s62, 29
	s_add_i32 s2, s22, s2
	s_ashr_i32 s7, s3, 6
	s_ashr_i32 s4, s2, 3
	s_and_b32 s2, s2, -8
	s_ashr_i32 s8, s3, 8
	s_lshl_b32 s61, s7, 10
	s_sub_i32 s2, s22, s2
	s_cmp_lt_i32 s2, 0
	s_movk_i32 s5, 0x49
	s_cselect_b32 s5, s5, 0x48
	s_mul_i32 s2, s2, s5
	s_add_i32 s2, s2, s4
	s_ashr_i32 s4, s2, 31
	s_lshr_b32 s4, s4, 25
	v_lshrrev_b32_e32 v4, 2, v2
	v_lshlrev_b32_e32 v5, 1, v2
	v_and_b32_e32 v1, 0xc0, v1
	s_add_i32 s4, s2, s4
	v_and_b32_e32 v4, 4, v4
	v_and_b32_e32 v5, 24, v5
	v_sub_u32_e32 v0, v0, v1
	s_ashr_i32 s5, s4, 7
	v_or3_b32 v3, v3, v4, v5
	v_lshlrev_b32_e32 v4, 5, v12
	v_ashrrev_i16_sdwa v0, v147, sext(v0) dst_sel:DWORD dst_unused:UNUSED_PAD src0_sel:DWORD src1_sel:BYTE_0
	s_lshl_b32 s6, s5, 3
	v_and_b32_e32 v4, 32, v4
	v_bfe_i32 v13, v0, 0, 16
	s_sub_i32 s5, 36, s6
	v_add_lshl_u32 v0, v4, v13, 1
	s_min_u32 s9, s5, 8
	s_and_b32 s4, s4, 0xffffff80
	v_lshl_add_u32 v144, v3, 12, v0
	s_sub_i32 s24, s2, s4
	v_cvt_f32_ubyte0_e32 v3, s9
	v_cvt_f32_i32_e32 v1, s24
	v_rcp_iflag_f32_e32 v4, v3
	v_lshl_add_u32 v132, v2, 12, v0
	s_ashr_i32 s2, s24, 30
	s_or_b32 s2, s2, 1
	v_mul_f32_e32 v0, v1, v4
	v_trunc_f32_e32 v0, v0
	v_fma_f32 v1, -v0, v3, v1
	v_cvt_i32_f32_e32 v0, v0
	v_cmp_ge_f32_e64 s[4:5], |v1|, v3
	s_and_b64 s[4:5], s[4:5], exec
	s_cselect_b32 s2, s2, 0
	v_readfirstlane_b32 s4, v0
	s_add_i32 s2, s4, s2
	s_mul_i32 s4, s2, s9
	s_sub_i32 s4, s24, s4
	s_sext_i32_i8 s4, s4
	s_add_i32 s4, s6, s4
	s_ashr_i32 s5, s4, 31
	s_bfe_i64 s[34:35], s[2:3], 0x80000
	s_lshl_b64 s[30:31], s[4:5], 20
	s_lshl_b64 s[34:35], s[34:35], 20
	s_add_u32 s72, s49, s34
	s_addc_u32 s73, s51, s35
	s_add_i32 s5, s61, 0
	s_add_i32 m0, s5, 0x10000
	v_mov_b32_e32 v129, v145
	global_load_lds_dwordx4 v144, s[72:73]
	s_add_i32 m0, s5, 0x12000
	s_add_u32 s34, s72, 0x80000
	global_load_lds_dwordx4 v128, s[72:73]
	s_addc_u32 s35, s73, 0
	s_add_i32 m0, s5, 0x14000
	v_mov_b32_e32 v133, v145
	global_load_lds_dwordx4 v144, s[34:35]
	s_add_i32 m0, s5, 0x16000
	s_add_u32 s74, s23, s30
	s_addc_u32 s75, s33, s31
	s_add_i32 s63, s5, 0x2000
	global_load_lds_dwordx4 v128, s[34:35]
	s_mov_b32 m0, s5
	s_add_u32 s30, s74, 0x80000
	global_load_lds_dwordx4 v132, s[74:75]
	s_mov_b32 m0, s63
	s_addc_u32 s31, s75, 0
	s_add_i32 s64, s5, 0x4000
	global_load_lds_dwordx4 v130, s[74:75]
	s_mov_b32 m0, s64
	s_add_i32 s65, s5, 0x6000
	global_load_lds_dwordx4 v132, s[30:31]
	s_mov_b32 m0, s65
	v_mov_b32_e32 v131, v145
	global_load_lds_dwordx4 v130, s[30:31]
	s_cmp_eq_u32 s8, 1
	v_lshl_add_u64 v[6:7], s[72:73], 0, v[144:145]
	v_lshl_add_u64 v[4:5], s[72:73], 0, v[128:129]
	v_lshl_add_u64 v[0:1], s[74:75], 0, v[132:133]
	s_cselect_b64 s[30:31], -1, 0
	s_cmp_lg_u32 s8, 1
	v_lshl_add_u64 v[2:3], s[74:75], 0, v[130:131]
	s_cbranch_scc1 .LBB0_109
	s_barrier

.LBB0_118:
	v_lshl_add_u32 v142, s4, 8, v146
	v_lshl_or_b32 v138, s6, 8, v163
	v_ashrrev_i32_e32 v143, 31, v142
	v_ashrrev_i32_e32 v139, 31, v138
	v_lshlrev_b64 v[140:141], 13, v[142:143]
	v_lshl_add_u64 v[140:141], s[34:35], 0, v[140:141]
	v_lshlrev_b64 v[160:161], 1, v[138:139]
	v_lshl_add_u64 v[138:139], v[140:141], 0, v[160:161]
	v_lshl_add_u64 v[140:141], v[142:143], 2, s[38:39]
	global_load_dword v200, v[140:141], off
	global_load_dword v201, v[140:141], off offset:64
	global_load_dword v202, v[140:141], off offset:128
	global_load_dword v203, v[140:141], off offset:192
	global_load_dword v204, v[140:141], off offset:512
	global_load_dword v205, v[140:141], off offset:576
	global_load_dword v206, v[140:141], off offset:640
	global_load_dword v207, v[140:141], off offset:704
	s_waitcnt vmcnt(0)
	v_mov_b32_e32 v143, v200
	s_mov_b32 s2, 0x100000
	s_mov_b32 s89, 0x18000
	v_fmamk_f32 v143, v143, 0x3a000000, v181
	v_cmp_gt_f32_e32 vcc, s80, v143
	v_mul_f32_e32 v165, 0x4b800000, v143
	s_nop 0
	v_cndmask_b32_e32 v143, v143, v165, vcc
	v_rsq_f32_e32 v143, v143
	s_nop 0
	v_mul_f32_e32 v165, 0x45800000, v143
	v_cndmask_b32_e32 v166, v143, v165, vcc
	v_pk_mul_f32 v[126:127], v[126:127], v[166:167] op_sel_hi:[1,0]
	v_pk_mul_f32 v[124:125], v[124:125], v[166:167] op_sel_hi:[1,0]
	v_pk_mul_f32 v[168:169], v[122:123], v[166:167] op_sel_hi:[1,0]
	v_pk_mul_f32 v[122:123], v[120:121], v[166:167] op_sel_hi:[1,0]
	v_cvt_pk_bf16_f32 v120, v124, v125
	v_cvt_pk_bf16_f32 v121, v126, v127
	v_pk_mul_f32 v[116:117], v[116:117], v[166:167] op_sel_hi:[1,0]
	v_cvt_pk_bf16_f32 v122, v122, v123
	v_cvt_pk_bf16_f32 v123, v168, v169
	flat_store_dwordx4 v[138:139], v[120:123]
	v_pk_mul_f32 v[118:119], v[118:119], v[166:167] op_sel_hi:[1,0]
	s_nop 0
	v_pk_mul_f32 v[120:121], v[114:115], v[166:167] op_sel_hi:[1,0]
	v_pk_mul_f32 v[114:115], v[112:113], v[166:167] op_sel_hi:[1,0]
	v_cvt_pk_bf16_f32 v112, v116, v117
	v_cvt_pk_bf16_f32 v113, v118, v119
	s_nop 0
	v_cvt_pk_bf16_f32 v114, v114, v115
	v_cvt_pk_bf16_f32 v115, v120, v121
	flat_store_dwordx4 v[138:139], v[112:115] offset:256
	s_nop 1
	v_or_b32_e32 v112, 16, v142
	v_ashrrev_i32_e32 v113, 31, v112
	v_lshlrev_b64 v[114:115], 13, v[112:113]
	v_lshl_add_u64 v[112:113], v[112:113], 2, s[38:39]
	s_nop 1
	v_mov_b32_e32 v112, v201
	v_lshl_add_u64 v[114:115], s[34:35], 0, v[114:115]
	v_lshl_add_u64 v[114:115], v[114:115], 0, v[160:161]
	v_fmamk_f32 v112, v112, 0x3a000000, v181
	v_cmp_gt_f32_e32 vcc, s80, v112
	v_mul_f32_e32 v113, 0x4b800000, v112
	s_nop 0
	v_cndmask_b32_e32 v112, v112, v113, vcc
	v_rsq_f32_e32 v112, v112
	s_nop 0
	v_mul_f32_e32 v113, 0x45800000, v112
	v_cndmask_b32_e32 v112, v112, v113, vcc
	v_pk_mul_f32 v[110:111], v[110:111], v[112:113] op_sel_hi:[1,0]
	v_pk_mul_f32 v[108:109], v[108:109], v[112:113] op_sel_hi:[1,0]
	v_pk_mul_f32 v[116:117], v[106:107], v[112:113] op_sel_hi:[1,0]
	v_pk_mul_f32 v[106:107], v[104:105], v[112:113] op_sel_hi:[1,0]
	v_cvt_pk_bf16_f32 v104, v108, v109
	v_cvt_pk_bf16_f32 v105, v110, v111
	v_pk_mul_f32 v[100:101], v[100:101], v[112:113] op_sel_hi:[1,0]
	v_cvt_pk_bf16_f32 v106, v106, v107
	v_cvt_pk_bf16_f32 v107, v116, v117
	flat_store_dwordx4 v[114:115], v[104:107]
	v_pk_mul_f32 v[102:103], v[102:103], v[112:113] op_sel_hi:[1,0]
	s_nop 0
	v_pk_mul_f32 v[104:105], v[98:99], v[112:113] op_sel_hi:[1,0]
	v_pk_mul_f32 v[98:99], v[96:97], v[112:113] op_sel_hi:[1,0]
	v_cvt_pk_bf16_f32 v96, v100, v101
	v_cvt_pk_bf16_f32 v97, v102, v103
	s_nop 0
	v_cvt_pk_bf16_f32 v98, v98, v99
	v_cvt_pk_bf16_f32 v99, v104, v105
	flat_store_dwordx4 v[114:115], v[96:99] offset:256
	s_nop 1
	v_or_b32_e32 v96, 32, v142
	v_ashrrev_i32_e32 v97, 31, v96
	v_lshlrev_b64 v[98:99], 13, v[96:97]
	v_lshl_add_u64 v[96:97], v[96:97], 2, s[38:39]
	s_nop 1
	v_mov_b32_e32 v96, v202
	v_lshl_add_u64 v[98:99], s[34:35], 0, v[98:99]
	v_lshl_add_u64 v[98:99], v[98:99], 0, v[160:161]
	v_fmamk_f32 v96, v96, 0x3a000000, v181
	v_cmp_gt_f32_e32 vcc, s80, v96
	v_mul_f32_e32 v97, 0x4b800000, v96
	s_nop 0
	v_cndmask_b32_e32 v96, v96, v97, vcc
	v_rsq_f32_e32 v96, v96
	s_nop 0
	v_mul_f32_e32 v97, 0x45800000, v96
	v_cndmask_b32_e32 v96, v96, v97, vcc
	v_pk_mul_f32 v[94:95], v[94:95], v[96:97] op_sel_hi:[1,0]
	v_pk_mul_f32 v[92:93], v[92:93], v[96:97] op_sel_hi:[1,0]
	v_pk_mul_f32 v[100:101], v[90:91], v[96:97] op_sel_hi:[1,0]
	v_pk_mul_f32 v[90:91], v[88:89], v[96:97] op_sel_hi:[1,0]
	v_cvt_pk_bf16_f32 v88, v92, v93
	v_cvt_pk_bf16_f32 v89, v94, v95
	v_pk_mul_f32 v[84:85], v[84:85], v[96:97] op_sel_hi:[1,0]
	v_cvt_pk_bf16_f32 v90, v90, v91
	v_cvt_pk_bf16_f32 v91, v100, v101
	flat_store_dwordx4 v[98:99], v[88:91]
	v_pk_mul_f32 v[86:87], v[86:87], v[96:97] op_sel_hi:[1,0]
	s_nop 0
	v_pk_mul_f32 v[88:89], v[82:83], v[96:97] op_sel_hi:[1,0]
	v_pk_mul_f32 v[82:83], v[80:81], v[96:97] op_sel_hi:[1,0]
	v_cvt_pk_bf16_f32 v80, v84, v85
	v_cvt_pk_bf16_f32 v81, v86, v87
	s_nop 0
	v_cvt_pk_bf16_f32 v82, v82, v83
	v_cvt_pk_bf16_f32 v83, v88, v89
	flat_store_dwordx4 v[98:99], v[80:83] offset:256
	s_nop 1
	v_or_b32_e32 v80, 48, v142
	v_ashrrev_i32_e32 v81, 31, v80
	v_lshlrev_b64 v[82:83], 13, v[80:81]
	v_lshl_add_u64 v[80:81], v[80:81], 2, s[38:39]
	s_nop 1
	v_mov_b32_e32 v80, v203
	v_lshl_add_u64 v[82:83], s[34:35], 0, v[82:83]
	v_lshl_add_u64 v[82:83], v[82:83], 0, v[160:161]
	v_fmamk_f32 v80, v80, 0x3a000000, v181
	v_cmp_gt_f32_e32 vcc, s80, v80
	v_mul_f32_e32 v81, 0x4b800000, v80
	s_nop 0
	v_cndmask_b32_e32 v80, v80, v81, vcc
	v_rsq_f32_e32 v80, v80
	s_nop 0
	v_mul_f32_e32 v81, 0x45800000, v80
	v_cndmask_b32_e32 v80, v80, v81, vcc
	v_pk_mul_f32 v[78:79], v[78:79], v[80:81] op_sel_hi:[1,0]
	v_pk_mul_f32 v[76:77], v[76:77], v[80:81] op_sel_hi:[1,0]
	v_pk_mul_f32 v[84:85], v[74:75], v[80:81] op_sel_hi:[1,0]
	v_pk_mul_f32 v[74:75], v[72:73], v[80:81] op_sel_hi:[1,0]
	v_cvt_pk_bf16_f32 v72, v76, v77
	v_cvt_pk_bf16_f32 v73, v78, v79
	v_pk_mul_f32 v[70:71], v[70:71], v[80:81] op_sel_hi:[1,0]
	v_cvt_pk_bf16_f32 v74, v74, v75
	v_cvt_pk_bf16_f32 v75, v84, v85
	flat_store_dwordx4 v[82:83], v[72:75]
	v_pk_mul_f32 v[68:69], v[68:69], v[80:81] op_sel_hi:[1,0]
	s_nop 0
	v_pk_mul_f32 v[72:73], v[66:67], v[80:81] op_sel_hi:[1,0]
	v_pk_mul_f32 v[66:67], v[64:65], v[80:81] op_sel_hi:[1,0]
	v_cvt_pk_bf16_f32 v64, v68, v69
	v_cvt_pk_bf16_f32 v65, v70, v71
	s_nop 0
	v_cvt_pk_bf16_f32 v66, v66, v67
	v_cvt_pk_bf16_f32 v67, v72, v73
	flat_store_dwordx4 v[82:83], v[64:67] offset:256
	s_nop 1
	v_mov_b32_e32 v66, v204
	s_nop 0
	v_lshl_add_u64 v[64:65], v[138:139], 0, s[96:97]
	v_fmamk_f32 v66, v66, 0x3a000000, v181
	v_cmp_gt_f32_e32 vcc, s80, v66
	v_mul_f32_e32 v67, 0x4b800000, v66
	s_nop 0
	v_cndmask_b32_e32 v66, v66, v67, vcc
	v_rsq_f32_e32 v66, v66
	s_nop 0
	v_mul_f32_e32 v67, 0x45800000, v66
	v_cndmask_b32_e32 v66, v66, v67, vcc
	v_pk_mul_f32 v[60:61], v[60:61], v[66:67] op_sel_hi:[1,0]
	v_pk_mul_f32 v[68:69], v[58:59], v[66:67] op_sel_hi:[1,0]
	v_pk_mul_f32 v[58:59], v[56:57], v[66:67] op_sel_hi:[1,0]
	v_cvt_pk_bf16_f32 v56, v60, v61
	v_add_co_u32_e32 v60, vcc, s2, v138
	v_pk_mul_f32 v[62:63], v[62:63], v[66:67] op_sel_hi:[1,0]
	s_nop 0
	v_addc_co_u32_e32 v61, vcc, 0, v139, vcc
	v_cvt_pk_bf16_f32 v57, v62, v63
	v_cvt_pk_bf16_f32 v58, v58, v59
	v_cvt_pk_bf16_f32 v59, v68, v69
	flat_store_dwordx4 v[60:61], v[56:59]
	v_pk_mul_f32 v[54:55], v[54:55], v[66:67] op_sel_hi:[1,0]
	v_pk_mul_f32 v[52:53], v[52:53], v[66:67] op_sel_hi:[1,0]
	v_pk_mul_f32 v[56:57], v[50:51], v[66:67] op_sel_hi:[1,0]
	v_pk_mul_f32 v[50:51], v[48:49], v[66:67] op_sel_hi:[1,0]
	v_cvt_pk_bf16_f32 v48, v52, v53
	v_cvt_pk_bf16_f32 v49, v54, v55
	s_mov_b64 s[2:3], 0x120000
	v_cvt_pk_bf16_f32 v50, v50, v51
	v_cvt_pk_bf16_f32 v51, v56, v57
	flat_store_dwordx4 v[64:65], v[48:51] offset:256
	s_nop 1
	v_mov_b32_e32 v50, v205
	s_nop 0
	v_lshl_add_u64 v[48:49], v[138:139], 0, s[2:3]
	s_mov_b32 s2, 0x120000
	v_fmamk_f32 v50, v50, 0x3a000000, v181
	v_cmp_gt_f32_e32 vcc, s80, v50
	v_mul_f32_e32 v51, 0x4b800000, v50
	s_nop 0
	v_cndmask_b32_e32 v50, v50, v51, vcc
	v_rsq_f32_e32 v50, v50
	s_nop 0
	v_mul_f32_e32 v51, 0x45800000, v50
	v_cndmask_b32_e32 v50, v50, v51, vcc
	v_pk_mul_f32 v[44:45], v[44:45], v[50:51] op_sel_hi:[1,0]
	v_pk_mul_f32 v[52:53], v[42:43], v[50:51] op_sel_hi:[1,0]
	v_pk_mul_f32 v[42:43], v[40:41], v[50:51] op_sel_hi:[1,0]
	v_cvt_pk_bf16_f32 v40, v44, v45
	v_add_co_u32_e32 v44, vcc, s2, v138
	v_pk_mul_f32 v[46:47], v[46:47], v[50:51] op_sel_hi:[1,0]
	s_nop 0
	v_addc_co_u32_e32 v45, vcc, 0, v139, vcc
	v_cvt_pk_bf16_f32 v41, v46, v47
	v_cvt_pk_bf16_f32 v42, v42, v43
	v_cvt_pk_bf16_f32 v43, v52, v53
	flat_store_dwordx4 v[44:45], v[40:43]
	v_pk_mul_f32 v[38:39], v[38:39], v[50:51] op_sel_hi:[1,0]
	v_pk_mul_f32 v[36:37], v[36:37], v[50:51] op_sel_hi:[1,0]
	v_pk_mul_f32 v[40:41], v[34:35], v[50:51] op_sel_hi:[1,0]
	v_pk_mul_f32 v[34:35], v[32:33], v[50:51] op_sel_hi:[1,0]
	v_cvt_pk_bf16_f32 v32, v36, v37
	v_cvt_pk_bf16_f32 v33, v38, v39
	s_mov_b64 s[2:3], 0x140000
	v_cvt_pk_bf16_f32 v34, v34, v35
	v_cvt_pk_bf16_f32 v35, v40, v41
	flat_store_dwordx4 v[48:49], v[32:35] offset:256
	s_nop 1
	v_mov_b32_e32 v34, v206
	s_nop 0
	v_lshl_add_u64 v[32:33], v[138:139], 0, s[2:3]
	s_mov_b32 s2, 0x140000
	v_fmamk_f32 v34, v34, 0x3a000000, v181
	v_cmp_gt_f32_e32 vcc, s80, v34
	v_mul_f32_e32 v35, 0x4b800000, v34
	s_nop 0
	v_cndmask_b32_e32 v34, v34, v35, vcc
	v_rsq_f32_e32 v34, v34
	s_nop 0
	v_mul_f32_e32 v35, 0x45800000, v34
	v_cndmask_b32_e32 v34, v34, v35, vcc
	v_pk_mul_f32 v[28:29], v[28:29], v[34:35] op_sel_hi:[1,0]
	v_pk_mul_f32 v[36:37], v[26:27], v[34:35] op_sel_hi:[1,0]
	v_pk_mul_f32 v[26:27], v[24:25], v[34:35] op_sel_hi:[1,0]
	v_cvt_pk_bf16_f32 v24, v28, v29
	v_add_co_u32_e32 v28, vcc, s2, v138
	v_pk_mul_f32 v[30:31], v[30:31], v[34:35] op_sel_hi:[1,0]
	s_nop 0
	v_addc_co_u32_e32 v29, vcc, 0, v139, vcc
	v_cvt_pk_bf16_f32 v25, v30, v31
	v_cvt_pk_bf16_f32 v26, v26, v27
	v_cvt_pk_bf16_f32 v27, v36, v37
	flat_store_dwordx4 v[28:29], v[24:27]
	v_pk_mul_f32 v[22:23], v[22:23], v[34:35] op_sel_hi:[1,0]
	v_pk_mul_f32 v[20:21], v[20:21], v[34:35] op_sel_hi:[1,0]
	v_pk_mul_f32 v[24:25], v[18:19], v[34:35] op_sel_hi:[1,0]
	v_pk_mul_f32 v[18:19], v[16:17], v[34:35] op_sel_hi:[1,0]
	v_cvt_pk_bf16_f32 v16, v20, v21
	v_cvt_pk_bf16_f32 v17, v22, v23
	s_mov_b64 s[2:3], 0x160000
	v_cvt_pk_bf16_f32 v18, v18, v19
	v_cvt_pk_bf16_f32 v19, v24, v25
	flat_store_dwordx4 v[32:33], v[16:19] offset:256
	s_nop 1
	v_mov_b32_e32 v16, v207
	s_nop 0
	v_lshl_add_u64 v[18:19], v[138:139], 0, s[2:3]
	s_mov_b32 s2, 0x160000
	v_fmamk_f32 v16, v16, 0x3a000000, v181
	v_cmp_gt_f32_e32 vcc, s80, v16
	v_mul_f32_e32 v17, 0x4b800000, v16
	s_nop 0
	v_cndmask_b32_e32 v16, v16, v17, vcc
	v_rsq_f32_e32 v16, v16
	s_nop 0
	v_mul_f32_e32 v17, 0x45800000, v16
	v_cndmask_b32_e32 v16, v16, v17, vcc
	v_pk_mul_f32 v[12:13], v[12:13], v[16:17] op_sel_hi:[1,0]
	v_pk_mul_f32 v[20:21], v[10:11], v[16:17] op_sel_hi:[1,0]
	v_pk_mul_f32 v[10:11], v[8:9], v[16:17] op_sel_hi:[1,0]
	v_cvt_pk_bf16_f32 v8, v12, v13
	v_add_co_u32_e32 v12, vcc, s2, v138
	v_pk_mul_f32 v[14:15], v[14:15], v[16:17] op_sel_hi:[1,0]
	s_nop 0
	v_addc_co_u32_e32 v13, vcc, 0, v139, vcc
	v_cvt_pk_bf16_f32 v9, v14, v15
	v_cvt_pk_bf16_f32 v10, v10, v11
	v_cvt_pk_bf16_f32 v11, v20, v21
	flat_store_dwordx4 v[12:13], v[8:11]
	s_mov_b64 s[2:3], -1
	s_andn2_b64 vcc, exec, s[36:37]
	v_pk_mul_f32 v[8:9], v[2:3], v[16:17] op_sel_hi:[1,0]
	v_pk_mul_f32 v[2:3], v[0:1], v[16:17] op_sel_hi:[1,0]
	v_pk_mul_f32 v[6:7], v[6:7], v[16:17] op_sel_hi:[1,0]
	v_pk_mul_f32 v[4:5], v[4:5], v[16:17] op_sel_hi:[1,0]
	s_nop 0
	v_cvt_pk_bf16_f32 v0, v4, v5
	v_cvt_pk_bf16_f32 v1, v6, v7
	v_cvt_pk_bf16_f32 v2, v2, v3
	v_cvt_pk_bf16_f32 v3, v8, v9
	flat_store_dwordx4 v[18:19], v[0:3] offset:256
	s_cbranch_vccnz .LBB0_111
	s_andn2_b64 vcc, exec, s[30:31]
	s_cbranch_vccnz .LBB0_110
	s_barrier
	s_branch .LBB0_110

.LBB0_196:
	s_cmp_le_i32 s46, s6
	s_cselect_b64 s[0:1], -1, 0
	s_and_b64 s[8:9], s[0:1], s[4:5]
	s_andn2_b64 vcc, exec, s[8:9]
	s_cbranch_vccnz .LBB0_328
	v_readlane_b32 s0, v246, 62
	v_readlane_b32 s1, v245, 37
	v_readlane_b32 s2, v245, 38
	v_readlane_b32 s0, v246, 63
	v_readlane_b32 s3, v245, 39
	v_readlane_b32 s4, v245, 40
	s_waitcnt lgkmcnt(0)
	v_readlane_b32 s0, v245, 0
	v_readlane_b32 s5, v245, 57
	v_readlane_b32 s64, v246, 0
	s_waitcnt lgkmcnt(0)
	v_readlane_b32 s0, v245, 1
	s_waitcnt lgkmcnt(0)
	s_nop 0
	v_readlane_b32 s0, v245, 2
	s_waitcnt lgkmcnt(0)
	s_nop 0
	v_readlane_b32 s0, v245, 3
	s_waitcnt lgkmcnt(0)
	s_nop 0
	v_readlane_b32 s0, v245, 4
	s_waitcnt lgkmcnt(0)
	s_nop 0
	v_readlane_b32 s0, v245, 5
	s_waitcnt lgkmcnt(0)
	s_nop 0
	v_readlane_b32 s0, v245, 6
	s_waitcnt lgkmcnt(0)
	s_nop 0
	v_readlane_b32 s0, v245, 7
	s_waitcnt lgkmcnt(0)
	s_nop 0
	v_readlane_b32 s0, v245, 8
	s_waitcnt lgkmcnt(0)
	s_nop 0
	v_mov_b32_e32 v0, s0
	ds_read_b32 v0, v0
	v_readlane_b32 s0, v245, 9
	s_waitcnt lgkmcnt(0)
	v_readfirstlane_b32 s12, v0
	v_mov_b32_e32 v0, s0
	ds_read_b32 v0, v0
	v_readlane_b32 s0, v245, 10
	s_waitcnt lgkmcnt(0)
	v_readfirstlane_b32 s13, v0
	v_mov_b32_e32 v0, s0
	ds_read_b32 v0, v0
	v_readlane_b32 s0, v245, 11
	s_waitcnt lgkmcnt(0)
	v_readfirstlane_b32 s14, v0
	v_mov_b32_e32 v0, s0
	ds_read_b32 v0, v0
	v_readlane_b32 s0, v245, 12
	s_waitcnt lgkmcnt(0)
	v_readfirstlane_b32 s15, v0
	v_readlane_b32 s0, v245, 13
	s_waitcnt lgkmcnt(0)
	s_nop 0
	v_readlane_b32 s0, v245, 14
	s_waitcnt lgkmcnt(0)
	s_nop 0
	v_readlane_b32 s0, v245, 15
	s_waitcnt lgkmcnt(0)
	s_nop 0
	v_readlane_b32 s0, v245, 16
	s_waitcnt lgkmcnt(0)
	s_nop 0
	v_readlane_b32 s0, v245, 17
	s_waitcnt lgkmcnt(0)
	s_nop 0
	v_readlane_b32 s0, v245, 18
	s_waitcnt lgkmcnt(0)
	s_nop 0
	v_readlane_b32 s0, v245, 19
	s_waitcnt lgkmcnt(0)
	s_nop 0
	v_readlane_b32 s0, v245, 20
	s_waitcnt lgkmcnt(0)
	s_nop 0
	v_readlane_b32 s0, v245, 21
	s_waitcnt lgkmcnt(0)
	s_nop 0
	v_readlane_b32 s0, v245, 22
	s_waitcnt lgkmcnt(0)
	s_nop 0
	v_readlane_b32 s0, v245, 23
	s_waitcnt lgkmcnt(0)
	s_nop 0
	v_readlane_b32 s0, v245, 24
	s_waitcnt lgkmcnt(0)
	s_nop 0
	v_readlane_b32 s0, v245, 25
	s_waitcnt lgkmcnt(0)
	s_nop 0
	v_readlane_b32 s0, v245, 26
	s_waitcnt lgkmcnt(0)
	s_nop 0
	v_readlane_b32 s0, v245, 27
	s_waitcnt lgkmcnt(0)
	s_nop 0
	v_readlane_b32 s0, v245, 28
	s_waitcnt lgkmcnt(0)
	s_nop 0
	v_readlane_b32 s0, v245, 29
	s_waitcnt lgkmcnt(0)
	s_nop 0
	v_readlane_b32 s0, v245, 30
	s_waitcnt lgkmcnt(0)
	s_nop 0
	v_readlane_b32 s0, v245, 31
	s_waitcnt lgkmcnt(0)
	s_nop 0
	v_readlane_b32 s0, v245, 32
	s_waitcnt lgkmcnt(0)
	s_nop 0
	v_readlane_b32 s0, v245, 33
	s_waitcnt lgkmcnt(0)
	s_nop 0
	v_readlane_b32 s0, v245, 34
	s_waitcnt lgkmcnt(0)
	s_nop 0
	v_readlane_b32 s0, v245, 35
	s_waitcnt lgkmcnt(0)
	s_nop 0
	v_readlane_b32 s0, v245, 36
	s_waitcnt lgkmcnt(0)
	s_nop 0
	v_mov_b32_e32 v0, s0
	ds_read_b32 v0, v0
	s_waitcnt lgkmcnt(0)
	v_readfirstlane_b32 s0, v0
	v_mov_b32_e32 v0, s1
	ds_read_b32 v0, v0
	s_waitcnt lgkmcnt(0)
	v_readfirstlane_b32 s1, v0
	v_mov_b32_e32 v0, s2
	ds_read_b32 v0, v0
	s_waitcnt lgkmcnt(0)
	v_readfirstlane_b32 s2, v0
	v_mov_b32_e32 v0, s3
	ds_read_b32 v0, v0
	s_waitcnt lgkmcnt(0)
	v_readfirstlane_b32 s3, v0
	v_readlane_b32 s4, v245, 41
	s_waitcnt lgkmcnt(0)
	s_nop 0
	v_readlane_b32 s4, v245, 42
	s_waitcnt lgkmcnt(0)
	s_nop 0
	v_mov_b32_e32 v0, s4
	ds_read_b32 v0, v0
	v_readlane_b32 s4, v245, 43
	s_waitcnt lgkmcnt(0)
	v_readfirstlane_b32 s16, v0
	v_mov_b32_e32 v0, s4
	ds_read_b32 v0, v0
	v_readlane_b32 s4, v245, 44
	s_waitcnt lgkmcnt(0)
	v_readfirstlane_b32 s17, v0
	v_readlane_b32 s4, v245, 45
	s_waitcnt lgkmcnt(0)
	s_nop 0
	v_readlane_b32 s4, v245, 46
	s_waitcnt lgkmcnt(0)
	s_nop 0
	v_mov_b32_e32 v0, s4
	ds_read_b32 v0, v0
	v_readlane_b32 s4, v245, 47
	s_waitcnt lgkmcnt(0)
	v_readfirstlane_b32 s24, v0
	v_mov_b32_e32 v0, s4
	ds_read_b32 v0, v0
	v_readlane_b32 s4, v245, 48
	s_waitcnt lgkmcnt(0)
	v_readfirstlane_b32 s25, v0
	v_mov_b32_e32 v0, s4
	ds_read_b32 v0, v0
	v_readlane_b32 s4, v245, 49
	s_waitcnt lgkmcnt(0)
	v_readfirstlane_b32 s26, v0
	v_mov_b32_e32 v0, s4
	ds_read_b32 v0, v0
	v_readlane_b32 s4, v245, 50
	s_waitcnt lgkmcnt(0)
	v_readfirstlane_b32 s27, v0
	v_readlane_b32 s4, v245, 51
	s_waitcnt lgkmcnt(0)
	s_nop 0
	v_readlane_b32 s4, v245, 52
	s_waitcnt lgkmcnt(0)
	s_nop 0
	v_readlane_b32 s4, v245, 53
	s_waitcnt lgkmcnt(0)
	s_nop 0
	v_readlane_b32 s4, v245, 54
	s_waitcnt lgkmcnt(0)
	s_nop 0
	v_mov_b32_e32 v0, s4
	ds_read_b32 v0, v0
	v_readlane_b32 s4, v245, 55
	s_waitcnt lgkmcnt(0)
	v_readfirstlane_b32 s22, v0
	v_mov_b32_e32 v0, s4
	ds_read_b32 v0, v0
	v_readlane_b32 s4, v245, 56
	s_waitcnt lgkmcnt(0)
	v_readfirstlane_b32 s23, v0
	v_mov_b32_e32 v0, s4
	ds_read_b32 v0, v0
	s_waitcnt lgkmcnt(0)
	v_readfirstlane_b32 s4, v0
	v_mov_b32_e32 v0, s5
	ds_read_b32 v0, v0
	s_cmpk_gt_i32 s64, 0x8ff
	s_waitcnt lgkmcnt(0)
	v_readfirstlane_b32 s5, v0
	s_cbranch_scc1 .LBB0_328
	s_add_u32 s65, s4, 0x7b00000
	s_addc_u32 s72, s5, 0
	s_add_u32 s73, s4, 0x7c00000
	s_addc_u32 s74, s5, 0
	s_add_u32 s75, s4, 0xe900000
	s_addc_u32 s62, s5, 0
	s_add_u32 s28, s4, 0x10d00000
	v_writelane_b32 v244, s33, 23
	s_addc_u32 s29, s5, 0
	s_add_u32 s49, s4, 0x21000000
	v_readlane_b32 s6, v244, 12
	s_addc_u32 s33, s5, 0
	s_lshl_b32 s4, s6, 15
	s_lshl_b32 s5, s6, 18
	s_lshl_b32 s30, s6, 11
	s_lshl_b32 s61, s6, 7
	s_lshl_b32 s51, s6, 2
	s_mov_b32 s31, s67
	s_add_u32 s34, s0, s4
	s_addc_u32 s35, s1, 0
	s_lshl_b64 s[0:1], s[30:31], 2
	s_add_u32 s40, s2, s0
	s_addc_u32 s41, s3, s1
	s_add_u32 s52, s22, 0x5058000
	s_addc_u32 s53, s23, 0
	s_add_u32 s54, s22, 0x15b88000
	s_addc_u32 s55, s23, 0
	s_lshl_b32 s31, s5, 1
	s_branch .LBB0_200

.LBB0_378:
	s_cmp_gt_i32 s46, s6
	s_cselect_b64 s[2:3], -1, 0
	s_xor_b64 s[0:1], s[0:1], -1
	s_or_b64 s[0:1], s[2:3], s[0:1]
	s_and_b64 vcc, exec, s[0:1]
	s_cbranch_vccnz .LBB0_497
	v_readlane_b32 s0, v246, 62
	v_readlane_b32 s1, v245, 13
	v_readlane_b32 s2, v245, 14
	v_readlane_b32 s0, v246, 63
	v_readlane_b32 s13, v246, 0
	v_mov_b32_e32 v9, v180
	s_waitcnt lgkmcnt(0)
	v_readlane_b32 s0, v245, 0
	s_waitcnt lgkmcnt(0)
	s_nop 0
	v_readlane_b32 s0, v245, 1
	s_waitcnt lgkmcnt(0)
	s_nop 0
	v_readlane_b32 s0, v245, 2
	s_waitcnt lgkmcnt(0)
	s_nop 0
	v_readlane_b32 s0, v245, 3
	s_waitcnt lgkmcnt(0)
	s_nop 0
	v_readlane_b32 s0, v245, 4
	s_waitcnt lgkmcnt(0)
	s_nop 0
	v_readlane_b32 s0, v245, 5
	s_waitcnt lgkmcnt(0)
	s_nop 0
	v_readlane_b32 s0, v245, 6
	s_waitcnt lgkmcnt(0)
	s_nop 0
	v_readlane_b32 s0, v245, 7
	s_waitcnt lgkmcnt(0)
	s_nop 0
	v_readlane_b32 s0, v245, 8
	s_waitcnt lgkmcnt(0)
	s_nop 0
	v_readlane_b32 s0, v245, 9
	s_waitcnt lgkmcnt(0)
	s_nop 0
	v_readlane_b32 s0, v245, 10
	s_waitcnt lgkmcnt(0)
	s_nop 0
	v_readlane_b32 s0, v245, 11
	s_waitcnt lgkmcnt(0)
	s_nop 0
	v_readlane_b32 s0, v245, 12
	s_waitcnt lgkmcnt(0)
	s_nop 0
	v_mov_b32_e32 v0, s0
	ds_read_b32 v0, v0
	s_waitcnt lgkmcnt(0)
	v_readfirstlane_b32 s0, v0
	v_mov_b32_e32 v0, s1
	ds_read_b32 v0, v0
	s_waitcnt lgkmcnt(0)
	v_readfirstlane_b32 s1, v0
	v_mov_b32_e32 v0, s2
	ds_read_b32 v0, v0
	v_readlane_b32 s2, v245, 15
	s_waitcnt lgkmcnt(0)
	v_readfirstlane_b32 s16, v0
	v_mov_b32_e32 v0, s2
	ds_read_b32 v0, v0
	v_readlane_b32 s2, v245, 16
	s_waitcnt lgkmcnt(0)
	v_readfirstlane_b32 s17, v0
	v_readlane_b32 s2, v245, 17
	s_waitcnt lgkmcnt(0)
	s_nop 0
	v_readlane_b32 s2, v245, 18
	s_waitcnt lgkmcnt(0)
	s_nop 0
	v_readlane_b32 s2, v245, 19
	s_waitcnt lgkmcnt(0)
	s_nop 0
	v_readlane_b32 s2, v245, 20
	s_waitcnt lgkmcnt(0)
	s_nop 0
	v_readlane_b32 s2, v245, 21
	s_waitcnt lgkmcnt(0)
	s_nop 0
	v_readlane_b32 s2, v245, 22
	s_waitcnt lgkmcnt(0)
	s_nop 0
	v_readlane_b32 s2, v245, 23
	s_waitcnt lgkmcnt(0)
	s_nop 0
	v_readlane_b32 s2, v245, 24
	s_waitcnt lgkmcnt(0)
	s_nop 0
	v_readlane_b32 s2, v245, 25
	s_waitcnt lgkmcnt(0)
	s_nop 0
	v_readlane_b32 s2, v245, 26
	s_waitcnt lgkmcnt(0)
	s_nop 0
	v_readlane_b32 s2, v245, 27
	s_waitcnt lgkmcnt(0)
	s_nop 0
	v_readlane_b32 s2, v245, 28
	s_waitcnt lgkmcnt(0)
	s_nop 0
	v_readlane_b32 s2, v245, 29
	s_waitcnt lgkmcnt(0)
	s_nop 0
	v_readlane_b32 s2, v245, 30
	s_waitcnt lgkmcnt(0)
	s_nop 0
	v_mov_b32_e32 v0, s2
	ds_read_b32 v0, v0
	v_readlane_b32 s2, v245, 31
	s_waitcnt lgkmcnt(0)
	v_readfirstlane_b32 s36, v0
	v_mov_b32_e32 v0, s2
	ds_read_b32 v0, v0
	v_readlane_b32 s2, v245, 32
	s_waitcnt lgkmcnt(0)
	v_readfirstlane_b32 s37, v0
	v_readlane_b32 s2, v245, 33
	s_waitcnt lgkmcnt(0)
	s_nop 0
	v_readlane_b32 s2, v245, 34
	s_waitcnt lgkmcnt(0)
	s_nop 0
	v_mov_b32_e32 v0, s2
	ds_read_b32 v0, v0
	v_readlane_b32 s2, v245, 35
	s_waitcnt lgkmcnt(0)
	v_readfirstlane_b32 s38, v0
	v_mov_b32_e32 v0, s2
	ds_read_b32 v0, v0
	v_readlane_b32 s2, v245, 36
	s_waitcnt lgkmcnt(0)
	v_readfirstlane_b32 s39, v0
	v_readlane_b32 s2, v245, 37
	s_waitcnt lgkmcnt(0)
	s_nop 0
	v_readlane_b32 s2, v245, 38
	s_waitcnt lgkmcnt(0)
	s_nop 0
	v_readlane_b32 s2, v245, 39
	s_waitcnt lgkmcnt(0)
	s_nop 0
	v_readlane_b32 s2, v245, 40
	s_waitcnt lgkmcnt(0)
	s_nop 0
	v_readlane_b32 s2, v245, 41
	s_waitcnt lgkmcnt(0)
	s_nop 0
	v_readlane_b32 s2, v245, 42
	s_waitcnt lgkmcnt(0)
	s_nop 0
	v_readlane_b32 s2, v245, 43
	s_waitcnt lgkmcnt(0)
	s_nop 0
	v_readlane_b32 s2, v245, 44
	s_waitcnt lgkmcnt(0)
	s_nop 0
	v_readlane_b32 s2, v245, 45
	s_waitcnt lgkmcnt(0)
	s_nop 0
	v_readlane_b32 s2, v245, 46
	s_waitcnt lgkmcnt(0)
	s_nop 0
	v_readlane_b32 s2, v245, 47
	s_waitcnt lgkmcnt(0)
	s_nop 0
	v_readlane_b32 s2, v245, 48
	s_waitcnt lgkmcnt(0)
	s_nop 0
	v_readlane_b32 s2, v245, 49
	s_waitcnt lgkmcnt(0)
	s_nop 0
	v_readlane_b32 s2, v245, 50
	s_waitcnt lgkmcnt(0)
	s_nop 0
	v_mov_b32_e32 v0, s2
	ds_read_b32 v0, v0
	v_readlane_b32 s2, v245, 51
	s_waitcnt lgkmcnt(0)
	v_readfirstlane_b32 s40, v0
	v_mov_b32_e32 v0, s2
	ds_read_b32 v0, v0
	v_readlane_b32 s2, v245, 52
	s_waitcnt lgkmcnt(0)
	v_readfirstlane_b32 s41, v0
	v_readlane_b32 s2, v245, 53
	s_waitcnt lgkmcnt(0)
	s_nop 0
	v_readlane_b32 s2, v245, 54
	s_waitcnt lgkmcnt(0)
	s_nop 0
	v_readlane_b32 s2, v245, 55
	s_waitcnt lgkmcnt(0)
	s_nop 0
	v_readlane_b32 s2, v245, 56
	s_waitcnt lgkmcnt(0)
	s_nop 0
	v_mov_b32_e32 v0, s2
	ds_read_b32 v0, v0
	v_readlane_b32 s2, v245, 57
	s_waitcnt lgkmcnt(0)
	v_readfirstlane_b32 s84, v0
	v_mov_b32_e32 v0, s2
	ds_read_b32 v0, v0
	s_cmpk_lt_i32 s13, 0x120
	s_cselect_b64 s[2:3], -1, 0
	s_waitcnt lgkmcnt(0)
	v_readfirstlane_b32 s12, v0
	v_readfirstlane_b32 s6, v9
	s_cmpk_gt_i32 s13, 0x11f
	s_cbranch_scc1 .LBB0_381
	s_ashr_i32 s4, s13, 31
	s_lshr_b32 s4, s4, 29
	s_add_i32 s4, s13, s4
	s_ashr_i32 s5, s4, 3
	s_and_b32 s4, s4, -8
	s_sub_i32 s4, s13, s4
	s_cmp_lt_i32 s4, 0
	s_cselect_b32 s7, 37, 36
	s_mul_i32 s4, s4, s7
	s_add_i32 s4, s4, s5
	s_ashr_i32 s5, s4, 31
	s_lshr_b32 s5, s5, 26
	s_add_i32 s5, s4, s5
	s_ashr_i32 s7, s5, 6
	s_lshl_b32 s7, s7, 3
	s_sub_i32 s8, 36, s7
	s_min_u32 s8, s8, 8
	s_andn2_b32 s5, s5, 63
	s_sub_i32 s9, s4, s5
	v_cvt_f32_ubyte0_e32 v1, s8
	v_cvt_f32_i32_e32 v0, s9
	v_rcp_iflag_f32_e32 v2, v1
	s_ashr_i32 s4, s9, 30
	s_or_b32 s14, s4, 1
	v_mul_f32_e32 v2, v0, v2
	v_trunc_f32_e32 v2, v2
	v_fma_f32 v0, -v2, v1, v0
	v_cvt_i32_f32_e32 v2, v2
	v_cmp_ge_f32_e64 s[4:5], |v0|, v1
	s_and_b64 s[4:5], s[4:5], exec
	s_cselect_b32 s4, s14, 0
	v_readfirstlane_b32 s5, v2
	s_add_i32 s5, s5, s4
	s_sext_i32_i8 s4, s5
	s_mul_i32 s5, s5, s8
	s_sub_i32 s5, s9, s5
	s_sext_i32_i8 s5, s5
	s_add_i32 s72, s7, s5

.LBB0_389:
	s_ashr_i32 s69, s68, 31
	s_lshl_b64 s[2:3], s[68:69], 20
	s_add_u32 s2, s22, s2
	s_addc_u32 s3, s23, s3
	s_and_b64 s[6:7], s[38:39], exec
	s_cselect_b32 s5, s3, s89
	s_cselect_b32 s6, s2, s88
	s_ashr_i32 s55, s54, 31
	s_lshl_b64 s[62:63], s[54:55], 20
	s_add_u32 s74, s14, s62
	s_addc_u32 s75, s15, s63
	s_and_b64 s[62:63], s[38:39], exec
	s_cselect_b32 s7, s75, s83
	s_cselect_b32 s33, s74, s82
	s_add_u32 s49, s82, 0x100
	s_addc_u32 s51, s83, 0
	s_add_u32 vcc_lo, s88, 0x80080
	v_mov_b32_e32 v0, 0
	s_addc_u32 vcc_hi, s89, 0
	s_mov_b32 s55, -2
	s_waitcnt lgkmcnt(0)
	v_lshrrev_b32_e32 v0, 8, v180
	v_and_b32_e32 v0, 1, v0
	v_lshlrev_b32_e32 v0, 6, v0
	v_and_b32_e32 v1, 15, v180
	v_or_b32_e32 v0, v0, v1
	v_lshlrev_b32_e32 v0, 13, v0
	v_lshrrev_b32_e32 v1, 6, v180
	v_and_b32_e32 v1, 3, v1
	v_lshl_or_b32 v0, v1, 7, v0
	v_lshrrev_b32_e32 v1, 4, v180
	v_and_b32_e32 v1, 3, v1
	v_lshl_or_b32 v0, v1, 4, v0
	s_cmp_gt_u32 s72, 31
	s_cbranch_scc1 .Lpre_lru_s
	s_lshl_b32 s32, s72, 21
	s_add_u32 s100, s26, s32
	s_addc_u32 s101, s27, 0
	s_branch .Lpre_lru_go
.Lpre_lru_s:
	s_sub_u32 s32, s72, 32
	s_lshl_b32 s32, s32, 21
	s_add_u32 s100, s30, s32
	s_addc_u32 s101, s31, 0
.Lpre_lru_go:
	s_lshl_b32 s32, s4, 10
	s_add_u32 s100, s100, s32
	s_addc_u32 s101, s101, 0
	global_load_dwordx4 v[140:143], v0, s[100:101]
	global_load_dwordx4 v[136:139], v0, s[100:101] offset:64
	global_load_dwordx4 v[132:135], v0, s[100:101] offset:512
	global_load_dwordx4 v[128:131], v0, s[100:101] offset:576
	s_add_u32 s100, s100, 0x20000
	s_addc_u32 s101, s101, 0
	global_load_dwordx4 v[124:127], v0, s[100:101]
	global_load_dwordx4 v[120:123], v0, s[100:101] offset:64
	global_load_dwordx4 v[116:119], v0, s[100:101] offset:512
	global_load_dwordx4 v[112:115], v0, s[100:101] offset:576
	s_add_u32 s100, s100, 0x20000
	s_addc_u32 s101, s101, 0
	global_load_dwordx4 v[108:111], v0, s[100:101]
	global_load_dwordx4 v[104:107], v0, s[100:101] offset:64
	global_load_dwordx4 v[100:103], v0, s[100:101] offset:512
	global_load_dwordx4 v[96:99], v0, s[100:101] offset:576
	s_add_u32 s100, s100, 0x20000
	s_addc_u32 s101, s101, 0
	global_load_dwordx4 v[92:95], v0, s[100:101]
	global_load_dwordx4 v[88:91], v0, s[100:101] offset:64
	global_load_dwordx4 v[84:87], v0, s[100:101] offset:512
	global_load_dwordx4 v[80:83], v0, s[100:101] offset:576
	s_add_u32 s100, s100, 0xa0000
	s_addc_u32 s101, s101, 0
	global_load_dwordx4 v[76:79], v0, s[100:101]
	global_load_dwordx4 v[72:75], v0, s[100:101] offset:64
	global_load_dwordx4 v[68:71], v0, s[100:101] offset:512
	global_load_dwordx4 v[64:67], v0, s[100:101] offset:576
	s_add_u32 s100, s100, 0x20000
	s_addc_u32 s101, s101, 0
	global_load_dwordx4 v[60:63], v0, s[100:101]
	global_load_dwordx4 v[56:59], v0, s[100:101] offset:64
	global_load_dwordx4 v[52:55], v0, s[100:101] offset:512
	global_load_dwordx4 v[48:51], v0, s[100:101] offset:576
	s_add_u32 s100, s100, 0x20000
	s_addc_u32 s101, s101, 0
	global_load_dwordx4 v[36:39], v0, s[100:101]
	global_load_dwordx4 v[24:27], v0, s[100:101] offset:64
	global_load_dwordx4 v[20:23], v0, s[100:101] offset:512
	global_load_dwordx4 v[16:19], v0, s[100:101] offset:576
	s_add_u32 s100, s100, 0x20000
	s_addc_u32 s101, s101, 0
	global_load_dwordx4 v[12:15], v0, s[100:101]
	global_load_dwordx4 v[8:11], v0, s[100:101] offset:64
	global_load_dwordx4 v[4:7], v0, s[100:101] offset:512
	global_load_dwordx4 v[0:3], v0, s[100:101] offset:576
	s_waitcnt vmcnt(0)

.LBB0_393:
	v_lshl_or_b32 v168, s4, 8, v179
	s_andn2_b64 vcc, exec, s[20:21]
	v_ashrrev_i32_e32 v169, 31, v168
	s_cbranch_vccnz .LBB0_395
	v_lshl_add_u64 v[28:29], v[168:169], 2, s[34:35]
	global_load_dwordx4 v[44:47], v[28:29], off
	global_load_dwordx4 v[40:43], v[28:29], off offset:64
	global_load_dwordx4 v[32:35], v[28:29], off offset:512
	s_nop 0
	global_load_dwordx4 v[28:31], v[28:29], off offset:576
.LBB0_395:
	v_lshl_add_u32 v170, s72, 8, v146
	v_cmp_lt_i32_e32 vcc, s70, v170
	s_and_saveexec_b64 s[4:5], vcc
	s_xor_b64 s[4:5], exec, s[4:5]
	v_add_u32_e32 v144, 0xffffe000, v170
	v_lshlrev_b64 v[172:173], 13, v[144:145]
	v_mov_b32_e32 v171, v145
	v_lshl_add_u64 v[174:175], s[30:31], 0, v[172:173]
	v_lshlrev_b64 v[176:177], 11, v[170:171]
	s_andn2_saveexec_b64 s[4:5], s[4:5]
	v_ashrrev_i32_e32 v171, 31, v170
	v_lshlrev_b64 v[172:173], 13, v[170:171]
	v_lshlrev_b64 v[176:177], 11, v[170:171]
	v_lshl_add_u64 v[174:175], s[26:27], 0, v[172:173]
	s_or_b64 exec, exec, s[4:5]
	v_lshlrev_b64 v[172:173], 2, v[168:169]
	v_lshl_add_u64 v[174:175], v[174:175], 0, v[172:173]
	v_lshl_add_u64 v[176:177], v[176:177], 2, s[26:27]
	s_mov_b64 s[4:5], -1
	s_and_b64 vcc, exec, s[18:19]
	v_lshl_add_u64 v[176:177], v[176:177], 0, v[172:173]
	s_waitcnt vmcnt(0) lgkmcnt(0)
	global_store_dwordx4 v[176:177], v[140:143], off
	s_cbranch_vccz .LBB0_401
	s_mov_b64 s[4:5], 0
	s_waitcnt lgkmcnt(0)
	global_store_dwordx4 v[176:177], v[136:139], off offset:64
	s_waitcnt lgkmcnt(0)
	global_store_dwordx4 v[176:177], v[132:135], off offset:512
	s_waitcnt lgkmcnt(0)
	global_store_dwordx4 v[176:177], v[128:131], off offset:576
.LBB0_401:
	s_andn2_b64 vcc, exec, s[4:5]
	s_cbranch_vccnz .LBB0_405
	v_mul_f32_e32 v144, v141, v141
	v_fmac_f32_e32 v144, v140, v140
	v_mul_f32_e32 v191, v143, v143
	v_mul_f32_e32 v140, v44, v140
	v_mul_f32_e32 v141, v45, v141
	v_fmac_f32_e32 v191, v142, v142
	v_cvt_pk_bf16_f32 v140, v140, v141
	v_mul_f32_e32 v141, v46, v142
	v_mul_f32_e32 v142, v47, v143
	v_cvt_pk_bf16_f32 v141, v141, v142
	v_lshlrev_b64 v[142:143], 12, v[170:171]
	v_lshl_add_u64 v[142:143], s[28:29], 0, v[142:143]
	v_lshl_add_u64 v[192:193], v[168:169], 1, v[142:143]
	global_store_dwordx2 v[192:193], v[140:141], off
	v_add_f32_e32 v144, v144, v191
	s_waitcnt lgkmcnt(0)
	v_mul_f32_e32 v140, v137, v137
	global_store_dwordx4 v[176:177], v[136:139], off offset:64
	v_fmac_f32_e32 v140, v136, v136
	v_mul_f32_e32 v141, v139, v139
	v_mul_f32_e32 v136, v40, v136
	v_mul_f32_e32 v137, v41, v137
	v_cvt_pk_bf16_f32 v136, v136, v137
	v_mul_f32_e32 v137, v42, v138
	v_fmac_f32_e32 v141, v138, v138
	v_mul_f32_e32 v138, v43, v139
	v_cvt_pk_bf16_f32 v137, v137, v138
	global_store_dwordx2 v[192:193], v[136:137], off offset:32
	v_add_f32_e32 v140, v140, v141
	v_add_f32_e32 v140, v144, v140
	s_waitcnt lgkmcnt(0)
	v_mul_f32_e32 v136, v133, v133
	global_store_dwordx4 v[176:177], v[132:135], off offset:512
	v_fmac_f32_e32 v136, v132, v132
	v_mul_f32_e32 v137, v135, v135
	v_mul_f32_e32 v132, v32, v132
	v_mul_f32_e32 v133, v33, v133
	v_cvt_pk_bf16_f32 v132, v132, v133
	v_mul_f32_e32 v133, v34, v134
	v_fmac_f32_e32 v137, v134, v134
	v_mul_f32_e32 v134, v35, v135
	v_cvt_pk_bf16_f32 v133, v133, v134
	global_store_dwordx2 v[192:193], v[132:133], off offset:256
	v_add_f32_e32 v136, v136, v137
	v_add_f32_e32 v136, v140, v136
	s_waitcnt lgkmcnt(0)
	global_store_dwordx4 v[176:177], v[128:131], off offset:576
	v_mul_f32_e32 v133, v29, v129
	v_mul_f32_e32 v132, v28, v128
	v_mul_f32_e32 v129, v129, v129
	v_fmac_f32_e32 v129, v128, v128
	v_mul_f32_e32 v128, v131, v131
	v_cvt_pk_bf16_f32 v132, v132, v133
	v_mul_f32_e32 v133, v30, v130
	v_fmac_f32_e32 v128, v130, v130
	v_and_b32_e32 v130, 64, v182
	v_add_f32_e32 v128, v129, v128
	v_xor_b32_e32 v129, 16, v182
	v_add_u32_e32 v130, 64, v130
	v_cmp_lt_i32_e32 vcc, v129, v130
	v_add_f32_e32 v128, v136, v128
	v_mul_f32_e32 v134, v31, v131
	v_cndmask_b32_e32 v129, v182, v129, vcc
	v_lshlrev_b32_e32 v129, 2, v129
	ds_bpermute_b32 v129, v129, v128
	v_cvt_pk_bf16_f32 v133, v133, v134
	global_store_dwordx2 v[192:193], v[132:133], off offset:288
	s_waitcnt lgkmcnt(0)
	v_add_f32_e32 v128, v128, v129
	v_xor_b32_e32 v129, 32, v182
	v_cmp_lt_i32_e32 vcc, v129, v130
	s_nop 1
	v_cndmask_b32_e32 v129, v182, v129, vcc
	v_lshlrev_b32_e32 v129, 2, v129
	ds_bpermute_b32 v129, v129, v128
	s_and_saveexec_b64 s[4:5], s[36:37]
	s_cbranch_execz .LBB0_404
	v_lshl_add_u64 v[130:131], v[170:171], 2, s[40:41]
	s_waitcnt lgkmcnt(0)
	v_add_f32_e32 v128, v128, v129
	global_atomic_add_f32 v[130:131], v128, off

.LBB0_405:
	s_waitcnt lgkmcnt(0)
	v_or_b32_e32 v128, 16, v170
	v_cmp_lt_i32_e32 vcc, s70, v128
	s_and_saveexec_b64 s[4:5], vcc
	s_xor_b64 s[4:5], exec, s[4:5]
	v_add_u32_e32 v144, 0xffffe010, v170
	v_lshlrev_b64 v[130:131], 13, v[144:145]
	v_mov_b32_e32 v129, v145
	v_lshl_add_u64 v[130:131], s[30:31], 0, v[130:131]
	v_lshlrev_b64 v[132:133], 11, v[128:129]
	s_andn2_saveexec_b64 s[4:5], s[4:5]
	v_ashrrev_i32_e32 v129, 31, v128
	v_lshlrev_b64 v[130:131], 13, v[128:129]
	v_lshlrev_b64 v[132:133], 11, v[128:129]
	v_lshl_add_u64 v[130:131], s[26:27], 0, v[130:131]
	s_or_b64 exec, exec, s[4:5]
	v_lshl_add_u64 v[130:131], v[130:131], 0, v[172:173]
	v_lshl_add_u64 v[132:133], v[132:133], 2, s[26:27]
	s_mov_b64 s[4:5], -1
	s_and_b64 vcc, exec, s[18:19]
	v_lshl_add_u64 v[132:133], v[132:133], 0, v[172:173]
	s_waitcnt lgkmcnt(0)
	global_store_dwordx4 v[132:133], v[124:127], off
	s_cbranch_vccz .LBB0_411
	s_mov_b64 s[4:5], 0
	s_waitcnt lgkmcnt(0)
	global_store_dwordx4 v[132:133], v[120:123], off offset:64
	s_waitcnt lgkmcnt(0)
	global_store_dwordx4 v[132:133], v[116:119], off offset:512
	s_waitcnt lgkmcnt(0)
	global_store_dwordx4 v[132:133], v[112:115], off offset:576
.LBB0_411:
	s_andn2_b64 vcc, exec, s[4:5]
	s_cbranch_vccnz .LBB0_415
	v_mul_f32_e32 v134, v125, v125
	v_fmac_f32_e32 v134, v124, v124
	v_mul_f32_e32 v135, v127, v127
	v_mul_f32_e32 v124, v44, v124
	v_mul_f32_e32 v125, v45, v125
	v_fmac_f32_e32 v135, v126, v126
	v_cvt_pk_bf16_f32 v124, v124, v125
	v_mul_f32_e32 v125, v46, v126
	v_mul_f32_e32 v126, v47, v127
	v_cvt_pk_bf16_f32 v125, v125, v126
	v_lshlrev_b64 v[126:127], 12, v[128:129]
	v_lshl_add_u64 v[126:127], s[28:29], 0, v[126:127]
	v_add_f32_e32 v136, v134, v135
	v_lshl_add_u64 v[134:135], v[168:169], 1, v[126:127]
	global_store_dwordx2 v[134:135], v[124:125], off
	s_waitcnt lgkmcnt(0)
	v_mul_f32_e32 v124, v121, v121
	global_store_dwordx4 v[132:133], v[120:123], off offset:64
	v_fmac_f32_e32 v124, v120, v120
	v_mul_f32_e32 v125, v123, v123
	v_mul_f32_e32 v120, v40, v120
	v_mul_f32_e32 v121, v41, v121
	v_cvt_pk_bf16_f32 v120, v120, v121
	v_mul_f32_e32 v121, v42, v122
	v_fmac_f32_e32 v125, v122, v122
	v_mul_f32_e32 v122, v43, v123
	v_cvt_pk_bf16_f32 v121, v121, v122
	global_store_dwordx2 v[134:135], v[120:121], off offset:32
	v_add_f32_e32 v124, v124, v125
	v_add_f32_e32 v124, v136, v124
	s_waitcnt lgkmcnt(0)
	v_mul_f32_e32 v120, v117, v117
	global_store_dwordx4 v[132:133], v[116:119], off offset:512
	v_fmac_f32_e32 v120, v116, v116
	v_mul_f32_e32 v121, v119, v119
	v_mul_f32_e32 v116, v32, v116
	v_mul_f32_e32 v117, v33, v117
	v_cvt_pk_bf16_f32 v116, v116, v117
	v_mul_f32_e32 v117, v34, v118
	v_fmac_f32_e32 v121, v118, v118
	v_mul_f32_e32 v118, v35, v119
	v_cvt_pk_bf16_f32 v117, v117, v118
	global_store_dwordx2 v[134:135], v[116:117], off offset:256
	v_add_f32_e32 v120, v120, v121
	v_add_f32_e32 v120, v124, v120
	s_waitcnt lgkmcnt(0)
	global_store_dwordx4 v[132:133], v[112:115], off offset:576
	v_mul_f32_e32 v117, v29, v113
	v_mul_f32_e32 v116, v28, v112
	v_mul_f32_e32 v113, v113, v113
	v_fmac_f32_e32 v113, v112, v112
	v_mul_f32_e32 v112, v115, v115
	v_cvt_pk_bf16_f32 v116, v116, v117
	v_mul_f32_e32 v117, v30, v114
	v_fmac_f32_e32 v112, v114, v114
	v_and_b32_e32 v114, 64, v182
	v_add_f32_e32 v112, v113, v112
	v_xor_b32_e32 v113, 16, v182
	v_add_u32_e32 v114, 64, v114
	v_cmp_lt_i32_e32 vcc, v113, v114
	v_add_f32_e32 v112, v120, v112
	v_mul_f32_e32 v118, v31, v115
	v_cndmask_b32_e32 v113, v182, v113, vcc
	v_lshlrev_b32_e32 v113, 2, v113
	ds_bpermute_b32 v113, v113, v112
	v_cvt_pk_bf16_f32 v117, v117, v118
	global_store_dwordx2 v[134:135], v[116:117], off offset:288
	s_waitcnt lgkmcnt(0)
	v_add_f32_e32 v112, v112, v113
	v_xor_b32_e32 v113, 32, v182
	v_cmp_lt_i32_e32 vcc, v113, v114
	s_nop 1
	v_cndmask_b32_e32 v113, v182, v113, vcc
	v_lshlrev_b32_e32 v113, 2, v113
	ds_bpermute_b32 v113, v113, v112
	s_and_saveexec_b64 s[4:5], s[36:37]
	s_cbranch_execz .LBB0_414
	v_lshl_add_u64 v[114:115], v[128:129], 2, s[40:41]
	s_waitcnt lgkmcnt(0)
	v_add_f32_e32 v112, v112, v113
	global_atomic_add_f32 v[114:115], v112, off

.LBB0_415:
	s_waitcnt lgkmcnt(0)
	v_or_b32_e32 v112, 32, v170
	v_cmp_lt_i32_e32 vcc, s70, v112
	s_and_saveexec_b64 s[4:5], vcc
	s_xor_b64 s[4:5], exec, s[4:5]
	v_add_u32_e32 v144, 0xffffe020, v170
	v_lshlrev_b64 v[114:115], 13, v[144:145]
	v_mov_b32_e32 v113, v145
	v_lshl_add_u64 v[114:115], s[30:31], 0, v[114:115]
	v_lshlrev_b64 v[116:117], 11, v[112:113]
	s_andn2_saveexec_b64 s[4:5], s[4:5]
	v_ashrrev_i32_e32 v113, 31, v112
	v_lshlrev_b64 v[114:115], 13, v[112:113]
	v_lshlrev_b64 v[116:117], 11, v[112:113]
	v_lshl_add_u64 v[114:115], s[26:27], 0, v[114:115]
	s_or_b64 exec, exec, s[4:5]
	v_lshl_add_u64 v[114:115], v[114:115], 0, v[172:173]
	v_lshl_add_u64 v[116:117], v[116:117], 2, s[26:27]
	s_mov_b64 s[4:5], -1
	s_and_b64 vcc, exec, s[18:19]
	v_lshl_add_u64 v[116:117], v[116:117], 0, v[172:173]
	s_waitcnt lgkmcnt(0)
	global_store_dwordx4 v[116:117], v[108:111], off
	s_cbranch_vccz .LBB0_421
	s_mov_b64 s[4:5], 0
	s_waitcnt lgkmcnt(0)
	global_store_dwordx4 v[116:117], v[104:107], off offset:64
	s_waitcnt lgkmcnt(0)
	global_store_dwordx4 v[116:117], v[100:103], off offset:512
	s_waitcnt lgkmcnt(0)
	global_store_dwordx4 v[116:117], v[96:99], off offset:576
.LBB0_421:
	s_andn2_b64 vcc, exec, s[4:5]
	s_cbranch_vccnz .LBB0_425
	v_mul_f32_e32 v118, v109, v109
	v_fmac_f32_e32 v118, v108, v108
	v_mul_f32_e32 v119, v111, v111
	v_mul_f32_e32 v108, v44, v108
	v_mul_f32_e32 v109, v45, v109
	v_fmac_f32_e32 v119, v110, v110
	v_cvt_pk_bf16_f32 v108, v108, v109
	v_mul_f32_e32 v109, v46, v110
	v_mul_f32_e32 v110, v47, v111
	v_cvt_pk_bf16_f32 v109, v109, v110
	v_lshlrev_b64 v[110:111], 12, v[112:113]
	v_lshl_add_u64 v[110:111], s[28:29], 0, v[110:111]
	v_add_f32_e32 v120, v118, v119
	v_lshl_add_u64 v[118:119], v[168:169], 1, v[110:111]
	global_store_dwordx2 v[118:119], v[108:109], off
	s_waitcnt lgkmcnt(0)
	v_mul_f32_e32 v108, v105, v105
	global_store_dwordx4 v[116:117], v[104:107], off offset:64
	v_fmac_f32_e32 v108, v104, v104
	v_mul_f32_e32 v109, v107, v107
	v_mul_f32_e32 v104, v40, v104
	v_mul_f32_e32 v105, v41, v105
	v_cvt_pk_bf16_f32 v104, v104, v105
	v_mul_f32_e32 v105, v42, v106
	v_fmac_f32_e32 v109, v106, v106
	v_mul_f32_e32 v106, v43, v107
	v_cvt_pk_bf16_f32 v105, v105, v106
	global_store_dwordx2 v[118:119], v[104:105], off offset:32
	v_add_f32_e32 v108, v108, v109
	v_add_f32_e32 v108, v120, v108
	s_waitcnt lgkmcnt(0)
	v_mul_f32_e32 v104, v101, v101
	global_store_dwordx4 v[116:117], v[100:103], off offset:512
	v_fmac_f32_e32 v104, v100, v100
	v_mul_f32_e32 v105, v103, v103
	v_mul_f32_e32 v100, v32, v100
	v_mul_f32_e32 v101, v33, v101
	v_cvt_pk_bf16_f32 v100, v100, v101
	v_mul_f32_e32 v101, v34, v102
	v_fmac_f32_e32 v105, v102, v102
	v_mul_f32_e32 v102, v35, v103
	v_cvt_pk_bf16_f32 v101, v101, v102
	global_store_dwordx2 v[118:119], v[100:101], off offset:256
	v_add_f32_e32 v104, v104, v105
	v_add_f32_e32 v104, v108, v104
	s_waitcnt lgkmcnt(0)
	global_store_dwordx4 v[116:117], v[96:99], off offset:576
	v_mul_f32_e32 v101, v29, v97
	v_mul_f32_e32 v100, v28, v96
	v_mul_f32_e32 v97, v97, v97
	v_fmac_f32_e32 v97, v96, v96
	v_mul_f32_e32 v96, v99, v99
	v_cvt_pk_bf16_f32 v100, v100, v101
	v_mul_f32_e32 v101, v30, v98
	v_fmac_f32_e32 v96, v98, v98
	v_and_b32_e32 v98, 64, v182
	v_add_f32_e32 v96, v97, v96
	v_xor_b32_e32 v97, 16, v182
	v_add_u32_e32 v98, 64, v98
	v_cmp_lt_i32_e32 vcc, v97, v98
	v_add_f32_e32 v96, v104, v96
	v_mul_f32_e32 v102, v31, v99
	v_cndmask_b32_e32 v97, v182, v97, vcc
	v_lshlrev_b32_e32 v97, 2, v97
	ds_bpermute_b32 v97, v97, v96
	v_cvt_pk_bf16_f32 v101, v101, v102
	global_store_dwordx2 v[118:119], v[100:101], off offset:288
	s_waitcnt lgkmcnt(0)
	v_add_f32_e32 v96, v96, v97
	v_xor_b32_e32 v97, 32, v182
	v_cmp_lt_i32_e32 vcc, v97, v98
	s_nop 1
	v_cndmask_b32_e32 v97, v182, v97, vcc
	v_lshlrev_b32_e32 v97, 2, v97
	ds_bpermute_b32 v97, v97, v96
	s_and_saveexec_b64 s[4:5], s[36:37]
	s_cbranch_execz .LBB0_424
	v_lshl_add_u64 v[98:99], v[112:113], 2, s[40:41]
	s_waitcnt lgkmcnt(0)
	v_add_f32_e32 v96, v96, v97
	global_atomic_add_f32 v[98:99], v96, off

.LBB0_425:
	s_waitcnt lgkmcnt(0)
	v_or_b32_e32 v96, 48, v170
	v_cmp_lt_i32_e32 vcc, s70, v96
	s_and_saveexec_b64 s[4:5], vcc
	s_xor_b64 s[4:5], exec, s[4:5]
	v_add_u32_e32 v144, 0xffffe030, v170
	v_lshlrev_b64 v[98:99], 13, v[144:145]
	v_mov_b32_e32 v97, v145
	v_lshl_add_u64 v[98:99], s[30:31], 0, v[98:99]
	v_lshlrev_b64 v[100:101], 11, v[96:97]
	s_andn2_saveexec_b64 s[4:5], s[4:5]
	v_ashrrev_i32_e32 v97, 31, v96
	v_lshlrev_b64 v[98:99], 13, v[96:97]
	v_lshlrev_b64 v[100:101], 11, v[96:97]
	v_lshl_add_u64 v[98:99], s[26:27], 0, v[98:99]
	s_or_b64 exec, exec, s[4:5]
	v_lshl_add_u64 v[98:99], v[98:99], 0, v[172:173]
	v_lshl_add_u64 v[100:101], v[100:101], 2, s[26:27]
	s_mov_b64 s[4:5], -1
	s_and_b64 vcc, exec, s[18:19]
	v_lshl_add_u64 v[100:101], v[100:101], 0, v[172:173]
	s_waitcnt lgkmcnt(0)
	global_store_dwordx4 v[100:101], v[92:95], off
	s_cbranch_vccz .LBB0_431
	s_mov_b64 s[4:5], 0
	s_waitcnt lgkmcnt(0)
	global_store_dwordx4 v[100:101], v[88:91], off offset:64
	s_waitcnt lgkmcnt(0)
	global_store_dwordx4 v[100:101], v[84:87], off offset:512
	s_waitcnt lgkmcnt(0)
	global_store_dwordx4 v[100:101], v[80:83], off offset:576
.LBB0_431:
	s_andn2_b64 vcc, exec, s[4:5]
	s_cbranch_vccnz .LBB0_435
	v_mul_f32_e32 v102, v93, v93
	v_fmac_f32_e32 v102, v92, v92
	v_mul_f32_e32 v103, v95, v95
	v_mul_f32_e32 v92, v44, v92
	v_mul_f32_e32 v93, v45, v93
	v_fmac_f32_e32 v103, v94, v94
	v_cvt_pk_bf16_f32 v92, v92, v93
	v_mul_f32_e32 v93, v46, v94
	v_mul_f32_e32 v94, v47, v95
	v_cvt_pk_bf16_f32 v93, v93, v94
	v_lshlrev_b64 v[94:95], 12, v[96:97]
	v_lshl_add_u64 v[94:95], s[28:29], 0, v[94:95]
	v_add_f32_e32 v104, v102, v103
	v_lshl_add_u64 v[102:103], v[168:169], 1, v[94:95]
	global_store_dwordx2 v[102:103], v[92:93], off
	s_waitcnt lgkmcnt(0)
	v_mul_f32_e32 v92, v89, v89
	global_store_dwordx4 v[100:101], v[88:91], off offset:64
	v_fmac_f32_e32 v92, v88, v88
	v_mul_f32_e32 v93, v91, v91
	v_mul_f32_e32 v88, v40, v88
	v_mul_f32_e32 v89, v41, v89
	v_cvt_pk_bf16_f32 v88, v88, v89
	v_mul_f32_e32 v89, v42, v90
	v_fmac_f32_e32 v93, v90, v90
	v_mul_f32_e32 v90, v43, v91
	v_cvt_pk_bf16_f32 v89, v89, v90
	global_store_dwordx2 v[102:103], v[88:89], off offset:32
	v_add_f32_e32 v92, v92, v93
	v_add_f32_e32 v92, v104, v92
	s_waitcnt lgkmcnt(0)
	v_mul_f32_e32 v88, v85, v85
	global_store_dwordx4 v[100:101], v[84:87], off offset:512
	v_fmac_f32_e32 v88, v84, v84
	v_mul_f32_e32 v89, v87, v87
	v_mul_f32_e32 v84, v32, v84
	v_mul_f32_e32 v85, v33, v85
	v_cvt_pk_bf16_f32 v84, v84, v85
	v_mul_f32_e32 v85, v34, v86
	v_fmac_f32_e32 v89, v86, v86
	v_mul_f32_e32 v86, v35, v87
	v_cvt_pk_bf16_f32 v85, v85, v86
	global_store_dwordx2 v[102:103], v[84:85], off offset:256
	v_add_f32_e32 v88, v88, v89
	v_add_f32_e32 v88, v92, v88
	s_waitcnt lgkmcnt(0)
	global_store_dwordx4 v[100:101], v[80:83], off offset:576
	v_mul_f32_e32 v85, v29, v81
	v_mul_f32_e32 v84, v28, v80
	v_mul_f32_e32 v81, v81, v81
	v_fmac_f32_e32 v81, v80, v80
	v_mul_f32_e32 v80, v83, v83
	v_cvt_pk_bf16_f32 v84, v84, v85
	v_mul_f32_e32 v85, v30, v82
	v_fmac_f32_e32 v80, v82, v82
	v_and_b32_e32 v82, 64, v182
	v_add_f32_e32 v80, v81, v80
	v_xor_b32_e32 v81, 16, v182
	v_add_u32_e32 v82, 64, v82
	v_cmp_lt_i32_e32 vcc, v81, v82
	v_add_f32_e32 v80, v88, v80
	v_mul_f32_e32 v86, v31, v83
	v_cndmask_b32_e32 v81, v182, v81, vcc
	v_lshlrev_b32_e32 v81, 2, v81
	ds_bpermute_b32 v81, v81, v80
	v_cvt_pk_bf16_f32 v85, v85, v86
	global_store_dwordx2 v[102:103], v[84:85], off offset:288
	s_waitcnt lgkmcnt(0)
	v_add_f32_e32 v80, v80, v81
	v_xor_b32_e32 v81, 32, v182
	v_cmp_lt_i32_e32 vcc, v81, v82
	s_nop 1
	v_cndmask_b32_e32 v81, v182, v81, vcc
	v_lshlrev_b32_e32 v81, 2, v81
	ds_bpermute_b32 v81, v81, v80
	s_and_saveexec_b64 s[4:5], s[36:37]
	s_cbranch_execz .LBB0_434
	v_lshl_add_u64 v[82:83], v[96:97], 2, s[40:41]
	s_waitcnt lgkmcnt(0)
	v_add_f32_e32 v80, v80, v81
	global_atomic_add_f32 v[82:83], v80, off

.LBB0_435:
	s_movk_i32 s4, 0x1f7f
	s_waitcnt lgkmcnt(0)
	v_add_u32_e32 v80, 0x80, v170
	v_cmp_lt_i32_e32 vcc, s4, v170
	s_and_saveexec_b64 s[4:5], vcc
	s_xor_b64 s[4:5], exec, s[4:5]
	v_add_u32_e32 v144, 0xffffe080, v170
	v_lshlrev_b64 v[82:83], 13, v[144:145]
	v_mov_b32_e32 v81, v145
	v_lshl_add_u64 v[82:83], s[30:31], 0, v[82:83]
	v_lshlrev_b64 v[84:85], 11, v[80:81]
	s_andn2_saveexec_b64 s[4:5], s[4:5]
	v_ashrrev_i32_e32 v81, 31, v80
	v_lshlrev_b64 v[82:83], 13, v[80:81]
	v_lshlrev_b64 v[84:85], 11, v[80:81]
	v_lshl_add_u64 v[82:83], s[26:27], 0, v[82:83]
	s_or_b64 exec, exec, s[4:5]
	v_lshl_add_u64 v[82:83], v[82:83], 0, v[172:173]
	v_lshl_add_u64 v[84:85], v[84:85], 2, s[26:27]
	s_mov_b64 s[4:5], -1
	s_and_b64 vcc, exec, s[18:19]
	v_lshl_add_u64 v[84:85], v[84:85], 0, v[172:173]
	s_waitcnt lgkmcnt(0)
	global_store_dwordx4 v[84:85], v[76:79], off
	s_cbranch_vccz .LBB0_441
	s_mov_b64 s[4:5], 0
	s_waitcnt lgkmcnt(0)
	global_store_dwordx4 v[84:85], v[72:75], off offset:64
	s_waitcnt lgkmcnt(0)
	global_store_dwordx4 v[84:85], v[68:71], off offset:512
	s_waitcnt lgkmcnt(0)
	global_store_dwordx4 v[84:85], v[64:67], off offset:576
.LBB0_441:
	s_andn2_b64 vcc, exec, s[4:5]
	s_cbranch_vccnz .LBB0_445
	v_mul_f32_e32 v86, v77, v77
	v_fmac_f32_e32 v86, v76, v76
	v_mul_f32_e32 v87, v79, v79
	v_mul_f32_e32 v76, v44, v76
	v_mul_f32_e32 v77, v45, v77
	v_fmac_f32_e32 v87, v78, v78
	v_cvt_pk_bf16_f32 v76, v76, v77
	v_mul_f32_e32 v77, v46, v78
	v_mul_f32_e32 v78, v47, v79
	v_cvt_pk_bf16_f32 v77, v77, v78
	v_lshlrev_b64 v[78:79], 12, v[80:81]
	v_lshl_add_u64 v[78:79], s[28:29], 0, v[78:79]
	v_add_f32_e32 v88, v86, v87
	v_lshl_add_u64 v[86:87], v[168:169], 1, v[78:79]
	global_store_dwordx2 v[86:87], v[76:77], off
	s_waitcnt lgkmcnt(0)
	v_mul_f32_e32 v76, v73, v73
	global_store_dwordx4 v[84:85], v[72:75], off offset:64
	v_fmac_f32_e32 v76, v72, v72
	v_mul_f32_e32 v77, v75, v75
	v_mul_f32_e32 v72, v40, v72
	v_mul_f32_e32 v73, v41, v73
	v_cvt_pk_bf16_f32 v72, v72, v73
	v_mul_f32_e32 v73, v42, v74
	v_fmac_f32_e32 v77, v74, v74
	v_mul_f32_e32 v74, v43, v75
	v_cvt_pk_bf16_f32 v73, v73, v74
	global_store_dwordx2 v[86:87], v[72:73], off offset:32
	v_add_f32_e32 v76, v76, v77
	v_add_f32_e32 v76, v88, v76
	s_waitcnt lgkmcnt(0)
	v_mul_f32_e32 v72, v69, v69
	global_store_dwordx4 v[84:85], v[68:71], off offset:512
	v_fmac_f32_e32 v72, v68, v68
	v_mul_f32_e32 v73, v71, v71
	v_mul_f32_e32 v68, v32, v68
	v_mul_f32_e32 v69, v33, v69
	v_cvt_pk_bf16_f32 v68, v68, v69
	v_mul_f32_e32 v69, v34, v70
	v_fmac_f32_e32 v73, v70, v70
	v_mul_f32_e32 v70, v35, v71
	v_cvt_pk_bf16_f32 v69, v69, v70
	global_store_dwordx2 v[86:87], v[68:69], off offset:256
	v_add_f32_e32 v72, v72, v73
	v_add_f32_e32 v72, v76, v72
	s_waitcnt lgkmcnt(0)
	global_store_dwordx4 v[84:85], v[64:67], off offset:576
	v_mul_f32_e32 v69, v29, v65
	v_mul_f32_e32 v68, v28, v64
	v_mul_f32_e32 v65, v65, v65
	v_fmac_f32_e32 v65, v64, v64
	v_mul_f32_e32 v64, v67, v67
	v_cvt_pk_bf16_f32 v68, v68, v69
	v_mul_f32_e32 v69, v30, v66
	v_fmac_f32_e32 v64, v66, v66
	v_and_b32_e32 v66, 64, v182
	v_add_f32_e32 v64, v65, v64
	v_xor_b32_e32 v65, 16, v182
	v_add_u32_e32 v66, 64, v66
	v_cmp_lt_i32_e32 vcc, v65, v66
	v_add_f32_e32 v64, v72, v64
	v_mul_f32_e32 v70, v31, v67
	v_cndmask_b32_e32 v65, v182, v65, vcc
	v_lshlrev_b32_e32 v65, 2, v65
	ds_bpermute_b32 v65, v65, v64
	v_cvt_pk_bf16_f32 v69, v69, v70
	global_store_dwordx2 v[86:87], v[68:69], off offset:288
	s_waitcnt lgkmcnt(0)
	v_add_f32_e32 v64, v64, v65
	v_xor_b32_e32 v65, 32, v182
	v_cmp_lt_i32_e32 vcc, v65, v66
	s_nop 1
	v_cndmask_b32_e32 v65, v182, v65, vcc
	v_lshlrev_b32_e32 v65, 2, v65
	ds_bpermute_b32 v65, v65, v64
	s_and_saveexec_b64 s[4:5], s[36:37]
	s_cbranch_execz .LBB0_444
	v_lshl_add_u64 v[66:67], v[80:81], 2, s[40:41]
	s_waitcnt lgkmcnt(0)
	v_add_f32_e32 v64, v64, v65
	global_atomic_add_f32 v[66:67], v64, off

.LBB0_445:
	s_movk_i32 s4, 0x1f6f
	s_waitcnt lgkmcnt(0)
	v_add_u32_e32 v64, 0x90, v170
	v_cmp_lt_i32_e32 vcc, s4, v170
	s_and_saveexec_b64 s[4:5], vcc
	s_xor_b64 s[4:5], exec, s[4:5]
	v_add_u32_e32 v144, 0xffffe090, v170
	v_lshlrev_b64 v[66:67], 13, v[144:145]
	v_mov_b32_e32 v65, v145
	v_lshl_add_u64 v[66:67], s[30:31], 0, v[66:67]
	v_lshlrev_b64 v[68:69], 11, v[64:65]
	s_andn2_saveexec_b64 s[4:5], s[4:5]
	v_ashrrev_i32_e32 v65, 31, v64
	v_lshlrev_b64 v[66:67], 13, v[64:65]
	v_lshlrev_b64 v[68:69], 11, v[64:65]
	v_lshl_add_u64 v[66:67], s[26:27], 0, v[66:67]
	s_or_b64 exec, exec, s[4:5]
	v_lshl_add_u64 v[66:67], v[66:67], 0, v[172:173]
	v_lshl_add_u64 v[68:69], v[68:69], 2, s[26:27]
	s_mov_b64 s[4:5], -1
	s_and_b64 vcc, exec, s[18:19]
	v_lshl_add_u64 v[68:69], v[68:69], 0, v[172:173]
	s_waitcnt lgkmcnt(0)
	global_store_dwordx4 v[68:69], v[60:63], off
	s_cbranch_vccz .LBB0_451
	s_mov_b64 s[4:5], 0
	s_waitcnt lgkmcnt(0)
	global_store_dwordx4 v[68:69], v[56:59], off offset:64
	s_waitcnt lgkmcnt(0)
	global_store_dwordx4 v[68:69], v[52:55], off offset:512
	s_waitcnt lgkmcnt(0)
	global_store_dwordx4 v[68:69], v[48:51], off offset:576
.LBB0_451:
	s_andn2_b64 vcc, exec, s[4:5]
	s_cbranch_vccnz .LBB0_455
	v_mul_f32_e32 v70, v61, v61
	v_fmac_f32_e32 v70, v60, v60
	v_mul_f32_e32 v71, v63, v63
	v_mul_f32_e32 v60, v44, v60
	v_mul_f32_e32 v61, v45, v61
	v_fmac_f32_e32 v71, v62, v62
	v_cvt_pk_bf16_f32 v60, v60, v61
	v_mul_f32_e32 v61, v46, v62
	v_mul_f32_e32 v62, v47, v63
	v_cvt_pk_bf16_f32 v61, v61, v62
	v_lshlrev_b64 v[62:63], 12, v[64:65]
	v_lshl_add_u64 v[62:63], s[28:29], 0, v[62:63]
	v_add_f32_e32 v72, v70, v71
	v_lshl_add_u64 v[70:71], v[168:169], 1, v[62:63]
	global_store_dwordx2 v[70:71], v[60:61], off
	s_waitcnt lgkmcnt(0)
	v_mul_f32_e32 v60, v57, v57
	global_store_dwordx4 v[68:69], v[56:59], off offset:64
	v_fmac_f32_e32 v60, v56, v56
	v_mul_f32_e32 v61, v59, v59
	v_mul_f32_e32 v56, v40, v56
	v_mul_f32_e32 v57, v41, v57
	v_cvt_pk_bf16_f32 v56, v56, v57
	v_mul_f32_e32 v57, v42, v58
	v_fmac_f32_e32 v61, v58, v58
	v_mul_f32_e32 v58, v43, v59
	v_cvt_pk_bf16_f32 v57, v57, v58
	global_store_dwordx2 v[70:71], v[56:57], off offset:32
	v_add_f32_e32 v60, v60, v61
	v_add_f32_e32 v60, v72, v60
	s_waitcnt lgkmcnt(0)
	v_mul_f32_e32 v56, v53, v53
	global_store_dwordx4 v[68:69], v[52:55], off offset:512
	v_fmac_f32_e32 v56, v52, v52
	v_mul_f32_e32 v57, v55, v55
	v_mul_f32_e32 v52, v32, v52
	v_mul_f32_e32 v53, v33, v53
	v_cvt_pk_bf16_f32 v52, v52, v53
	v_mul_f32_e32 v53, v34, v54
	v_fmac_f32_e32 v57, v54, v54
	v_mul_f32_e32 v54, v35, v55
	v_cvt_pk_bf16_f32 v53, v53, v54
	global_store_dwordx2 v[70:71], v[52:53], off offset:256
	v_add_f32_e32 v56, v56, v57
	v_add_f32_e32 v56, v60, v56
	s_waitcnt lgkmcnt(0)
	global_store_dwordx4 v[68:69], v[48:51], off offset:576
	v_mul_f32_e32 v53, v29, v49
	v_mul_f32_e32 v52, v28, v48
	v_mul_f32_e32 v49, v49, v49
	v_fmac_f32_e32 v49, v48, v48
	v_mul_f32_e32 v48, v51, v51
	v_cvt_pk_bf16_f32 v52, v52, v53
	v_mul_f32_e32 v53, v30, v50
	v_fmac_f32_e32 v48, v50, v50
	v_and_b32_e32 v50, 64, v182
	v_add_f32_e32 v48, v49, v48
	v_xor_b32_e32 v49, 16, v182
	v_add_u32_e32 v50, 64, v50
	v_cmp_lt_i32_e32 vcc, v49, v50
	v_add_f32_e32 v48, v56, v48
	v_mul_f32_e32 v54, v31, v51
	v_cndmask_b32_e32 v49, v182, v49, vcc
	v_lshlrev_b32_e32 v49, 2, v49
	ds_bpermute_b32 v49, v49, v48
	v_cvt_pk_bf16_f32 v53, v53, v54
	global_store_dwordx2 v[70:71], v[52:53], off offset:288
	s_waitcnt lgkmcnt(0)
	v_add_f32_e32 v48, v48, v49
	v_xor_b32_e32 v49, 32, v182
	v_cmp_lt_i32_e32 vcc, v49, v50
	s_nop 1
	v_cndmask_b32_e32 v49, v182, v49, vcc
	v_lshlrev_b32_e32 v49, 2, v49
	ds_bpermute_b32 v49, v49, v48
	s_and_saveexec_b64 s[4:5], s[36:37]
	s_cbranch_execz .LBB0_454
	v_lshl_add_u64 v[50:51], v[64:65], 2, s[40:41]
	s_waitcnt lgkmcnt(0)
	v_add_f32_e32 v48, v48, v49
	global_atomic_add_f32 v[50:51], v48, off

.LBB0_455:
	s_movk_i32 s4, 0x1f5f
	s_waitcnt lgkmcnt(0)
	v_add_u32_e32 v48, 0xa0, v170
	v_cmp_lt_i32_e32 vcc, s4, v170
	s_and_saveexec_b64 s[4:5], vcc
	s_xor_b64 s[4:5], exec, s[4:5]
	v_add_u32_e32 v144, 0xffffe0a0, v170
	v_lshlrev_b64 v[50:51], 13, v[144:145]
	v_mov_b32_e32 v49, v145
	v_lshl_add_u64 v[50:51], s[30:31], 0, v[50:51]
	v_lshlrev_b64 v[52:53], 11, v[48:49]
	s_andn2_saveexec_b64 s[4:5], s[4:5]
	v_ashrrev_i32_e32 v49, 31, v48
	v_lshlrev_b64 v[50:51], 13, v[48:49]
	v_lshlrev_b64 v[52:53], 11, v[48:49]
	v_lshl_add_u64 v[50:51], s[26:27], 0, v[50:51]
	s_or_b64 exec, exec, s[4:5]
	v_lshl_add_u64 v[50:51], v[50:51], 0, v[172:173]
	v_lshl_add_u64 v[52:53], v[52:53], 2, s[26:27]
	s_mov_b64 s[4:5], -1
	s_and_b64 vcc, exec, s[18:19]
	v_lshl_add_u64 v[52:53], v[52:53], 0, v[172:173]
	s_waitcnt lgkmcnt(0)
	global_store_dwordx4 v[52:53], v[36:39], off
	s_cbranch_vccz .LBB0_461
	s_mov_b64 s[4:5], 0
	s_waitcnt lgkmcnt(0)
	global_store_dwordx4 v[52:53], v[24:27], off offset:64
	s_waitcnt lgkmcnt(0)
	global_store_dwordx4 v[52:53], v[20:23], off offset:512
	s_waitcnt lgkmcnt(0)
	global_store_dwordx4 v[52:53], v[16:19], off offset:576
.LBB0_461:
	s_andn2_b64 vcc, exec, s[4:5]
	s_cbranch_vccnz .LBB0_465
	v_mul_f32_e32 v54, v37, v37
	v_fmac_f32_e32 v54, v36, v36
	v_mul_f32_e32 v55, v39, v39
	v_mul_f32_e32 v36, v44, v36
	v_mul_f32_e32 v37, v45, v37
	v_fmac_f32_e32 v55, v38, v38
	v_cvt_pk_bf16_f32 v36, v36, v37
	v_mul_f32_e32 v37, v46, v38
	v_mul_f32_e32 v38, v47, v39
	v_cvt_pk_bf16_f32 v37, v37, v38
	v_lshlrev_b64 v[38:39], 12, v[48:49]
	v_lshl_add_u64 v[38:39], s[28:29], 0, v[38:39]
	v_add_f32_e32 v56, v54, v55
	v_lshl_add_u64 v[54:55], v[168:169], 1, v[38:39]
	global_store_dwordx2 v[54:55], v[36:37], off
	s_waitcnt lgkmcnt(0)
	v_mul_f32_e32 v36, v25, v25
	global_store_dwordx4 v[52:53], v[24:27], off offset:64
	v_fmac_f32_e32 v36, v24, v24
	v_mul_f32_e32 v37, v27, v27
	v_mul_f32_e32 v24, v40, v24
	v_mul_f32_e32 v25, v41, v25
	v_cvt_pk_bf16_f32 v24, v24, v25
	v_mul_f32_e32 v25, v42, v26
	v_fmac_f32_e32 v37, v26, v26
	v_mul_f32_e32 v26, v43, v27
	v_cvt_pk_bf16_f32 v25, v25, v26
	global_store_dwordx2 v[54:55], v[24:25], off offset:32
	v_add_f32_e32 v36, v36, v37
	v_add_f32_e32 v36, v56, v36
	s_waitcnt lgkmcnt(0)
	v_mul_f32_e32 v24, v21, v21
	global_store_dwordx4 v[52:53], v[20:23], off offset:512
	v_fmac_f32_e32 v24, v20, v20
	v_mul_f32_e32 v25, v23, v23
	v_mul_f32_e32 v20, v32, v20
	v_mul_f32_e32 v21, v33, v21
	v_cvt_pk_bf16_f32 v20, v20, v21
	v_mul_f32_e32 v21, v34, v22
	v_fmac_f32_e32 v25, v22, v22
	v_mul_f32_e32 v22, v35, v23
	v_cvt_pk_bf16_f32 v21, v21, v22
	global_store_dwordx2 v[54:55], v[20:21], off offset:256
	v_add_f32_e32 v24, v24, v25
	v_add_f32_e32 v24, v36, v24
	s_waitcnt lgkmcnt(0)
	global_store_dwordx4 v[52:53], v[16:19], off offset:576
	v_mul_f32_e32 v21, v29, v17
	v_mul_f32_e32 v20, v28, v16
	v_mul_f32_e32 v17, v17, v17
	v_fmac_f32_e32 v17, v16, v16
	v_mul_f32_e32 v16, v19, v19
	v_cvt_pk_bf16_f32 v20, v20, v21
	v_mul_f32_e32 v21, v30, v18
	v_fmac_f32_e32 v16, v18, v18
	v_and_b32_e32 v18, 64, v182
	v_add_f32_e32 v16, v17, v16
	v_xor_b32_e32 v17, 16, v182
	v_add_u32_e32 v18, 64, v18
	v_cmp_lt_i32_e32 vcc, v17, v18
	v_add_f32_e32 v16, v24, v16
	v_mul_f32_e32 v22, v31, v19
	v_cndmask_b32_e32 v17, v182, v17, vcc
	v_lshlrev_b32_e32 v17, 2, v17
	ds_bpermute_b32 v17, v17, v16
	v_cvt_pk_bf16_f32 v21, v21, v22
	global_store_dwordx2 v[54:55], v[20:21], off offset:288
	s_waitcnt lgkmcnt(0)
	v_add_f32_e32 v16, v16, v17
	v_xor_b32_e32 v17, 32, v182
	v_cmp_lt_i32_e32 vcc, v17, v18
	s_nop 1
	v_cndmask_b32_e32 v17, v182, v17, vcc
	v_lshlrev_b32_e32 v17, 2, v17
	ds_bpermute_b32 v17, v17, v16
	s_and_saveexec_b64 s[4:5], s[36:37]
	s_cbranch_execz .LBB0_464
	v_lshl_add_u64 v[18:19], v[48:49], 2, s[40:41]
	s_waitcnt lgkmcnt(0)
	v_add_f32_e32 v16, v16, v17
	global_atomic_add_f32 v[18:19], v16, off

.LBB0_465:
	s_movk_i32 s4, 0x1f4f
	s_waitcnt lgkmcnt(0)
	v_add_u32_e32 v16, 0xb0, v170
	v_cmp_lt_i32_e32 vcc, s4, v170
	s_and_saveexec_b64 s[4:5], vcc
	s_xor_b64 s[4:5], exec, s[4:5]
	v_add_u32_e32 v144, 0xffffe0b0, v170
	v_lshlrev_b64 v[18:19], 13, v[144:145]
	v_mov_b32_e32 v17, v145
	v_lshl_add_u64 v[18:19], s[30:31], 0, v[18:19]
	v_lshlrev_b64 v[22:23], 11, v[16:17]
	s_andn2_saveexec_b64 s[4:5], s[4:5]
	v_ashrrev_i32_e32 v17, 31, v16
	v_lshlrev_b64 v[18:19], 13, v[16:17]
	v_lshlrev_b64 v[22:23], 11, v[16:17]
	v_lshl_add_u64 v[18:19], s[26:27], 0, v[18:19]
	s_or_b64 exec, exec, s[4:5]
	v_lshl_add_u64 v[20:21], v[18:19], 0, v[172:173]
	v_lshl_add_u64 v[18:19], v[22:23], 2, s[26:27]
	v_lshl_add_u64 v[18:19], v[18:19], 0, v[172:173]
	s_mov_b64 s[4:5], -1
	s_and_b64 vcc, exec, s[18:19]
	s_waitcnt lgkmcnt(0)
	global_store_dwordx4 v[18:19], v[12:15], off
	s_cbranch_vccnz .LBB0_472
	s_andn2_b64 vcc, exec, s[4:5]
	s_cbranch_vccz .LBB0_473

.LBB0_472:
	s_waitcnt lgkmcnt(0)
	global_store_dwordx4 v[18:19], v[8:11], off offset:64
	s_waitcnt lgkmcnt(0)
	global_store_dwordx4 v[18:19], v[4:7], off offset:512
	s_waitcnt lgkmcnt(0)
	global_store_dwordx4 v[18:19], v[0:3], off offset:576
	s_cbranch_execnz .LBB0_471
.LBB0_473:
	s_nop 0
	v_mul_f32_e32 v22, v13, v13
	v_fmac_f32_e32 v22, v12, v12
	v_mul_f32_e32 v23, v15, v15
	v_mul_f32_e32 v12, v44, v12
	v_mul_f32_e32 v13, v45, v13
	v_fmac_f32_e32 v23, v14, v14
	v_cvt_pk_bf16_f32 v12, v12, v13
	v_mul_f32_e32 v13, v46, v14
	v_mul_f32_e32 v14, v47, v15
	v_cvt_pk_bf16_f32 v13, v13, v14
	v_lshlrev_b64 v[14:15], 12, v[16:17]
	v_lshl_add_u64 v[14:15], s[28:29], 0, v[14:15]
	v_add_f32_e32 v24, v22, v23
	v_lshl_add_u64 v[22:23], v[168:169], 1, v[14:15]
	global_store_dwordx2 v[22:23], v[12:13], off
	s_waitcnt lgkmcnt(0)
	v_mul_f32_e32 v12, v9, v9
	global_store_dwordx4 v[18:19], v[8:11], off offset:64
	v_fmac_f32_e32 v12, v8, v8
	v_mul_f32_e32 v13, v11, v11
	v_mul_f32_e32 v8, v40, v8
	v_mul_f32_e32 v9, v41, v9
	v_cvt_pk_bf16_f32 v8, v8, v9
	v_mul_f32_e32 v9, v42, v10
	v_fmac_f32_e32 v13, v10, v10
	v_mul_f32_e32 v10, v43, v11
	v_cvt_pk_bf16_f32 v9, v9, v10
	global_store_dwordx2 v[22:23], v[8:9], off offset:32
	v_add_f32_e32 v12, v12, v13
	v_add_f32_e32 v12, v24, v12
	s_waitcnt lgkmcnt(0)
	v_mul_f32_e32 v8, v5, v5
	global_store_dwordx4 v[18:19], v[4:7], off offset:512
	v_fmac_f32_e32 v8, v4, v4
	v_mul_f32_e32 v9, v7, v7
	v_mul_f32_e32 v4, v32, v4
	v_mul_f32_e32 v5, v33, v5
	v_cvt_pk_bf16_f32 v4, v4, v5
	v_mul_f32_e32 v5, v34, v6
	v_fmac_f32_e32 v9, v6, v6
	v_mul_f32_e32 v6, v35, v7
	v_cvt_pk_bf16_f32 v5, v5, v6
	global_store_dwordx2 v[22:23], v[4:5], off offset:256
	v_add_f32_e32 v8, v8, v9
	v_add_f32_e32 v8, v12, v8
	s_waitcnt lgkmcnt(0)
	global_store_dwordx4 v[18:19], v[0:3], off offset:576
	v_mul_f32_e32 v5, v29, v1
	v_mul_f32_e32 v4, v28, v0
	v_mul_f32_e32 v1, v1, v1
	v_fmac_f32_e32 v1, v0, v0
	v_mul_f32_e32 v0, v3, v3
	v_cvt_pk_bf16_f32 v4, v4, v5
	v_mul_f32_e32 v5, v30, v2
	v_fmac_f32_e32 v0, v2, v2
	v_and_b32_e32 v2, 64, v182
	v_add_f32_e32 v0, v1, v0
	v_xor_b32_e32 v1, 16, v182
	v_add_u32_e32 v2, 64, v2
	v_cmp_lt_i32_e32 vcc, v1, v2
	v_add_f32_e32 v0, v8, v0
	v_mul_f32_e32 v6, v31, v3
	v_cndmask_b32_e32 v1, v182, v1, vcc
	v_lshlrev_b32_e32 v1, 2, v1
	ds_bpermute_b32 v1, v1, v0
	v_cvt_pk_bf16_f32 v5, v5, v6
	flat_store_dwordx2 v[22:23], v[4:5] offset:288
	s_waitcnt lgkmcnt(0)
	v_add_f32_e32 v0, v0, v1
	v_xor_b32_e32 v1, 32, v182
	v_cmp_lt_i32_e32 vcc, v1, v2
	s_nop 1
	v_cndmask_b32_e32 v1, v182, v1, vcc
	v_lshlrev_b32_e32 v1, 2, v1
	ds_bpermute_b32 v1, v1, v0
	s_and_saveexec_b64 s[4:5], s[36:37]
	s_cbranch_execz .LBB0_475
	v_lshl_add_u64 v[2:3], v[16:17], 2, s[40:41]
	s_waitcnt lgkmcnt(0)
	v_add_f32_e32 v0, v0, v1
	flat_atomic_add_f32 v[2:3], v0

.LBB0_602:
	s_add_i32 s2, s33, 4
	s_cmp_gt_i32 s46, s2
	s_cselect_b64 s[0:1], -1, 0
	s_cmp_ge_i32 s2, s47
	s_cselect_b64 s[2:3], -1, 0
	s_or_b64 s[0:1], s[0:1], s[2:3]
	s_and_b64 vcc, exec, s[0:1]
	s_cbranch_vccnz .LBB0_608
	v_readlane_b32 s0, v246, 62
	s_cmp_lg_u32 s90, 3
	s_waitcnt lgkmcnt(0)
	v_mov_b32_e32 v1, v180
	v_readlane_b32 s0, v246, 63
	s_waitcnt lgkmcnt(0)
	s_nop 0
	v_readlane_b32 s0, v245, 0
	s_waitcnt lgkmcnt(0)
	s_nop 0
	v_readlane_b32 s0, v245, 1
	s_waitcnt lgkmcnt(0)
	s_nop 0
	v_readlane_b32 s0, v245, 2
	s_waitcnt lgkmcnt(0)
	s_nop 0
	v_readlane_b32 s0, v245, 3
	s_waitcnt lgkmcnt(0)
	s_nop 0
	v_readlane_b32 s0, v245, 4
	s_waitcnt lgkmcnt(0)
	s_nop 0
	v_readlane_b32 s0, v245, 5
	s_waitcnt lgkmcnt(0)
	s_nop 0
	v_readlane_b32 s0, v245, 6
	s_waitcnt lgkmcnt(0)
	s_nop 0
	v_readlane_b32 s0, v245, 7
	s_waitcnt lgkmcnt(0)
	s_nop 0
	v_readlane_b32 s0, v245, 8
	s_waitcnt lgkmcnt(0)
	s_nop 0
	v_readlane_b32 s0, v245, 9
	s_waitcnt lgkmcnt(0)
	s_nop 0
	v_readlane_b32 s0, v245, 10
	s_waitcnt lgkmcnt(0)
	s_nop 0
	v_readlane_b32 s0, v245, 11
	s_waitcnt lgkmcnt(0)
	s_nop 0
	v_readlane_b32 s0, v245, 12
	s_waitcnt lgkmcnt(0)
	s_nop 0
	v_readlane_b32 s0, v245, 13
	s_waitcnt lgkmcnt(0)
	s_nop 0
	v_readlane_b32 s0, v245, 14
	s_waitcnt lgkmcnt(0)
	s_nop 0
	v_readlane_b32 s0, v245, 15
	s_waitcnt lgkmcnt(0)
	s_nop 0
	v_readlane_b32 s0, v245, 16
	s_waitcnt lgkmcnt(0)
	s_nop 0
	v_readlane_b32 s0, v245, 17
	s_waitcnt lgkmcnt(0)
	s_nop 0
	v_readlane_b32 s0, v245, 18
	s_waitcnt lgkmcnt(0)
	s_nop 0
	v_readlane_b32 s0, v245, 19
	s_waitcnt lgkmcnt(0)
	s_nop 0
	v_readlane_b32 s0, v245, 20
	s_waitcnt lgkmcnt(0)
	s_nop 0
	v_readlane_b32 s0, v245, 21
	s_waitcnt lgkmcnt(0)
	s_nop 0
	v_readlane_b32 s0, v245, 22
	s_waitcnt lgkmcnt(0)
	s_nop 0
	v_readlane_b32 s0, v245, 23
	s_waitcnt lgkmcnt(0)
	s_nop 0
	v_readlane_b32 s0, v245, 24
	s_waitcnt lgkmcnt(0)
	s_nop 0
	v_readlane_b32 s0, v245, 25
	s_waitcnt lgkmcnt(0)
	s_nop 0
	v_readlane_b32 s0, v245, 26
	s_waitcnt lgkmcnt(0)
	s_nop 0
	v_readlane_b32 s0, v245, 27
	s_waitcnt lgkmcnt(0)
	s_nop 0
	v_readlane_b32 s0, v245, 28
	s_waitcnt lgkmcnt(0)
	s_nop 0
	v_readlane_b32 s0, v245, 29
	s_waitcnt lgkmcnt(0)
	s_nop 0
	v_readlane_b32 s0, v245, 30
	s_waitcnt lgkmcnt(0)
	s_nop 0
	v_readlane_b32 s0, v245, 31
	s_waitcnt lgkmcnt(0)
	s_nop 0
	v_readlane_b32 s0, v245, 32
	s_waitcnt lgkmcnt(0)
	s_nop 0
	v_readlane_b32 s0, v245, 33
	s_waitcnt lgkmcnt(0)
	s_nop 0
	v_readlane_b32 s0, v245, 34
	s_waitcnt lgkmcnt(0)
	s_nop 0
	v_readlane_b32 s0, v245, 35
	s_waitcnt lgkmcnt(0)
	s_nop 0
	v_readlane_b32 s0, v245, 36
	s_waitcnt lgkmcnt(0)
	s_nop 0
	v_readlane_b32 s0, v245, 37
	s_waitcnt lgkmcnt(0)
	s_nop 0
	v_readlane_b32 s0, v245, 38
	s_waitcnt lgkmcnt(0)
	s_nop 0
	v_readlane_b32 s0, v245, 39
	s_waitcnt lgkmcnt(0)
	s_nop 0
	v_readlane_b32 s0, v245, 40
	s_waitcnt lgkmcnt(0)
	s_nop 0
	v_readlane_b32 s0, v245, 41
	s_waitcnt lgkmcnt(0)
	s_nop 0
	v_readlane_b32 s0, v245, 42
	s_waitcnt lgkmcnt(0)
	s_nop 0
	v_readlane_b32 s0, v245, 43
	s_waitcnt lgkmcnt(0)
	s_nop 0
	v_readlane_b32 s0, v245, 44
	s_waitcnt lgkmcnt(0)
	s_nop 0
	v_readlane_b32 s0, v245, 45
	s_waitcnt lgkmcnt(0)
	s_nop 0
	v_readlane_b32 s0, v245, 46
	s_waitcnt lgkmcnt(0)
	s_nop 0
	v_readlane_b32 s0, v245, 47
	s_waitcnt lgkmcnt(0)
	s_nop 0
	v_readlane_b32 s0, v245, 48
	s_waitcnt lgkmcnt(0)
	s_nop 0
	v_readlane_b32 s0, v245, 49
	s_waitcnt lgkmcnt(0)
	s_nop 0
	v_readlane_b32 s0, v245, 50
	s_waitcnt lgkmcnt(0)
	s_nop 0
	v_readlane_b32 s0, v245, 51
	s_waitcnt lgkmcnt(0)
	s_nop 0
	v_readlane_b32 s0, v245, 52
	s_waitcnt lgkmcnt(0)
	s_nop 0
	v_mov_b32_e32 v0, s0
	ds_read_b32 v0, v0
	v_readlane_b32 s0, v245, 53
	s_waitcnt lgkmcnt(0)
	v_readfirstlane_b32 s4, v0
	v_mov_b32_e32 v0, s0
	ds_read_b32 v0, v0
	v_readlane_b32 s0, v245, 54
	s_waitcnt lgkmcnt(0)
	v_readfirstlane_b32 s5, v0
	v_mov_b32_e32 v0, s0
	ds_read_b32 v0, v0
	v_readlane_b32 s0, v245, 55
	s_waitcnt lgkmcnt(0)
	v_readfirstlane_b32 s2, v0
	v_mov_b32_e32 v0, s0
	ds_read_b32 v0, v0
	v_readlane_b32 s0, v245, 56
	s_waitcnt lgkmcnt(0)
	v_readfirstlane_b32 s3, v0
	v_mov_b32_e32 v0, s0
	ds_read_b32 v0, v0
	v_readlane_b32 s0, v245, 57
	s_waitcnt lgkmcnt(0)
	v_readfirstlane_b32 s8, v0
	v_mov_b32_e32 v0, s0
	ds_read_b32 v0, v0
	v_readlane_b32 s0, v246, 0
	s_waitcnt lgkmcnt(0)
	v_readfirstlane_b32 s9, v0
	s_cbranch_scc1 .LBB0_608
	s_lshl_b32 s12, s0, 3
	v_ashrrev_i32_e32 v0, 6, v1
	v_add_u32_e32 v47, s12, v0
	s_movk_i32 s0, 0x2400
	v_cmp_gt_i32_e32 vcc, s0, v47
	s_and_saveexec_b64 s[0:1], vcc
	v_readlane_b32 s16, v245, 63
	s_movk_i32 s14, 0x1000
	v_readlane_b32 s17, v244, 0
	s_cbranch_execz .LBB0_607
	v_and_b32_e32 v2, 64, v182
	v_add_u32_e32 v2, 64, v2
	v_xor_b32_e32 v3, 1, v182
	v_cmp_lt_i32_e32 vcc, v3, v2
	s_ashr_i32 s13, s12, 31
	s_nop 0
	v_cndmask_b32_e32 v3, v182, v3, vcc
	v_lshlrev_b32_e32 v50, 2, v3
	v_xor_b32_e32 v3, 2, v182
	v_cmp_lt_i32_e32 vcc, v3, v2
	s_nop 1
	v_cndmask_b32_e32 v3, v182, v3, vcc
	v_lshlrev_b32_e32 v51, 2, v3
	v_xor_b32_e32 v3, 4, v182
	v_cmp_lt_i32_e32 vcc, v3, v2
	s_nop 1
	v_cndmask_b32_e32 v3, v182, v3, vcc
	v_lshlrev_b32_e32 v52, 2, v3
	v_xor_b32_e32 v3, 8, v182
	v_cmp_lt_i32_e32 vcc, v3, v2
	s_nop 1
	v_cndmask_b32_e32 v3, v182, v3, vcc
	v_lshlrev_b32_e32 v53, 2, v3
	v_xor_b32_e32 v3, 16, v182
	v_cmp_lt_i32_e32 vcc, v3, v2
	s_nop 1
	v_cndmask_b32_e32 v3, v182, v3, vcc
	v_lshlrev_b32_e32 v54, 2, v3
	v_xor_b32_e32 v3, 32, v182
	v_cmp_lt_i32_e32 vcc, v3, v2
	s_nop 1
	v_cndmask_b32_e32 v2, v182, v3, vcc
	v_lshlrev_b32_e32 v55, 2, v2
	v_lshlrev_b32_e32 v2, 4, v1
	v_and_b32_e32 v144, 0x3f0, v2
	v_or_b32_e32 v2, 0x1000, v144
	v_mov_b32_e32 v3, v145
	v_lshl_add_u64 v[34:35], s[4:5], 0, v[2:3]
	v_or_b32_e32 v2, 0x1400, v144
	v_lshl_add_u64 v[32:33], s[4:5], 0, v[144:145]
	v_lshl_add_u64 v[36:37], s[4:5], 0, v[2:3]
	v_or_b32_e32 v2, 0x1800, v144
	v_or_b32_e32 v144, 0x1c00, v144
	v_and_b32_e32 v1, 63, v1
	v_lshl_add_u64 v[40:41], s[4:5], 0, v[144:145]
	v_lshlrev_b32_e32 v144, 4, v1
	v_ashrrev_i32_e32 v1, 31, v0
	v_lshl_add_u64 v[0:1], v[0:1], 0, s[12:13]
	v_lshlrev_b64 v[0:1], 13, v[0:1]
	v_lshl_add_u64 v[38:39], s[4:5], 0, v[2:3]
	v_lshl_add_u64 v[42:43], s[2:3], 0, v[0:1]
	v_lshl_add_u64 v[44:45], s[8:9], 0, v[0:1]
	s_mov_b64 s[4:5], 0

.LBB0_609:
	s_and_b64 vcc, exec, s[0:1]
	s_cbranch_vccz .LBB0_103
	s_cmp_eq_u32 s90, 0
	s_cselect_b64 s[0:1], -1, 0
	v_writelane_b32 v244, s0, 13
	s_nop 1
	v_writelane_b32 v244, s1, 14
	s_and_b64 s[0:1], s[0:1], exec
	s_cselect_b32 s2, 1, 12
	s_cmp_le_i32 s46, s2
	s_cselect_b64 s[0:1], -1, 0
	s_cmp_lt_i32 s2, s47
	v_writelane_b32 v244, s2, 15
	s_cselect_b64 s[2:3], -1, 0
	s_and_b64 s[0:1], s[0:1], s[2:3]
	s_mul_i32 s2, s90, 0x2400
	s_andn2_b64 vcc, exec, s[0:1]
	v_writelane_b32 v244, s2, 17
	s_nop 1
	v_writelane_b32 v244, s3, 18
	s_cbranch_vccnz .LBB0_692
	v_readlane_b32 s2, v246, 62
	v_readlane_b32 s6, v246, 0
	v_mov_b32_e32 v8, v180
	v_readlane_b32 s2, v246, 63
	s_waitcnt lgkmcnt(0)
	s_nop 0
	v_readlane_b32 s2, v245, 0
	s_waitcnt lgkmcnt(0)
	s_nop 0
	v_readlane_b32 s2, v245, 1
	s_waitcnt lgkmcnt(0)
	s_nop 0
	v_readlane_b32 s2, v245, 2
	s_waitcnt lgkmcnt(0)
	s_nop 0
	v_readlane_b32 s2, v245, 3
	s_waitcnt lgkmcnt(0)
	s_nop 0
	v_readlane_b32 s2, v245, 4
	s_waitcnt lgkmcnt(0)
	s_nop 0
	v_readlane_b32 s2, v245, 5
	s_waitcnt lgkmcnt(0)
	s_nop 0
	v_readlane_b32 s2, v245, 6
	s_waitcnt lgkmcnt(0)
	s_nop 0
	v_readlane_b32 s2, v245, 7
	s_waitcnt lgkmcnt(0)
	s_nop 0
	v_readlane_b32 s2, v245, 8
	s_waitcnt lgkmcnt(0)
	s_nop 0
	v_readlane_b32 s2, v245, 9
	s_waitcnt lgkmcnt(0)
	s_nop 0
	v_readlane_b32 s2, v245, 10
	s_waitcnt lgkmcnt(0)
	s_nop 0
	v_readlane_b32 s2, v245, 11
	s_waitcnt lgkmcnt(0)
	s_nop 0
	v_readlane_b32 s2, v245, 12
	s_waitcnt lgkmcnt(0)
	s_nop 0
	v_readlane_b32 s2, v245, 13
	s_waitcnt lgkmcnt(0)
	s_nop 0
	v_readlane_b32 s2, v245, 14
	s_waitcnt lgkmcnt(0)
	s_nop 0
	v_mov_b32_e32 v0, s2
	v_readlane_b32 s2, v245, 15
	ds_read_b32 v0, v0
	s_waitcnt lgkmcnt(0)
	v_readfirstlane_b32 s16, v0
	v_mov_b32_e32 v1, s2
	v_readlane_b32 s2, v245, 16
	ds_read_b32 v1, v1
	s_waitcnt lgkmcnt(0)
	v_readfirstlane_b32 s17, v1
	v_readlane_b32 s2, v245, 17
	s_waitcnt lgkmcnt(0)
	s_nop 0
	v_readlane_b32 s2, v245, 18
	s_waitcnt lgkmcnt(0)
	s_nop 0
	v_readlane_b32 s2, v245, 19
	s_waitcnt lgkmcnt(0)
	s_nop 0
	v_readlane_b32 s2, v245, 20
	s_waitcnt lgkmcnt(0)
	s_nop 0
	v_readlane_b32 s2, v245, 21
	s_waitcnt lgkmcnt(0)
	s_nop 0
	v_readlane_b32 s2, v245, 22
	s_waitcnt lgkmcnt(0)
	s_nop 0
	v_readlane_b32 s2, v245, 23
	s_waitcnt lgkmcnt(0)
	s_nop 0
	v_readlane_b32 s2, v245, 24
	s_waitcnt lgkmcnt(0)
	s_nop 0
	v_readlane_b32 s2, v245, 25
	s_waitcnt lgkmcnt(0)
	s_nop 0
	v_readlane_b32 s2, v245, 26
	s_waitcnt lgkmcnt(0)
	s_nop 0
	v_readlane_b32 s2, v245, 27
	s_waitcnt lgkmcnt(0)
	s_nop 0
	v_readlane_b32 s2, v245, 28
	s_waitcnt lgkmcnt(0)
	s_nop 0
	v_readlane_b32 s2, v245, 29
	s_waitcnt lgkmcnt(0)
	s_nop 0
	v_readlane_b32 s2, v245, 30
	s_waitcnt lgkmcnt(0)
	s_nop 0
	v_mov_b32_e32 v2, s2
	v_readlane_b32 s2, v245, 31
	ds_read_b32 v2, v2
	s_waitcnt lgkmcnt(0)
	v_readfirstlane_b32 s24, v2
	v_mov_b32_e32 v3, s2
	v_readlane_b32 s2, v245, 32
	ds_read_b32 v3, v3
	s_waitcnt lgkmcnt(0)
	v_readfirstlane_b32 s25, v3
	v_readlane_b32 s2, v245, 33
	s_waitcnt lgkmcnt(0)
	s_nop 0
	v_readlane_b32 s2, v245, 34
	s_waitcnt lgkmcnt(0)
	s_nop 0
	v_mov_b32_e32 v0, s2
	v_readlane_b32 s2, v245, 35
	ds_read_b32 v0, v0
	s_waitcnt lgkmcnt(0)
	v_readfirstlane_b32 s64, v0
	v_mov_b32_e32 v1, s2
	v_readlane_b32 s2, v245, 36
	ds_read_b32 v1, v1
	s_waitcnt lgkmcnt(0)
	v_readfirstlane_b32 s65, v1
	v_readlane_b32 s2, v245, 37
	s_waitcnt lgkmcnt(0)
	s_nop 0
	v_readlane_b32 s2, v245, 38
	s_waitcnt lgkmcnt(0)
	s_nop 0
	v_readlane_b32 s2, v245, 39
	s_waitcnt lgkmcnt(0)
	s_nop 0
	v_readlane_b32 s2, v245, 40
	s_waitcnt lgkmcnt(0)
	s_nop 0
	v_mov_b32_e32 v2, s2
	v_readlane_b32 s2, v245, 41
	ds_read_b32 v2, v2
	s_waitcnt lgkmcnt(0)
	v_readfirstlane_b32 s22, v2
	v_mov_b32_e32 v3, s2
	v_readlane_b32 s2, v245, 42
	ds_read_b32 v3, v3
	s_waitcnt lgkmcnt(0)
	v_readfirstlane_b32 s23, v3
	v_readlane_b32 s2, v245, 43
	s_waitcnt lgkmcnt(0)
	s_nop 0
	v_readlane_b32 s2, v245, 44
	s_waitcnt lgkmcnt(0)
	s_nop 0
	v_mov_b32_e32 v4, s2
	v_readlane_b32 s2, v245, 45
	ds_read_b32 v4, v4
	s_waitcnt lgkmcnt(0)
	v_readfirstlane_b32 s20, v4
	v_mov_b32_e32 v0, s2
	v_readlane_b32 s2, v245, 46
	ds_read_b32 v0, v0
	s_waitcnt lgkmcnt(0)
	v_readfirstlane_b32 s21, v0
	v_readlane_b32 s2, v245, 47
	s_waitcnt lgkmcnt(0)
	s_nop 0
	v_readlane_b32 s2, v245, 48
	s_waitcnt lgkmcnt(0)
	s_nop 0
	v_readlane_b32 s2, v245, 49
	s_waitcnt lgkmcnt(0)
	s_nop 0
	v_readlane_b32 s2, v245, 50
	s_waitcnt lgkmcnt(0)
	s_nop 0
	v_mov_b32_e32 v1, s2
	v_readlane_b32 s2, v245, 51
	ds_read_b32 v1, v1
	s_waitcnt lgkmcnt(0)
	v_readfirstlane_b32 s34, v1
	v_mov_b32_e32 v2, s2
	v_readlane_b32 s2, v245, 52
	ds_read_b32 v2, v2
	s_waitcnt lgkmcnt(0)
	v_readfirstlane_b32 s35, v2
	v_readlane_b32 s2, v245, 53
	s_waitcnt lgkmcnt(0)
	s_nop 0
	v_readlane_b32 s2, v245, 54
	s_waitcnt lgkmcnt(0)
	s_nop 0
	v_readlane_b32 s2, v245, 55
	s_waitcnt lgkmcnt(0)
	s_nop 0
	v_readlane_b32 s2, v245, 56
	s_waitcnt lgkmcnt(0)
	s_nop 0
	v_mov_b32_e32 v3, s2
	v_readlane_b32 s2, v245, 57
	ds_read_b32 v3, v3
	s_waitcnt lgkmcnt(0)
	v_readfirstlane_b32 s12, v3
	v_mov_b32_e32 v4, s2
	ds_read_b32 v4, v4
	s_cmpk_lt_i32 s6, 0x414
	s_cselect_b64 s[2:3], -1, 0
	s_waitcnt lgkmcnt(0)
	v_readfirstlane_b32 s13, v4
	s_cmpk_gt_i32 s6, 0x413
	v_readfirstlane_b32 s8, v8
	s_cbranch_scc1 .LBB0_617
	s_ashr_i32 s4, s6, 31
	s_lshr_b32 s4, s4, 29
	s_add_i32 s7, s6, s4
	s_and_b32 s4, s7, -8
	s_sub_i32 s9, s6, s4
	s_cmp_gt_i32 s9, 3
	s_mov_b64 s[4:5], -1
	s_cbranch_scc0 .LBB0_614
	s_mul_i32 s4, s9, 0x82
	s_add_i32 s18, s4, 4
	s_mov_b64 s[4:5], 0

.LBB0_633:
	v_lshl_add_u32 v138, s38, 8, v143
	v_cndmask_b32_e64 v140, 0, 1, s[54:55]
	v_ashrrev_i32_e32 v139, 31, v138
	v_mov_b32_e32 v142, 1.0
	v_cmp_ne_u32_e64 s[38:39], 1, v140
	s_andn2_b64 vcc, exec, s[54:55]
	v_mov_b32_e32 v146, 1.0
	s_cbranch_vccnz .LBB0_635
	v_lshl_add_u64 v[140:141], v[138:139], 2, s[40:41]
	global_load_dword v200, v[140:141], off
	global_load_dword v201, v[140:141], off offset:64
	global_load_dword v202, v[140:141], off offset:128
	global_load_dword v203, v[140:141], off offset:192
	global_load_dword v204, v[140:141], off offset:512
	global_load_dword v205, v[140:141], off offset:576
	global_load_dword v206, v[140:141], off offset:640
	global_load_dword v207, v[140:141], off offset:704
	s_waitcnt vmcnt(0)
	v_mov_b32_e32 v139, v200
	v_fmamk_f32 v139, v139, 0x3a000000, v181
	v_mul_f32_e32 v140, 0x4b800000, v139
	v_cmp_gt_f32_e32 vcc, s80, v139
	s_nop 1
	v_cndmask_b32_e32 v139, v139, v140, vcc
	v_rsq_f32_e32 v139, v139
	s_nop 0
	v_mul_f32_e32 v140, 0x45800000, v139
	v_cndmask_b32_e32 v146, v139, v140, vcc
.LBB0_635:
	v_lshl_or_b32 v140, s4, 8, v161
	v_mov_b64_e32 v[164:165], s[30:31]
	v_ashrrev_i32_e32 v141, 31, v140
	v_mad_i64_i32 v[164:165], s[2:3], v138, s86, v[164:165]
	v_lshl_add_u64 v[164:165], v[140:141], 1, v[164:165]
	v_pk_mul_f32 v[126:127], v[126:127], v[146:147] op_sel_hi:[1,0]
	v_pk_mul_f32 v[124:125], v[124:125], v[146:147] op_sel_hi:[1,0]
	v_pk_mul_f32 v[166:167], v[122:123], v[146:147] op_sel_hi:[1,0]
	v_pk_mul_f32 v[122:123], v[120:121], v[146:147] op_sel_hi:[1,0]
	v_cvt_pk_bf16_f32 v120, v124, v125
	v_cvt_pk_bf16_f32 v121, v126, v127
	v_pk_mul_f32 v[116:117], v[116:117], v[146:147] op_sel_hi:[1,0]
	v_cvt_pk_bf16_f32 v122, v122, v123
	v_cvt_pk_bf16_f32 v123, v166, v167
	flat_store_dwordx4 v[164:165], v[120:123]
	v_pk_mul_f32 v[118:119], v[118:119], v[146:147] op_sel_hi:[1,0]
	s_and_b64 vcc, exec, s[38:39]
	v_pk_mul_f32 v[120:121], v[114:115], v[146:147] op_sel_hi:[1,0]
	v_pk_mul_f32 v[114:115], v[112:113], v[146:147] op_sel_hi:[1,0]
	v_cvt_pk_bf16_f32 v112, v116, v117
	v_cvt_pk_bf16_f32 v113, v118, v119
	s_nop 0
	v_cvt_pk_bf16_f32 v114, v114, v115
	v_cvt_pk_bf16_f32 v115, v120, v121
	flat_store_dwordx4 v[164:165], v[112:115] offset:256
	s_nop 1
	v_or_b32_e32 v112, 16, v138
	v_ashrrev_i32_e32 v113, 31, v112
	s_cbranch_vccnz .LBB0_637
	v_lshl_add_u64 v[114:115], v[112:113], 2, s[40:41]
	s_nop 1
	v_mov_b32_e32 v113, v201
	v_fmamk_f32 v113, v113, 0x3a000000, v181
	v_mul_f32_e32 v114, 0x4b800000, v113
	v_cmp_gt_f32_e32 vcc, s80, v113
	s_nop 1
	v_cndmask_b32_e32 v113, v113, v114, vcc
	v_rsq_f32_e32 v113, v113
	s_nop 0
	v_mul_f32_e32 v114, 0x45800000, v113
	v_cndmask_b32_e32 v142, v113, v114, vcc
.LBB0_637:
	v_mov_b64_e32 v[114:115], s[30:31]
	v_mad_i64_i32 v[112:113], s[2:3], v112, s86, v[114:115]
	v_lshl_add_u64 v[112:113], v[140:141], 1, v[112:113]
	v_pk_mul_f32 v[110:111], v[110:111], v[142:143] op_sel_hi:[1,0]
	v_pk_mul_f32 v[108:109], v[108:109], v[142:143] op_sel_hi:[1,0]
	v_pk_mul_f32 v[114:115], v[106:107], v[142:143] op_sel_hi:[1,0]
	v_pk_mul_f32 v[106:107], v[104:105], v[142:143] op_sel_hi:[1,0]
	v_cvt_pk_bf16_f32 v104, v108, v109
	v_cvt_pk_bf16_f32 v105, v110, v111
	v_pk_mul_f32 v[100:101], v[100:101], v[142:143] op_sel_hi:[1,0]
	v_cvt_pk_bf16_f32 v106, v106, v107
	v_cvt_pk_bf16_f32 v107, v114, v115
	flat_store_dwordx4 v[112:113], v[104:107]
	v_pk_mul_f32 v[102:103], v[102:103], v[142:143] op_sel_hi:[1,0]
	s_and_b64 vcc, exec, s[38:39]
	v_pk_mul_f32 v[104:105], v[98:99], v[142:143] op_sel_hi:[1,0]
	v_pk_mul_f32 v[98:99], v[96:97], v[142:143] op_sel_hi:[1,0]
	v_cvt_pk_bf16_f32 v96, v100, v101
	v_cvt_pk_bf16_f32 v97, v102, v103
	v_or_b32_e32 v100, 32, v138
	v_cvt_pk_bf16_f32 v98, v98, v99
	v_cvt_pk_bf16_f32 v99, v104, v105
	flat_store_dwordx4 v[112:113], v[96:99] offset:256
	v_ashrrev_i32_e32 v101, 31, v100
	s_nop 0
	v_mov_b32_e32 v96, 1.0
	v_mov_b32_e32 v98, 1.0
	s_cbranch_vccnz .LBB0_639
	v_lshl_add_u64 v[98:99], v[100:101], 2, s[40:41]
	s_nop 1
	v_mov_b32_e32 v97, v202
	v_fmamk_f32 v97, v97, 0x3a000000, v181
	v_mul_f32_e32 v98, 0x4b800000, v97
	v_cmp_gt_f32_e32 vcc, s80, v97
	s_nop 1
	v_cndmask_b32_e32 v97, v97, v98, vcc
	v_rsq_f32_e32 v97, v97
	s_nop 0
	v_mul_f32_e32 v98, 0x45800000, v97
	v_cndmask_b32_e32 v98, v97, v98, vcc
.LBB0_639:
	v_mov_b64_e32 v[102:103], s[30:31]
	v_mad_i64_i32 v[100:101], s[2:3], v100, s86, v[102:103]
	v_lshl_add_u64 v[100:101], v[140:141], 1, v[100:101]
	v_pk_mul_f32 v[94:95], v[94:95], v[98:99] op_sel_hi:[1,0]
	v_pk_mul_f32 v[92:93], v[92:93], v[98:99] op_sel_hi:[1,0]
	v_pk_mul_f32 v[102:103], v[90:91], v[98:99] op_sel_hi:[1,0]
	v_pk_mul_f32 v[90:91], v[88:89], v[98:99] op_sel_hi:[1,0]
	v_cvt_pk_bf16_f32 v88, v92, v93
	v_cvt_pk_bf16_f32 v89, v94, v95
	v_pk_mul_f32 v[84:85], v[84:85], v[98:99] op_sel_hi:[1,0]
	v_cvt_pk_bf16_f32 v90, v90, v91
	v_cvt_pk_bf16_f32 v91, v102, v103
	flat_store_dwordx4 v[100:101], v[88:91]
	v_pk_mul_f32 v[86:87], v[86:87], v[98:99] op_sel_hi:[1,0]
	s_and_b64 vcc, exec, s[38:39]
	v_pk_mul_f32 v[88:89], v[82:83], v[98:99] op_sel_hi:[1,0]
	v_pk_mul_f32 v[82:83], v[80:81], v[98:99] op_sel_hi:[1,0]
	v_cvt_pk_bf16_f32 v80, v84, v85
	v_cvt_pk_bf16_f32 v81, v86, v87
	s_nop 0
	v_cvt_pk_bf16_f32 v82, v82, v83
	v_cvt_pk_bf16_f32 v83, v88, v89
	flat_store_dwordx4 v[100:101], v[80:83] offset:256
	s_nop 1
	v_or_b32_e32 v80, 48, v138
	v_ashrrev_i32_e32 v81, 31, v80
	s_cbranch_vccnz .LBB0_641
	v_lshl_add_u64 v[82:83], v[80:81], 2, s[40:41]
	s_nop 1
	v_mov_b32_e32 v81, v203
	v_fmamk_f32 v81, v81, 0x3a000000, v181
	v_mul_f32_e32 v82, 0x4b800000, v81
	v_cmp_gt_f32_e32 vcc, s80, v81
	s_nop 1
	v_cndmask_b32_e32 v81, v81, v82, vcc
	v_rsq_f32_e32 v81, v81
	s_nop 0
	v_mul_f32_e32 v82, 0x45800000, v81
	v_cndmask_b32_e32 v96, v81, v82, vcc
.LBB0_641:
	v_mov_b64_e32 v[82:83], s[30:31]
	v_mad_i64_i32 v[80:81], s[2:3], v80, s86, v[82:83]
	v_lshl_add_u64 v[80:81], v[140:141], 1, v[80:81]
	v_pk_mul_f32 v[78:79], v[78:79], v[96:97] op_sel_hi:[1,0]
	v_pk_mul_f32 v[76:77], v[76:77], v[96:97] op_sel_hi:[1,0]
	v_pk_mul_f32 v[82:83], v[74:75], v[96:97] op_sel_hi:[1,0]
	v_pk_mul_f32 v[74:75], v[72:73], v[96:97] op_sel_hi:[1,0]
	v_cvt_pk_bf16_f32 v72, v76, v77
	v_cvt_pk_bf16_f32 v73, v78, v79
	v_pk_mul_f32 v[68:69], v[68:69], v[96:97] op_sel_hi:[1,0]
	v_cvt_pk_bf16_f32 v74, v74, v75
	v_cvt_pk_bf16_f32 v75, v82, v83
	flat_store_dwordx4 v[80:81], v[72:75]
	v_pk_mul_f32 v[70:71], v[70:71], v[96:97] op_sel_hi:[1,0]
	s_and_b64 vcc, exec, s[38:39]
	v_pk_mul_f32 v[72:73], v[66:67], v[96:97] op_sel_hi:[1,0]
	v_pk_mul_f32 v[66:67], v[64:65], v[96:97] op_sel_hi:[1,0]
	v_cvt_pk_bf16_f32 v64, v68, v69
	v_cvt_pk_bf16_f32 v65, v70, v71
	v_add_u32_e32 v68, 0x80, v138
	v_cvt_pk_bf16_f32 v66, v66, v67
	v_cvt_pk_bf16_f32 v67, v72, v73
	flat_store_dwordx4 v[80:81], v[64:67] offset:256
	v_ashrrev_i32_e32 v69, 31, v68
	s_nop 0
	v_mov_b32_e32 v64, 1.0
	v_mov_b32_e32 v66, 1.0
	s_cbranch_vccnz .LBB0_643
	v_lshl_add_u64 v[66:67], v[68:69], 2, s[40:41]
	s_nop 1
	v_mov_b32_e32 v65, v204
	v_fmamk_f32 v65, v65, 0x3a000000, v181
	v_mul_f32_e32 v66, 0x4b800000, v65
	v_cmp_gt_f32_e32 vcc, s80, v65
	s_nop 1
	v_cndmask_b32_e32 v65, v65, v66, vcc
	v_rsq_f32_e32 v65, v65
	s_nop 0
	v_mul_f32_e32 v66, 0x45800000, v65
	v_cndmask_b32_e32 v66, v65, v66, vcc
.LBB0_643:
	v_mov_b64_e32 v[70:71], s[30:31]
	v_mad_i64_i32 v[68:69], s[2:3], v68, s86, v[70:71]
	v_lshl_add_u64 v[68:69], v[140:141], 1, v[68:69]
	v_pk_mul_f32 v[62:63], v[62:63], v[66:67] op_sel_hi:[1,0]
	v_pk_mul_f32 v[60:61], v[60:61], v[66:67] op_sel_hi:[1,0]
	v_pk_mul_f32 v[70:71], v[58:59], v[66:67] op_sel_hi:[1,0]
	v_pk_mul_f32 v[58:59], v[56:57], v[66:67] op_sel_hi:[1,0]
	v_cvt_pk_bf16_f32 v56, v60, v61
	v_cvt_pk_bf16_f32 v57, v62, v63
	v_pk_mul_f32 v[52:53], v[52:53], v[66:67] op_sel_hi:[1,0]
	v_cvt_pk_bf16_f32 v58, v58, v59
	v_cvt_pk_bf16_f32 v59, v70, v71
	flat_store_dwordx4 v[68:69], v[56:59]
	v_pk_mul_f32 v[54:55], v[54:55], v[66:67] op_sel_hi:[1,0]
	s_and_b64 vcc, exec, s[38:39]
	v_pk_mul_f32 v[56:57], v[50:51], v[66:67] op_sel_hi:[1,0]
	v_pk_mul_f32 v[50:51], v[48:49], v[66:67] op_sel_hi:[1,0]
	v_cvt_pk_bf16_f32 v48, v52, v53
	v_cvt_pk_bf16_f32 v49, v54, v55
	s_nop 0
	v_cvt_pk_bf16_f32 v50, v50, v51
	v_cvt_pk_bf16_f32 v51, v56, v57
	flat_store_dwordx4 v[68:69], v[48:51] offset:256
	s_nop 1
	v_add_u32_e32 v48, 0x90, v138
	v_ashrrev_i32_e32 v49, 31, v48
	s_cbranch_vccnz .LBB0_645
	v_lshl_add_u64 v[50:51], v[48:49], 2, s[40:41]
	s_nop 1
	v_mov_b32_e32 v49, v205
	v_fmamk_f32 v49, v49, 0x3a000000, v181
	v_mul_f32_e32 v50, 0x4b800000, v49
	v_cmp_gt_f32_e32 vcc, s80, v49
	s_nop 1
	v_cndmask_b32_e32 v49, v49, v50, vcc
	v_rsq_f32_e32 v49, v49
	s_nop 0
	v_mul_f32_e32 v50, 0x45800000, v49
	v_cndmask_b32_e32 v64, v49, v50, vcc
.LBB0_645:
	v_mov_b64_e32 v[50:51], s[30:31]
	v_mad_i64_i32 v[48:49], s[2:3], v48, s86, v[50:51]
	v_lshl_add_u64 v[48:49], v[140:141], 1, v[48:49]
	v_pk_mul_f32 v[46:47], v[46:47], v[64:65] op_sel_hi:[1,0]
	v_pk_mul_f32 v[44:45], v[44:45], v[64:65] op_sel_hi:[1,0]
	v_pk_mul_f32 v[50:51], v[42:43], v[64:65] op_sel_hi:[1,0]
	v_pk_mul_f32 v[42:43], v[40:41], v[64:65] op_sel_hi:[1,0]
	v_cvt_pk_bf16_f32 v40, v44, v45
	v_cvt_pk_bf16_f32 v41, v46, v47
	v_pk_mul_f32 v[36:37], v[36:37], v[64:65] op_sel_hi:[1,0]
	v_cvt_pk_bf16_f32 v42, v42, v43
	v_cvt_pk_bf16_f32 v43, v50, v51
	flat_store_dwordx4 v[48:49], v[40:43]
	v_pk_mul_f32 v[38:39], v[38:39], v[64:65] op_sel_hi:[1,0]
	s_and_b64 vcc, exec, s[38:39]
	v_pk_mul_f32 v[40:41], v[34:35], v[64:65] op_sel_hi:[1,0]
	v_pk_mul_f32 v[34:35], v[32:33], v[64:65] op_sel_hi:[1,0]
	v_cvt_pk_bf16_f32 v32, v36, v37
	v_cvt_pk_bf16_f32 v33, v38, v39
	v_add_u32_e32 v36, 0xa0, v138
	v_cvt_pk_bf16_f32 v34, v34, v35
	v_cvt_pk_bf16_f32 v35, v40, v41
	flat_store_dwordx4 v[48:49], v[32:35] offset:256
	v_ashrrev_i32_e32 v37, 31, v36
	s_nop 0
	v_mov_b32_e32 v32, 1.0
	v_mov_b32_e32 v34, 1.0
	s_cbranch_vccnz .LBB0_647
	v_lshl_add_u64 v[34:35], v[36:37], 2, s[40:41]
	s_nop 1
	v_mov_b32_e32 v33, v206
	v_fmamk_f32 v33, v33, 0x3a000000, v181
	v_mul_f32_e32 v34, 0x4b800000, v33
	v_cmp_gt_f32_e32 vcc, s80, v33
	s_nop 1
	v_cndmask_b32_e32 v33, v33, v34, vcc
	v_rsq_f32_e32 v33, v33
	s_nop 0
	v_mul_f32_e32 v34, 0x45800000, v33
	v_cndmask_b32_e32 v34, v33, v34, vcc
.LBB0_647:
	v_mov_b64_e32 v[38:39], s[30:31]
	v_mad_i64_i32 v[36:37], s[2:3], v36, s86, v[38:39]
	v_lshl_add_u64 v[36:37], v[140:141], 1, v[36:37]
	v_pk_mul_f32 v[30:31], v[30:31], v[34:35] op_sel_hi:[1,0]
	v_pk_mul_f32 v[28:29], v[28:29], v[34:35] op_sel_hi:[1,0]
	v_pk_mul_f32 v[38:39], v[26:27], v[34:35] op_sel_hi:[1,0]
	v_pk_mul_f32 v[26:27], v[24:25], v[34:35] op_sel_hi:[1,0]
	v_cvt_pk_bf16_f32 v24, v28, v29
	v_cvt_pk_bf16_f32 v25, v30, v31
	v_pk_mul_f32 v[20:21], v[20:21], v[34:35] op_sel_hi:[1,0]
	v_cvt_pk_bf16_f32 v26, v26, v27
	v_cvt_pk_bf16_f32 v27, v38, v39
	flat_store_dwordx4 v[36:37], v[24:27]
	v_pk_mul_f32 v[22:23], v[22:23], v[34:35] op_sel_hi:[1,0]
	s_and_b64 vcc, exec, s[38:39]
	v_pk_mul_f32 v[24:25], v[18:19], v[34:35] op_sel_hi:[1,0]
	v_pk_mul_f32 v[18:19], v[16:17], v[34:35] op_sel_hi:[1,0]
	v_cvt_pk_bf16_f32 v16, v20, v21
	v_cvt_pk_bf16_f32 v17, v22, v23
	s_nop 0
	v_cvt_pk_bf16_f32 v18, v18, v19
	v_cvt_pk_bf16_f32 v19, v24, v25
	flat_store_dwordx4 v[36:37], v[16:19] offset:256
	s_nop 1
	v_add_u32_e32 v16, 0xb0, v138
	v_ashrrev_i32_e32 v17, 31, v16
	s_cbranch_vccnz .LBB0_649
	v_lshl_add_u64 v[18:19], v[16:17], 2, s[40:41]
	s_nop 1
	v_mov_b32_e32 v17, v207
	v_fmamk_f32 v17, v17, 0x3a000000, v181
	v_mul_f32_e32 v18, 0x4b800000, v17
	v_cmp_gt_f32_e32 vcc, s80, v17
	s_nop 1
	v_cndmask_b32_e32 v17, v17, v18, vcc
	v_rsq_f32_e32 v17, v17
	s_nop 0
	v_mul_f32_e32 v18, 0x45800000, v17
	v_cndmask_b32_e32 v32, v17, v18, vcc

.LBB0_742:
	s_cmp_le_i32 s46, s6
	s_cselect_b64 s[0:1], -1, 0
	s_and_b64 s[24:25], s[0:1], s[4:5]
	v_readlane_b32 s0, v244, 12
	s_mul_i32 s1, s0, 0xc000
	s_lshl_b32 s22, s0, 15
	s_mov_b32 s23, s67
	s_lshl_b32 s21, s0, 9
	v_writelane_b32 v244, s1, 25
	s_andn2_b64 vcc, exec, s[24:25]
	s_lshl_b32 s0, s0, 3
	v_writelane_b32 v244, s0, 23
	s_cbranch_vccnz .LBB0_920
	v_readlane_b32 s0, v246, 62
	v_readlane_b32 s1, v245, 17
	v_readlane_b32 s2, v245, 18
	v_readlane_b32 s0, v246, 63
	v_readlane_b32 s3, v245, 55
	v_readlane_b32 s4, v245, 56
	s_waitcnt lgkmcnt(0)
	v_readlane_b32 s0, v245, 0
	v_readlane_b32 s5, v245, 57
	v_readlane_b32 s54, v246, 0
	s_waitcnt lgkmcnt(0)
	v_readlane_b32 s0, v245, 1
	s_waitcnt lgkmcnt(0)
	s_nop 0
	v_readlane_b32 s0, v245, 2
	s_waitcnt lgkmcnt(0)
	s_nop 0
	v_readlane_b32 s0, v245, 3
	s_waitcnt lgkmcnt(0)
	s_nop 0
	v_readlane_b32 s0, v245, 4
	s_waitcnt lgkmcnt(0)
	s_nop 0
	v_readlane_b32 s0, v245, 5
	s_waitcnt lgkmcnt(0)
	s_nop 0
	v_readlane_b32 s0, v245, 6
	s_waitcnt lgkmcnt(0)
	s_nop 0
	v_readlane_b32 s0, v245, 7
	s_waitcnt lgkmcnt(0)
	s_nop 0
	v_readlane_b32 s0, v245, 8
	s_waitcnt lgkmcnt(0)
	s_nop 0
	v_readlane_b32 s0, v245, 9
	s_waitcnt lgkmcnt(0)
	s_nop 0
	v_readlane_b32 s0, v245, 10
	s_waitcnt lgkmcnt(0)
	s_nop 0
	v_readlane_b32 s0, v245, 11
	s_waitcnt lgkmcnt(0)
	s_nop 0
	v_readlane_b32 s0, v245, 12
	s_waitcnt lgkmcnt(0)
	s_nop 0
	v_readlane_b32 s0, v245, 13
	s_waitcnt lgkmcnt(0)
	s_nop 0
	v_readlane_b32 s0, v245, 14
	s_waitcnt lgkmcnt(0)
	s_nop 0
	v_readlane_b32 s0, v245, 15
	s_waitcnt lgkmcnt(0)
	s_nop 0
	v_readlane_b32 s0, v245, 16
	s_waitcnt lgkmcnt(0)
	s_nop 0
	v_mov_b32_e32 v0, s0
	ds_read_b32 v0, v0
	s_waitcnt lgkmcnt(0)
	v_readfirstlane_b32 s0, v0
	v_mov_b32_e32 v0, s1
	ds_read_b32 v0, v0
	s_waitcnt lgkmcnt(0)
	v_readfirstlane_b32 s1, v0
	v_mov_b32_e32 v0, s2
	ds_read_b32 v0, v0
	v_readlane_b32 s2, v245, 19
	s_waitcnt lgkmcnt(0)
	v_readfirstlane_b32 s18, v0
	v_mov_b32_e32 v0, s2
	ds_read_b32 v0, v0
	v_readlane_b32 s2, v245, 20
	s_waitcnt lgkmcnt(0)
	v_readfirstlane_b32 s19, v0
	v_mov_b32_e32 v0, s2
	ds_read_b32 v0, v0
	v_readlane_b32 s2, v245, 21
	s_waitcnt lgkmcnt(0)
	v_readfirstlane_b32 s20, v0
	v_mov_b32_e32 v0, s2
	ds_read_b32 v0, v0
	v_readlane_b32 s2, v245, 22
	s_waitcnt lgkmcnt(0)
	v_readfirstlane_b32 s41, v0
	v_readlane_b32 s2, v245, 23
	s_waitcnt lgkmcnt(0)
	s_nop 0
	v_readlane_b32 s2, v245, 24
	s_waitcnt lgkmcnt(0)
	s_nop 0
	v_mov_b32_e32 v0, s2
	ds_read_b32 v0, v0
	v_readlane_b32 s2, v245, 25
	s_waitcnt lgkmcnt(0)
	v_readfirstlane_b32 s52, v0
	v_mov_b32_e32 v0, s2
	ds_read_b32 v0, v0
	v_readlane_b32 s2, v245, 26
	s_waitcnt lgkmcnt(0)
	v_readfirstlane_b32 s53, v0
	v_mov_b32_e32 v0, s2
	ds_read_b32 v0, v0
	v_readlane_b32 s2, v245, 27
	s_waitcnt lgkmcnt(0)
	v_readfirstlane_b32 s26, v0
	v_mov_b32_e32 v0, s2
	ds_read_b32 v0, v0
	v_readlane_b32 s2, v245, 28
	s_waitcnt lgkmcnt(0)
	v_readfirstlane_b32 s27, v0
	v_readlane_b32 s2, v245, 29
	s_waitcnt lgkmcnt(0)
	s_nop 0
	v_readlane_b32 s2, v245, 30
	s_waitcnt lgkmcnt(0)
	s_nop 0
	v_readlane_b32 s2, v245, 31
	s_waitcnt lgkmcnt(0)
	s_nop 0
	v_readlane_b32 s2, v245, 32
	s_waitcnt lgkmcnt(0)
	s_nop 0
	v_readlane_b32 s2, v245, 33
	s_waitcnt lgkmcnt(0)
	s_nop 0
	v_readlane_b32 s2, v245, 34
	s_waitcnt lgkmcnt(0)
	s_nop 0
	v_readlane_b32 s2, v245, 35
	s_waitcnt lgkmcnt(0)
	s_nop 0
	v_readlane_b32 s2, v245, 36
	s_waitcnt lgkmcnt(0)
	s_nop 0
	v_readlane_b32 s2, v245, 37
	s_waitcnt lgkmcnt(0)
	s_nop 0
	v_readlane_b32 s2, v245, 38
	s_waitcnt lgkmcnt(0)
	s_nop 0
	v_readlane_b32 s2, v245, 39
	s_waitcnt lgkmcnt(0)
	s_nop 0
	v_readlane_b32 s2, v245, 40
	s_waitcnt lgkmcnt(0)
	s_nop 0
	v_readlane_b32 s2, v245, 41
	s_waitcnt lgkmcnt(0)
	s_nop 0
	v_readlane_b32 s2, v245, 42
	s_waitcnt lgkmcnt(0)
	s_nop 0
	v_readlane_b32 s2, v245, 43
	s_waitcnt lgkmcnt(0)
	s_nop 0
	v_readlane_b32 s2, v245, 44
	s_waitcnt lgkmcnt(0)
	s_nop 0
	v_readlane_b32 s2, v245, 45
	s_waitcnt lgkmcnt(0)
	s_nop 0
	v_readlane_b32 s2, v245, 46
	s_waitcnt lgkmcnt(0)
	s_nop 0
	v_readlane_b32 s2, v245, 47
	s_waitcnt lgkmcnt(0)
	s_nop 0
	v_readlane_b32 s2, v245, 48
	s_waitcnt lgkmcnt(0)
	s_nop 0
	v_readlane_b32 s2, v245, 49
	s_waitcnt lgkmcnt(0)
	s_nop 0
	v_readlane_b32 s2, v245, 50
	s_waitcnt lgkmcnt(0)
	s_nop 0
	v_readlane_b32 s2, v245, 51
	s_waitcnt lgkmcnt(0)
	s_nop 0
	v_readlane_b32 s2, v245, 52
	s_waitcnt lgkmcnt(0)
	s_nop 0
	v_readlane_b32 s2, v245, 53
	s_waitcnt lgkmcnt(0)
	s_nop 0
	v_readlane_b32 s2, v245, 54
	s_waitcnt lgkmcnt(0)
	s_nop 0
	v_mov_b32_e32 v0, s2
	ds_read_b32 v0, v0
	s_waitcnt lgkmcnt(0)
	v_readfirstlane_b32 s2, v0
	v_mov_b32_e32 v0, s3
	ds_read_b32 v0, v0
	s_waitcnt lgkmcnt(0)
	v_readfirstlane_b32 s3, v0
	v_mov_b32_e32 v0, s4
	ds_read_b32 v0, v0
	s_waitcnt lgkmcnt(0)
	v_readfirstlane_b32 s4, v0
	v_mov_b32_e32 v0, s5
	ds_read_b32 v0, v0
	s_cmpk_gt_i32 s54, 0x5ff
	s_waitcnt lgkmcnt(0)
	v_readfirstlane_b32 s5, v0
	s_cbranch_scc1 .LBB0_920
	s_add_u32 s28, s4, 0x10d00000
	s_addc_u32 s29, s5, 0
	s_add_u32 s6, s4, 0x19000000
	v_writelane_b32 v244, s6, 21
	s_addc_u32 s6, s5, 0
	v_writelane_b32 v244, s6, 19
	s_add_u32 s6, s4, 0x1a000000
	v_writelane_b32 v244, s6, 26
	s_addc_u32 s6, s5, 0
	v_writelane_b32 v244, s6, 28
	s_add_u32 s6, s4, 0x1b000000
	v_writelane_b32 v244, s6, 29
	s_addc_u32 s6, s5, 0
	s_add_u32 s82, s4, 0x1c000000
	s_addc_u32 s83, s5, 0
	v_writelane_b32 v244, s6, 30
	s_add_u32 s6, s4, 0x1c800000
	v_writelane_b32 v244, s6, 31
	s_addc_u32 s6, s5, 0
	v_writelane_b32 v244, s6, 32
	s_add_u32 s6, s4, 0x1e800000
	v_writelane_b32 v244, s6, 33
	s_addc_u32 s6, s5, 0
	v_writelane_b32 v244, s6, 34
	s_add_u32 s6, s4, 0x1f000000
	v_writelane_b32 v244, s6, 35
	s_addc_u32 s6, s5, 0
	s_add_u32 s68, s4, 0x1f800000
	s_addc_u32 s69, s5, 0
	v_writelane_b32 v244, s6, 36
	s_add_u32 s6, s4, 0x1fc00000
	v_writelane_b32 v244, s6, 37
	s_addc_u32 s6, s5, 0
	s_add_u32 s75, s4, 0x20c00000
	v_writelane_b32 v244, s6, 38
	s_addc_u32 s84, s5, 0
	s_add_u32 s88, s4, 0x20d00000
	v_readlane_b32 s4, v244, 12
	s_addc_u32 s89, s5, 0
	s_lshl_b32 s40, s4, 2
	v_readlane_b32 s4, v244, 25
	s_add_u32 s30, s0, s4
	s_addc_u32 s31, s1, 0
	s_add_u32 s34, s2, 0x4c00000
	s_addc_u32 s35, s3, 0
	s_branch .LBB0_747

.LBB0_870:
	s_or_b64 exec, exec, s[2:3]
	s_movk_i32 s0, 0x100
	v_cmp_gt_i32_e64 s[0:1], s0, v30
	s_waitcnt lgkmcnt(0)
	s_barrier
	s_and_saveexec_b64 s[12:13], s[0:1]
	s_cbranch_execz .LBB0_911
	v_lshrrev_b32_e32 v2, 6, v30
	v_lshlrev_b32_e32 v0, 2, v30
	v_readfirstlane_b32 s14, v2
	v_mov_b32_e32 v1, 0x18c00
	v_lshlrev_b32_e32 v3, 2, v182
	v_add_u32_e32 v3, 0x1cc00, v3
	ds_read_b32 v82, v3
	s_cmp_lt_u32 s14, 2
	s_cbranch_scc1 .Lsv_vcol
	v_add_u32_e32 v0, 0x8200, v0
	ds_read_b32 v83, v3 offset:256
	s_waitcnt lgkmcnt(0)
	v_mul_f32_e32 v83, 0x3fb8aa3b, v83
	v_exp_f32_e32 v83, v83
	s_nop 0
	v_mul_f32_e32 v82, v82, v83
	s_branch .Lsv_common
.Lsv_vcol:
	v_add_u32_e32 v0, 0x10800, v0
.Lsv_common:
	ds_read_b32 v190, v0 offset:0
	ds_read_b32 v191, v0 offset:528
	ds_read_b32 v192, v0 offset:1056
	ds_read_b32 v193, v0 offset:1584
	ds_read_b32 v194, v0 offset:2112
	ds_read_b32 v195, v0 offset:2640
	ds_read_b32 v196, v0 offset:3168
	ds_read_b32 v197, v0 offset:3696
	ds_read_b32 v198, v0 offset:4224
	ds_read_b32 v199, v0 offset:4752
	ds_read_b32 v200, v0 offset:5280
	ds_read_b32 v201, v0 offset:5808
	ds_read_b32 v202, v0 offset:6336
	ds_read_b32 v203, v0 offset:6864
	ds_read_b32 v204, v0 offset:7392
	ds_read_b32 v205, v0 offset:7920
	ds_read_b32 v206, v0 offset:8448
	ds_read_b32 v207, v0 offset:8976
	ds_read_b32 v208, v0 offset:9504
	ds_read_b32 v209, v0 offset:10032
	ds_read_b32 v210, v0 offset:10560
	ds_read_b32 v211, v0 offset:11088
	ds_read_b32 v212, v0 offset:11616
	ds_read_b32 v213, v0 offset:12144
	ds_read_b32 v214, v0 offset:12672
	ds_read_b32 v215, v0 offset:13200
	ds_read_b32 v216, v0 offset:13728
	ds_read_b32 v217, v0 offset:14256
	ds_read_b32 v218, v0 offset:14784
	ds_read_b32 v219, v0 offset:15312
	ds_read_b32 v220, v0 offset:15840
	ds_read_b32 v221, v0 offset:16368
	ds_read_b32 v222, v0 offset:16896
	ds_read_b32 v223, v0 offset:17424
	ds_read_b32 v224, v0 offset:17952
	ds_read_b32 v225, v0 offset:18480
	ds_read_b32 v226, v0 offset:19008
	ds_read_b32 v227, v0 offset:19536
	ds_read_b32 v228, v0 offset:20064
	ds_read_b32 v229, v0 offset:20592
	ds_read_b32 v230, v0 offset:21120
	ds_read_b32 v231, v0 offset:21648
	ds_read_b32 v232, v0 offset:22176
	ds_read_b32 v233, v0 offset:22704
	ds_read_b32 v234, v0 offset:23232
	ds_read_b32 v235, v0 offset:23760
	ds_read_b32 v236, v0 offset:24288
	ds_read_b32 v237, v0 offset:24816
	ds_read_b32 v238, v0 offset:25344
	ds_read_b32 v239, v0 offset:25872
	ds_read_b32 v240, v0 offset:26400
	ds_read_b32 v241, v0 offset:26928
	ds_read_b32 v242, v0 offset:27456
	ds_read_b32 v243, v0 offset:27984
	ds_read_b32 v248, v0 offset:28512
	ds_read_b32 v249, v0 offset:29040
	ds_read_b32 v250, v0 offset:29568
	ds_read_b32 v251, v0 offset:30096
	ds_read_b32 v252, v0 offset:30624
	ds_read_b32 v253, v0 offset:31152
	ds_read_b32 v254, v0 offset:31680
	ds_read_b32 v255, v0 offset:32208
	ds_read_b32 v106, v0 offset:32736
	ds_read_b32 v107, v0 offset:33264
	s_waitcnt lgkmcnt(0)
	ds_read_b128 v[32:35], v1 offset:0
	ds_read_b128 v[36:39], v1 offset:16
	ds_read_b128 v[40:43], v1 offset:32
	ds_read_b128 v[44:47], v1 offset:48
	ds_read_b128 v[48:51], v1 offset:256
	ds_read_b128 v[52:55], v1 offset:272
	ds_read_b128 v[56:59], v1 offset:288
	ds_read_b128 v[60:63], v1 offset:304
	v_readlane_b32 s0, v82, 0
	v_readlane_b32 s1, v82, 1
	v_readlane_b32 s2, v82, 2
	v_readlane_b32 s3, v82, 3
	v_readlane_b32 s4, v82, 4
	v_readlane_b32 s5, v82, 5
	v_readlane_b32 s6, v82, 6
	v_readlane_b32 s7, v82, 7
	v_mul_f32_e32 v190, s0, v190
	v_mul_f32_e32 v191, s1, v191
	v_mul_f32_e32 v192, s2, v192
	v_mul_f32_e32 v193, s3, v193
	v_mul_f32_e32 v194, s4, v194
	v_mul_f32_e32 v195, s5, v195
	v_mul_f32_e32 v196, s6, v196
	v_mul_f32_e32 v197, s7, v197
	v_readlane_b32 s0, v82, 8
	v_readlane_b32 s1, v82, 9
	v_readlane_b32 s2, v82, 10
	v_readlane_b32 s3, v82, 11
	v_readlane_b32 s4, v82, 12
	v_readlane_b32 s5, v82, 13
	v_readlane_b32 s6, v82, 14
	v_readlane_b32 s7, v82, 15
	v_mul_f32_e32 v198, s0, v198
	v_mul_f32_e32 v199, s1, v199
	v_mul_f32_e32 v200, s2, v200
	v_mul_f32_e32 v201, s3, v201
	v_mul_f32_e32 v202, s4, v202
	v_mul_f32_e32 v203, s5, v203
	v_mul_f32_e32 v204, s6, v204
	v_mul_f32_e32 v205, s7, v205
	v_readlane_b32 s0, v82, 16
	v_readlane_b32 s1, v82, 17
	v_readlane_b32 s2, v82, 18
	v_readlane_b32 s3, v82, 19
	v_readlane_b32 s4, v82, 20
	v_readlane_b32 s5, v82, 21
	v_readlane_b32 s6, v82, 22
	v_readlane_b32 s7, v82, 23
	v_mul_f32_e32 v206, s0, v206
	v_mul_f32_e32 v207, s1, v207
	v_mul_f32_e32 v208, s2, v208
	v_mul_f32_e32 v209, s3, v209
	v_mul_f32_e32 v210, s4, v210
	v_mul_f32_e32 v211, s5, v211
	v_mul_f32_e32 v212, s6, v212
	v_mul_f32_e32 v213, s7, v213
	v_readlane_b32 s0, v82, 24
	v_readlane_b32 s1, v82, 25
	v_readlane_b32 s2, v82, 26
	v_readlane_b32 s3, v82, 27
	v_readlane_b32 s4, v82, 28
	v_readlane_b32 s5, v82, 29
	v_readlane_b32 s6, v82, 30
	v_readlane_b32 s7, v82, 31
	v_mul_f32_e32 v214, s0, v214
	v_mul_f32_e32 v215, s1, v215
	v_mul_f32_e32 v216, s2, v216
	v_mul_f32_e32 v217, s3, v217
	v_mul_f32_e32 v218, s4, v218
	v_mul_f32_e32 v219, s5, v219
	v_mul_f32_e32 v220, s6, v220
	v_mul_f32_e32 v221, s7, v221
	v_readlane_b32 s0, v82, 32
	v_readlane_b32 s1, v82, 33
	v_readlane_b32 s2, v82, 34
	v_readlane_b32 s3, v82, 35
	v_readlane_b32 s4, v82, 36
	v_readlane_b32 s5, v82, 37
	v_readlane_b32 s6, v82, 38
	v_readlane_b32 s7, v82, 39
	v_mul_f32_e32 v222, s0, v222
	v_mul_f32_e32 v223, s1, v223
	v_mul_f32_e32 v224, s2, v224
	v_mul_f32_e32 v225, s3, v225
	v_mul_f32_e32 v226, s4, v226
	v_mul_f32_e32 v227, s5, v227
	v_mul_f32_e32 v228, s6, v228
	v_mul_f32_e32 v229, s7, v229
	v_readlane_b32 s0, v82, 40
	v_readlane_b32 s1, v82, 41
	v_readlane_b32 s2, v82, 42
	v_readlane_b32 s3, v82, 43
	v_readlane_b32 s4, v82, 44
	v_readlane_b32 s5, v82, 45
	v_readlane_b32 s6, v82, 46
	v_readlane_b32 s7, v82, 47
	v_mul_f32_e32 v230, s0, v230
	v_mul_f32_e32 v231, s1, v231
	v_mul_f32_e32 v232, s2, v232
	v_mul_f32_e32 v233, s3, v233
	v_mul_f32_e32 v234, s4, v234
	v_mul_f32_e32 v235, s5, v235
	v_mul_f32_e32 v236, s6, v236
	v_mul_f32_e32 v237, s7, v237
	v_readlane_b32 s0, v82, 48
	v_readlane_b32 s1, v82, 49
	v_readlane_b32 s2, v82, 50
	v_readlane_b32 s3, v82, 51
	v_readlane_b32 s4, v82, 52
	v_readlane_b32 s5, v82, 53
	v_readlane_b32 s6, v82, 54
	v_readlane_b32 s7, v82, 55
	v_mul_f32_e32 v238, s0, v238
	v_mul_f32_e32 v239, s1, v239
	v_mul_f32_e32 v240, s2, v240
	v_mul_f32_e32 v241, s3, v241
	v_mul_f32_e32 v242, s4, v242
	v_mul_f32_e32 v243, s5, v243
	v_mul_f32_e32 v248, s6, v248
	v_mul_f32_e32 v249, s7, v249
	v_readlane_b32 s0, v82, 56
	v_readlane_b32 s1, v82, 57
	v_readlane_b32 s2, v82, 58
	v_readlane_b32 s3, v82, 59
	v_readlane_b32 s4, v82, 60
	v_readlane_b32 s5, v82, 61
	v_readlane_b32 s6, v82, 62
	v_readlane_b32 s7, v82, 63
	v_mul_f32_e32 v250, s0, v250
	v_mul_f32_e32 v251, s1, v251
	v_mul_f32_e32 v252, s2, v252
	v_mul_f32_e32 v253, s3, v253
	v_mul_f32_e32 v254, s4, v254
	v_mul_f32_e32 v255, s5, v255
	v_mul_f32_e32 v106, s6, v106
	v_mul_f32_e32 v107, s7, v107
	ds_read_b128 v[64:67], v1 offset:512
	ds_read_b128 v[68:71], v1 offset:528
	ds_read_b128 v[72:75], v1 offset:544
	ds_read_b128 v[76:79], v1 offset:560
	s_waitcnt lgkmcnt(8)
	v_fma_f32 v191, -v190, v33, v191
	v_pk_fma_f32 v[192:193], v[190:191], v[34:35], v[192:193] op_sel_hi:[0,1,1] neg_lo:[1,0,0] neg_hi:[1,0,0]
	v_pk_fma_f32 v[194:195], v[190:191], v[36:37], v[194:195] op_sel_hi:[0,1,1] neg_lo:[1,0,0] neg_hi:[1,0,0]
	v_pk_fma_f32 v[196:197], v[190:191], v[38:39], v[196:197] op_sel_hi:[0,1,1] neg_lo:[1,0,0] neg_hi:[1,0,0]
	v_pk_fma_f32 v[198:199], v[190:191], v[40:41], v[198:199] op_sel_hi:[0,1,1] neg_lo:[1,0,0] neg_hi:[1,0,0]
	v_pk_fma_f32 v[200:201], v[190:191], v[42:43], v[200:201] op_sel_hi:[0,1,1] neg_lo:[1,0,0] neg_hi:[1,0,0]
	v_pk_fma_f32 v[202:203], v[190:191], v[44:45], v[202:203] op_sel_hi:[0,1,1] neg_lo:[1,0,0] neg_hi:[1,0,0]
	v_pk_fma_f32 v[204:205], v[190:191], v[46:47], v[204:205] op_sel_hi:[0,1,1] neg_lo:[1,0,0] neg_hi:[1,0,0]
	ds_read_b128 v[36:39], v1 offset:784
	ds_read_b128 v[40:43], v1 offset:800
	ds_read_b128 v[44:47], v1 offset:816
	s_waitcnt lgkmcnt(7)
	v_mov_b32_e32 v80, v191
	v_pk_fma_f32 v[192:193], v[80:81], v[50:51], v[192:193] op_sel_hi:[0,1,1] neg_lo:[1,0,0] neg_hi:[1,0,0]
	v_pk_fma_f32 v[194:195], v[80:81], v[52:53], v[194:195] op_sel_hi:[0,1,1] neg_lo:[1,0,0] neg_hi:[1,0,0]
	v_pk_fma_f32 v[196:197], v[80:81], v[54:55], v[196:197] op_sel_hi:[0,1,1] neg_lo:[1,0,0] neg_hi:[1,0,0]
	v_pk_fma_f32 v[198:199], v[80:81], v[56:57], v[198:199] op_sel_hi:[0,1,1] neg_lo:[1,0,0] neg_hi:[1,0,0]
	v_pk_fma_f32 v[200:201], v[80:81], v[58:59], v[200:201] op_sel_hi:[0,1,1] neg_lo:[1,0,0] neg_hi:[1,0,0]
	v_pk_fma_f32 v[202:203], v[80:81], v[60:61], v[202:203] op_sel_hi:[0,1,1] neg_lo:[1,0,0] neg_hi:[1,0,0]
	v_pk_fma_f32 v[204:205], v[80:81], v[62:63], v[204:205] op_sel_hi:[0,1,1] neg_lo:[1,0,0] neg_hi:[1,0,0]
	ds_read_b128 v[52:55], v1 offset:1040
	ds_read_b128 v[56:59], v1 offset:1056
	ds_read_b128 v[60:63], v1 offset:1072
	s_waitcnt lgkmcnt(6)
	v_fma_f32 v193, -v192, v67, v193
	v_pk_fma_f32 v[194:195], v[192:193], v[68:69], v[194:195] op_sel_hi:[0,1,1] neg_lo:[1,0,0] neg_hi:[1,0,0]
	v_pk_fma_f32 v[196:197], v[192:193], v[70:71], v[196:197] op_sel_hi:[0,1,1] neg_lo:[1,0,0] neg_hi:[1,0,0]
	v_pk_fma_f32 v[198:199], v[192:193], v[72:73], v[198:199] op_sel_hi:[0,1,1] neg_lo:[1,0,0] neg_hi:[1,0,0]
	v_pk_fma_f32 v[200:201], v[192:193], v[74:75], v[200:201] op_sel_hi:[0,1,1] neg_lo:[1,0,0] neg_hi:[1,0,0]
	v_pk_fma_f32 v[202:203], v[192:193], v[76:77], v[202:203] op_sel_hi:[0,1,1] neg_lo:[1,0,0] neg_hi:[1,0,0]
	v_pk_fma_f32 v[204:205], v[192:193], v[78:79], v[204:205] op_sel_hi:[0,1,1] neg_lo:[1,0,0] neg_hi:[1,0,0]
	ds_read_b128 v[68:71], v1 offset:1296
	ds_read_b128 v[72:75], v1 offset:1312
	ds_read_b128 v[76:79], v1 offset:1328
	s_waitcnt lgkmcnt(6)
	v_mov_b32_e32 v80, v193
	v_pk_fma_f32 v[194:195], v[80:81], v[36:37], v[194:195] op_sel_hi:[0,1,1] neg_lo:[1,0,0] neg_hi:[1,0,0]
	v_pk_fma_f32 v[196:197], v[80:81], v[38:39], v[196:197] op_sel_hi:[0,1,1] neg_lo:[1,0,0] neg_hi:[1,0,0]
	v_pk_fma_f32 v[198:199], v[80:81], v[40:41], v[198:199] op_sel_hi:[0,1,1] neg_lo:[1,0,0] neg_hi:[1,0,0]
	v_pk_fma_f32 v[200:201], v[80:81], v[42:43], v[200:201] op_sel_hi:[0,1,1] neg_lo:[1,0,0] neg_hi:[1,0,0]
	v_pk_fma_f32 v[202:203], v[80:81], v[44:45], v[202:203] op_sel_hi:[0,1,1] neg_lo:[1,0,0] neg_hi:[1,0,0]
	v_pk_fma_f32 v[204:205], v[80:81], v[46:47], v[204:205] op_sel_hi:[0,1,1] neg_lo:[1,0,0] neg_hi:[1,0,0]
	ds_read_b128 v[36:39], v1 offset:1552
	ds_read_b128 v[40:43], v1 offset:1568
	ds_read_b128 v[44:47], v1 offset:1584
	s_waitcnt lgkmcnt(6)
	v_fma_f32 v195, -v194, v53, v195
	v_pk_fma_f32 v[196:197], v[194:195], v[54:55], v[196:197] op_sel_hi:[0,1,1] neg_lo:[1,0,0] neg_hi:[1,0,0]
	v_pk_fma_f32 v[198:199], v[194:195], v[56:57], v[198:199] op_sel_hi:[0,1,1] neg_lo:[1,0,0] neg_hi:[1,0,0]
	v_pk_fma_f32 v[200:201], v[194:195], v[58:59], v[200:201] op_sel_hi:[0,1,1] neg_lo:[1,0,0] neg_hi:[1,0,0]
	v_pk_fma_f32 v[202:203], v[194:195], v[60:61], v[202:203] op_sel_hi:[0,1,1] neg_lo:[1,0,0] neg_hi:[1,0,0]
	v_pk_fma_f32 v[204:205], v[194:195], v[62:63], v[204:205] op_sel_hi:[0,1,1] neg_lo:[1,0,0] neg_hi:[1,0,0]
	ds_read_b128 v[56:59], v1 offset:1824
	ds_read_b128 v[60:63], v1 offset:1840
	s_waitcnt lgkmcnt(5)
	v_mov_b32_e32 v80, v195
	v_pk_fma_f32 v[196:197], v[80:81], v[70:71], v[196:197] op_sel_hi:[0,1,1] neg_lo:[1,0,0] neg_hi:[1,0,0]
	v_pk_fma_f32 v[198:199], v[80:81], v[72:73], v[198:199] op_sel_hi:[0,1,1] neg_lo:[1,0,0] neg_hi:[1,0,0]
	v_pk_fma_f32 v[200:201], v[80:81], v[74:75], v[200:201] op_sel_hi:[0,1,1] neg_lo:[1,0,0] neg_hi:[1,0,0]
	v_pk_fma_f32 v[202:203], v[80:81], v[76:77], v[202:203] op_sel_hi:[0,1,1] neg_lo:[1,0,0] neg_hi:[1,0,0]
	v_pk_fma_f32 v[204:205], v[80:81], v[78:79], v[204:205] op_sel_hi:[0,1,1] neg_lo:[1,0,0] neg_hi:[1,0,0]
	ds_read_b128 v[72:75], v1 offset:2080
	ds_read_b128 v[76:79], v1 offset:2096
	s_waitcnt lgkmcnt(4)
	v_fma_f32 v197, -v196, v39, v197
	v_pk_fma_f32 v[198:199], v[196:197], v[40:41], v[198:199] op_sel_hi:[0,1,1] neg_lo:[1,0,0] neg_hi:[1,0,0]
	v_pk_fma_f32 v[200:201], v[196:197], v[42:43], v[200:201] op_sel_hi:[0,1,1] neg_lo:[1,0,0] neg_hi:[1,0,0]
	v_pk_fma_f32 v[202:203], v[196:197], v[44:45], v[202:203] op_sel_hi:[0,1,1] neg_lo:[1,0,0] neg_hi:[1,0,0]
	v_pk_fma_f32 v[204:205], v[196:197], v[46:47], v[204:205] op_sel_hi:[0,1,1] neg_lo:[1,0,0] neg_hi:[1,0,0]
	ds_read_b128 v[40:43], v1 offset:2336
	ds_read_b128 v[44:47], v1 offset:2352
	s_waitcnt lgkmcnt(4)
	v_mov_b32_e32 v80, v197
	v_pk_fma_f32 v[198:199], v[80:81], v[56:57], v[198:199] op_sel_hi:[0,1,1] neg_lo:[1,0,0] neg_hi:[1,0,0]
	v_pk_fma_f32 v[200:201], v[80:81], v[58:59], v[200:201] op_sel_hi:[0,1,1] neg_lo:[1,0,0] neg_hi:[1,0,0]
	v_pk_fma_f32 v[202:203], v[80:81], v[60:61], v[202:203] op_sel_hi:[0,1,1] neg_lo:[1,0,0] neg_hi:[1,0,0]
	v_pk_fma_f32 v[204:205], v[80:81], v[62:63], v[204:205] op_sel_hi:[0,1,1] neg_lo:[1,0,0] neg_hi:[1,0,0]
	ds_read_b128 v[56:59], v1 offset:2592
	ds_read_b128 v[60:63], v1 offset:2608
	s_waitcnt lgkmcnt(4)
	v_fma_f32 v199, -v198, v73, v199
	v_pk_fma_f32 v[200:201], v[198:199], v[74:75], v[200:201] op_sel_hi:[0,1,1] neg_lo:[1,0,0] neg_hi:[1,0,0]
	v_pk_fma_f32 v[202:203], v[198:199], v[76:77], v[202:203] op_sel_hi:[0,1,1] neg_lo:[1,0,0] neg_hi:[1,0,0]
	v_pk_fma_f32 v[204:205], v[198:199], v[78:79], v[204:205] op_sel_hi:[0,1,1] neg_lo:[1,0,0] neg_hi:[1,0,0]
	ds_read_b128 v[76:79], v1 offset:2864
	s_waitcnt lgkmcnt(3)
	v_mov_b32_e32 v80, v199
	v_pk_fma_f32 v[200:201], v[80:81], v[42:43], v[200:201] op_sel_hi:[0,1,1] neg_lo:[1,0,0] neg_hi:[1,0,0]
	v_pk_fma_f32 v[202:203], v[80:81], v[44:45], v[202:203] op_sel_hi:[0,1,1] neg_lo:[1,0,0] neg_hi:[1,0,0]
	v_pk_fma_f32 v[204:205], v[80:81], v[46:47], v[204:205] op_sel_hi:[0,1,1] neg_lo:[1,0,0] neg_hi:[1,0,0]
	ds_read_b128 v[44:47], v1 offset:3120
	s_waitcnt lgkmcnt(2)
	v_fma_f32 v201, -v200, v59, v201
	v_pk_fma_f32 v[202:203], v[200:201], v[60:61], v[202:203] op_sel_hi:[0,1,1] neg_lo:[1,0,0] neg_hi:[1,0,0]
	v_pk_fma_f32 v[204:205], v[200:201], v[62:63], v[204:205] op_sel_hi:[0,1,1] neg_lo:[1,0,0] neg_hi:[1,0,0]
	ds_read_b128 v[60:63], v1 offset:3376
	s_waitcnt lgkmcnt(2)
	v_mov_b32_e32 v80, v201
	v_pk_fma_f32 v[202:203], v[80:81], v[76:77], v[202:203] op_sel_hi:[0,1,1] neg_lo:[1,0,0] neg_hi:[1,0,0]
	v_pk_fma_f32 v[204:205], v[80:81], v[78:79], v[204:205] op_sel_hi:[0,1,1] neg_lo:[1,0,0] neg_hi:[1,0,0]
	ds_read_b128 v[76:79], v1 offset:3632
	s_waitcnt lgkmcnt(2)
	v_fma_f32 v203, -v202, v45, v203
	v_pk_fma_f32 v[204:205], v[202:203], v[46:47], v[204:205] op_sel_hi:[0,1,1] neg_lo:[1,0,0] neg_hi:[1,0,0]
	ds_read_b128 v[32:35], v1 offset:64
	ds_read_b128 v[36:39], v1 offset:80
	ds_read_b128 v[40:43], v1 offset:96
	ds_read_b128 v[44:47], v1 offset:112
	s_waitcnt lgkmcnt(5)
	v_mov_b32_e32 v80, v203
	v_pk_fma_f32 v[204:205], v[80:81], v[62:63], v[204:205] op_sel_hi:[0,1,1] neg_lo:[1,0,0] neg_hi:[1,0,0]
	ds_read_b128 v[48:51], v1 offset:320
	ds_read_b128 v[52:55], v1 offset:336
	ds_read_b128 v[56:59], v1 offset:352
	ds_read_b128 v[60:63], v1 offset:368
	s_waitcnt lgkmcnt(8)
	v_fma_f32 v205, -v204, v79, v205
	ds_read_b128 v[64:67], v1 offset:576
	ds_read_b128 v[68:71], v1 offset:592
	ds_read_b128 v[72:75], v1 offset:608
	ds_read_b128 v[76:79], v1 offset:624
	s_waitcnt lgkmcnt(8)
	v_pk_fma_f32 v[206:207], v[190:191], v[32:33], v[206:207] op_sel_hi:[0,1,1] neg_lo:[1,0,0] neg_hi:[1,0,0]
	v_pk_fma_f32 v[208:209], v[190:191], v[34:35], v[208:209] op_sel_hi:[0,1,1] neg_lo:[1,0,0] neg_hi:[1,0,0]
	v_pk_fma_f32 v[210:211], v[190:191], v[36:37], v[210:211] op_sel_hi:[0,1,1] neg_lo:[1,0,0] neg_hi:[1,0,0]
	v_pk_fma_f32 v[212:213], v[190:191], v[38:39], v[212:213] op_sel_hi:[0,1,1] neg_lo:[1,0,0] neg_hi:[1,0,0]
	v_pk_fma_f32 v[214:215], v[190:191], v[40:41], v[214:215] op_sel_hi:[0,1,1] neg_lo:[1,0,0] neg_hi:[1,0,0]
	v_pk_fma_f32 v[216:217], v[190:191], v[42:43], v[216:217] op_sel_hi:[0,1,1] neg_lo:[1,0,0] neg_hi:[1,0,0]
	v_pk_fma_f32 v[218:219], v[190:191], v[44:45], v[218:219] op_sel_hi:[0,1,1] neg_lo:[1,0,0] neg_hi:[1,0,0]
	v_pk_fma_f32 v[220:221], v[190:191], v[46:47], v[220:221] op_sel_hi:[0,1,1] neg_lo:[1,0,0] neg_hi:[1,0,0]
	ds_read_b128 v[32:35], v1 offset:832
	ds_read_b128 v[36:39], v1 offset:848
	ds_read_b128 v[40:43], v1 offset:864
	ds_read_b128 v[44:47], v1 offset:880
	s_waitcnt lgkmcnt(8)
	v_mov_b32_e32 v80, v191
	v_pk_fma_f32 v[206:207], v[80:81], v[48:49], v[206:207] op_sel_hi:[0,1,1] neg_lo:[1,0,0] neg_hi:[1,0,0]
	v_pk_fma_f32 v[208:209], v[80:81], v[50:51], v[208:209] op_sel_hi:[0,1,1] neg_lo:[1,0,0] neg_hi:[1,0,0]
	v_pk_fma_f32 v[210:211], v[80:81], v[52:53], v[210:211] op_sel_hi:[0,1,1] neg_lo:[1,0,0] neg_hi:[1,0,0]
	v_pk_fma_f32 v[212:213], v[80:81], v[54:55], v[212:213] op_sel_hi:[0,1,1] neg_lo:[1,0,0] neg_hi:[1,0,0]
	v_pk_fma_f32 v[214:215], v[80:81], v[56:57], v[214:215] op_sel_hi:[0,1,1] neg_lo:[1,0,0] neg_hi:[1,0,0]
	v_pk_fma_f32 v[216:217], v[80:81], v[58:59], v[216:217] op_sel_hi:[0,1,1] neg_lo:[1,0,0] neg_hi:[1,0,0]
	v_pk_fma_f32 v[218:219], v[80:81], v[60:61], v[218:219] op_sel_hi:[0,1,1] neg_lo:[1,0,0] neg_hi:[1,0,0]
	v_pk_fma_f32 v[220:221], v[80:81], v[62:63], v[220:221] op_sel_hi:[0,1,1] neg_lo:[1,0,0] neg_hi:[1,0,0]
	ds_read_b128 v[48:51], v1 offset:1088
	ds_read_b128 v[52:55], v1 offset:1104
	ds_read_b128 v[56:59], v1 offset:1120
	ds_read_b128 v[60:63], v1 offset:1136
	s_waitcnt lgkmcnt(8)
	v_pk_fma_f32 v[206:207], v[192:193], v[64:65], v[206:207] op_sel_hi:[0,1,1] neg_lo:[1,0,0] neg_hi:[1,0,0]
	v_pk_fma_f32 v[208:209], v[192:193], v[66:67], v[208:209] op_sel_hi:[0,1,1] neg_lo:[1,0,0] neg_hi:[1,0,0]
	v_pk_fma_f32 v[210:211], v[192:193], v[68:69], v[210:211] op_sel_hi:[0,1,1] neg_lo:[1,0,0] neg_hi:[1,0,0]
	v_pk_fma_f32 v[212:213], v[192:193], v[70:71], v[212:213] op_sel_hi:[0,1,1] neg_lo:[1,0,0] neg_hi:[1,0,0]
	v_pk_fma_f32 v[214:215], v[192:193], v[72:73], v[214:215] op_sel_hi:[0,1,1] neg_lo:[1,0,0] neg_hi:[1,0,0]
	v_pk_fma_f32 v[216:217], v[192:193], v[74:75], v[216:217] op_sel_hi:[0,1,1] neg_lo:[1,0,0] neg_hi:[1,0,0]
	v_pk_fma_f32 v[218:219], v[192:193], v[76:77], v[218:219] op_sel_hi:[0,1,1] neg_lo:[1,0,0] neg_hi:[1,0,0]
	v_pk_fma_f32 v[220:221], v[192:193], v[78:79], v[220:221] op_sel_hi:[0,1,1] neg_lo:[1,0,0] neg_hi:[1,0,0]
	ds_read_b128 v[64:67], v1 offset:1344
	ds_read_b128 v[68:71], v1 offset:1360
	ds_read_b128 v[72:75], v1 offset:1376
	ds_read_b128 v[76:79], v1 offset:1392
	s_waitcnt lgkmcnt(8)
	v_mov_b32_e32 v80, v193
	v_pk_fma_f32 v[206:207], v[80:81], v[32:33], v[206:207] op_sel_hi:[0,1,1] neg_lo:[1,0,0] neg_hi:[1,0,0]
	v_pk_fma_f32 v[208:209], v[80:81], v[34:35], v[208:209] op_sel_hi:[0,1,1] neg_lo:[1,0,0] neg_hi:[1,0,0]
	v_pk_fma_f32 v[210:211], v[80:81], v[36:37], v[210:211] op_sel_hi:[0,1,1] neg_lo:[1,0,0] neg_hi:[1,0,0]
	v_pk_fma_f32 v[212:213], v[80:81], v[38:39], v[212:213] op_sel_hi:[0,1,1] neg_lo:[1,0,0] neg_hi:[1,0,0]
	v_pk_fma_f32 v[214:215], v[80:81], v[40:41], v[214:215] op_sel_hi:[0,1,1] neg_lo:[1,0,0] neg_hi:[1,0,0]
	v_pk_fma_f32 v[216:217], v[80:81], v[42:43], v[216:217] op_sel_hi:[0,1,1] neg_lo:[1,0,0] neg_hi:[1,0,0]
	v_pk_fma_f32 v[218:219], v[80:81], v[44:45], v[218:219] op_sel_hi:[0,1,1] neg_lo:[1,0,0] neg_hi:[1,0,0]
	v_pk_fma_f32 v[220:221], v[80:81], v[46:47], v[220:221] op_sel_hi:[0,1,1] neg_lo:[1,0,0] neg_hi:[1,0,0]
	ds_read_b128 v[32:35], v1 offset:1600
	ds_read_b128 v[36:39], v1 offset:1616
	ds_read_b128 v[40:43], v1 offset:1632
	ds_read_b128 v[44:47], v1 offset:1648
	s_waitcnt lgkmcnt(8)
	v_pk_fma_f32 v[206:207], v[194:195], v[48:49], v[206:207] op_sel_hi:[0,1,1] neg_lo:[1,0,0] neg_hi:[1,0,0]
	v_pk_fma_f32 v[208:209], v[194:195], v[50:51], v[208:209] op_sel_hi:[0,1,1] neg_lo:[1,0,0] neg_hi:[1,0,0]
	v_pk_fma_f32 v[210:211], v[194:195], v[52:53], v[210:211] op_sel_hi:[0,1,1] neg_lo:[1,0,0] neg_hi:[1,0,0]
	v_pk_fma_f32 v[212:213], v[194:195], v[54:55], v[212:213] op_sel_hi:[0,1,1] neg_lo:[1,0,0] neg_hi:[1,0,0]
	v_pk_fma_f32 v[214:215], v[194:195], v[56:57], v[214:215] op_sel_hi:[0,1,1] neg_lo:[1,0,0] neg_hi:[1,0,0]
	v_pk_fma_f32 v[216:217], v[194:195], v[58:59], v[216:217] op_sel_hi:[0,1,1] neg_lo:[1,0,0] neg_hi:[1,0,0]
	v_pk_fma_f32 v[218:219], v[194:195], v[60:61], v[218:219] op_sel_hi:[0,1,1] neg_lo:[1,0,0] neg_hi:[1,0,0]
	v_pk_fma_f32 v[220:221], v[194:195], v[62:63], v[220:221] op_sel_hi:[0,1,1] neg_lo:[1,0,0] neg_hi:[1,0,0]
	ds_read_b128 v[48:51], v1 offset:1856
	ds_read_b128 v[52:55], v1 offset:1872
	ds_read_b128 v[56:59], v1 offset:1888
	ds_read_b128 v[60:63], v1 offset:1904
	s_waitcnt lgkmcnt(8)
	v_mov_b32_e32 v80, v195
	v_pk_fma_f32 v[206:207], v[80:81], v[64:65], v[206:207] op_sel_hi:[0,1,1] neg_lo:[1,0,0] neg_hi:[1,0,0]
	v_pk_fma_f32 v[208:209], v[80:81], v[66:67], v[208:209] op_sel_hi:[0,1,1] neg_lo:[1,0,0] neg_hi:[1,0,0]
	v_pk_fma_f32 v[210:211], v[80:81], v[68:69], v[210:211] op_sel_hi:[0,1,1] neg_lo:[1,0,0] neg_hi:[1,0,0]
	v_pk_fma_f32 v[212:213], v[80:81], v[70:71], v[212:213] op_sel_hi:[0,1,1] neg_lo:[1,0,0] neg_hi:[1,0,0]
	v_pk_fma_f32 v[214:215], v[80:81], v[72:73], v[214:215] op_sel_hi:[0,1,1] neg_lo:[1,0,0] neg_hi:[1,0,0]
	v_pk_fma_f32 v[216:217], v[80:81], v[74:75], v[216:217] op_sel_hi:[0,1,1] neg_lo:[1,0,0] neg_hi:[1,0,0]
	v_pk_fma_f32 v[218:219], v[80:81], v[76:77], v[218:219] op_sel_hi:[0,1,1] neg_lo:[1,0,0] neg_hi:[1,0,0]
	v_pk_fma_f32 v[220:221], v[80:81], v[78:79], v[220:221] op_sel_hi:[0,1,1] neg_lo:[1,0,0] neg_hi:[1,0,0]
	ds_read_b128 v[64:67], v1 offset:2112
	ds_read_b128 v[68:71], v1 offset:2128
	ds_read_b128 v[72:75], v1 offset:2144
	ds_read_b128 v[76:79], v1 offset:2160
	s_waitcnt lgkmcnt(8)
	v_pk_fma_f32 v[206:207], v[196:197], v[32:33], v[206:207] op_sel_hi:[0,1,1] neg_lo:[1,0,0] neg_hi:[1,0,0]
	v_pk_fma_f32 v[208:209], v[196:197], v[34:35], v[208:209] op_sel_hi:[0,1,1] neg_lo:[1,0,0] neg_hi:[1,0,0]
	v_pk_fma_f32 v[210:211], v[196:197], v[36:37], v[210:211] op_sel_hi:[0,1,1] neg_lo:[1,0,0] neg_hi:[1,0,0]
	v_pk_fma_f32 v[212:213], v[196:197], v[38:39], v[212:213] op_sel_hi:[0,1,1] neg_lo:[1,0,0] neg_hi:[1,0,0]
	v_pk_fma_f32 v[214:215], v[196:197], v[40:41], v[214:215] op_sel_hi:[0,1,1] neg_lo:[1,0,0] neg_hi:[1,0,0]
	v_pk_fma_f32 v[216:217], v[196:197], v[42:43], v[216:217] op_sel_hi:[0,1,1] neg_lo:[1,0,0] neg_hi:[1,0,0]
	v_pk_fma_f32 v[218:219], v[196:197], v[44:45], v[218:219] op_sel_hi:[0,1,1] neg_lo:[1,0,0] neg_hi:[1,0,0]
	v_pk_fma_f32 v[220:221], v[196:197], v[46:47], v[220:221] op_sel_hi:[0,1,1] neg_lo:[1,0,0] neg_hi:[1,0,0]
	ds_read_b128 v[32:35], v1 offset:2368
	ds_read_b128 v[36:39], v1 offset:2384
	ds_read_b128 v[40:43], v1 offset:2400
	ds_read_b128 v[44:47], v1 offset:2416
	s_waitcnt lgkmcnt(8)
	v_mov_b32_e32 v80, v197
	v_pk_fma_f32 v[206:207], v[80:81], v[48:49], v[206:207] op_sel_hi:[0,1,1] neg_lo:[1,0,0] neg_hi:[1,0,0]
	v_pk_fma_f32 v[208:209], v[80:81], v[50:51], v[208:209] op_sel_hi:[0,1,1] neg_lo:[1,0,0] neg_hi:[1,0,0]
	v_pk_fma_f32 v[210:211], v[80:81], v[52:53], v[210:211] op_sel_hi:[0,1,1] neg_lo:[1,0,0] neg_hi:[1,0,0]
	v_pk_fma_f32 v[212:213], v[80:81], v[54:55], v[212:213] op_sel_hi:[0,1,1] neg_lo:[1,0,0] neg_hi:[1,0,0]
	v_pk_fma_f32 v[214:215], v[80:81], v[56:57], v[214:215] op_sel_hi:[0,1,1] neg_lo:[1,0,0] neg_hi:[1,0,0]
	v_pk_fma_f32 v[216:217], v[80:81], v[58:59], v[216:217] op_sel_hi:[0,1,1] neg_lo:[1,0,0] neg_hi:[1,0,0]
	v_pk_fma_f32 v[218:219], v[80:81], v[60:61], v[218:219] op_sel_hi:[0,1,1] neg_lo:[1,0,0] neg_hi:[1,0,0]
	v_pk_fma_f32 v[220:221], v[80:81], v[62:63], v[220:221] op_sel_hi:[0,1,1] neg_lo:[1,0,0] neg_hi:[1,0,0]
	ds_read_b128 v[48:51], v1 offset:2624
	ds_read_b128 v[52:55], v1 offset:2640
	ds_read_b128 v[56:59], v1 offset:2656
	ds_read_b128 v[60:63], v1 offset:2672
	s_waitcnt lgkmcnt(8)
	v_pk_fma_f32 v[206:207], v[198:199], v[64:65], v[206:207] op_sel_hi:[0,1,1] neg_lo:[1,0,0] neg_hi:[1,0,0]
	v_pk_fma_f32 v[208:209], v[198:199], v[66:67], v[208:209] op_sel_hi:[0,1,1] neg_lo:[1,0,0] neg_hi:[1,0,0]
	v_pk_fma_f32 v[210:211], v[198:199], v[68:69], v[210:211] op_sel_hi:[0,1,1] neg_lo:[1,0,0] neg_hi:[1,0,0]
	v_pk_fma_f32 v[212:213], v[198:199], v[70:71], v[212:213] op_sel_hi:[0,1,1] neg_lo:[1,0,0] neg_hi:[1,0,0]
	v_pk_fma_f32 v[214:215], v[198:199], v[72:73], v[214:215] op_sel_hi:[0,1,1] neg_lo:[1,0,0] neg_hi:[1,0,0]
	v_pk_fma_f32 v[216:217], v[198:199], v[74:75], v[216:217] op_sel_hi:[0,1,1] neg_lo:[1,0,0] neg_hi:[1,0,0]
	v_pk_fma_f32 v[218:219], v[198:199], v[76:77], v[218:219] op_sel_hi:[0,1,1] neg_lo:[1,0,0] neg_hi:[1,0,0]
	v_pk_fma_f32 v[220:221], v[198:199], v[78:79], v[220:221] op_sel_hi:[0,1,1] neg_lo:[1,0,0] neg_hi:[1,0,0]
	ds_read_b128 v[64:67], v1 offset:2880
	ds_read_b128 v[68:71], v1 offset:2896
	ds_read_b128 v[72:75], v1 offset:2912
	ds_read_b128 v[76:79], v1 offset:2928
	s_waitcnt lgkmcnt(8)
	v_mov_b32_e32 v80, v199
	v_pk_fma_f32 v[206:207], v[80:81], v[32:33], v[206:207] op_sel_hi:[0,1,1] neg_lo:[1,0,0] neg_hi:[1,0,0]
	v_pk_fma_f32 v[208:209], v[80:81], v[34:35], v[208:209] op_sel_hi:[0,1,1] neg_lo:[1,0,0] neg_hi:[1,0,0]
	v_pk_fma_f32 v[210:211], v[80:81], v[36:37], v[210:211] op_sel_hi:[0,1,1] neg_lo:[1,0,0] neg_hi:[1,0,0]
	v_pk_fma_f32 v[212:213], v[80:81], v[38:39], v[212:213] op_sel_hi:[0,1,1] neg_lo:[1,0,0] neg_hi:[1,0,0]
	v_pk_fma_f32 v[214:215], v[80:81], v[40:41], v[214:215] op_sel_hi:[0,1,1] neg_lo:[1,0,0] neg_hi:[1,0,0]
	v_pk_fma_f32 v[216:217], v[80:81], v[42:43], v[216:217] op_sel_hi:[0,1,1] neg_lo:[1,0,0] neg_hi:[1,0,0]
	v_pk_fma_f32 v[218:219], v[80:81], v[44:45], v[218:219] op_sel_hi:[0,1,1] neg_lo:[1,0,0] neg_hi:[1,0,0]
	v_pk_fma_f32 v[220:221], v[80:81], v[46:47], v[220:221] op_sel_hi:[0,1,1] neg_lo:[1,0,0] neg_hi:[1,0,0]
	ds_read_b128 v[32:35], v1 offset:3136
	ds_read_b128 v[36:39], v1 offset:3152
	ds_read_b128 v[40:43], v1 offset:3168
	ds_read_b128 v[44:47], v1 offset:3184
	s_waitcnt lgkmcnt(8)
	v_pk_fma_f32 v[206:207], v[200:201], v[48:49], v[206:207] op_sel_hi:[0,1,1] neg_lo:[1,0,0] neg_hi:[1,0,0]
	v_pk_fma_f32 v[208:209], v[200:201], v[50:51], v[208:209] op_sel_hi:[0,1,1] neg_lo:[1,0,0] neg_hi:[1,0,0]
	v_pk_fma_f32 v[210:211], v[200:201], v[52:53], v[210:211] op_sel_hi:[0,1,1] neg_lo:[1,0,0] neg_hi:[1,0,0]
	v_pk_fma_f32 v[212:213], v[200:201], v[54:55], v[212:213] op_sel_hi:[0,1,1] neg_lo:[1,0,0] neg_hi:[1,0,0]
	v_pk_fma_f32 v[214:215], v[200:201], v[56:57], v[214:215] op_sel_hi:[0,1,1] neg_lo:[1,0,0] neg_hi:[1,0,0]
	v_pk_fma_f32 v[216:217], v[200:201], v[58:59], v[216:217] op_sel_hi:[0,1,1] neg_lo:[1,0,0] neg_hi:[1,0,0]
	v_pk_fma_f32 v[218:219], v[200:201], v[60:61], v[218:219] op_sel_hi:[0,1,1] neg_lo:[1,0,0] neg_hi:[1,0,0]
	v_pk_fma_f32 v[220:221], v[200:201], v[62:63], v[220:221] op_sel_hi:[0,1,1] neg_lo:[1,0,0] neg_hi:[1,0,0]
	ds_read_b128 v[48:51], v1 offset:3392
	ds_read_b128 v[52:55], v1 offset:3408
	ds_read_b128 v[56:59], v1 offset:3424
	ds_read_b128 v[60:63], v1 offset:3440
	s_waitcnt lgkmcnt(8)
	v_mov_b32_e32 v80, v201
	v_pk_fma_f32 v[206:207], v[80:81], v[64:65], v[206:207] op_sel_hi:[0,1,1] neg_lo:[1,0,0] neg_hi:[1,0,0]
	v_pk_fma_f32 v[208:209], v[80:81], v[66:67], v[208:209] op_sel_hi:[0,1,1] neg_lo:[1,0,0] neg_hi:[1,0,0]
	v_pk_fma_f32 v[210:211], v[80:81], v[68:69], v[210:211] op_sel_hi:[0,1,1] neg_lo:[1,0,0] neg_hi:[1,0,0]
	v_pk_fma_f32 v[212:213], v[80:81], v[70:71], v[212:213] op_sel_hi:[0,1,1] neg_lo:[1,0,0] neg_hi:[1,0,0]
	v_pk_fma_f32 v[214:215], v[80:81], v[72:73], v[214:215] op_sel_hi:[0,1,1] neg_lo:[1,0,0] neg_hi:[1,0,0]
	v_pk_fma_f32 v[216:217], v[80:81], v[74:75], v[216:217] op_sel_hi:[0,1,1] neg_lo:[1,0,0] neg_hi:[1,0,0]
	v_pk_fma_f32 v[218:219], v[80:81], v[76:77], v[218:219] op_sel_hi:[0,1,1] neg_lo:[1,0,0] neg_hi:[1,0,0]
	v_pk_fma_f32 v[220:221], v[80:81], v[78:79], v[220:221] op_sel_hi:[0,1,1] neg_lo:[1,0,0] neg_hi:[1,0,0]
	ds_read_b128 v[64:67], v1 offset:3648
	ds_read_b128 v[68:71], v1 offset:3664
	ds_read_b128 v[72:75], v1 offset:3680
	ds_read_b128 v[76:79], v1 offset:3696
	s_waitcnt lgkmcnt(8)
	v_pk_fma_f32 v[206:207], v[202:203], v[32:33], v[206:207] op_sel_hi:[0,1,1] neg_lo:[1,0,0] neg_hi:[1,0,0]
	v_pk_fma_f32 v[208:209], v[202:203], v[34:35], v[208:209] op_sel_hi:[0,1,1] neg_lo:[1,0,0] neg_hi:[1,0,0]
	v_pk_fma_f32 v[210:211], v[202:203], v[36:37], v[210:211] op_sel_hi:[0,1,1] neg_lo:[1,0,0] neg_hi:[1,0,0]
	v_pk_fma_f32 v[212:213], v[202:203], v[38:39], v[212:213] op_sel_hi:[0,1,1] neg_lo:[1,0,0] neg_hi:[1,0,0]
	v_pk_fma_f32 v[214:215], v[202:203], v[40:41], v[214:215] op_sel_hi:[0,1,1] neg_lo:[1,0,0] neg_hi:[1,0,0]
	v_pk_fma_f32 v[216:217], v[202:203], v[42:43], v[216:217] op_sel_hi:[0,1,1] neg_lo:[1,0,0] neg_hi:[1,0,0]
	v_pk_fma_f32 v[218:219], v[202:203], v[44:45], v[218:219] op_sel_hi:[0,1,1] neg_lo:[1,0,0] neg_hi:[1,0,0]
	v_pk_fma_f32 v[220:221], v[202:203], v[46:47], v[220:221] op_sel_hi:[0,1,1] neg_lo:[1,0,0] neg_hi:[1,0,0]
	ds_read_b128 v[32:35], v1 offset:3904
	ds_read_b128 v[36:39], v1 offset:3920
	ds_read_b128 v[40:43], v1 offset:3936
	ds_read_b128 v[44:47], v1 offset:3952
	s_waitcnt lgkmcnt(8)
	v_mov_b32_e32 v80, v203
	v_pk_fma_f32 v[206:207], v[80:81], v[48:49], v[206:207] op_sel_hi:[0,1,1] neg_lo:[1,0,0] neg_hi:[1,0,0]
	v_pk_fma_f32 v[208:209], v[80:81], v[50:51], v[208:209] op_sel_hi:[0,1,1] neg_lo:[1,0,0] neg_hi:[1,0,0]
	v_pk_fma_f32 v[210:211], v[80:81], v[52:53], v[210:211] op_sel_hi:[0,1,1] neg_lo:[1,0,0] neg_hi:[1,0,0]
	v_pk_fma_f32 v[212:213], v[80:81], v[54:55], v[212:213] op_sel_hi:[0,1,1] neg_lo:[1,0,0] neg_hi:[1,0,0]
	v_pk_fma_f32 v[214:215], v[80:81], v[56:57], v[214:215] op_sel_hi:[0,1,1] neg_lo:[1,0,0] neg_hi:[1,0,0]
	v_pk_fma_f32 v[216:217], v[80:81], v[58:59], v[216:217] op_sel_hi:[0,1,1] neg_lo:[1,0,0] neg_hi:[1,0,0]
	v_pk_fma_f32 v[218:219], v[80:81], v[60:61], v[218:219] op_sel_hi:[0,1,1] neg_lo:[1,0,0] neg_hi:[1,0,0]
	v_pk_fma_f32 v[220:221], v[80:81], v[62:63], v[220:221] op_sel_hi:[0,1,1] neg_lo:[1,0,0] neg_hi:[1,0,0]
	ds_read_b128 v[48:51], v1 offset:4160
	ds_read_b128 v[52:55], v1 offset:4176
	ds_read_b128 v[56:59], v1 offset:4192
	ds_read_b128 v[60:63], v1 offset:4208
	s_waitcnt lgkmcnt(8)
	v_pk_fma_f32 v[206:207], v[204:205], v[64:65], v[206:207] op_sel_hi:[0,1,1] neg_lo:[1,0,0] neg_hi:[1,0,0]
	v_pk_fma_f32 v[208:209], v[204:205], v[66:67], v[208:209] op_sel_hi:[0,1,1] neg_lo:[1,0,0] neg_hi:[1,0,0]
	v_pk_fma_f32 v[210:211], v[204:205], v[68:69], v[210:211] op_sel_hi:[0,1,1] neg_lo:[1,0,0] neg_hi:[1,0,0]
	v_pk_fma_f32 v[212:213], v[204:205], v[70:71], v[212:213] op_sel_hi:[0,1,1] neg_lo:[1,0,0] neg_hi:[1,0,0]
	v_pk_fma_f32 v[214:215], v[204:205], v[72:73], v[214:215] op_sel_hi:[0,1,1] neg_lo:[1,0,0] neg_hi:[1,0,0]
	v_pk_fma_f32 v[216:217], v[204:205], v[74:75], v[216:217] op_sel_hi:[0,1,1] neg_lo:[1,0,0] neg_hi:[1,0,0]
	v_pk_fma_f32 v[218:219], v[204:205], v[76:77], v[218:219] op_sel_hi:[0,1,1] neg_lo:[1,0,0] neg_hi:[1,0,0]
	v_pk_fma_f32 v[220:221], v[204:205], v[78:79], v[220:221] op_sel_hi:[0,1,1] neg_lo:[1,0,0] neg_hi:[1,0,0]
	ds_read_b128 v[64:67], v1 offset:4416
	ds_read_b128 v[68:71], v1 offset:4432
	ds_read_b128 v[72:75], v1 offset:4448
	ds_read_b128 v[76:79], v1 offset:4464
	s_waitcnt lgkmcnt(8)
	v_mov_b32_e32 v80, v205
	v_pk_fma_f32 v[206:207], v[80:81], v[32:33], v[206:207] op_sel_hi:[0,1,1] neg_lo:[1,0,0] neg_hi:[1,0,0]
	v_pk_fma_f32 v[208:209], v[80:81], v[34:35], v[208:209] op_sel_hi:[0,1,1] neg_lo:[1,0,0] neg_hi:[1,0,0]
	v_pk_fma_f32 v[210:211], v[80:81], v[36:37], v[210:211] op_sel_hi:[0,1,1] neg_lo:[1,0,0] neg_hi:[1,0,0]
	v_pk_fma_f32 v[212:213], v[80:81], v[38:39], v[212:213] op_sel_hi:[0,1,1] neg_lo:[1,0,0] neg_hi:[1,0,0]
	v_pk_fma_f32 v[214:215], v[80:81], v[40:41], v[214:215] op_sel_hi:[0,1,1] neg_lo:[1,0,0] neg_hi:[1,0,0]
	v_pk_fma_f32 v[216:217], v[80:81], v[42:43], v[216:217] op_sel_hi:[0,1,1] neg_lo:[1,0,0] neg_hi:[1,0,0]
	v_pk_fma_f32 v[218:219], v[80:81], v[44:45], v[218:219] op_sel_hi:[0,1,1] neg_lo:[1,0,0] neg_hi:[1,0,0]
	v_pk_fma_f32 v[220:221], v[80:81], v[46:47], v[220:221] op_sel_hi:[0,1,1] neg_lo:[1,0,0] neg_hi:[1,0,0]
	ds_read_b128 v[32:35], v1 offset:4672
	ds_read_b128 v[36:39], v1 offset:4688
	ds_read_b128 v[40:43], v1 offset:4704
	ds_read_b128 v[44:47], v1 offset:4720
	s_waitcnt lgkmcnt(8)
	v_fma_f32 v207, -v206, v49, v207
	v_pk_fma_f32 v[208:209], v[206:207], v[50:51], v[208:209] op_sel_hi:[0,1,1] neg_lo:[1,0,0] neg_hi:[1,0,0]
	v_pk_fma_f32 v[210:211], v[206:207], v[52:53], v[210:211] op_sel_hi:[0,1,1] neg_lo:[1,0,0] neg_hi:[1,0,0]
	v_pk_fma_f32 v[212:213], v[206:207], v[54:55], v[212:213] op_sel_hi:[0,1,1] neg_lo:[1,0,0] neg_hi:[1,0,0]
	v_pk_fma_f32 v[214:215], v[206:207], v[56:57], v[214:215] op_sel_hi:[0,1,1] neg_lo:[1,0,0] neg_hi:[1,0,0]
	v_pk_fma_f32 v[216:217], v[206:207], v[58:59], v[216:217] op_sel_hi:[0,1,1] neg_lo:[1,0,0] neg_hi:[1,0,0]
	v_pk_fma_f32 v[218:219], v[206:207], v[60:61], v[218:219] op_sel_hi:[0,1,1] neg_lo:[1,0,0] neg_hi:[1,0,0]
	v_pk_fma_f32 v[220:221], v[206:207], v[62:63], v[220:221] op_sel_hi:[0,1,1] neg_lo:[1,0,0] neg_hi:[1,0,0]
	ds_read_b128 v[52:55], v1 offset:4944
	ds_read_b128 v[56:59], v1 offset:4960
	ds_read_b128 v[60:63], v1 offset:4976
	s_waitcnt lgkmcnt(7)
	v_mov_b32_e32 v80, v207
	v_pk_fma_f32 v[208:209], v[80:81], v[66:67], v[208:209] op_sel_hi:[0,1,1] neg_lo:[1,0,0] neg_hi:[1,0,0]
	v_pk_fma_f32 v[210:211], v[80:81], v[68:69], v[210:211] op_sel_hi:[0,1,1] neg_lo:[1,0,0] neg_hi:[1,0,0]
	v_pk_fma_f32 v[212:213], v[80:81], v[70:71], v[212:213] op_sel_hi:[0,1,1] neg_lo:[1,0,0] neg_hi:[1,0,0]
	v_pk_fma_f32 v[214:215], v[80:81], v[72:73], v[214:215] op_sel_hi:[0,1,1] neg_lo:[1,0,0] neg_hi:[1,0,0]
	v_pk_fma_f32 v[216:217], v[80:81], v[74:75], v[216:217] op_sel_hi:[0,1,1] neg_lo:[1,0,0] neg_hi:[1,0,0]
	v_pk_fma_f32 v[218:219], v[80:81], v[76:77], v[218:219] op_sel_hi:[0,1,1] neg_lo:[1,0,0] neg_hi:[1,0,0]
	v_pk_fma_f32 v[220:221], v[80:81], v[78:79], v[220:221] op_sel_hi:[0,1,1] neg_lo:[1,0,0] neg_hi:[1,0,0]
	ds_read_b128 v[68:71], v1 offset:5200
	ds_read_b128 v[72:75], v1 offset:5216
	ds_read_b128 v[76:79], v1 offset:5232
	s_waitcnt lgkmcnt(6)
	v_fma_f32 v209, -v208, v35, v209
	v_pk_fma_f32 v[210:211], v[208:209], v[36:37], v[210:211] op_sel_hi:[0,1,1] neg_lo:[1,0,0] neg_hi:[1,0,0]
	v_pk_fma_f32 v[212:213], v[208:209], v[38:39], v[212:213] op_sel_hi:[0,1,1] neg_lo:[1,0,0] neg_hi:[1,0,0]
	v_pk_fma_f32 v[214:215], v[208:209], v[40:41], v[214:215] op_sel_hi:[0,1,1] neg_lo:[1,0,0] neg_hi:[1,0,0]
	v_pk_fma_f32 v[216:217], v[208:209], v[42:43], v[216:217] op_sel_hi:[0,1,1] neg_lo:[1,0,0] neg_hi:[1,0,0]
	v_pk_fma_f32 v[218:219], v[208:209], v[44:45], v[218:219] op_sel_hi:[0,1,1] neg_lo:[1,0,0] neg_hi:[1,0,0]
	v_pk_fma_f32 v[220:221], v[208:209], v[46:47], v[220:221] op_sel_hi:[0,1,1] neg_lo:[1,0,0] neg_hi:[1,0,0]
	ds_read_b128 v[36:39], v1 offset:5456
	ds_read_b128 v[40:43], v1 offset:5472
	ds_read_b128 v[44:47], v1 offset:5488
	s_waitcnt lgkmcnt(6)
	v_mov_b32_e32 v80, v209
	v_pk_fma_f32 v[210:211], v[80:81], v[52:53], v[210:211] op_sel_hi:[0,1,1] neg_lo:[1,0,0] neg_hi:[1,0,0]
	v_pk_fma_f32 v[212:213], v[80:81], v[54:55], v[212:213] op_sel_hi:[0,1,1] neg_lo:[1,0,0] neg_hi:[1,0,0]
	v_pk_fma_f32 v[214:215], v[80:81], v[56:57], v[214:215] op_sel_hi:[0,1,1] neg_lo:[1,0,0] neg_hi:[1,0,0]
	v_pk_fma_f32 v[216:217], v[80:81], v[58:59], v[216:217] op_sel_hi:[0,1,1] neg_lo:[1,0,0] neg_hi:[1,0,0]
	v_pk_fma_f32 v[218:219], v[80:81], v[60:61], v[218:219] op_sel_hi:[0,1,1] neg_lo:[1,0,0] neg_hi:[1,0,0]
	v_pk_fma_f32 v[220:221], v[80:81], v[62:63], v[220:221] op_sel_hi:[0,1,1] neg_lo:[1,0,0] neg_hi:[1,0,0]
	ds_read_b128 v[52:55], v1 offset:5712
	ds_read_b128 v[56:59], v1 offset:5728
	ds_read_b128 v[60:63], v1 offset:5744
	s_waitcnt lgkmcnt(6)
	v_fma_f32 v211, -v210, v69, v211
	v_pk_fma_f32 v[212:213], v[210:211], v[70:71], v[212:213] op_sel_hi:[0,1,1] neg_lo:[1,0,0] neg_hi:[1,0,0]
	v_pk_fma_f32 v[214:215], v[210:211], v[72:73], v[214:215] op_sel_hi:[0,1,1] neg_lo:[1,0,0] neg_hi:[1,0,0]
	v_pk_fma_f32 v[216:217], v[210:211], v[74:75], v[216:217] op_sel_hi:[0,1,1] neg_lo:[1,0,0] neg_hi:[1,0,0]
	v_pk_fma_f32 v[218:219], v[210:211], v[76:77], v[218:219] op_sel_hi:[0,1,1] neg_lo:[1,0,0] neg_hi:[1,0,0]
	v_pk_fma_f32 v[220:221], v[210:211], v[78:79], v[220:221] op_sel_hi:[0,1,1] neg_lo:[1,0,0] neg_hi:[1,0,0]
	ds_read_b128 v[72:75], v1 offset:5984
	ds_read_b128 v[76:79], v1 offset:6000
	s_waitcnt lgkmcnt(5)
	v_mov_b32_e32 v80, v211
	v_pk_fma_f32 v[212:213], v[80:81], v[38:39], v[212:213] op_sel_hi:[0,1,1] neg_lo:[1,0,0] neg_hi:[1,0,0]
	v_pk_fma_f32 v[214:215], v[80:81], v[40:41], v[214:215] op_sel_hi:[0,1,1] neg_lo:[1,0,0] neg_hi:[1,0,0]
	v_pk_fma_f32 v[216:217], v[80:81], v[42:43], v[216:217] op_sel_hi:[0,1,1] neg_lo:[1,0,0] neg_hi:[1,0,0]
	v_pk_fma_f32 v[218:219], v[80:81], v[44:45], v[218:219] op_sel_hi:[0,1,1] neg_lo:[1,0,0] neg_hi:[1,0,0]
	v_pk_fma_f32 v[220:221], v[80:81], v[46:47], v[220:221] op_sel_hi:[0,1,1] neg_lo:[1,0,0] neg_hi:[1,0,0]
	ds_read_b128 v[40:43], v1 offset:6240
	ds_read_b128 v[44:47], v1 offset:6256
	s_waitcnt lgkmcnt(4)
	v_fma_f32 v213, -v212, v55, v213
	v_pk_fma_f32 v[214:215], v[212:213], v[56:57], v[214:215] op_sel_hi:[0,1,1] neg_lo:[1,0,0] neg_hi:[1,0,0]
	v_pk_fma_f32 v[216:217], v[212:213], v[58:59], v[216:217] op_sel_hi:[0,1,1] neg_lo:[1,0,0] neg_hi:[1,0,0]
	v_pk_fma_f32 v[218:219], v[212:213], v[60:61], v[218:219] op_sel_hi:[0,1,1] neg_lo:[1,0,0] neg_hi:[1,0,0]
	v_pk_fma_f32 v[220:221], v[212:213], v[62:63], v[220:221] op_sel_hi:[0,1,1] neg_lo:[1,0,0] neg_hi:[1,0,0]
	ds_read_b128 v[56:59], v1 offset:6496
	ds_read_b128 v[60:63], v1 offset:6512
	s_waitcnt lgkmcnt(4)
	v_mov_b32_e32 v80, v213
	v_pk_fma_f32 v[214:215], v[80:81], v[72:73], v[214:215] op_sel_hi:[0,1,1] neg_lo:[1,0,0] neg_hi:[1,0,0]
	v_pk_fma_f32 v[216:217], v[80:81], v[74:75], v[216:217] op_sel_hi:[0,1,1] neg_lo:[1,0,0] neg_hi:[1,0,0]
	v_pk_fma_f32 v[218:219], v[80:81], v[76:77], v[218:219] op_sel_hi:[0,1,1] neg_lo:[1,0,0] neg_hi:[1,0,0]
	v_pk_fma_f32 v[220:221], v[80:81], v[78:79], v[220:221] op_sel_hi:[0,1,1] neg_lo:[1,0,0] neg_hi:[1,0,0]
	ds_read_b128 v[72:75], v1 offset:6752
	ds_read_b128 v[76:79], v1 offset:6768
	s_waitcnt lgkmcnt(4)
	v_fma_f32 v215, -v214, v41, v215
	v_pk_fma_f32 v[216:217], v[214:215], v[42:43], v[216:217] op_sel_hi:[0,1,1] neg_lo:[1,0,0] neg_hi:[1,0,0]
	v_pk_fma_f32 v[218:219], v[214:215], v[44:45], v[218:219] op_sel_hi:[0,1,1] neg_lo:[1,0,0] neg_hi:[1,0,0]
	v_pk_fma_f32 v[220:221], v[214:215], v[46:47], v[220:221] op_sel_hi:[0,1,1] neg_lo:[1,0,0] neg_hi:[1,0,0]
	ds_read_b128 v[44:47], v1 offset:7024
	s_waitcnt lgkmcnt(3)
	v_mov_b32_e32 v80, v215
	v_pk_fma_f32 v[216:217], v[80:81], v[58:59], v[216:217] op_sel_hi:[0,1,1] neg_lo:[1,0,0] neg_hi:[1,0,0]
	v_pk_fma_f32 v[218:219], v[80:81], v[60:61], v[218:219] op_sel_hi:[0,1,1] neg_lo:[1,0,0] neg_hi:[1,0,0]
	v_pk_fma_f32 v[220:221], v[80:81], v[62:63], v[220:221] op_sel_hi:[0,1,1] neg_lo:[1,0,0] neg_hi:[1,0,0]
	ds_read_b128 v[60:63], v1 offset:7280
	s_waitcnt lgkmcnt(2)
	v_fma_f32 v217, -v216, v75, v217
	v_pk_fma_f32 v[218:219], v[216:217], v[76:77], v[218:219] op_sel_hi:[0,1,1] neg_lo:[1,0,0] neg_hi:[1,0,0]
	v_pk_fma_f32 v[220:221], v[216:217], v[78:79], v[220:221] op_sel_hi:[0,1,1] neg_lo:[1,0,0] neg_hi:[1,0,0]
	ds_read_b128 v[76:79], v1 offset:7536
	s_waitcnt lgkmcnt(2)
	v_mov_b32_e32 v80, v217
	v_pk_fma_f32 v[218:219], v[80:81], v[44:45], v[218:219] op_sel_hi:[0,1,1] neg_lo:[1,0,0] neg_hi:[1,0,0]
	v_pk_fma_f32 v[220:221], v[80:81], v[46:47], v[220:221] op_sel_hi:[0,1,1] neg_lo:[1,0,0] neg_hi:[1,0,0]
	ds_read_b128 v[44:47], v1 offset:7792
	s_waitcnt lgkmcnt(2)
	v_fma_f32 v219, -v218, v61, v219
	v_pk_fma_f32 v[220:221], v[218:219], v[62:63], v[220:221] op_sel_hi:[0,1,1] neg_lo:[1,0,0] neg_hi:[1,0,0]
	ds_read_b128 v[48:51], v1 offset:128
	ds_read_b128 v[52:55], v1 offset:144
	ds_read_b128 v[56:59], v1 offset:160
	ds_read_b128 v[60:63], v1 offset:176
	s_waitcnt lgkmcnt(5)
	v_mov_b32_e32 v80, v219
	v_pk_fma_f32 v[220:221], v[80:81], v[78:79], v[220:221] op_sel_hi:[0,1,1] neg_lo:[1,0,0] neg_hi:[1,0,0]
	ds_read_b128 v[64:67], v1 offset:384
	ds_read_b128 v[68:71], v1 offset:400
	ds_read_b128 v[72:75], v1 offset:416
	ds_read_b128 v[76:79], v1 offset:432
	s_waitcnt lgkmcnt(8)
	v_fma_f32 v221, -v220, v47, v221
	ds_read_b128 v[32:35], v1 offset:640
	ds_read_b128 v[36:39], v1 offset:656
	ds_read_b128 v[40:43], v1 offset:672
	ds_read_b128 v[44:47], v1 offset:688
	s_waitcnt lgkmcnt(8)
	v_pk_fma_f32 v[222:223], v[190:191], v[48:49], v[222:223] op_sel_hi:[0,1,1] neg_lo:[1,0,0] neg_hi:[1,0,0]
	v_pk_fma_f32 v[224:225], v[190:191], v[50:51], v[224:225] op_sel_hi:[0,1,1] neg_lo:[1,0,0] neg_hi:[1,0,0]
	v_pk_fma_f32 v[226:227], v[190:191], v[52:53], v[226:227] op_sel_hi:[0,1,1] neg_lo:[1,0,0] neg_hi:[1,0,0]
	v_pk_fma_f32 v[228:229], v[190:191], v[54:55], v[228:229] op_sel_hi:[0,1,1] neg_lo:[1,0,0] neg_hi:[1,0,0]
	v_pk_fma_f32 v[230:231], v[190:191], v[56:57], v[230:231] op_sel_hi:[0,1,1] neg_lo:[1,0,0] neg_hi:[1,0,0]
	v_pk_fma_f32 v[232:233], v[190:191], v[58:59], v[232:233] op_sel_hi:[0,1,1] neg_lo:[1,0,0] neg_hi:[1,0,0]
	v_pk_fma_f32 v[234:235], v[190:191], v[60:61], v[234:235] op_sel_hi:[0,1,1] neg_lo:[1,0,0] neg_hi:[1,0,0]
	v_pk_fma_f32 v[236:237], v[190:191], v[62:63], v[236:237] op_sel_hi:[0,1,1] neg_lo:[1,0,0] neg_hi:[1,0,0]
	ds_read_b128 v[48:51], v1 offset:896
	ds_read_b128 v[52:55], v1 offset:912
	ds_read_b128 v[56:59], v1 offset:928
	ds_read_b128 v[60:63], v1 offset:944
	s_waitcnt lgkmcnt(8)
	v_mov_b32_e32 v80, v191
	v_pk_fma_f32 v[222:223], v[80:81], v[64:65], v[222:223] op_sel_hi:[0,1,1] neg_lo:[1,0,0] neg_hi:[1,0,0]
	v_pk_fma_f32 v[224:225], v[80:81], v[66:67], v[224:225] op_sel_hi:[0,1,1] neg_lo:[1,0,0] neg_hi:[1,0,0]
	v_pk_fma_f32 v[226:227], v[80:81], v[68:69], v[226:227] op_sel_hi:[0,1,1] neg_lo:[1,0,0] neg_hi:[1,0,0]
	v_pk_fma_f32 v[228:229], v[80:81], v[70:71], v[228:229] op_sel_hi:[0,1,1] neg_lo:[1,0,0] neg_hi:[1,0,0]
	v_pk_fma_f32 v[230:231], v[80:81], v[72:73], v[230:231] op_sel_hi:[0,1,1] neg_lo:[1,0,0] neg_hi:[1,0,0]
	v_pk_fma_f32 v[232:233], v[80:81], v[74:75], v[232:233] op_sel_hi:[0,1,1] neg_lo:[1,0,0] neg_hi:[1,0,0]
	v_pk_fma_f32 v[234:235], v[80:81], v[76:77], v[234:235] op_sel_hi:[0,1,1] neg_lo:[1,0,0] neg_hi:[1,0,0]
	v_pk_fma_f32 v[236:237], v[80:81], v[78:79], v[236:237] op_sel_hi:[0,1,1] neg_lo:[1,0,0] neg_hi:[1,0,0]
	ds_read_b128 v[64:67], v1 offset:1152
	ds_read_b128 v[68:71], v1 offset:1168
	ds_read_b128 v[72:75], v1 offset:1184
	ds_read_b128 v[76:79], v1 offset:1200
	s_waitcnt lgkmcnt(8)
	v_pk_fma_f32 v[222:223], v[192:193], v[32:33], v[222:223] op_sel_hi:[0,1,1] neg_lo:[1,0,0] neg_hi:[1,0,0]
	v_pk_fma_f32 v[224:225], v[192:193], v[34:35], v[224:225] op_sel_hi:[0,1,1] neg_lo:[1,0,0] neg_hi:[1,0,0]
	v_pk_fma_f32 v[226:227], v[192:193], v[36:37], v[226:227] op_sel_hi:[0,1,1] neg_lo:[1,0,0] neg_hi:[1,0,0]
	v_pk_fma_f32 v[228:229], v[192:193], v[38:39], v[228:229] op_sel_hi:[0,1,1] neg_lo:[1,0,0] neg_hi:[1,0,0]
	v_pk_fma_f32 v[230:231], v[192:193], v[40:41], v[230:231] op_sel_hi:[0,1,1] neg_lo:[1,0,0] neg_hi:[1,0,0]
	v_pk_fma_f32 v[232:233], v[192:193], v[42:43], v[232:233] op_sel_hi:[0,1,1] neg_lo:[1,0,0] neg_hi:[1,0,0]
	v_pk_fma_f32 v[234:235], v[192:193], v[44:45], v[234:235] op_sel_hi:[0,1,1] neg_lo:[1,0,0] neg_hi:[1,0,0]
	v_pk_fma_f32 v[236:237], v[192:193], v[46:47], v[236:237] op_sel_hi:[0,1,1] neg_lo:[1,0,0] neg_hi:[1,0,0]
	ds_read_b128 v[32:35], v1 offset:1408
	ds_read_b128 v[36:39], v1 offset:1424
	ds_read_b128 v[40:43], v1 offset:1440
	ds_read_b128 v[44:47], v1 offset:1456
	s_waitcnt lgkmcnt(8)
	v_mov_b32_e32 v80, v193
	v_pk_fma_f32 v[222:223], v[80:81], v[48:49], v[222:223] op_sel_hi:[0,1,1] neg_lo:[1,0,0] neg_hi:[1,0,0]
	v_pk_fma_f32 v[224:225], v[80:81], v[50:51], v[224:225] op_sel_hi:[0,1,1] neg_lo:[1,0,0] neg_hi:[1,0,0]
	v_pk_fma_f32 v[226:227], v[80:81], v[52:53], v[226:227] op_sel_hi:[0,1,1] neg_lo:[1,0,0] neg_hi:[1,0,0]
	v_pk_fma_f32 v[228:229], v[80:81], v[54:55], v[228:229] op_sel_hi:[0,1,1] neg_lo:[1,0,0] neg_hi:[1,0,0]
	v_pk_fma_f32 v[230:231], v[80:81], v[56:57], v[230:231] op_sel_hi:[0,1,1] neg_lo:[1,0,0] neg_hi:[1,0,0]
	v_pk_fma_f32 v[232:233], v[80:81], v[58:59], v[232:233] op_sel_hi:[0,1,1] neg_lo:[1,0,0] neg_hi:[1,0,0]
	v_pk_fma_f32 v[234:235], v[80:81], v[60:61], v[234:235] op_sel_hi:[0,1,1] neg_lo:[1,0,0] neg_hi:[1,0,0]
	v_pk_fma_f32 v[236:237], v[80:81], v[62:63], v[236:237] op_sel_hi:[0,1,1] neg_lo:[1,0,0] neg_hi:[1,0,0]
	ds_read_b128 v[48:51], v1 offset:1664
	ds_read_b128 v[52:55], v1 offset:1680
	ds_read_b128 v[56:59], v1 offset:1696
	ds_read_b128 v[60:63], v1 offset:1712
	s_waitcnt lgkmcnt(8)
	v_pk_fma_f32 v[222:223], v[194:195], v[64:65], v[222:223] op_sel_hi:[0,1,1] neg_lo:[1,0,0] neg_hi:[1,0,0]
	v_pk_fma_f32 v[224:225], v[194:195], v[66:67], v[224:225] op_sel_hi:[0,1,1] neg_lo:[1,0,0] neg_hi:[1,0,0]
	v_pk_fma_f32 v[226:227], v[194:195], v[68:69], v[226:227] op_sel_hi:[0,1,1] neg_lo:[1,0,0] neg_hi:[1,0,0]
	v_pk_fma_f32 v[228:229], v[194:195], v[70:71], v[228:229] op_sel_hi:[0,1,1] neg_lo:[1,0,0] neg_hi:[1,0,0]
	v_pk_fma_f32 v[230:231], v[194:195], v[72:73], v[230:231] op_sel_hi:[0,1,1] neg_lo:[1,0,0] neg_hi:[1,0,0]
	v_pk_fma_f32 v[232:233], v[194:195], v[74:75], v[232:233] op_sel_hi:[0,1,1] neg_lo:[1,0,0] neg_hi:[1,0,0]
	v_pk_fma_f32 v[234:235], v[194:195], v[76:77], v[234:235] op_sel_hi:[0,1,1] neg_lo:[1,0,0] neg_hi:[1,0,0]
	v_pk_fma_f32 v[236:237], v[194:195], v[78:79], v[236:237] op_sel_hi:[0,1,1] neg_lo:[1,0,0] neg_hi:[1,0,0]
	ds_read_b128 v[64:67], v1 offset:1920
	ds_read_b128 v[68:71], v1 offset:1936
	ds_read_b128 v[72:75], v1 offset:1952
	ds_read_b128 v[76:79], v1 offset:1968
	s_waitcnt lgkmcnt(8)
	v_mov_b32_e32 v80, v195
	v_pk_fma_f32 v[222:223], v[80:81], v[32:33], v[222:223] op_sel_hi:[0,1,1] neg_lo:[1,0,0] neg_hi:[1,0,0]
	v_pk_fma_f32 v[224:225], v[80:81], v[34:35], v[224:225] op_sel_hi:[0,1,1] neg_lo:[1,0,0] neg_hi:[1,0,0]
	v_pk_fma_f32 v[226:227], v[80:81], v[36:37], v[226:227] op_sel_hi:[0,1,1] neg_lo:[1,0,0] neg_hi:[1,0,0]
	v_pk_fma_f32 v[228:229], v[80:81], v[38:39], v[228:229] op_sel_hi:[0,1,1] neg_lo:[1,0,0] neg_hi:[1,0,0]
	v_pk_fma_f32 v[230:231], v[80:81], v[40:41], v[230:231] op_sel_hi:[0,1,1] neg_lo:[1,0,0] neg_hi:[1,0,0]
	v_pk_fma_f32 v[232:233], v[80:81], v[42:43], v[232:233] op_sel_hi:[0,1,1] neg_lo:[1,0,0] neg_hi:[1,0,0]
	v_pk_fma_f32 v[234:235], v[80:81], v[44:45], v[234:235] op_sel_hi:[0,1,1] neg_lo:[1,0,0] neg_hi:[1,0,0]
	v_pk_fma_f32 v[236:237], v[80:81], v[46:47], v[236:237] op_sel_hi:[0,1,1] neg_lo:[1,0,0] neg_hi:[1,0,0]
	ds_read_b128 v[32:35], v1 offset:2176
	ds_read_b128 v[36:39], v1 offset:2192
	ds_read_b128 v[40:43], v1 offset:2208
	ds_read_b128 v[44:47], v1 offset:2224
	s_waitcnt lgkmcnt(8)
	v_pk_fma_f32 v[222:223], v[196:197], v[48:49], v[222:223] op_sel_hi:[0,1,1] neg_lo:[1,0,0] neg_hi:[1,0,0]
	v_pk_fma_f32 v[224:225], v[196:197], v[50:51], v[224:225] op_sel_hi:[0,1,1] neg_lo:[1,0,0] neg_hi:[1,0,0]
	v_pk_fma_f32 v[226:227], v[196:197], v[52:53], v[226:227] op_sel_hi:[0,1,1] neg_lo:[1,0,0] neg_hi:[1,0,0]
	v_pk_fma_f32 v[228:229], v[196:197], v[54:55], v[228:229] op_sel_hi:[0,1,1] neg_lo:[1,0,0] neg_hi:[1,0,0]
	v_pk_fma_f32 v[230:231], v[196:197], v[56:57], v[230:231] op_sel_hi:[0,1,1] neg_lo:[1,0,0] neg_hi:[1,0,0]
	v_pk_fma_f32 v[232:233], v[196:197], v[58:59], v[232:233] op_sel_hi:[0,1,1] neg_lo:[1,0,0] neg_hi:[1,0,0]
	v_pk_fma_f32 v[234:235], v[196:197], v[60:61], v[234:235] op_sel_hi:[0,1,1] neg_lo:[1,0,0] neg_hi:[1,0,0]
	v_pk_fma_f32 v[236:237], v[196:197], v[62:63], v[236:237] op_sel_hi:[0,1,1] neg_lo:[1,0,0] neg_hi:[1,0,0]
	ds_read_b128 v[48:51], v1 offset:2432
	ds_read_b128 v[52:55], v1 offset:2448
	ds_read_b128 v[56:59], v1 offset:2464
	ds_read_b128 v[60:63], v1 offset:2480
	s_waitcnt lgkmcnt(8)
	v_mov_b32_e32 v80, v197
	v_pk_fma_f32 v[222:223], v[80:81], v[64:65], v[222:223] op_sel_hi:[0,1,1] neg_lo:[1,0,0] neg_hi:[1,0,0]
	v_pk_fma_f32 v[224:225], v[80:81], v[66:67], v[224:225] op_sel_hi:[0,1,1] neg_lo:[1,0,0] neg_hi:[1,0,0]
	v_pk_fma_f32 v[226:227], v[80:81], v[68:69], v[226:227] op_sel_hi:[0,1,1] neg_lo:[1,0,0] neg_hi:[1,0,0]
	v_pk_fma_f32 v[228:229], v[80:81], v[70:71], v[228:229] op_sel_hi:[0,1,1] neg_lo:[1,0,0] neg_hi:[1,0,0]
	v_pk_fma_f32 v[230:231], v[80:81], v[72:73], v[230:231] op_sel_hi:[0,1,1] neg_lo:[1,0,0] neg_hi:[1,0,0]
	v_pk_fma_f32 v[232:233], v[80:81], v[74:75], v[232:233] op_sel_hi:[0,1,1] neg_lo:[1,0,0] neg_hi:[1,0,0]
	v_pk_fma_f32 v[234:235], v[80:81], v[76:77], v[234:235] op_sel_hi:[0,1,1] neg_lo:[1,0,0] neg_hi:[1,0,0]
	v_pk_fma_f32 v[236:237], v[80:81], v[78:79], v[236:237] op_sel_hi:[0,1,1] neg_lo:[1,0,0] neg_hi:[1,0,0]
	ds_read_b128 v[64:67], v1 offset:2688
	ds_read_b128 v[68:71], v1 offset:2704
	ds_read_b128 v[72:75], v1 offset:2720
	ds_read_b128 v[76:79], v1 offset:2736
	s_waitcnt lgkmcnt(8)
	v_pk_fma_f32 v[222:223], v[198:199], v[32:33], v[222:223] op_sel_hi:[0,1,1] neg_lo:[1,0,0] neg_hi:[1,0,0]
	v_pk_fma_f32 v[224:225], v[198:199], v[34:35], v[224:225] op_sel_hi:[0,1,1] neg_lo:[1,0,0] neg_hi:[1,0,0]
	v_pk_fma_f32 v[226:227], v[198:199], v[36:37], v[226:227] op_sel_hi:[0,1,1] neg_lo:[1,0,0] neg_hi:[1,0,0]
	v_pk_fma_f32 v[228:229], v[198:199], v[38:39], v[228:229] op_sel_hi:[0,1,1] neg_lo:[1,0,0] neg_hi:[1,0,0]
	v_pk_fma_f32 v[230:231], v[198:199], v[40:41], v[230:231] op_sel_hi:[0,1,1] neg_lo:[1,0,0] neg_hi:[1,0,0]
	v_pk_fma_f32 v[232:233], v[198:199], v[42:43], v[232:233] op_sel_hi:[0,1,1] neg_lo:[1,0,0] neg_hi:[1,0,0]
	v_pk_fma_f32 v[234:235], v[198:199], v[44:45], v[234:235] op_sel_hi:[0,1,1] neg_lo:[1,0,0] neg_hi:[1,0,0]
	v_pk_fma_f32 v[236:237], v[198:199], v[46:47], v[236:237] op_sel_hi:[0,1,1] neg_lo:[1,0,0] neg_hi:[1,0,0]
	ds_read_b128 v[32:35], v1 offset:2944
	ds_read_b128 v[36:39], v1 offset:2960
	ds_read_b128 v[40:43], v1 offset:2976
	ds_read_b128 v[44:47], v1 offset:2992
	s_waitcnt lgkmcnt(8)
	v_mov_b32_e32 v80, v199
	v_pk_fma_f32 v[222:223], v[80:81], v[48:49], v[222:223] op_sel_hi:[0,1,1] neg_lo:[1,0,0] neg_hi:[1,0,0]
	v_pk_fma_f32 v[224:225], v[80:81], v[50:51], v[224:225] op_sel_hi:[0,1,1] neg_lo:[1,0,0] neg_hi:[1,0,0]
	v_pk_fma_f32 v[226:227], v[80:81], v[52:53], v[226:227] op_sel_hi:[0,1,1] neg_lo:[1,0,0] neg_hi:[1,0,0]
	v_pk_fma_f32 v[228:229], v[80:81], v[54:55], v[228:229] op_sel_hi:[0,1,1] neg_lo:[1,0,0] neg_hi:[1,0,0]
	v_pk_fma_f32 v[230:231], v[80:81], v[56:57], v[230:231] op_sel_hi:[0,1,1] neg_lo:[1,0,0] neg_hi:[1,0,0]
	v_pk_fma_f32 v[232:233], v[80:81], v[58:59], v[232:233] op_sel_hi:[0,1,1] neg_lo:[1,0,0] neg_hi:[1,0,0]
	v_pk_fma_f32 v[234:235], v[80:81], v[60:61], v[234:235] op_sel_hi:[0,1,1] neg_lo:[1,0,0] neg_hi:[1,0,0]
	v_pk_fma_f32 v[236:237], v[80:81], v[62:63], v[236:237] op_sel_hi:[0,1,1] neg_lo:[1,0,0] neg_hi:[1,0,0]
	ds_read_b128 v[48:51], v1 offset:3200
	ds_read_b128 v[52:55], v1 offset:3216
	ds_read_b128 v[56:59], v1 offset:3232
	ds_read_b128 v[60:63], v1 offset:3248
	s_waitcnt lgkmcnt(8)
	v_pk_fma_f32 v[222:223], v[200:201], v[64:65], v[222:223] op_sel_hi:[0,1,1] neg_lo:[1,0,0] neg_hi:[1,0,0]
	v_pk_fma_f32 v[224:225], v[200:201], v[66:67], v[224:225] op_sel_hi:[0,1,1] neg_lo:[1,0,0] neg_hi:[1,0,0]
	v_pk_fma_f32 v[226:227], v[200:201], v[68:69], v[226:227] op_sel_hi:[0,1,1] neg_lo:[1,0,0] neg_hi:[1,0,0]
	v_pk_fma_f32 v[228:229], v[200:201], v[70:71], v[228:229] op_sel_hi:[0,1,1] neg_lo:[1,0,0] neg_hi:[1,0,0]
	v_pk_fma_f32 v[230:231], v[200:201], v[72:73], v[230:231] op_sel_hi:[0,1,1] neg_lo:[1,0,0] neg_hi:[1,0,0]
	v_pk_fma_f32 v[232:233], v[200:201], v[74:75], v[232:233] op_sel_hi:[0,1,1] neg_lo:[1,0,0] neg_hi:[1,0,0]
	v_pk_fma_f32 v[234:235], v[200:201], v[76:77], v[234:235] op_sel_hi:[0,1,1] neg_lo:[1,0,0] neg_hi:[1,0,0]
	v_pk_fma_f32 v[236:237], v[200:201], v[78:79], v[236:237] op_sel_hi:[0,1,1] neg_lo:[1,0,0] neg_hi:[1,0,0]
	ds_read_b128 v[64:67], v1 offset:3456
	ds_read_b128 v[68:71], v1 offset:3472
	ds_read_b128 v[72:75], v1 offset:3488
	ds_read_b128 v[76:79], v1 offset:3504
	s_waitcnt lgkmcnt(8)
	v_mov_b32_e32 v80, v201
	v_pk_fma_f32 v[222:223], v[80:81], v[32:33], v[222:223] op_sel_hi:[0,1,1] neg_lo:[1,0,0] neg_hi:[1,0,0]
	v_pk_fma_f32 v[224:225], v[80:81], v[34:35], v[224:225] op_sel_hi:[0,1,1] neg_lo:[1,0,0] neg_hi:[1,0,0]
	v_pk_fma_f32 v[226:227], v[80:81], v[36:37], v[226:227] op_sel_hi:[0,1,1] neg_lo:[1,0,0] neg_hi:[1,0,0]
	v_pk_fma_f32 v[228:229], v[80:81], v[38:39], v[228:229] op_sel_hi:[0,1,1] neg_lo:[1,0,0] neg_hi:[1,0,0]
	v_pk_fma_f32 v[230:231], v[80:81], v[40:41], v[230:231] op_sel_hi:[0,1,1] neg_lo:[1,0,0] neg_hi:[1,0,0]
	v_pk_fma_f32 v[232:233], v[80:81], v[42:43], v[232:233] op_sel_hi:[0,1,1] neg_lo:[1,0,0] neg_hi:[1,0,0]
	v_pk_fma_f32 v[234:235], v[80:81], v[44:45], v[234:235] op_sel_hi:[0,1,1] neg_lo:[1,0,0] neg_hi:[1,0,0]
	v_pk_fma_f32 v[236:237], v[80:81], v[46:47], v[236:237] op_sel_hi:[0,1,1] neg_lo:[1,0,0] neg_hi:[1,0,0]
	ds_read_b128 v[32:35], v1 offset:3712
	ds_read_b128 v[36:39], v1 offset:3728
	ds_read_b128 v[40:43], v1 offset:3744
	ds_read_b128 v[44:47], v1 offset:3760
	s_waitcnt lgkmcnt(8)
	v_pk_fma_f32 v[222:223], v[202:203], v[48:49], v[222:223] op_sel_hi:[0,1,1] neg_lo:[1,0,0] neg_hi:[1,0,0]
	v_pk_fma_f32 v[224:225], v[202:203], v[50:51], v[224:225] op_sel_hi:[0,1,1] neg_lo:[1,0,0] neg_hi:[1,0,0]
	v_pk_fma_f32 v[226:227], v[202:203], v[52:53], v[226:227] op_sel_hi:[0,1,1] neg_lo:[1,0,0] neg_hi:[1,0,0]
	v_pk_fma_f32 v[228:229], v[202:203], v[54:55], v[228:229] op_sel_hi:[0,1,1] neg_lo:[1,0,0] neg_hi:[1,0,0]
	v_pk_fma_f32 v[230:231], v[202:203], v[56:57], v[230:231] op_sel_hi:[0,1,1] neg_lo:[1,0,0] neg_hi:[1,0,0]
	v_pk_fma_f32 v[232:233], v[202:203], v[58:59], v[232:233] op_sel_hi:[0,1,1] neg_lo:[1,0,0] neg_hi:[1,0,0]
	v_pk_fma_f32 v[234:235], v[202:203], v[60:61], v[234:235] op_sel_hi:[0,1,1] neg_lo:[1,0,0] neg_hi:[1,0,0]
	v_pk_fma_f32 v[236:237], v[202:203], v[62:63], v[236:237] op_sel_hi:[0,1,1] neg_lo:[1,0,0] neg_hi:[1,0,0]
	ds_read_b128 v[48:51], v1 offset:3968
	ds_read_b128 v[52:55], v1 offset:3984
	ds_read_b128 v[56:59], v1 offset:4000
	ds_read_b128 v[60:63], v1 offset:4016
	s_waitcnt lgkmcnt(8)
	v_mov_b32_e32 v80, v203
	v_pk_fma_f32 v[222:223], v[80:81], v[64:65], v[222:223] op_sel_hi:[0,1,1] neg_lo:[1,0,0] neg_hi:[1,0,0]
	v_pk_fma_f32 v[224:225], v[80:81], v[66:67], v[224:225] op_sel_hi:[0,1,1] neg_lo:[1,0,0] neg_hi:[1,0,0]
	v_pk_fma_f32 v[226:227], v[80:81], v[68:69], v[226:227] op_sel_hi:[0,1,1] neg_lo:[1,0,0] neg_hi:[1,0,0]
	v_pk_fma_f32 v[228:229], v[80:81], v[70:71], v[228:229] op_sel_hi:[0,1,1] neg_lo:[1,0,0] neg_hi:[1,0,0]
	v_pk_fma_f32 v[230:231], v[80:81], v[72:73], v[230:231] op_sel_hi:[0,1,1] neg_lo:[1,0,0] neg_hi:[1,0,0]
	v_pk_fma_f32 v[232:233], v[80:81], v[74:75], v[232:233] op_sel_hi:[0,1,1] neg_lo:[1,0,0] neg_hi:[1,0,0]
	v_pk_fma_f32 v[234:235], v[80:81], v[76:77], v[234:235] op_sel_hi:[0,1,1] neg_lo:[1,0,0] neg_hi:[1,0,0]
	v_pk_fma_f32 v[236:237], v[80:81], v[78:79], v[236:237] op_sel_hi:[0,1,1] neg_lo:[1,0,0] neg_hi:[1,0,0]
	ds_read_b128 v[64:67], v1 offset:4224
	ds_read_b128 v[68:71], v1 offset:4240
	ds_read_b128 v[72:75], v1 offset:4256
	ds_read_b128 v[76:79], v1 offset:4272
	s_waitcnt lgkmcnt(8)
	v_pk_fma_f32 v[222:223], v[204:205], v[32:33], v[222:223] op_sel_hi:[0,1,1] neg_lo:[1,0,0] neg_hi:[1,0,0]
	v_pk_fma_f32 v[224:225], v[204:205], v[34:35], v[224:225] op_sel_hi:[0,1,1] neg_lo:[1,0,0] neg_hi:[1,0,0]
	v_pk_fma_f32 v[226:227], v[204:205], v[36:37], v[226:227] op_sel_hi:[0,1,1] neg_lo:[1,0,0] neg_hi:[1,0,0]
	v_pk_fma_f32 v[228:229], v[204:205], v[38:39], v[228:229] op_sel_hi:[0,1,1] neg_lo:[1,0,0] neg_hi:[1,0,0]
	v_pk_fma_f32 v[230:231], v[204:205], v[40:41], v[230:231] op_sel_hi:[0,1,1] neg_lo:[1,0,0] neg_hi:[1,0,0]
	v_pk_fma_f32 v[232:233], v[204:205], v[42:43], v[232:233] op_sel_hi:[0,1,1] neg_lo:[1,0,0] neg_hi:[1,0,0]
	v_pk_fma_f32 v[234:235], v[204:205], v[44:45], v[234:235] op_sel_hi:[0,1,1] neg_lo:[1,0,0] neg_hi:[1,0,0]
	v_pk_fma_f32 v[236:237], v[204:205], v[46:47], v[236:237] op_sel_hi:[0,1,1] neg_lo:[1,0,0] neg_hi:[1,0,0]
	ds_read_b128 v[32:35], v1 offset:4480
	ds_read_b128 v[36:39], v1 offset:4496
	ds_read_b128 v[40:43], v1 offset:4512
	ds_read_b128 v[44:47], v1 offset:4528
	s_waitcnt lgkmcnt(8)
	v_mov_b32_e32 v80, v205
	v_pk_fma_f32 v[222:223], v[80:81], v[48:49], v[222:223] op_sel_hi:[0,1,1] neg_lo:[1,0,0] neg_hi:[1,0,0]
	v_pk_fma_f32 v[224:225], v[80:81], v[50:51], v[224:225] op_sel_hi:[0,1,1] neg_lo:[1,0,0] neg_hi:[1,0,0]
	v_pk_fma_f32 v[226:227], v[80:81], v[52:53], v[226:227] op_sel_hi:[0,1,1] neg_lo:[1,0,0] neg_hi:[1,0,0]
	v_pk_fma_f32 v[228:229], v[80:81], v[54:55], v[228:229] op_sel_hi:[0,1,1] neg_lo:[1,0,0] neg_hi:[1,0,0]
	v_pk_fma_f32 v[230:231], v[80:81], v[56:57], v[230:231] op_sel_hi:[0,1,1] neg_lo:[1,0,0] neg_hi:[1,0,0]
	v_pk_fma_f32 v[232:233], v[80:81], v[58:59], v[232:233] op_sel_hi:[0,1,1] neg_lo:[1,0,0] neg_hi:[1,0,0]
	v_pk_fma_f32 v[234:235], v[80:81], v[60:61], v[234:235] op_sel_hi:[0,1,1] neg_lo:[1,0,0] neg_hi:[1,0,0]
	v_pk_fma_f32 v[236:237], v[80:81], v[62:63], v[236:237] op_sel_hi:[0,1,1] neg_lo:[1,0,0] neg_hi:[1,0,0]
	ds_read_b128 v[48:51], v1 offset:4736
	ds_read_b128 v[52:55], v1 offset:4752
	ds_read_b128 v[56:59], v1 offset:4768
	ds_read_b128 v[60:63], v1 offset:4784
	s_waitcnt lgkmcnt(8)
	v_pk_fma_f32 v[222:223], v[206:207], v[64:65], v[222:223] op_sel_hi:[0,1,1] neg_lo:[1,0,0] neg_hi:[1,0,0]
	v_pk_fma_f32 v[224:225], v[206:207], v[66:67], v[224:225] op_sel_hi:[0,1,1] neg_lo:[1,0,0] neg_hi:[1,0,0]
	v_pk_fma_f32 v[226:227], v[206:207], v[68:69], v[226:227] op_sel_hi:[0,1,1] neg_lo:[1,0,0] neg_hi:[1,0,0]
	v_pk_fma_f32 v[228:229], v[206:207], v[70:71], v[228:229] op_sel_hi:[0,1,1] neg_lo:[1,0,0] neg_hi:[1,0,0]
	v_pk_fma_f32 v[230:231], v[206:207], v[72:73], v[230:231] op_sel_hi:[0,1,1] neg_lo:[1,0,0] neg_hi:[1,0,0]
	v_pk_fma_f32 v[232:233], v[206:207], v[74:75], v[232:233] op_sel_hi:[0,1,1] neg_lo:[1,0,0] neg_hi:[1,0,0]
	v_pk_fma_f32 v[234:235], v[206:207], v[76:77], v[234:235] op_sel_hi:[0,1,1] neg_lo:[1,0,0] neg_hi:[1,0,0]
	v_pk_fma_f32 v[236:237], v[206:207], v[78:79], v[236:237] op_sel_hi:[0,1,1] neg_lo:[1,0,0] neg_hi:[1,0,0]
	ds_read_b128 v[64:67], v1 offset:4992
	ds_read_b128 v[68:71], v1 offset:5008
	ds_read_b128 v[72:75], v1 offset:5024
	ds_read_b128 v[76:79], v1 offset:5040
	s_waitcnt lgkmcnt(8)
	v_mov_b32_e32 v80, v207
	v_pk_fma_f32 v[222:223], v[80:81], v[32:33], v[222:223] op_sel_hi:[0,1,1] neg_lo:[1,0,0] neg_hi:[1,0,0]
	v_pk_fma_f32 v[224:225], v[80:81], v[34:35], v[224:225] op_sel_hi:[0,1,1] neg_lo:[1,0,0] neg_hi:[1,0,0]
	v_pk_fma_f32 v[226:227], v[80:81], v[36:37], v[226:227] op_sel_hi:[0,1,1] neg_lo:[1,0,0] neg_hi:[1,0,0]
	v_pk_fma_f32 v[228:229], v[80:81], v[38:39], v[228:229] op_sel_hi:[0,1,1] neg_lo:[1,0,0] neg_hi:[1,0,0]
	v_pk_fma_f32 v[230:231], v[80:81], v[40:41], v[230:231] op_sel_hi:[0,1,1] neg_lo:[1,0,0] neg_hi:[1,0,0]
	v_pk_fma_f32 v[232:233], v[80:81], v[42:43], v[232:233] op_sel_hi:[0,1,1] neg_lo:[1,0,0] neg_hi:[1,0,0]
	v_pk_fma_f32 v[234:235], v[80:81], v[44:45], v[234:235] op_sel_hi:[0,1,1] neg_lo:[1,0,0] neg_hi:[1,0,0]
	v_pk_fma_f32 v[236:237], v[80:81], v[46:47], v[236:237] op_sel_hi:[0,1,1] neg_lo:[1,0,0] neg_hi:[1,0,0]
	ds_read_b128 v[32:35], v1 offset:5248
	ds_read_b128 v[36:39], v1 offset:5264
	ds_read_b128 v[40:43], v1 offset:5280
	ds_read_b128 v[44:47], v1 offset:5296
	s_waitcnt lgkmcnt(8)
	v_pk_fma_f32 v[222:223], v[208:209], v[48:49], v[222:223] op_sel_hi:[0,1,1] neg_lo:[1,0,0] neg_hi:[1,0,0]
	v_pk_fma_f32 v[224:225], v[208:209], v[50:51], v[224:225] op_sel_hi:[0,1,1] neg_lo:[1,0,0] neg_hi:[1,0,0]
	v_pk_fma_f32 v[226:227], v[208:209], v[52:53], v[226:227] op_sel_hi:[0,1,1] neg_lo:[1,0,0] neg_hi:[1,0,0]
	v_pk_fma_f32 v[228:229], v[208:209], v[54:55], v[228:229] op_sel_hi:[0,1,1] neg_lo:[1,0,0] neg_hi:[1,0,0]
	v_pk_fma_f32 v[230:231], v[208:209], v[56:57], v[230:231] op_sel_hi:[0,1,1] neg_lo:[1,0,0] neg_hi:[1,0,0]
	v_pk_fma_f32 v[232:233], v[208:209], v[58:59], v[232:233] op_sel_hi:[0,1,1] neg_lo:[1,0,0] neg_hi:[1,0,0]
	v_pk_fma_f32 v[234:235], v[208:209], v[60:61], v[234:235] op_sel_hi:[0,1,1] neg_lo:[1,0,0] neg_hi:[1,0,0]
	v_pk_fma_f32 v[236:237], v[208:209], v[62:63], v[236:237] op_sel_hi:[0,1,1] neg_lo:[1,0,0] neg_hi:[1,0,0]
	ds_read_b128 v[48:51], v1 offset:5504
	ds_read_b128 v[52:55], v1 offset:5520
	ds_read_b128 v[56:59], v1 offset:5536
	ds_read_b128 v[60:63], v1 offset:5552
	s_waitcnt lgkmcnt(8)
	v_mov_b32_e32 v80, v209
	v_pk_fma_f32 v[222:223], v[80:81], v[64:65], v[222:223] op_sel_hi:[0,1,1] neg_lo:[1,0,0] neg_hi:[1,0,0]
	v_pk_fma_f32 v[224:225], v[80:81], v[66:67], v[224:225] op_sel_hi:[0,1,1] neg_lo:[1,0,0] neg_hi:[1,0,0]
	v_pk_fma_f32 v[226:227], v[80:81], v[68:69], v[226:227] op_sel_hi:[0,1,1] neg_lo:[1,0,0] neg_hi:[1,0,0]
	v_pk_fma_f32 v[228:229], v[80:81], v[70:71], v[228:229] op_sel_hi:[0,1,1] neg_lo:[1,0,0] neg_hi:[1,0,0]
	v_pk_fma_f32 v[230:231], v[80:81], v[72:73], v[230:231] op_sel_hi:[0,1,1] neg_lo:[1,0,0] neg_hi:[1,0,0]
	v_pk_fma_f32 v[232:233], v[80:81], v[74:75], v[232:233] op_sel_hi:[0,1,1] neg_lo:[1,0,0] neg_hi:[1,0,0]
	v_pk_fma_f32 v[234:235], v[80:81], v[76:77], v[234:235] op_sel_hi:[0,1,1] neg_lo:[1,0,0] neg_hi:[1,0,0]
	v_pk_fma_f32 v[236:237], v[80:81], v[78:79], v[236:237] op_sel_hi:[0,1,1] neg_lo:[1,0,0] neg_hi:[1,0,0]
	ds_read_b128 v[64:67], v1 offset:5760
	ds_read_b128 v[68:71], v1 offset:5776
	ds_read_b128 v[72:75], v1 offset:5792
	ds_read_b128 v[76:79], v1 offset:5808
	s_waitcnt lgkmcnt(8)
	v_pk_fma_f32 v[222:223], v[210:211], v[32:33], v[222:223] op_sel_hi:[0,1,1] neg_lo:[1,0,0] neg_hi:[1,0,0]
	v_pk_fma_f32 v[224:225], v[210:211], v[34:35], v[224:225] op_sel_hi:[0,1,1] neg_lo:[1,0,0] neg_hi:[1,0,0]
	v_pk_fma_f32 v[226:227], v[210:211], v[36:37], v[226:227] op_sel_hi:[0,1,1] neg_lo:[1,0,0] neg_hi:[1,0,0]
	v_pk_fma_f32 v[228:229], v[210:211], v[38:39], v[228:229] op_sel_hi:[0,1,1] neg_lo:[1,0,0] neg_hi:[1,0,0]
	v_pk_fma_f32 v[230:231], v[210:211], v[40:41], v[230:231] op_sel_hi:[0,1,1] neg_lo:[1,0,0] neg_hi:[1,0,0]
	v_pk_fma_f32 v[232:233], v[210:211], v[42:43], v[232:233] op_sel_hi:[0,1,1] neg_lo:[1,0,0] neg_hi:[1,0,0]
	v_pk_fma_f32 v[234:235], v[210:211], v[44:45], v[234:235] op_sel_hi:[0,1,1] neg_lo:[1,0,0] neg_hi:[1,0,0]
	v_pk_fma_f32 v[236:237], v[210:211], v[46:47], v[236:237] op_sel_hi:[0,1,1] neg_lo:[1,0,0] neg_hi:[1,0,0]
	ds_read_b128 v[32:35], v1 offset:6016
	ds_read_b128 v[36:39], v1 offset:6032
	ds_read_b128 v[40:43], v1 offset:6048
	ds_read_b128 v[44:47], v1 offset:6064
	s_waitcnt lgkmcnt(8)
	v_mov_b32_e32 v80, v211
	v_pk_fma_f32 v[222:223], v[80:81], v[48:49], v[222:223] op_sel_hi:[0,1,1] neg_lo:[1,0,0] neg_hi:[1,0,0]
	v_pk_fma_f32 v[224:225], v[80:81], v[50:51], v[224:225] op_sel_hi:[0,1,1] neg_lo:[1,0,0] neg_hi:[1,0,0]
	v_pk_fma_f32 v[226:227], v[80:81], v[52:53], v[226:227] op_sel_hi:[0,1,1] neg_lo:[1,0,0] neg_hi:[1,0,0]
	v_pk_fma_f32 v[228:229], v[80:81], v[54:55], v[228:229] op_sel_hi:[0,1,1] neg_lo:[1,0,0] neg_hi:[1,0,0]
	v_pk_fma_f32 v[230:231], v[80:81], v[56:57], v[230:231] op_sel_hi:[0,1,1] neg_lo:[1,0,0] neg_hi:[1,0,0]
	v_pk_fma_f32 v[232:233], v[80:81], v[58:59], v[232:233] op_sel_hi:[0,1,1] neg_lo:[1,0,0] neg_hi:[1,0,0]
	v_pk_fma_f32 v[234:235], v[80:81], v[60:61], v[234:235] op_sel_hi:[0,1,1] neg_lo:[1,0,0] neg_hi:[1,0,0]
	v_pk_fma_f32 v[236:237], v[80:81], v[62:63], v[236:237] op_sel_hi:[0,1,1] neg_lo:[1,0,0] neg_hi:[1,0,0]
	ds_read_b128 v[48:51], v1 offset:6272
	ds_read_b128 v[52:55], v1 offset:6288
	ds_read_b128 v[56:59], v1 offset:6304
	ds_read_b128 v[60:63], v1 offset:6320
	s_waitcnt lgkmcnt(8)
	v_pk_fma_f32 v[222:223], v[212:213], v[64:65], v[222:223] op_sel_hi:[0,1,1] neg_lo:[1,0,0] neg_hi:[1,0,0]
	v_pk_fma_f32 v[224:225], v[212:213], v[66:67], v[224:225] op_sel_hi:[0,1,1] neg_lo:[1,0,0] neg_hi:[1,0,0]
	v_pk_fma_f32 v[226:227], v[212:213], v[68:69], v[226:227] op_sel_hi:[0,1,1] neg_lo:[1,0,0] neg_hi:[1,0,0]
	v_pk_fma_f32 v[228:229], v[212:213], v[70:71], v[228:229] op_sel_hi:[0,1,1] neg_lo:[1,0,0] neg_hi:[1,0,0]
	v_pk_fma_f32 v[230:231], v[212:213], v[72:73], v[230:231] op_sel_hi:[0,1,1] neg_lo:[1,0,0] neg_hi:[1,0,0]
	v_pk_fma_f32 v[232:233], v[212:213], v[74:75], v[232:233] op_sel_hi:[0,1,1] neg_lo:[1,0,0] neg_hi:[1,0,0]
	v_pk_fma_f32 v[234:235], v[212:213], v[76:77], v[234:235] op_sel_hi:[0,1,1] neg_lo:[1,0,0] neg_hi:[1,0,0]
	v_pk_fma_f32 v[236:237], v[212:213], v[78:79], v[236:237] op_sel_hi:[0,1,1] neg_lo:[1,0,0] neg_hi:[1,0,0]
	ds_read_b128 v[64:67], v1 offset:6528
	ds_read_b128 v[68:71], v1 offset:6544
	ds_read_b128 v[72:75], v1 offset:6560
	ds_read_b128 v[76:79], v1 offset:6576
	s_waitcnt lgkmcnt(8)
	v_mov_b32_e32 v80, v213
	v_pk_fma_f32 v[222:223], v[80:81], v[32:33], v[222:223] op_sel_hi:[0,1,1] neg_lo:[1,0,0] neg_hi:[1,0,0]
	v_pk_fma_f32 v[224:225], v[80:81], v[34:35], v[224:225] op_sel_hi:[0,1,1] neg_lo:[1,0,0] neg_hi:[1,0,0]
	v_pk_fma_f32 v[226:227], v[80:81], v[36:37], v[226:227] op_sel_hi:[0,1,1] neg_lo:[1,0,0] neg_hi:[1,0,0]
	v_pk_fma_f32 v[228:229], v[80:81], v[38:39], v[228:229] op_sel_hi:[0,1,1] neg_lo:[1,0,0] neg_hi:[1,0,0]
	v_pk_fma_f32 v[230:231], v[80:81], v[40:41], v[230:231] op_sel_hi:[0,1,1] neg_lo:[1,0,0] neg_hi:[1,0,0]
	v_pk_fma_f32 v[232:233], v[80:81], v[42:43], v[232:233] op_sel_hi:[0,1,1] neg_lo:[1,0,0] neg_hi:[1,0,0]
	v_pk_fma_f32 v[234:235], v[80:81], v[44:45], v[234:235] op_sel_hi:[0,1,1] neg_lo:[1,0,0] neg_hi:[1,0,0]
	v_pk_fma_f32 v[236:237], v[80:81], v[46:47], v[236:237] op_sel_hi:[0,1,1] neg_lo:[1,0,0] neg_hi:[1,0,0]
	ds_read_b128 v[32:35], v1 offset:6784
	ds_read_b128 v[36:39], v1 offset:6800
	ds_read_b128 v[40:43], v1 offset:6816
	ds_read_b128 v[44:47], v1 offset:6832
	s_waitcnt lgkmcnt(8)
	v_pk_fma_f32 v[222:223], v[214:215], v[48:49], v[222:223] op_sel_hi:[0,1,1] neg_lo:[1,0,0] neg_hi:[1,0,0]
	v_pk_fma_f32 v[224:225], v[214:215], v[50:51], v[224:225] op_sel_hi:[0,1,1] neg_lo:[1,0,0] neg_hi:[1,0,0]
	v_pk_fma_f32 v[226:227], v[214:215], v[52:53], v[226:227] op_sel_hi:[0,1,1] neg_lo:[1,0,0] neg_hi:[1,0,0]
	v_pk_fma_f32 v[228:229], v[214:215], v[54:55], v[228:229] op_sel_hi:[0,1,1] neg_lo:[1,0,0] neg_hi:[1,0,0]
	v_pk_fma_f32 v[230:231], v[214:215], v[56:57], v[230:231] op_sel_hi:[0,1,1] neg_lo:[1,0,0] neg_hi:[1,0,0]
	v_pk_fma_f32 v[232:233], v[214:215], v[58:59], v[232:233] op_sel_hi:[0,1,1] neg_lo:[1,0,0] neg_hi:[1,0,0]
	v_pk_fma_f32 v[234:235], v[214:215], v[60:61], v[234:235] op_sel_hi:[0,1,1] neg_lo:[1,0,0] neg_hi:[1,0,0]
	v_pk_fma_f32 v[236:237], v[214:215], v[62:63], v[236:237] op_sel_hi:[0,1,1] neg_lo:[1,0,0] neg_hi:[1,0,0]
	ds_read_b128 v[48:51], v1 offset:7040
	ds_read_b128 v[52:55], v1 offset:7056
	ds_read_b128 v[56:59], v1 offset:7072
	ds_read_b128 v[60:63], v1 offset:7088
	s_waitcnt lgkmcnt(8)
	v_mov_b32_e32 v80, v215
	v_pk_fma_f32 v[222:223], v[80:81], v[64:65], v[222:223] op_sel_hi:[0,1,1] neg_lo:[1,0,0] neg_hi:[1,0,0]
	v_pk_fma_f32 v[224:225], v[80:81], v[66:67], v[224:225] op_sel_hi:[0,1,1] neg_lo:[1,0,0] neg_hi:[1,0,0]
	v_pk_fma_f32 v[226:227], v[80:81], v[68:69], v[226:227] op_sel_hi:[0,1,1] neg_lo:[1,0,0] neg_hi:[1,0,0]
	v_pk_fma_f32 v[228:229], v[80:81], v[70:71], v[228:229] op_sel_hi:[0,1,1] neg_lo:[1,0,0] neg_hi:[1,0,0]
	v_pk_fma_f32 v[230:231], v[80:81], v[72:73], v[230:231] op_sel_hi:[0,1,1] neg_lo:[1,0,0] neg_hi:[1,0,0]
	v_pk_fma_f32 v[232:233], v[80:81], v[74:75], v[232:233] op_sel_hi:[0,1,1] neg_lo:[1,0,0] neg_hi:[1,0,0]
	v_pk_fma_f32 v[234:235], v[80:81], v[76:77], v[234:235] op_sel_hi:[0,1,1] neg_lo:[1,0,0] neg_hi:[1,0,0]
	v_pk_fma_f32 v[236:237], v[80:81], v[78:79], v[236:237] op_sel_hi:[0,1,1] neg_lo:[1,0,0] neg_hi:[1,0,0]
	ds_read_b128 v[64:67], v1 offset:7296
	ds_read_b128 v[68:71], v1 offset:7312
	ds_read_b128 v[72:75], v1 offset:7328
	ds_read_b128 v[76:79], v1 offset:7344
	s_waitcnt lgkmcnt(8)
	v_pk_fma_f32 v[222:223], v[216:217], v[32:33], v[222:223] op_sel_hi:[0,1,1] neg_lo:[1,0,0] neg_hi:[1,0,0]
	v_pk_fma_f32 v[224:225], v[216:217], v[34:35], v[224:225] op_sel_hi:[0,1,1] neg_lo:[1,0,0] neg_hi:[1,0,0]
	v_pk_fma_f32 v[226:227], v[216:217], v[36:37], v[226:227] op_sel_hi:[0,1,1] neg_lo:[1,0,0] neg_hi:[1,0,0]
	v_pk_fma_f32 v[228:229], v[216:217], v[38:39], v[228:229] op_sel_hi:[0,1,1] neg_lo:[1,0,0] neg_hi:[1,0,0]
	v_pk_fma_f32 v[230:231], v[216:217], v[40:41], v[230:231] op_sel_hi:[0,1,1] neg_lo:[1,0,0] neg_hi:[1,0,0]
	v_pk_fma_f32 v[232:233], v[216:217], v[42:43], v[232:233] op_sel_hi:[0,1,1] neg_lo:[1,0,0] neg_hi:[1,0,0]
	v_pk_fma_f32 v[234:235], v[216:217], v[44:45], v[234:235] op_sel_hi:[0,1,1] neg_lo:[1,0,0] neg_hi:[1,0,0]
	v_pk_fma_f32 v[236:237], v[216:217], v[46:47], v[236:237] op_sel_hi:[0,1,1] neg_lo:[1,0,0] neg_hi:[1,0,0]
	ds_read_b128 v[32:35], v1 offset:7552
	ds_read_b128 v[36:39], v1 offset:7568
	ds_read_b128 v[40:43], v1 offset:7584
	ds_read_b128 v[44:47], v1 offset:7600
	s_waitcnt lgkmcnt(8)
	v_mov_b32_e32 v80, v217
	v_pk_fma_f32 v[222:223], v[80:81], v[48:49], v[222:223] op_sel_hi:[0,1,1] neg_lo:[1,0,0] neg_hi:[1,0,0]
	v_pk_fma_f32 v[224:225], v[80:81], v[50:51], v[224:225] op_sel_hi:[0,1,1] neg_lo:[1,0,0] neg_hi:[1,0,0]
	v_pk_fma_f32 v[226:227], v[80:81], v[52:53], v[226:227] op_sel_hi:[0,1,1] neg_lo:[1,0,0] neg_hi:[1,0,0]
	v_pk_fma_f32 v[228:229], v[80:81], v[54:55], v[228:229] op_sel_hi:[0,1,1] neg_lo:[1,0,0] neg_hi:[1,0,0]
	v_pk_fma_f32 v[230:231], v[80:81], v[56:57], v[230:231] op_sel_hi:[0,1,1] neg_lo:[1,0,0] neg_hi:[1,0,0]
	v_pk_fma_f32 v[232:233], v[80:81], v[58:59], v[232:233] op_sel_hi:[0,1,1] neg_lo:[1,0,0] neg_hi:[1,0,0]
	v_pk_fma_f32 v[234:235], v[80:81], v[60:61], v[234:235] op_sel_hi:[0,1,1] neg_lo:[1,0,0] neg_hi:[1,0,0]
	v_pk_fma_f32 v[236:237], v[80:81], v[62:63], v[236:237] op_sel_hi:[0,1,1] neg_lo:[1,0,0] neg_hi:[1,0,0]
	ds_read_b128 v[48:51], v1 offset:7808
	ds_read_b128 v[52:55], v1 offset:7824
	ds_read_b128 v[56:59], v1 offset:7840
	ds_read_b128 v[60:63], v1 offset:7856
	s_waitcnt lgkmcnt(8)
	v_pk_fma_f32 v[222:223], v[218:219], v[64:65], v[222:223] op_sel_hi:[0,1,1] neg_lo:[1,0,0] neg_hi:[1,0,0]
	v_pk_fma_f32 v[224:225], v[218:219], v[66:67], v[224:225] op_sel_hi:[0,1,1] neg_lo:[1,0,0] neg_hi:[1,0,0]
	v_pk_fma_f32 v[226:227], v[218:219], v[68:69], v[226:227] op_sel_hi:[0,1,1] neg_lo:[1,0,0] neg_hi:[1,0,0]
	v_pk_fma_f32 v[228:229], v[218:219], v[70:71], v[228:229] op_sel_hi:[0,1,1] neg_lo:[1,0,0] neg_hi:[1,0,0]
	v_pk_fma_f32 v[230:231], v[218:219], v[72:73], v[230:231] op_sel_hi:[0,1,1] neg_lo:[1,0,0] neg_hi:[1,0,0]
	v_pk_fma_f32 v[232:233], v[218:219], v[74:75], v[232:233] op_sel_hi:[0,1,1] neg_lo:[1,0,0] neg_hi:[1,0,0]
	v_pk_fma_f32 v[234:235], v[218:219], v[76:77], v[234:235] op_sel_hi:[0,1,1] neg_lo:[1,0,0] neg_hi:[1,0,0]
	v_pk_fma_f32 v[236:237], v[218:219], v[78:79], v[236:237] op_sel_hi:[0,1,1] neg_lo:[1,0,0] neg_hi:[1,0,0]
	ds_read_b128 v[64:67], v1 offset:8064
	ds_read_b128 v[68:71], v1 offset:8080
	ds_read_b128 v[72:75], v1 offset:8096
	ds_read_b128 v[76:79], v1 offset:8112
	s_waitcnt lgkmcnt(8)
	v_mov_b32_e32 v80, v219
	v_pk_fma_f32 v[222:223], v[80:81], v[32:33], v[222:223] op_sel_hi:[0,1,1] neg_lo:[1,0,0] neg_hi:[1,0,0]
	v_pk_fma_f32 v[224:225], v[80:81], v[34:35], v[224:225] op_sel_hi:[0,1,1] neg_lo:[1,0,0] neg_hi:[1,0,0]
	v_pk_fma_f32 v[226:227], v[80:81], v[36:37], v[226:227] op_sel_hi:[0,1,1] neg_lo:[1,0,0] neg_hi:[1,0,0]
	v_pk_fma_f32 v[228:229], v[80:81], v[38:39], v[228:229] op_sel_hi:[0,1,1] neg_lo:[1,0,0] neg_hi:[1,0,0]
	v_pk_fma_f32 v[230:231], v[80:81], v[40:41], v[230:231] op_sel_hi:[0,1,1] neg_lo:[1,0,0] neg_hi:[1,0,0]
	v_pk_fma_f32 v[232:233], v[80:81], v[42:43], v[232:233] op_sel_hi:[0,1,1] neg_lo:[1,0,0] neg_hi:[1,0,0]
	v_pk_fma_f32 v[234:235], v[80:81], v[44:45], v[234:235] op_sel_hi:[0,1,1] neg_lo:[1,0,0] neg_hi:[1,0,0]
	v_pk_fma_f32 v[236:237], v[80:81], v[46:47], v[236:237] op_sel_hi:[0,1,1] neg_lo:[1,0,0] neg_hi:[1,0,0]
	ds_read_b128 v[32:35], v1 offset:8320
	ds_read_b128 v[36:39], v1 offset:8336
	ds_read_b128 v[40:43], v1 offset:8352
	ds_read_b128 v[44:47], v1 offset:8368
	s_waitcnt lgkmcnt(8)
	v_pk_fma_f32 v[222:223], v[220:221], v[48:49], v[222:223] op_sel_hi:[0,1,1] neg_lo:[1,0,0] neg_hi:[1,0,0]
	v_pk_fma_f32 v[224:225], v[220:221], v[50:51], v[224:225] op_sel_hi:[0,1,1] neg_lo:[1,0,0] neg_hi:[1,0,0]
	v_pk_fma_f32 v[226:227], v[220:221], v[52:53], v[226:227] op_sel_hi:[0,1,1] neg_lo:[1,0,0] neg_hi:[1,0,0]
	v_pk_fma_f32 v[228:229], v[220:221], v[54:55], v[228:229] op_sel_hi:[0,1,1] neg_lo:[1,0,0] neg_hi:[1,0,0]
	v_pk_fma_f32 v[230:231], v[220:221], v[56:57], v[230:231] op_sel_hi:[0,1,1] neg_lo:[1,0,0] neg_hi:[1,0,0]
	v_pk_fma_f32 v[232:233], v[220:221], v[58:59], v[232:233] op_sel_hi:[0,1,1] neg_lo:[1,0,0] neg_hi:[1,0,0]
	v_pk_fma_f32 v[234:235], v[220:221], v[60:61], v[234:235] op_sel_hi:[0,1,1] neg_lo:[1,0,0] neg_hi:[1,0,0]
	v_pk_fma_f32 v[236:237], v[220:221], v[62:63], v[236:237] op_sel_hi:[0,1,1] neg_lo:[1,0,0] neg_hi:[1,0,0]
	ds_read_b128 v[48:51], v1 offset:8576
	ds_read_b128 v[52:55], v1 offset:8592
	ds_read_b128 v[56:59], v1 offset:8608
	ds_read_b128 v[60:63], v1 offset:8624
	s_waitcnt lgkmcnt(8)
	v_mov_b32_e32 v80, v221
	v_pk_fma_f32 v[222:223], v[80:81], v[64:65], v[222:223] op_sel_hi:[0,1,1] neg_lo:[1,0,0] neg_hi:[1,0,0]
	v_pk_fma_f32 v[224:225], v[80:81], v[66:67], v[224:225] op_sel_hi:[0,1,1] neg_lo:[1,0,0] neg_hi:[1,0,0]
	v_pk_fma_f32 v[226:227], v[80:81], v[68:69], v[226:227] op_sel_hi:[0,1,1] neg_lo:[1,0,0] neg_hi:[1,0,0]
	v_pk_fma_f32 v[228:229], v[80:81], v[70:71], v[228:229] op_sel_hi:[0,1,1] neg_lo:[1,0,0] neg_hi:[1,0,0]
	v_pk_fma_f32 v[230:231], v[80:81], v[72:73], v[230:231] op_sel_hi:[0,1,1] neg_lo:[1,0,0] neg_hi:[1,0,0]
	v_pk_fma_f32 v[232:233], v[80:81], v[74:75], v[232:233] op_sel_hi:[0,1,1] neg_lo:[1,0,0] neg_hi:[1,0,0]
	v_pk_fma_f32 v[234:235], v[80:81], v[76:77], v[234:235] op_sel_hi:[0,1,1] neg_lo:[1,0,0] neg_hi:[1,0,0]
	v_pk_fma_f32 v[236:237], v[80:81], v[78:79], v[236:237] op_sel_hi:[0,1,1] neg_lo:[1,0,0] neg_hi:[1,0,0]
	ds_read_b128 v[64:67], v1 offset:8832
	ds_read_b128 v[68:71], v1 offset:8848
	ds_read_b128 v[72:75], v1 offset:8864
	ds_read_b128 v[76:79], v1 offset:8880
	s_waitcnt lgkmcnt(8)
	v_fma_f32 v223, -v222, v33, v223
	v_pk_fma_f32 v[224:225], v[222:223], v[34:35], v[224:225] op_sel_hi:[0,1,1] neg_lo:[1,0,0] neg_hi:[1,0,0]
	v_pk_fma_f32 v[226:227], v[222:223], v[36:37], v[226:227] op_sel_hi:[0,1,1] neg_lo:[1,0,0] neg_hi:[1,0,0]
	v_pk_fma_f32 v[228:229], v[222:223], v[38:39], v[228:229] op_sel_hi:[0,1,1] neg_lo:[1,0,0] neg_hi:[1,0,0]
	v_pk_fma_f32 v[230:231], v[222:223], v[40:41], v[230:231] op_sel_hi:[0,1,1] neg_lo:[1,0,0] neg_hi:[1,0,0]
	v_pk_fma_f32 v[232:233], v[222:223], v[42:43], v[232:233] op_sel_hi:[0,1,1] neg_lo:[1,0,0] neg_hi:[1,0,0]
	v_pk_fma_f32 v[234:235], v[222:223], v[44:45], v[234:235] op_sel_hi:[0,1,1] neg_lo:[1,0,0] neg_hi:[1,0,0]
	v_pk_fma_f32 v[236:237], v[222:223], v[46:47], v[236:237] op_sel_hi:[0,1,1] neg_lo:[1,0,0] neg_hi:[1,0,0]
	ds_read_b128 v[36:39], v1 offset:9104
	ds_read_b128 v[40:43], v1 offset:9120
	ds_read_b128 v[44:47], v1 offset:9136
	s_waitcnt lgkmcnt(7)
	v_mov_b32_e32 v80, v223
	v_pk_fma_f32 v[224:225], v[80:81], v[50:51], v[224:225] op_sel_hi:[0,1,1] neg_lo:[1,0,0] neg_hi:[1,0,0]
	v_pk_fma_f32 v[226:227], v[80:81], v[52:53], v[226:227] op_sel_hi:[0,1,1] neg_lo:[1,0,0] neg_hi:[1,0,0]
	v_pk_fma_f32 v[228:229], v[80:81], v[54:55], v[228:229] op_sel_hi:[0,1,1] neg_lo:[1,0,0] neg_hi:[1,0,0]
	v_pk_fma_f32 v[230:231], v[80:81], v[56:57], v[230:231] op_sel_hi:[0,1,1] neg_lo:[1,0,0] neg_hi:[1,0,0]
	v_pk_fma_f32 v[232:233], v[80:81], v[58:59], v[232:233] op_sel_hi:[0,1,1] neg_lo:[1,0,0] neg_hi:[1,0,0]
	v_pk_fma_f32 v[234:235], v[80:81], v[60:61], v[234:235] op_sel_hi:[0,1,1] neg_lo:[1,0,0] neg_hi:[1,0,0]
	v_pk_fma_f32 v[236:237], v[80:81], v[62:63], v[236:237] op_sel_hi:[0,1,1] neg_lo:[1,0,0] neg_hi:[1,0,0]
	ds_read_b128 v[52:55], v1 offset:9360
	ds_read_b128 v[56:59], v1 offset:9376
	ds_read_b128 v[60:63], v1 offset:9392
	s_waitcnt lgkmcnt(6)
	v_fma_f32 v225, -v224, v67, v225
	v_pk_fma_f32 v[226:227], v[224:225], v[68:69], v[226:227] op_sel_hi:[0,1,1] neg_lo:[1,0,0] neg_hi:[1,0,0]
	v_pk_fma_f32 v[228:229], v[224:225], v[70:71], v[228:229] op_sel_hi:[0,1,1] neg_lo:[1,0,0] neg_hi:[1,0,0]
	v_pk_fma_f32 v[230:231], v[224:225], v[72:73], v[230:231] op_sel_hi:[0,1,1] neg_lo:[1,0,0] neg_hi:[1,0,0]
	v_pk_fma_f32 v[232:233], v[224:225], v[74:75], v[232:233] op_sel_hi:[0,1,1] neg_lo:[1,0,0] neg_hi:[1,0,0]
	v_pk_fma_f32 v[234:235], v[224:225], v[76:77], v[234:235] op_sel_hi:[0,1,1] neg_lo:[1,0,0] neg_hi:[1,0,0]
	v_pk_fma_f32 v[236:237], v[224:225], v[78:79], v[236:237] op_sel_hi:[0,1,1] neg_lo:[1,0,0] neg_hi:[1,0,0]
	ds_read_b128 v[68:71], v1 offset:9616
	ds_read_b128 v[72:75], v1 offset:9632
	ds_read_b128 v[76:79], v1 offset:9648
	s_waitcnt lgkmcnt(6)
	v_mov_b32_e32 v80, v225
	v_pk_fma_f32 v[226:227], v[80:81], v[36:37], v[226:227] op_sel_hi:[0,1,1] neg_lo:[1,0,0] neg_hi:[1,0,0]
	v_pk_fma_f32 v[228:229], v[80:81], v[38:39], v[228:229] op_sel_hi:[0,1,1] neg_lo:[1,0,0] neg_hi:[1,0,0]
	v_pk_fma_f32 v[230:231], v[80:81], v[40:41], v[230:231] op_sel_hi:[0,1,1] neg_lo:[1,0,0] neg_hi:[1,0,0]
	v_pk_fma_f32 v[232:233], v[80:81], v[42:43], v[232:233] op_sel_hi:[0,1,1] neg_lo:[1,0,0] neg_hi:[1,0,0]
	v_pk_fma_f32 v[234:235], v[80:81], v[44:45], v[234:235] op_sel_hi:[0,1,1] neg_lo:[1,0,0] neg_hi:[1,0,0]
	v_pk_fma_f32 v[236:237], v[80:81], v[46:47], v[236:237] op_sel_hi:[0,1,1] neg_lo:[1,0,0] neg_hi:[1,0,0]
	ds_read_b128 v[36:39], v1 offset:9872
	ds_read_b128 v[40:43], v1 offset:9888
	ds_read_b128 v[44:47], v1 offset:9904
	s_waitcnt lgkmcnt(6)
	v_fma_f32 v227, -v226, v53, v227
	v_pk_fma_f32 v[228:229], v[226:227], v[54:55], v[228:229] op_sel_hi:[0,1,1] neg_lo:[1,0,0] neg_hi:[1,0,0]
	v_pk_fma_f32 v[230:231], v[226:227], v[56:57], v[230:231] op_sel_hi:[0,1,1] neg_lo:[1,0,0] neg_hi:[1,0,0]
	v_pk_fma_f32 v[232:233], v[226:227], v[58:59], v[232:233] op_sel_hi:[0,1,1] neg_lo:[1,0,0] neg_hi:[1,0,0]
	v_pk_fma_f32 v[234:235], v[226:227], v[60:61], v[234:235] op_sel_hi:[0,1,1] neg_lo:[1,0,0] neg_hi:[1,0,0]
	v_pk_fma_f32 v[236:237], v[226:227], v[62:63], v[236:237] op_sel_hi:[0,1,1] neg_lo:[1,0,0] neg_hi:[1,0,0]
	ds_read_b128 v[56:59], v1 offset:10144
	ds_read_b128 v[60:63], v1 offset:10160
	s_waitcnt lgkmcnt(5)
	v_mov_b32_e32 v80, v227
	v_pk_fma_f32 v[228:229], v[80:81], v[70:71], v[228:229] op_sel_hi:[0,1,1] neg_lo:[1,0,0] neg_hi:[1,0,0]
	v_pk_fma_f32 v[230:231], v[80:81], v[72:73], v[230:231] op_sel_hi:[0,1,1] neg_lo:[1,0,0] neg_hi:[1,0,0]
	v_pk_fma_f32 v[232:233], v[80:81], v[74:75], v[232:233] op_sel_hi:[0,1,1] neg_lo:[1,0,0] neg_hi:[1,0,0]
	v_pk_fma_f32 v[234:235], v[80:81], v[76:77], v[234:235] op_sel_hi:[0,1,1] neg_lo:[1,0,0] neg_hi:[1,0,0]
	v_pk_fma_f32 v[236:237], v[80:81], v[78:79], v[236:237] op_sel_hi:[0,1,1] neg_lo:[1,0,0] neg_hi:[1,0,0]
	ds_read_b128 v[72:75], v1 offset:10400
	ds_read_b128 v[76:79], v1 offset:10416
	s_waitcnt lgkmcnt(4)
	v_fma_f32 v229, -v228, v39, v229
	v_pk_fma_f32 v[230:231], v[228:229], v[40:41], v[230:231] op_sel_hi:[0,1,1] neg_lo:[1,0,0] neg_hi:[1,0,0]
	v_pk_fma_f32 v[232:233], v[228:229], v[42:43], v[232:233] op_sel_hi:[0,1,1] neg_lo:[1,0,0] neg_hi:[1,0,0]
	v_pk_fma_f32 v[234:235], v[228:229], v[44:45], v[234:235] op_sel_hi:[0,1,1] neg_lo:[1,0,0] neg_hi:[1,0,0]
	v_pk_fma_f32 v[236:237], v[228:229], v[46:47], v[236:237] op_sel_hi:[0,1,1] neg_lo:[1,0,0] neg_hi:[1,0,0]
	ds_read_b128 v[40:43], v1 offset:10656
	ds_read_b128 v[44:47], v1 offset:10672
	s_waitcnt lgkmcnt(4)
	v_mov_b32_e32 v80, v229
	v_pk_fma_f32 v[230:231], v[80:81], v[56:57], v[230:231] op_sel_hi:[0,1,1] neg_lo:[1,0,0] neg_hi:[1,0,0]
	v_pk_fma_f32 v[232:233], v[80:81], v[58:59], v[232:233] op_sel_hi:[0,1,1] neg_lo:[1,0,0] neg_hi:[1,0,0]
	v_pk_fma_f32 v[234:235], v[80:81], v[60:61], v[234:235] op_sel_hi:[0,1,1] neg_lo:[1,0,0] neg_hi:[1,0,0]
	v_pk_fma_f32 v[236:237], v[80:81], v[62:63], v[236:237] op_sel_hi:[0,1,1] neg_lo:[1,0,0] neg_hi:[1,0,0]
	ds_read_b128 v[56:59], v1 offset:10912
	ds_read_b128 v[60:63], v1 offset:10928
	s_waitcnt lgkmcnt(4)
	v_fma_f32 v231, -v230, v73, v231
	v_pk_fma_f32 v[232:233], v[230:231], v[74:75], v[232:233] op_sel_hi:[0,1,1] neg_lo:[1,0,0] neg_hi:[1,0,0]
	v_pk_fma_f32 v[234:235], v[230:231], v[76:77], v[234:235] op_sel_hi:[0,1,1] neg_lo:[1,0,0] neg_hi:[1,0,0]
	v_pk_fma_f32 v[236:237], v[230:231], v[78:79], v[236:237] op_sel_hi:[0,1,1] neg_lo:[1,0,0] neg_hi:[1,0,0]
	ds_read_b128 v[76:79], v1 offset:11184
	s_waitcnt lgkmcnt(3)
	v_mov_b32_e32 v80, v231
	v_pk_fma_f32 v[232:233], v[80:81], v[42:43], v[232:233] op_sel_hi:[0,1,1] neg_lo:[1,0,0] neg_hi:[1,0,0]
	v_pk_fma_f32 v[234:235], v[80:81], v[44:45], v[234:235] op_sel_hi:[0,1,1] neg_lo:[1,0,0] neg_hi:[1,0,0]
	v_pk_fma_f32 v[236:237], v[80:81], v[46:47], v[236:237] op_sel_hi:[0,1,1] neg_lo:[1,0,0] neg_hi:[1,0,0]
	ds_read_b128 v[44:47], v1 offset:11440
	s_waitcnt lgkmcnt(2)
	v_fma_f32 v233, -v232, v59, v233
	v_pk_fma_f32 v[234:235], v[232:233], v[60:61], v[234:235] op_sel_hi:[0,1,1] neg_lo:[1,0,0] neg_hi:[1,0,0]
	v_pk_fma_f32 v[236:237], v[232:233], v[62:63], v[236:237] op_sel_hi:[0,1,1] neg_lo:[1,0,0] neg_hi:[1,0,0]
	ds_read_b128 v[60:63], v1 offset:11696
	s_waitcnt lgkmcnt(2)
	v_mov_b32_e32 v80, v233
	v_pk_fma_f32 v[234:235], v[80:81], v[76:77], v[234:235] op_sel_hi:[0,1,1] neg_lo:[1,0,0] neg_hi:[1,0,0]
	v_pk_fma_f32 v[236:237], v[80:81], v[78:79], v[236:237] op_sel_hi:[0,1,1] neg_lo:[1,0,0] neg_hi:[1,0,0]
	ds_read_b128 v[76:79], v1 offset:11952
	s_waitcnt lgkmcnt(2)
	v_fma_f32 v235, -v234, v45, v235
	v_pk_fma_f32 v[236:237], v[234:235], v[46:47], v[236:237] op_sel_hi:[0,1,1] neg_lo:[1,0,0] neg_hi:[1,0,0]
	ds_read_b128 v[32:35], v1 offset:192
	ds_read_b128 v[36:39], v1 offset:208
	ds_read_b128 v[40:43], v1 offset:224
	ds_read_b128 v[44:47], v1 offset:240
	s_waitcnt lgkmcnt(5)
	v_mov_b32_e32 v80, v235
	v_pk_fma_f32 v[236:237], v[80:81], v[62:63], v[236:237] op_sel_hi:[0,1,1] neg_lo:[1,0,0] neg_hi:[1,0,0]
	ds_read_b128 v[48:51], v1 offset:448
	ds_read_b128 v[52:55], v1 offset:464
	ds_read_b128 v[56:59], v1 offset:480
	ds_read_b128 v[60:63], v1 offset:496
	s_waitcnt lgkmcnt(8)
	v_fma_f32 v237, -v236, v79, v237
	ds_read_b128 v[64:67], v1 offset:704
	ds_read_b128 v[68:71], v1 offset:720
	ds_read_b128 v[72:75], v1 offset:736
	ds_read_b128 v[76:79], v1 offset:752
	s_waitcnt lgkmcnt(8)
	v_pk_fma_f32 v[238:239], v[190:191], v[32:33], v[238:239] op_sel_hi:[0,1,1] neg_lo:[1,0,0] neg_hi:[1,0,0]
	v_pk_fma_f32 v[240:241], v[190:191], v[34:35], v[240:241] op_sel_hi:[0,1,1] neg_lo:[1,0,0] neg_hi:[1,0,0]
	v_pk_fma_f32 v[242:243], v[190:191], v[36:37], v[242:243] op_sel_hi:[0,1,1] neg_lo:[1,0,0] neg_hi:[1,0,0]
	v_pk_fma_f32 v[248:249], v[190:191], v[38:39], v[248:249] op_sel_hi:[0,1,1] neg_lo:[1,0,0] neg_hi:[1,0,0]
	v_pk_fma_f32 v[250:251], v[190:191], v[40:41], v[250:251] op_sel_hi:[0,1,1] neg_lo:[1,0,0] neg_hi:[1,0,0]
	v_pk_fma_f32 v[252:253], v[190:191], v[42:43], v[252:253] op_sel_hi:[0,1,1] neg_lo:[1,0,0] neg_hi:[1,0,0]
	v_pk_fma_f32 v[254:255], v[190:191], v[44:45], v[254:255] op_sel_hi:[0,1,1] neg_lo:[1,0,0] neg_hi:[1,0,0]
	v_pk_fma_f32 v[106:107], v[190:191], v[46:47], v[106:107] op_sel_hi:[0,1,1] neg_lo:[1,0,0] neg_hi:[1,0,0]
	ds_read_b128 v[32:35], v1 offset:960
	ds_read_b128 v[36:39], v1 offset:976
	ds_read_b128 v[40:43], v1 offset:992
	ds_read_b128 v[44:47], v1 offset:1008
	s_waitcnt lgkmcnt(8)
	v_mov_b32_e32 v80, v191
	v_pk_fma_f32 v[238:239], v[80:81], v[48:49], v[238:239] op_sel_hi:[0,1,1] neg_lo:[1,0,0] neg_hi:[1,0,0]
	v_pk_fma_f32 v[240:241], v[80:81], v[50:51], v[240:241] op_sel_hi:[0,1,1] neg_lo:[1,0,0] neg_hi:[1,0,0]
	v_pk_fma_f32 v[242:243], v[80:81], v[52:53], v[242:243] op_sel_hi:[0,1,1] neg_lo:[1,0,0] neg_hi:[1,0,0]
	v_pk_fma_f32 v[248:249], v[80:81], v[54:55], v[248:249] op_sel_hi:[0,1,1] neg_lo:[1,0,0] neg_hi:[1,0,0]
	v_pk_fma_f32 v[250:251], v[80:81], v[56:57], v[250:251] op_sel_hi:[0,1,1] neg_lo:[1,0,0] neg_hi:[1,0,0]
	v_pk_fma_f32 v[252:253], v[80:81], v[58:59], v[252:253] op_sel_hi:[0,1,1] neg_lo:[1,0,0] neg_hi:[1,0,0]
	v_pk_fma_f32 v[254:255], v[80:81], v[60:61], v[254:255] op_sel_hi:[0,1,1] neg_lo:[1,0,0] neg_hi:[1,0,0]
	v_pk_fma_f32 v[106:107], v[80:81], v[62:63], v[106:107] op_sel_hi:[0,1,1] neg_lo:[1,0,0] neg_hi:[1,0,0]
	ds_read_b128 v[48:51], v1 offset:1216
	ds_read_b128 v[52:55], v1 offset:1232
	ds_read_b128 v[56:59], v1 offset:1248
	ds_read_b128 v[60:63], v1 offset:1264
	s_waitcnt lgkmcnt(8)
	v_pk_fma_f32 v[238:239], v[192:193], v[64:65], v[238:239] op_sel_hi:[0,1,1] neg_lo:[1,0,0] neg_hi:[1,0,0]
	v_pk_fma_f32 v[240:241], v[192:193], v[66:67], v[240:241] op_sel_hi:[0,1,1] neg_lo:[1,0,0] neg_hi:[1,0,0]
	v_pk_fma_f32 v[242:243], v[192:193], v[68:69], v[242:243] op_sel_hi:[0,1,1] neg_lo:[1,0,0] neg_hi:[1,0,0]
	v_pk_fma_f32 v[248:249], v[192:193], v[70:71], v[248:249] op_sel_hi:[0,1,1] neg_lo:[1,0,0] neg_hi:[1,0,0]
	v_pk_fma_f32 v[250:251], v[192:193], v[72:73], v[250:251] op_sel_hi:[0,1,1] neg_lo:[1,0,0] neg_hi:[1,0,0]
	v_pk_fma_f32 v[252:253], v[192:193], v[74:75], v[252:253] op_sel_hi:[0,1,1] neg_lo:[1,0,0] neg_hi:[1,0,0]
	v_pk_fma_f32 v[254:255], v[192:193], v[76:77], v[254:255] op_sel_hi:[0,1,1] neg_lo:[1,0,0] neg_hi:[1,0,0]
	v_pk_fma_f32 v[106:107], v[192:193], v[78:79], v[106:107] op_sel_hi:[0,1,1] neg_lo:[1,0,0] neg_hi:[1,0,0]
	ds_read_b128 v[64:67], v1 offset:1472
	ds_read_b128 v[68:71], v1 offset:1488
	ds_read_b128 v[72:75], v1 offset:1504
	ds_read_b128 v[76:79], v1 offset:1520
	s_waitcnt lgkmcnt(8)
	v_mov_b32_e32 v80, v193
	v_pk_fma_f32 v[238:239], v[80:81], v[32:33], v[238:239] op_sel_hi:[0,1,1] neg_lo:[1,0,0] neg_hi:[1,0,0]
	v_pk_fma_f32 v[240:241], v[80:81], v[34:35], v[240:241] op_sel_hi:[0,1,1] neg_lo:[1,0,0] neg_hi:[1,0,0]
	v_pk_fma_f32 v[242:243], v[80:81], v[36:37], v[242:243] op_sel_hi:[0,1,1] neg_lo:[1,0,0] neg_hi:[1,0,0]
	v_pk_fma_f32 v[248:249], v[80:81], v[38:39], v[248:249] op_sel_hi:[0,1,1] neg_lo:[1,0,0] neg_hi:[1,0,0]
	v_pk_fma_f32 v[250:251], v[80:81], v[40:41], v[250:251] op_sel_hi:[0,1,1] neg_lo:[1,0,0] neg_hi:[1,0,0]
	v_pk_fma_f32 v[252:253], v[80:81], v[42:43], v[252:253] op_sel_hi:[0,1,1] neg_lo:[1,0,0] neg_hi:[1,0,0]
	v_pk_fma_f32 v[254:255], v[80:81], v[44:45], v[254:255] op_sel_hi:[0,1,1] neg_lo:[1,0,0] neg_hi:[1,0,0]
	v_pk_fma_f32 v[106:107], v[80:81], v[46:47], v[106:107] op_sel_hi:[0,1,1] neg_lo:[1,0,0] neg_hi:[1,0,0]
	ds_read_b128 v[32:35], v1 offset:1728
	ds_read_b128 v[36:39], v1 offset:1744
	ds_read_b128 v[40:43], v1 offset:1760
	ds_read_b128 v[44:47], v1 offset:1776
	s_waitcnt lgkmcnt(8)
	v_pk_fma_f32 v[238:239], v[194:195], v[48:49], v[238:239] op_sel_hi:[0,1,1] neg_lo:[1,0,0] neg_hi:[1,0,0]
	v_pk_fma_f32 v[240:241], v[194:195], v[50:51], v[240:241] op_sel_hi:[0,1,1] neg_lo:[1,0,0] neg_hi:[1,0,0]
	v_pk_fma_f32 v[242:243], v[194:195], v[52:53], v[242:243] op_sel_hi:[0,1,1] neg_lo:[1,0,0] neg_hi:[1,0,0]
	v_pk_fma_f32 v[248:249], v[194:195], v[54:55], v[248:249] op_sel_hi:[0,1,1] neg_lo:[1,0,0] neg_hi:[1,0,0]
	v_pk_fma_f32 v[250:251], v[194:195], v[56:57], v[250:251] op_sel_hi:[0,1,1] neg_lo:[1,0,0] neg_hi:[1,0,0]
	v_pk_fma_f32 v[252:253], v[194:195], v[58:59], v[252:253] op_sel_hi:[0,1,1] neg_lo:[1,0,0] neg_hi:[1,0,0]
	v_pk_fma_f32 v[254:255], v[194:195], v[60:61], v[254:255] op_sel_hi:[0,1,1] neg_lo:[1,0,0] neg_hi:[1,0,0]
	v_pk_fma_f32 v[106:107], v[194:195], v[62:63], v[106:107] op_sel_hi:[0,1,1] neg_lo:[1,0,0] neg_hi:[1,0,0]
	ds_read_b128 v[48:51], v1 offset:1984
	ds_read_b128 v[52:55], v1 offset:2000
	ds_read_b128 v[56:59], v1 offset:2016
	ds_read_b128 v[60:63], v1 offset:2032
	s_waitcnt lgkmcnt(8)
	v_mov_b32_e32 v80, v195
	v_pk_fma_f32 v[238:239], v[80:81], v[64:65], v[238:239] op_sel_hi:[0,1,1] neg_lo:[1,0,0] neg_hi:[1,0,0]
	v_pk_fma_f32 v[240:241], v[80:81], v[66:67], v[240:241] op_sel_hi:[0,1,1] neg_lo:[1,0,0] neg_hi:[1,0,0]
	v_pk_fma_f32 v[242:243], v[80:81], v[68:69], v[242:243] op_sel_hi:[0,1,1] neg_lo:[1,0,0] neg_hi:[1,0,0]
	v_pk_fma_f32 v[248:249], v[80:81], v[70:71], v[248:249] op_sel_hi:[0,1,1] neg_lo:[1,0,0] neg_hi:[1,0,0]
	v_pk_fma_f32 v[250:251], v[80:81], v[72:73], v[250:251] op_sel_hi:[0,1,1] neg_lo:[1,0,0] neg_hi:[1,0,0]
	v_pk_fma_f32 v[252:253], v[80:81], v[74:75], v[252:253] op_sel_hi:[0,1,1] neg_lo:[1,0,0] neg_hi:[1,0,0]
	v_pk_fma_f32 v[254:255], v[80:81], v[76:77], v[254:255] op_sel_hi:[0,1,1] neg_lo:[1,0,0] neg_hi:[1,0,0]
	v_pk_fma_f32 v[106:107], v[80:81], v[78:79], v[106:107] op_sel_hi:[0,1,1] neg_lo:[1,0,0] neg_hi:[1,0,0]
	ds_read_b128 v[64:67], v1 offset:2240
	ds_read_b128 v[68:71], v1 offset:2256
	ds_read_b128 v[72:75], v1 offset:2272
	ds_read_b128 v[76:79], v1 offset:2288
	s_waitcnt lgkmcnt(8)
	v_pk_fma_f32 v[238:239], v[196:197], v[32:33], v[238:239] op_sel_hi:[0,1,1] neg_lo:[1,0,0] neg_hi:[1,0,0]
	v_pk_fma_f32 v[240:241], v[196:197], v[34:35], v[240:241] op_sel_hi:[0,1,1] neg_lo:[1,0,0] neg_hi:[1,0,0]
	v_pk_fma_f32 v[242:243], v[196:197], v[36:37], v[242:243] op_sel_hi:[0,1,1] neg_lo:[1,0,0] neg_hi:[1,0,0]
	v_pk_fma_f32 v[248:249], v[196:197], v[38:39], v[248:249] op_sel_hi:[0,1,1] neg_lo:[1,0,0] neg_hi:[1,0,0]
	v_pk_fma_f32 v[250:251], v[196:197], v[40:41], v[250:251] op_sel_hi:[0,1,1] neg_lo:[1,0,0] neg_hi:[1,0,0]
	v_pk_fma_f32 v[252:253], v[196:197], v[42:43], v[252:253] op_sel_hi:[0,1,1] neg_lo:[1,0,0] neg_hi:[1,0,0]
	v_pk_fma_f32 v[254:255], v[196:197], v[44:45], v[254:255] op_sel_hi:[0,1,1] neg_lo:[1,0,0] neg_hi:[1,0,0]
	v_pk_fma_f32 v[106:107], v[196:197], v[46:47], v[106:107] op_sel_hi:[0,1,1] neg_lo:[1,0,0] neg_hi:[1,0,0]
	ds_read_b128 v[32:35], v1 offset:2496
	ds_read_b128 v[36:39], v1 offset:2512
	ds_read_b128 v[40:43], v1 offset:2528
	ds_read_b128 v[44:47], v1 offset:2544
	s_waitcnt lgkmcnt(8)
	v_mov_b32_e32 v80, v197
	v_pk_fma_f32 v[238:239], v[80:81], v[48:49], v[238:239] op_sel_hi:[0,1,1] neg_lo:[1,0,0] neg_hi:[1,0,0]
	v_pk_fma_f32 v[240:241], v[80:81], v[50:51], v[240:241] op_sel_hi:[0,1,1] neg_lo:[1,0,0] neg_hi:[1,0,0]
	v_pk_fma_f32 v[242:243], v[80:81], v[52:53], v[242:243] op_sel_hi:[0,1,1] neg_lo:[1,0,0] neg_hi:[1,0,0]
	v_pk_fma_f32 v[248:249], v[80:81], v[54:55], v[248:249] op_sel_hi:[0,1,1] neg_lo:[1,0,0] neg_hi:[1,0,0]
	v_pk_fma_f32 v[250:251], v[80:81], v[56:57], v[250:251] op_sel_hi:[0,1,1] neg_lo:[1,0,0] neg_hi:[1,0,0]
	v_pk_fma_f32 v[252:253], v[80:81], v[58:59], v[252:253] op_sel_hi:[0,1,1] neg_lo:[1,0,0] neg_hi:[1,0,0]
	v_pk_fma_f32 v[254:255], v[80:81], v[60:61], v[254:255] op_sel_hi:[0,1,1] neg_lo:[1,0,0] neg_hi:[1,0,0]
	v_pk_fma_f32 v[106:107], v[80:81], v[62:63], v[106:107] op_sel_hi:[0,1,1] neg_lo:[1,0,0] neg_hi:[1,0,0]
	ds_read_b128 v[48:51], v1 offset:2752
	ds_read_b128 v[52:55], v1 offset:2768
	ds_read_b128 v[56:59], v1 offset:2784
	ds_read_b128 v[60:63], v1 offset:2800
	s_waitcnt lgkmcnt(8)
	v_pk_fma_f32 v[238:239], v[198:199], v[64:65], v[238:239] op_sel_hi:[0,1,1] neg_lo:[1,0,0] neg_hi:[1,0,0]
	v_pk_fma_f32 v[240:241], v[198:199], v[66:67], v[240:241] op_sel_hi:[0,1,1] neg_lo:[1,0,0] neg_hi:[1,0,0]
	v_pk_fma_f32 v[242:243], v[198:199], v[68:69], v[242:243] op_sel_hi:[0,1,1] neg_lo:[1,0,0] neg_hi:[1,0,0]
	v_pk_fma_f32 v[248:249], v[198:199], v[70:71], v[248:249] op_sel_hi:[0,1,1] neg_lo:[1,0,0] neg_hi:[1,0,0]
	v_pk_fma_f32 v[250:251], v[198:199], v[72:73], v[250:251] op_sel_hi:[0,1,1] neg_lo:[1,0,0] neg_hi:[1,0,0]
	v_pk_fma_f32 v[252:253], v[198:199], v[74:75], v[252:253] op_sel_hi:[0,1,1] neg_lo:[1,0,0] neg_hi:[1,0,0]
	v_pk_fma_f32 v[254:255], v[198:199], v[76:77], v[254:255] op_sel_hi:[0,1,1] neg_lo:[1,0,0] neg_hi:[1,0,0]
	v_pk_fma_f32 v[106:107], v[198:199], v[78:79], v[106:107] op_sel_hi:[0,1,1] neg_lo:[1,0,0] neg_hi:[1,0,0]
	ds_read_b128 v[64:67], v1 offset:3008
	ds_read_b128 v[68:71], v1 offset:3024
	ds_read_b128 v[72:75], v1 offset:3040
	ds_read_b128 v[76:79], v1 offset:3056
	s_waitcnt lgkmcnt(8)
	v_mov_b32_e32 v80, v199
	v_pk_fma_f32 v[238:239], v[80:81], v[32:33], v[238:239] op_sel_hi:[0,1,1] neg_lo:[1,0,0] neg_hi:[1,0,0]
	v_pk_fma_f32 v[240:241], v[80:81], v[34:35], v[240:241] op_sel_hi:[0,1,1] neg_lo:[1,0,0] neg_hi:[1,0,0]
	v_pk_fma_f32 v[242:243], v[80:81], v[36:37], v[242:243] op_sel_hi:[0,1,1] neg_lo:[1,0,0] neg_hi:[1,0,0]
	v_pk_fma_f32 v[248:249], v[80:81], v[38:39], v[248:249] op_sel_hi:[0,1,1] neg_lo:[1,0,0] neg_hi:[1,0,0]
	v_pk_fma_f32 v[250:251], v[80:81], v[40:41], v[250:251] op_sel_hi:[0,1,1] neg_lo:[1,0,0] neg_hi:[1,0,0]
	v_pk_fma_f32 v[252:253], v[80:81], v[42:43], v[252:253] op_sel_hi:[0,1,1] neg_lo:[1,0,0] neg_hi:[1,0,0]
	v_pk_fma_f32 v[254:255], v[80:81], v[44:45], v[254:255] op_sel_hi:[0,1,1] neg_lo:[1,0,0] neg_hi:[1,0,0]
	v_pk_fma_f32 v[106:107], v[80:81], v[46:47], v[106:107] op_sel_hi:[0,1,1] neg_lo:[1,0,0] neg_hi:[1,0,0]
	ds_read_b128 v[32:35], v1 offset:3264
	ds_read_b128 v[36:39], v1 offset:3280
	ds_read_b128 v[40:43], v1 offset:3296
	ds_read_b128 v[44:47], v1 offset:3312
	s_waitcnt lgkmcnt(8)
	v_pk_fma_f32 v[238:239], v[200:201], v[48:49], v[238:239] op_sel_hi:[0,1,1] neg_lo:[1,0,0] neg_hi:[1,0,0]
	v_pk_fma_f32 v[240:241], v[200:201], v[50:51], v[240:241] op_sel_hi:[0,1,1] neg_lo:[1,0,0] neg_hi:[1,0,0]
	v_pk_fma_f32 v[242:243], v[200:201], v[52:53], v[242:243] op_sel_hi:[0,1,1] neg_lo:[1,0,0] neg_hi:[1,0,0]
	v_pk_fma_f32 v[248:249], v[200:201], v[54:55], v[248:249] op_sel_hi:[0,1,1] neg_lo:[1,0,0] neg_hi:[1,0,0]
	v_pk_fma_f32 v[250:251], v[200:201], v[56:57], v[250:251] op_sel_hi:[0,1,1] neg_lo:[1,0,0] neg_hi:[1,0,0]
	v_pk_fma_f32 v[252:253], v[200:201], v[58:59], v[252:253] op_sel_hi:[0,1,1] neg_lo:[1,0,0] neg_hi:[1,0,0]
	v_pk_fma_f32 v[254:255], v[200:201], v[60:61], v[254:255] op_sel_hi:[0,1,1] neg_lo:[1,0,0] neg_hi:[1,0,0]
	v_pk_fma_f32 v[106:107], v[200:201], v[62:63], v[106:107] op_sel_hi:[0,1,1] neg_lo:[1,0,0] neg_hi:[1,0,0]
	ds_read_b128 v[48:51], v1 offset:3520
	ds_read_b128 v[52:55], v1 offset:3536
	ds_read_b128 v[56:59], v1 offset:3552
	ds_read_b128 v[60:63], v1 offset:3568
	s_waitcnt lgkmcnt(8)
	v_mov_b32_e32 v80, v201
	v_pk_fma_f32 v[238:239], v[80:81], v[64:65], v[238:239] op_sel_hi:[0,1,1] neg_lo:[1,0,0] neg_hi:[1,0,0]
	v_pk_fma_f32 v[240:241], v[80:81], v[66:67], v[240:241] op_sel_hi:[0,1,1] neg_lo:[1,0,0] neg_hi:[1,0,0]
	v_pk_fma_f32 v[242:243], v[80:81], v[68:69], v[242:243] op_sel_hi:[0,1,1] neg_lo:[1,0,0] neg_hi:[1,0,0]
	v_pk_fma_f32 v[248:249], v[80:81], v[70:71], v[248:249] op_sel_hi:[0,1,1] neg_lo:[1,0,0] neg_hi:[1,0,0]
	v_pk_fma_f32 v[250:251], v[80:81], v[72:73], v[250:251] op_sel_hi:[0,1,1] neg_lo:[1,0,0] neg_hi:[1,0,0]
	v_pk_fma_f32 v[252:253], v[80:81], v[74:75], v[252:253] op_sel_hi:[0,1,1] neg_lo:[1,0,0] neg_hi:[1,0,0]
	v_pk_fma_f32 v[254:255], v[80:81], v[76:77], v[254:255] op_sel_hi:[0,1,1] neg_lo:[1,0,0] neg_hi:[1,0,0]
	v_pk_fma_f32 v[106:107], v[80:81], v[78:79], v[106:107] op_sel_hi:[0,1,1] neg_lo:[1,0,0] neg_hi:[1,0,0]
	ds_read_b128 v[64:67], v1 offset:3776
	ds_read_b128 v[68:71], v1 offset:3792
	ds_read_b128 v[72:75], v1 offset:3808
	ds_read_b128 v[76:79], v1 offset:3824
	s_waitcnt lgkmcnt(8)
	v_pk_fma_f32 v[238:239], v[202:203], v[32:33], v[238:239] op_sel_hi:[0,1,1] neg_lo:[1,0,0] neg_hi:[1,0,0]
	v_pk_fma_f32 v[240:241], v[202:203], v[34:35], v[240:241] op_sel_hi:[0,1,1] neg_lo:[1,0,0] neg_hi:[1,0,0]
	v_pk_fma_f32 v[242:243], v[202:203], v[36:37], v[242:243] op_sel_hi:[0,1,1] neg_lo:[1,0,0] neg_hi:[1,0,0]
	v_pk_fma_f32 v[248:249], v[202:203], v[38:39], v[248:249] op_sel_hi:[0,1,1] neg_lo:[1,0,0] neg_hi:[1,0,0]
	v_pk_fma_f32 v[250:251], v[202:203], v[40:41], v[250:251] op_sel_hi:[0,1,1] neg_lo:[1,0,0] neg_hi:[1,0,0]
	v_pk_fma_f32 v[252:253], v[202:203], v[42:43], v[252:253] op_sel_hi:[0,1,1] neg_lo:[1,0,0] neg_hi:[1,0,0]
	v_pk_fma_f32 v[254:255], v[202:203], v[44:45], v[254:255] op_sel_hi:[0,1,1] neg_lo:[1,0,0] neg_hi:[1,0,0]
	v_pk_fma_f32 v[106:107], v[202:203], v[46:47], v[106:107] op_sel_hi:[0,1,1] neg_lo:[1,0,0] neg_hi:[1,0,0]
	ds_read_b128 v[32:35], v1 offset:4032
	ds_read_b128 v[36:39], v1 offset:4048
	ds_read_b128 v[40:43], v1 offset:4064
	ds_read_b128 v[44:47], v1 offset:4080
	s_waitcnt lgkmcnt(8)
	v_mov_b32_e32 v80, v203
	v_pk_fma_f32 v[238:239], v[80:81], v[48:49], v[238:239] op_sel_hi:[0,1,1] neg_lo:[1,0,0] neg_hi:[1,0,0]
	v_pk_fma_f32 v[240:241], v[80:81], v[50:51], v[240:241] op_sel_hi:[0,1,1] neg_lo:[1,0,0] neg_hi:[1,0,0]
	v_pk_fma_f32 v[242:243], v[80:81], v[52:53], v[242:243] op_sel_hi:[0,1,1] neg_lo:[1,0,0] neg_hi:[1,0,0]
	v_pk_fma_f32 v[248:249], v[80:81], v[54:55], v[248:249] op_sel_hi:[0,1,1] neg_lo:[1,0,0] neg_hi:[1,0,0]
	v_pk_fma_f32 v[250:251], v[80:81], v[56:57], v[250:251] op_sel_hi:[0,1,1] neg_lo:[1,0,0] neg_hi:[1,0,0]
	v_pk_fma_f32 v[252:253], v[80:81], v[58:59], v[252:253] op_sel_hi:[0,1,1] neg_lo:[1,0,0] neg_hi:[1,0,0]
	v_pk_fma_f32 v[254:255], v[80:81], v[60:61], v[254:255] op_sel_hi:[0,1,1] neg_lo:[1,0,0] neg_hi:[1,0,0]
	v_pk_fma_f32 v[106:107], v[80:81], v[62:63], v[106:107] op_sel_hi:[0,1,1] neg_lo:[1,0,0] neg_hi:[1,0,0]
	ds_read_b128 v[48:51], v1 offset:4288
	ds_read_b128 v[52:55], v1 offset:4304
	ds_read_b128 v[56:59], v1 offset:4320
	ds_read_b128 v[60:63], v1 offset:4336
	s_waitcnt lgkmcnt(8)
	v_pk_fma_f32 v[238:239], v[204:205], v[64:65], v[238:239] op_sel_hi:[0,1,1] neg_lo:[1,0,0] neg_hi:[1,0,0]
	v_pk_fma_f32 v[240:241], v[204:205], v[66:67], v[240:241] op_sel_hi:[0,1,1] neg_lo:[1,0,0] neg_hi:[1,0,0]
	v_pk_fma_f32 v[242:243], v[204:205], v[68:69], v[242:243] op_sel_hi:[0,1,1] neg_lo:[1,0,0] neg_hi:[1,0,0]
	v_pk_fma_f32 v[248:249], v[204:205], v[70:71], v[248:249] op_sel_hi:[0,1,1] neg_lo:[1,0,0] neg_hi:[1,0,0]
	v_pk_fma_f32 v[250:251], v[204:205], v[72:73], v[250:251] op_sel_hi:[0,1,1] neg_lo:[1,0,0] neg_hi:[1,0,0]
	v_pk_fma_f32 v[252:253], v[204:205], v[74:75], v[252:253] op_sel_hi:[0,1,1] neg_lo:[1,0,0] neg_hi:[1,0,0]
	v_pk_fma_f32 v[254:255], v[204:205], v[76:77], v[254:255] op_sel_hi:[0,1,1] neg_lo:[1,0,0] neg_hi:[1,0,0]
	v_pk_fma_f32 v[106:107], v[204:205], v[78:79], v[106:107] op_sel_hi:[0,1,1] neg_lo:[1,0,0] neg_hi:[1,0,0]
	ds_read_b128 v[64:67], v1 offset:4544
	ds_read_b128 v[68:71], v1 offset:4560
	ds_read_b128 v[72:75], v1 offset:4576
	ds_read_b128 v[76:79], v1 offset:4592
	s_waitcnt lgkmcnt(8)
	v_mov_b32_e32 v80, v205
	v_pk_fma_f32 v[238:239], v[80:81], v[32:33], v[238:239] op_sel_hi:[0,1,1] neg_lo:[1,0,0] neg_hi:[1,0,0]
	v_pk_fma_f32 v[240:241], v[80:81], v[34:35], v[240:241] op_sel_hi:[0,1,1] neg_lo:[1,0,0] neg_hi:[1,0,0]
	v_pk_fma_f32 v[242:243], v[80:81], v[36:37], v[242:243] op_sel_hi:[0,1,1] neg_lo:[1,0,0] neg_hi:[1,0,0]
	v_pk_fma_f32 v[248:249], v[80:81], v[38:39], v[248:249] op_sel_hi:[0,1,1] neg_lo:[1,0,0] neg_hi:[1,0,0]
	v_pk_fma_f32 v[250:251], v[80:81], v[40:41], v[250:251] op_sel_hi:[0,1,1] neg_lo:[1,0,0] neg_hi:[1,0,0]
	v_pk_fma_f32 v[252:253], v[80:81], v[42:43], v[252:253] op_sel_hi:[0,1,1] neg_lo:[1,0,0] neg_hi:[1,0,0]
	v_pk_fma_f32 v[254:255], v[80:81], v[44:45], v[254:255] op_sel_hi:[0,1,1] neg_lo:[1,0,0] neg_hi:[1,0,0]
	v_pk_fma_f32 v[106:107], v[80:81], v[46:47], v[106:107] op_sel_hi:[0,1,1] neg_lo:[1,0,0] neg_hi:[1,0,0]
	ds_read_b128 v[32:35], v1 offset:4800
	ds_read_b128 v[36:39], v1 offset:4816
	ds_read_b128 v[40:43], v1 offset:4832
	ds_read_b128 v[44:47], v1 offset:4848
	s_waitcnt lgkmcnt(8)
	v_pk_fma_f32 v[238:239], v[206:207], v[48:49], v[238:239] op_sel_hi:[0,1,1] neg_lo:[1,0,0] neg_hi:[1,0,0]
	v_pk_fma_f32 v[240:241], v[206:207], v[50:51], v[240:241] op_sel_hi:[0,1,1] neg_lo:[1,0,0] neg_hi:[1,0,0]
	v_pk_fma_f32 v[242:243], v[206:207], v[52:53], v[242:243] op_sel_hi:[0,1,1] neg_lo:[1,0,0] neg_hi:[1,0,0]
	v_pk_fma_f32 v[248:249], v[206:207], v[54:55], v[248:249] op_sel_hi:[0,1,1] neg_lo:[1,0,0] neg_hi:[1,0,0]
	v_pk_fma_f32 v[250:251], v[206:207], v[56:57], v[250:251] op_sel_hi:[0,1,1] neg_lo:[1,0,0] neg_hi:[1,0,0]
	v_pk_fma_f32 v[252:253], v[206:207], v[58:59], v[252:253] op_sel_hi:[0,1,1] neg_lo:[1,0,0] neg_hi:[1,0,0]
	v_pk_fma_f32 v[254:255], v[206:207], v[60:61], v[254:255] op_sel_hi:[0,1,1] neg_lo:[1,0,0] neg_hi:[1,0,0]
	v_pk_fma_f32 v[106:107], v[206:207], v[62:63], v[106:107] op_sel_hi:[0,1,1] neg_lo:[1,0,0] neg_hi:[1,0,0]
	ds_read_b128 v[48:51], v1 offset:5056
	ds_read_b128 v[52:55], v1 offset:5072
	ds_read_b128 v[56:59], v1 offset:5088
	ds_read_b128 v[60:63], v1 offset:5104
	s_waitcnt lgkmcnt(8)
	v_mov_b32_e32 v80, v207
	v_pk_fma_f32 v[238:239], v[80:81], v[64:65], v[238:239] op_sel_hi:[0,1,1] neg_lo:[1,0,0] neg_hi:[1,0,0]
	v_pk_fma_f32 v[240:241], v[80:81], v[66:67], v[240:241] op_sel_hi:[0,1,1] neg_lo:[1,0,0] neg_hi:[1,0,0]
	v_pk_fma_f32 v[242:243], v[80:81], v[68:69], v[242:243] op_sel_hi:[0,1,1] neg_lo:[1,0,0] neg_hi:[1,0,0]
	v_pk_fma_f32 v[248:249], v[80:81], v[70:71], v[248:249] op_sel_hi:[0,1,1] neg_lo:[1,0,0] neg_hi:[1,0,0]
	v_pk_fma_f32 v[250:251], v[80:81], v[72:73], v[250:251] op_sel_hi:[0,1,1] neg_lo:[1,0,0] neg_hi:[1,0,0]
	v_pk_fma_f32 v[252:253], v[80:81], v[74:75], v[252:253] op_sel_hi:[0,1,1] neg_lo:[1,0,0] neg_hi:[1,0,0]
	v_pk_fma_f32 v[254:255], v[80:81], v[76:77], v[254:255] op_sel_hi:[0,1,1] neg_lo:[1,0,0] neg_hi:[1,0,0]
	v_pk_fma_f32 v[106:107], v[80:81], v[78:79], v[106:107] op_sel_hi:[0,1,1] neg_lo:[1,0,0] neg_hi:[1,0,0]
	ds_read_b128 v[64:67], v1 offset:5312
	ds_read_b128 v[68:71], v1 offset:5328
	ds_read_b128 v[72:75], v1 offset:5344
	ds_read_b128 v[76:79], v1 offset:5360
	s_waitcnt lgkmcnt(8)
	v_pk_fma_f32 v[238:239], v[208:209], v[32:33], v[238:239] op_sel_hi:[0,1,1] neg_lo:[1,0,0] neg_hi:[1,0,0]
	v_pk_fma_f32 v[240:241], v[208:209], v[34:35], v[240:241] op_sel_hi:[0,1,1] neg_lo:[1,0,0] neg_hi:[1,0,0]
	v_pk_fma_f32 v[242:243], v[208:209], v[36:37], v[242:243] op_sel_hi:[0,1,1] neg_lo:[1,0,0] neg_hi:[1,0,0]
	v_pk_fma_f32 v[248:249], v[208:209], v[38:39], v[248:249] op_sel_hi:[0,1,1] neg_lo:[1,0,0] neg_hi:[1,0,0]
	v_pk_fma_f32 v[250:251], v[208:209], v[40:41], v[250:251] op_sel_hi:[0,1,1] neg_lo:[1,0,0] neg_hi:[1,0,0]
	v_pk_fma_f32 v[252:253], v[208:209], v[42:43], v[252:253] op_sel_hi:[0,1,1] neg_lo:[1,0,0] neg_hi:[1,0,0]
	v_pk_fma_f32 v[254:255], v[208:209], v[44:45], v[254:255] op_sel_hi:[0,1,1] neg_lo:[1,0,0] neg_hi:[1,0,0]
	v_pk_fma_f32 v[106:107], v[208:209], v[46:47], v[106:107] op_sel_hi:[0,1,1] neg_lo:[1,0,0] neg_hi:[1,0,0]
	ds_read_b128 v[32:35], v1 offset:5568
	ds_read_b128 v[36:39], v1 offset:5584
	ds_read_b128 v[40:43], v1 offset:5600
	ds_read_b128 v[44:47], v1 offset:5616
	s_waitcnt lgkmcnt(8)
	v_mov_b32_e32 v80, v209
	v_pk_fma_f32 v[238:239], v[80:81], v[48:49], v[238:239] op_sel_hi:[0,1,1] neg_lo:[1,0,0] neg_hi:[1,0,0]
	v_pk_fma_f32 v[240:241], v[80:81], v[50:51], v[240:241] op_sel_hi:[0,1,1] neg_lo:[1,0,0] neg_hi:[1,0,0]
	v_pk_fma_f32 v[242:243], v[80:81], v[52:53], v[242:243] op_sel_hi:[0,1,1] neg_lo:[1,0,0] neg_hi:[1,0,0]
	v_pk_fma_f32 v[248:249], v[80:81], v[54:55], v[248:249] op_sel_hi:[0,1,1] neg_lo:[1,0,0] neg_hi:[1,0,0]
	v_pk_fma_f32 v[250:251], v[80:81], v[56:57], v[250:251] op_sel_hi:[0,1,1] neg_lo:[1,0,0] neg_hi:[1,0,0]
	v_pk_fma_f32 v[252:253], v[80:81], v[58:59], v[252:253] op_sel_hi:[0,1,1] neg_lo:[1,0,0] neg_hi:[1,0,0]
	v_pk_fma_f32 v[254:255], v[80:81], v[60:61], v[254:255] op_sel_hi:[0,1,1] neg_lo:[1,0,0] neg_hi:[1,0,0]
	v_pk_fma_f32 v[106:107], v[80:81], v[62:63], v[106:107] op_sel_hi:[0,1,1] neg_lo:[1,0,0] neg_hi:[1,0,0]
	ds_read_b128 v[48:51], v1 offset:5824
	ds_read_b128 v[52:55], v1 offset:5840
	ds_read_b128 v[56:59], v1 offset:5856
	ds_read_b128 v[60:63], v1 offset:5872
	s_waitcnt lgkmcnt(8)
	v_pk_fma_f32 v[238:239], v[210:211], v[64:65], v[238:239] op_sel_hi:[0,1,1] neg_lo:[1,0,0] neg_hi:[1,0,0]
	v_pk_fma_f32 v[240:241], v[210:211], v[66:67], v[240:241] op_sel_hi:[0,1,1] neg_lo:[1,0,0] neg_hi:[1,0,0]
	v_pk_fma_f32 v[242:243], v[210:211], v[68:69], v[242:243] op_sel_hi:[0,1,1] neg_lo:[1,0,0] neg_hi:[1,0,0]
	v_pk_fma_f32 v[248:249], v[210:211], v[70:71], v[248:249] op_sel_hi:[0,1,1] neg_lo:[1,0,0] neg_hi:[1,0,0]
	v_pk_fma_f32 v[250:251], v[210:211], v[72:73], v[250:251] op_sel_hi:[0,1,1] neg_lo:[1,0,0] neg_hi:[1,0,0]
	v_pk_fma_f32 v[252:253], v[210:211], v[74:75], v[252:253] op_sel_hi:[0,1,1] neg_lo:[1,0,0] neg_hi:[1,0,0]
	v_pk_fma_f32 v[254:255], v[210:211], v[76:77], v[254:255] op_sel_hi:[0,1,1] neg_lo:[1,0,0] neg_hi:[1,0,0]
	v_pk_fma_f32 v[106:107], v[210:211], v[78:79], v[106:107] op_sel_hi:[0,1,1] neg_lo:[1,0,0] neg_hi:[1,0,0]
	ds_read_b128 v[64:67], v1 offset:6080
	ds_read_b128 v[68:71], v1 offset:6096
	ds_read_b128 v[72:75], v1 offset:6112
	ds_read_b128 v[76:79], v1 offset:6128
	s_waitcnt lgkmcnt(8)
	v_mov_b32_e32 v80, v211
	v_pk_fma_f32 v[238:239], v[80:81], v[32:33], v[238:239] op_sel_hi:[0,1,1] neg_lo:[1,0,0] neg_hi:[1,0,0]
	v_pk_fma_f32 v[240:241], v[80:81], v[34:35], v[240:241] op_sel_hi:[0,1,1] neg_lo:[1,0,0] neg_hi:[1,0,0]
	v_pk_fma_f32 v[242:243], v[80:81], v[36:37], v[242:243] op_sel_hi:[0,1,1] neg_lo:[1,0,0] neg_hi:[1,0,0]
	v_pk_fma_f32 v[248:249], v[80:81], v[38:39], v[248:249] op_sel_hi:[0,1,1] neg_lo:[1,0,0] neg_hi:[1,0,0]
	v_pk_fma_f32 v[250:251], v[80:81], v[40:41], v[250:251] op_sel_hi:[0,1,1] neg_lo:[1,0,0] neg_hi:[1,0,0]
	v_pk_fma_f32 v[252:253], v[80:81], v[42:43], v[252:253] op_sel_hi:[0,1,1] neg_lo:[1,0,0] neg_hi:[1,0,0]
	v_pk_fma_f32 v[254:255], v[80:81], v[44:45], v[254:255] op_sel_hi:[0,1,1] neg_lo:[1,0,0] neg_hi:[1,0,0]
	v_pk_fma_f32 v[106:107], v[80:81], v[46:47], v[106:107] op_sel_hi:[0,1,1] neg_lo:[1,0,0] neg_hi:[1,0,0]
	ds_read_b128 v[32:35], v1 offset:6336
	ds_read_b128 v[36:39], v1 offset:6352
	ds_read_b128 v[40:43], v1 offset:6368
	ds_read_b128 v[44:47], v1 offset:6384
	s_waitcnt lgkmcnt(8)
	v_pk_fma_f32 v[238:239], v[212:213], v[48:49], v[238:239] op_sel_hi:[0,1,1] neg_lo:[1,0,0] neg_hi:[1,0,0]
	v_pk_fma_f32 v[240:241], v[212:213], v[50:51], v[240:241] op_sel_hi:[0,1,1] neg_lo:[1,0,0] neg_hi:[1,0,0]
	v_pk_fma_f32 v[242:243], v[212:213], v[52:53], v[242:243] op_sel_hi:[0,1,1] neg_lo:[1,0,0] neg_hi:[1,0,0]
	v_pk_fma_f32 v[248:249], v[212:213], v[54:55], v[248:249] op_sel_hi:[0,1,1] neg_lo:[1,0,0] neg_hi:[1,0,0]
	v_pk_fma_f32 v[250:251], v[212:213], v[56:57], v[250:251] op_sel_hi:[0,1,1] neg_lo:[1,0,0] neg_hi:[1,0,0]
	v_pk_fma_f32 v[252:253], v[212:213], v[58:59], v[252:253] op_sel_hi:[0,1,1] neg_lo:[1,0,0] neg_hi:[1,0,0]
	v_pk_fma_f32 v[254:255], v[212:213], v[60:61], v[254:255] op_sel_hi:[0,1,1] neg_lo:[1,0,0] neg_hi:[1,0,0]
	v_pk_fma_f32 v[106:107], v[212:213], v[62:63], v[106:107] op_sel_hi:[0,1,1] neg_lo:[1,0,0] neg_hi:[1,0,0]
	ds_read_b128 v[48:51], v1 offset:6592
	ds_read_b128 v[52:55], v1 offset:6608
	ds_read_b128 v[56:59], v1 offset:6624
	ds_read_b128 v[60:63], v1 offset:6640
	s_waitcnt lgkmcnt(8)
	v_mov_b32_e32 v80, v213
	v_pk_fma_f32 v[238:239], v[80:81], v[64:65], v[238:239] op_sel_hi:[0,1,1] neg_lo:[1,0,0] neg_hi:[1,0,0]
	v_pk_fma_f32 v[240:241], v[80:81], v[66:67], v[240:241] op_sel_hi:[0,1,1] neg_lo:[1,0,0] neg_hi:[1,0,0]
	v_pk_fma_f32 v[242:243], v[80:81], v[68:69], v[242:243] op_sel_hi:[0,1,1] neg_lo:[1,0,0] neg_hi:[1,0,0]
	v_pk_fma_f32 v[248:249], v[80:81], v[70:71], v[248:249] op_sel_hi:[0,1,1] neg_lo:[1,0,0] neg_hi:[1,0,0]
	v_pk_fma_f32 v[250:251], v[80:81], v[72:73], v[250:251] op_sel_hi:[0,1,1] neg_lo:[1,0,0] neg_hi:[1,0,0]
	v_pk_fma_f32 v[252:253], v[80:81], v[74:75], v[252:253] op_sel_hi:[0,1,1] neg_lo:[1,0,0] neg_hi:[1,0,0]
	v_pk_fma_f32 v[254:255], v[80:81], v[76:77], v[254:255] op_sel_hi:[0,1,1] neg_lo:[1,0,0] neg_hi:[1,0,0]
	v_pk_fma_f32 v[106:107], v[80:81], v[78:79], v[106:107] op_sel_hi:[0,1,1] neg_lo:[1,0,0] neg_hi:[1,0,0]
	ds_read_b128 v[64:67], v1 offset:6848
	ds_read_b128 v[68:71], v1 offset:6864
	ds_read_b128 v[72:75], v1 offset:6880
	ds_read_b128 v[76:79], v1 offset:6896
	s_waitcnt lgkmcnt(8)
	v_pk_fma_f32 v[238:239], v[214:215], v[32:33], v[238:239] op_sel_hi:[0,1,1] neg_lo:[1,0,0] neg_hi:[1,0,0]
	v_pk_fma_f32 v[240:241], v[214:215], v[34:35], v[240:241] op_sel_hi:[0,1,1] neg_lo:[1,0,0] neg_hi:[1,0,0]
	v_pk_fma_f32 v[242:243], v[214:215], v[36:37], v[242:243] op_sel_hi:[0,1,1] neg_lo:[1,0,0] neg_hi:[1,0,0]
	v_pk_fma_f32 v[248:249], v[214:215], v[38:39], v[248:249] op_sel_hi:[0,1,1] neg_lo:[1,0,0] neg_hi:[1,0,0]
	v_pk_fma_f32 v[250:251], v[214:215], v[40:41], v[250:251] op_sel_hi:[0,1,1] neg_lo:[1,0,0] neg_hi:[1,0,0]
	v_pk_fma_f32 v[252:253], v[214:215], v[42:43], v[252:253] op_sel_hi:[0,1,1] neg_lo:[1,0,0] neg_hi:[1,0,0]
	v_pk_fma_f32 v[254:255], v[214:215], v[44:45], v[254:255] op_sel_hi:[0,1,1] neg_lo:[1,0,0] neg_hi:[1,0,0]
	v_pk_fma_f32 v[106:107], v[214:215], v[46:47], v[106:107] op_sel_hi:[0,1,1] neg_lo:[1,0,0] neg_hi:[1,0,0]
	ds_read_b128 v[32:35], v1 offset:7104
	ds_read_b128 v[36:39], v1 offset:7120
	ds_read_b128 v[40:43], v1 offset:7136
	ds_read_b128 v[44:47], v1 offset:7152
	s_waitcnt lgkmcnt(8)
	v_mov_b32_e32 v80, v215
	v_pk_fma_f32 v[238:239], v[80:81], v[48:49], v[238:239] op_sel_hi:[0,1,1] neg_lo:[1,0,0] neg_hi:[1,0,0]
	v_pk_fma_f32 v[240:241], v[80:81], v[50:51], v[240:241] op_sel_hi:[0,1,1] neg_lo:[1,0,0] neg_hi:[1,0,0]
	v_pk_fma_f32 v[242:243], v[80:81], v[52:53], v[242:243] op_sel_hi:[0,1,1] neg_lo:[1,0,0] neg_hi:[1,0,0]
	v_pk_fma_f32 v[248:249], v[80:81], v[54:55], v[248:249] op_sel_hi:[0,1,1] neg_lo:[1,0,0] neg_hi:[1,0,0]
	v_pk_fma_f32 v[250:251], v[80:81], v[56:57], v[250:251] op_sel_hi:[0,1,1] neg_lo:[1,0,0] neg_hi:[1,0,0]
	v_pk_fma_f32 v[252:253], v[80:81], v[58:59], v[252:253] op_sel_hi:[0,1,1] neg_lo:[1,0,0] neg_hi:[1,0,0]
	v_pk_fma_f32 v[254:255], v[80:81], v[60:61], v[254:255] op_sel_hi:[0,1,1] neg_lo:[1,0,0] neg_hi:[1,0,0]
	v_pk_fma_f32 v[106:107], v[80:81], v[62:63], v[106:107] op_sel_hi:[0,1,1] neg_lo:[1,0,0] neg_hi:[1,0,0]
	ds_read_b128 v[48:51], v1 offset:7360
	ds_read_b128 v[52:55], v1 offset:7376
	ds_read_b128 v[56:59], v1 offset:7392
	ds_read_b128 v[60:63], v1 offset:7408
	s_waitcnt lgkmcnt(8)
	v_pk_fma_f32 v[238:239], v[216:217], v[64:65], v[238:239] op_sel_hi:[0,1,1] neg_lo:[1,0,0] neg_hi:[1,0,0]
	v_pk_fma_f32 v[240:241], v[216:217], v[66:67], v[240:241] op_sel_hi:[0,1,1] neg_lo:[1,0,0] neg_hi:[1,0,0]
	v_pk_fma_f32 v[242:243], v[216:217], v[68:69], v[242:243] op_sel_hi:[0,1,1] neg_lo:[1,0,0] neg_hi:[1,0,0]
	v_pk_fma_f32 v[248:249], v[216:217], v[70:71], v[248:249] op_sel_hi:[0,1,1] neg_lo:[1,0,0] neg_hi:[1,0,0]
	v_pk_fma_f32 v[250:251], v[216:217], v[72:73], v[250:251] op_sel_hi:[0,1,1] neg_lo:[1,0,0] neg_hi:[1,0,0]
	v_pk_fma_f32 v[252:253], v[216:217], v[74:75], v[252:253] op_sel_hi:[0,1,1] neg_lo:[1,0,0] neg_hi:[1,0,0]
	v_pk_fma_f32 v[254:255], v[216:217], v[76:77], v[254:255] op_sel_hi:[0,1,1] neg_lo:[1,0,0] neg_hi:[1,0,0]
	v_pk_fma_f32 v[106:107], v[216:217], v[78:79], v[106:107] op_sel_hi:[0,1,1] neg_lo:[1,0,0] neg_hi:[1,0,0]
	ds_read_b128 v[64:67], v1 offset:7616
	ds_read_b128 v[68:71], v1 offset:7632
	ds_read_b128 v[72:75], v1 offset:7648
	ds_read_b128 v[76:79], v1 offset:7664
	s_waitcnt lgkmcnt(8)
	v_mov_b32_e32 v80, v217
	v_pk_fma_f32 v[238:239], v[80:81], v[32:33], v[238:239] op_sel_hi:[0,1,1] neg_lo:[1,0,0] neg_hi:[1,0,0]
	v_pk_fma_f32 v[240:241], v[80:81], v[34:35], v[240:241] op_sel_hi:[0,1,1] neg_lo:[1,0,0] neg_hi:[1,0,0]
	v_pk_fma_f32 v[242:243], v[80:81], v[36:37], v[242:243] op_sel_hi:[0,1,1] neg_lo:[1,0,0] neg_hi:[1,0,0]
	v_pk_fma_f32 v[248:249], v[80:81], v[38:39], v[248:249] op_sel_hi:[0,1,1] neg_lo:[1,0,0] neg_hi:[1,0,0]
	v_pk_fma_f32 v[250:251], v[80:81], v[40:41], v[250:251] op_sel_hi:[0,1,1] neg_lo:[1,0,0] neg_hi:[1,0,0]
	v_pk_fma_f32 v[252:253], v[80:81], v[42:43], v[252:253] op_sel_hi:[0,1,1] neg_lo:[1,0,0] neg_hi:[1,0,0]
	v_pk_fma_f32 v[254:255], v[80:81], v[44:45], v[254:255] op_sel_hi:[0,1,1] neg_lo:[1,0,0] neg_hi:[1,0,0]
	v_pk_fma_f32 v[106:107], v[80:81], v[46:47], v[106:107] op_sel_hi:[0,1,1] neg_lo:[1,0,0] neg_hi:[1,0,0]
	ds_read_b128 v[32:35], v1 offset:7872
	ds_read_b128 v[36:39], v1 offset:7888
	ds_read_b128 v[40:43], v1 offset:7904
	ds_read_b128 v[44:47], v1 offset:7920
	s_waitcnt lgkmcnt(8)
	v_pk_fma_f32 v[238:239], v[218:219], v[48:49], v[238:239] op_sel_hi:[0,1,1] neg_lo:[1,0,0] neg_hi:[1,0,0]
	v_pk_fma_f32 v[240:241], v[218:219], v[50:51], v[240:241] op_sel_hi:[0,1,1] neg_lo:[1,0,0] neg_hi:[1,0,0]
	v_pk_fma_f32 v[242:243], v[218:219], v[52:53], v[242:243] op_sel_hi:[0,1,1] neg_lo:[1,0,0] neg_hi:[1,0,0]
	v_pk_fma_f32 v[248:249], v[218:219], v[54:55], v[248:249] op_sel_hi:[0,1,1] neg_lo:[1,0,0] neg_hi:[1,0,0]
	v_pk_fma_f32 v[250:251], v[218:219], v[56:57], v[250:251] op_sel_hi:[0,1,1] neg_lo:[1,0,0] neg_hi:[1,0,0]
	v_pk_fma_f32 v[252:253], v[218:219], v[58:59], v[252:253] op_sel_hi:[0,1,1] neg_lo:[1,0,0] neg_hi:[1,0,0]
	v_pk_fma_f32 v[254:255], v[218:219], v[60:61], v[254:255] op_sel_hi:[0,1,1] neg_lo:[1,0,0] neg_hi:[1,0,0]
	v_pk_fma_f32 v[106:107], v[218:219], v[62:63], v[106:107] op_sel_hi:[0,1,1] neg_lo:[1,0,0] neg_hi:[1,0,0]
	ds_read_b128 v[48:51], v1 offset:8128
	ds_read_b128 v[52:55], v1 offset:8144
	ds_read_b128 v[56:59], v1 offset:8160
	ds_read_b128 v[60:63], v1 offset:8176
	s_waitcnt lgkmcnt(8)
	v_mov_b32_e32 v80, v219
	v_pk_fma_f32 v[238:239], v[80:81], v[64:65], v[238:239] op_sel_hi:[0,1,1] neg_lo:[1,0,0] neg_hi:[1,0,0]
	v_pk_fma_f32 v[240:241], v[80:81], v[66:67], v[240:241] op_sel_hi:[0,1,1] neg_lo:[1,0,0] neg_hi:[1,0,0]
	v_pk_fma_f32 v[242:243], v[80:81], v[68:69], v[242:243] op_sel_hi:[0,1,1] neg_lo:[1,0,0] neg_hi:[1,0,0]
	v_pk_fma_f32 v[248:249], v[80:81], v[70:71], v[248:249] op_sel_hi:[0,1,1] neg_lo:[1,0,0] neg_hi:[1,0,0]
	v_pk_fma_f32 v[250:251], v[80:81], v[72:73], v[250:251] op_sel_hi:[0,1,1] neg_lo:[1,0,0] neg_hi:[1,0,0]
	v_pk_fma_f32 v[252:253], v[80:81], v[74:75], v[252:253] op_sel_hi:[0,1,1] neg_lo:[1,0,0] neg_hi:[1,0,0]
	v_pk_fma_f32 v[254:255], v[80:81], v[76:77], v[254:255] op_sel_hi:[0,1,1] neg_lo:[1,0,0] neg_hi:[1,0,0]
	v_pk_fma_f32 v[106:107], v[80:81], v[78:79], v[106:107] op_sel_hi:[0,1,1] neg_lo:[1,0,0] neg_hi:[1,0,0]
	ds_read_b128 v[64:67], v1 offset:8384
	ds_read_b128 v[68:71], v1 offset:8400
	ds_read_b128 v[72:75], v1 offset:8416
	ds_read_b128 v[76:79], v1 offset:8432
	s_waitcnt lgkmcnt(8)
	v_pk_fma_f32 v[238:239], v[220:221], v[32:33], v[238:239] op_sel_hi:[0,1,1] neg_lo:[1,0,0] neg_hi:[1,0,0]
	v_pk_fma_f32 v[240:241], v[220:221], v[34:35], v[240:241] op_sel_hi:[0,1,1] neg_lo:[1,0,0] neg_hi:[1,0,0]
	v_pk_fma_f32 v[242:243], v[220:221], v[36:37], v[242:243] op_sel_hi:[0,1,1] neg_lo:[1,0,0] neg_hi:[1,0,0]
	v_pk_fma_f32 v[248:249], v[220:221], v[38:39], v[248:249] op_sel_hi:[0,1,1] neg_lo:[1,0,0] neg_hi:[1,0,0]
	v_pk_fma_f32 v[250:251], v[220:221], v[40:41], v[250:251] op_sel_hi:[0,1,1] neg_lo:[1,0,0] neg_hi:[1,0,0]
	v_pk_fma_f32 v[252:253], v[220:221], v[42:43], v[252:253] op_sel_hi:[0,1,1] neg_lo:[1,0,0] neg_hi:[1,0,0]
	v_pk_fma_f32 v[254:255], v[220:221], v[44:45], v[254:255] op_sel_hi:[0,1,1] neg_lo:[1,0,0] neg_hi:[1,0,0]
	v_pk_fma_f32 v[106:107], v[220:221], v[46:47], v[106:107] op_sel_hi:[0,1,1] neg_lo:[1,0,0] neg_hi:[1,0,0]
	ds_read_b128 v[32:35], v1 offset:8640
	ds_read_b128 v[36:39], v1 offset:8656
	ds_read_b128 v[40:43], v1 offset:8672
	ds_read_b128 v[44:47], v1 offset:8688
	s_waitcnt lgkmcnt(8)
	v_mov_b32_e32 v80, v221
	v_pk_fma_f32 v[238:239], v[80:81], v[48:49], v[238:239] op_sel_hi:[0,1,1] neg_lo:[1,0,0] neg_hi:[1,0,0]
	v_pk_fma_f32 v[240:241], v[80:81], v[50:51], v[240:241] op_sel_hi:[0,1,1] neg_lo:[1,0,0] neg_hi:[1,0,0]
	v_pk_fma_f32 v[242:243], v[80:81], v[52:53], v[242:243] op_sel_hi:[0,1,1] neg_lo:[1,0,0] neg_hi:[1,0,0]
	v_pk_fma_f32 v[248:249], v[80:81], v[54:55], v[248:249] op_sel_hi:[0,1,1] neg_lo:[1,0,0] neg_hi:[1,0,0]
	v_pk_fma_f32 v[250:251], v[80:81], v[56:57], v[250:251] op_sel_hi:[0,1,1] neg_lo:[1,0,0] neg_hi:[1,0,0]
	v_pk_fma_f32 v[252:253], v[80:81], v[58:59], v[252:253] op_sel_hi:[0,1,1] neg_lo:[1,0,0] neg_hi:[1,0,0]
	v_pk_fma_f32 v[254:255], v[80:81], v[60:61], v[254:255] op_sel_hi:[0,1,1] neg_lo:[1,0,0] neg_hi:[1,0,0]
	v_pk_fma_f32 v[106:107], v[80:81], v[62:63], v[106:107] op_sel_hi:[0,1,1] neg_lo:[1,0,0] neg_hi:[1,0,0]
	ds_read_b128 v[48:51], v1 offset:8896
	ds_read_b128 v[52:55], v1 offset:8912
	ds_read_b128 v[56:59], v1 offset:8928
	ds_read_b128 v[60:63], v1 offset:8944
	s_waitcnt lgkmcnt(8)
	v_pk_fma_f32 v[238:239], v[222:223], v[64:65], v[238:239] op_sel_hi:[0,1,1] neg_lo:[1,0,0] neg_hi:[1,0,0]
	v_pk_fma_f32 v[240:241], v[222:223], v[66:67], v[240:241] op_sel_hi:[0,1,1] neg_lo:[1,0,0] neg_hi:[1,0,0]
	v_pk_fma_f32 v[242:243], v[222:223], v[68:69], v[242:243] op_sel_hi:[0,1,1] neg_lo:[1,0,0] neg_hi:[1,0,0]
	v_pk_fma_f32 v[248:249], v[222:223], v[70:71], v[248:249] op_sel_hi:[0,1,1] neg_lo:[1,0,0] neg_hi:[1,0,0]
	v_pk_fma_f32 v[250:251], v[222:223], v[72:73], v[250:251] op_sel_hi:[0,1,1] neg_lo:[1,0,0] neg_hi:[1,0,0]
	v_pk_fma_f32 v[252:253], v[222:223], v[74:75], v[252:253] op_sel_hi:[0,1,1] neg_lo:[1,0,0] neg_hi:[1,0,0]
	v_pk_fma_f32 v[254:255], v[222:223], v[76:77], v[254:255] op_sel_hi:[0,1,1] neg_lo:[1,0,0] neg_hi:[1,0,0]
	v_pk_fma_f32 v[106:107], v[222:223], v[78:79], v[106:107] op_sel_hi:[0,1,1] neg_lo:[1,0,0] neg_hi:[1,0,0]
	ds_read_b128 v[64:67], v1 offset:9152
	ds_read_b128 v[68:71], v1 offset:9168
	ds_read_b128 v[72:75], v1 offset:9184
	ds_read_b128 v[76:79], v1 offset:9200
	s_waitcnt lgkmcnt(8)
	v_mov_b32_e32 v80, v223
	v_pk_fma_f32 v[238:239], v[80:81], v[32:33], v[238:239] op_sel_hi:[0,1,1] neg_lo:[1,0,0] neg_hi:[1,0,0]
	v_pk_fma_f32 v[240:241], v[80:81], v[34:35], v[240:241] op_sel_hi:[0,1,1] neg_lo:[1,0,0] neg_hi:[1,0,0]
	v_pk_fma_f32 v[242:243], v[80:81], v[36:37], v[242:243] op_sel_hi:[0,1,1] neg_lo:[1,0,0] neg_hi:[1,0,0]
	v_pk_fma_f32 v[248:249], v[80:81], v[38:39], v[248:249] op_sel_hi:[0,1,1] neg_lo:[1,0,0] neg_hi:[1,0,0]
	v_pk_fma_f32 v[250:251], v[80:81], v[40:41], v[250:251] op_sel_hi:[0,1,1] neg_lo:[1,0,0] neg_hi:[1,0,0]
	v_pk_fma_f32 v[252:253], v[80:81], v[42:43], v[252:253] op_sel_hi:[0,1,1] neg_lo:[1,0,0] neg_hi:[1,0,0]
	v_pk_fma_f32 v[254:255], v[80:81], v[44:45], v[254:255] op_sel_hi:[0,1,1] neg_lo:[1,0,0] neg_hi:[1,0,0]
	v_pk_fma_f32 v[106:107], v[80:81], v[46:47], v[106:107] op_sel_hi:[0,1,1] neg_lo:[1,0,0] neg_hi:[1,0,0]
	ds_read_b128 v[32:35], v1 offset:9408
	ds_read_b128 v[36:39], v1 offset:9424
	ds_read_b128 v[40:43], v1 offset:9440
	ds_read_b128 v[44:47], v1 offset:9456
	s_waitcnt lgkmcnt(8)
	v_pk_fma_f32 v[238:239], v[224:225], v[48:49], v[238:239] op_sel_hi:[0,1,1] neg_lo:[1,0,0] neg_hi:[1,0,0]
	v_pk_fma_f32 v[240:241], v[224:225], v[50:51], v[240:241] op_sel_hi:[0,1,1] neg_lo:[1,0,0] neg_hi:[1,0,0]
	v_pk_fma_f32 v[242:243], v[224:225], v[52:53], v[242:243] op_sel_hi:[0,1,1] neg_lo:[1,0,0] neg_hi:[1,0,0]
	v_pk_fma_f32 v[248:249], v[224:225], v[54:55], v[248:249] op_sel_hi:[0,1,1] neg_lo:[1,0,0] neg_hi:[1,0,0]
	v_pk_fma_f32 v[250:251], v[224:225], v[56:57], v[250:251] op_sel_hi:[0,1,1] neg_lo:[1,0,0] neg_hi:[1,0,0]
	v_pk_fma_f32 v[252:253], v[224:225], v[58:59], v[252:253] op_sel_hi:[0,1,1] neg_lo:[1,0,0] neg_hi:[1,0,0]
	v_pk_fma_f32 v[254:255], v[224:225], v[60:61], v[254:255] op_sel_hi:[0,1,1] neg_lo:[1,0,0] neg_hi:[1,0,0]
	v_pk_fma_f32 v[106:107], v[224:225], v[62:63], v[106:107] op_sel_hi:[0,1,1] neg_lo:[1,0,0] neg_hi:[1,0,0]
	ds_read_b128 v[48:51], v1 offset:9664
	ds_read_b128 v[52:55], v1 offset:9680
	ds_read_b128 v[56:59], v1 offset:9696
	ds_read_b128 v[60:63], v1 offset:9712
	s_waitcnt lgkmcnt(8)
	v_mov_b32_e32 v80, v225
	v_pk_fma_f32 v[238:239], v[80:81], v[64:65], v[238:239] op_sel_hi:[0,1,1] neg_lo:[1,0,0] neg_hi:[1,0,0]
	v_pk_fma_f32 v[240:241], v[80:81], v[66:67], v[240:241] op_sel_hi:[0,1,1] neg_lo:[1,0,0] neg_hi:[1,0,0]
	v_pk_fma_f32 v[242:243], v[80:81], v[68:69], v[242:243] op_sel_hi:[0,1,1] neg_lo:[1,0,0] neg_hi:[1,0,0]
	v_pk_fma_f32 v[248:249], v[80:81], v[70:71], v[248:249] op_sel_hi:[0,1,1] neg_lo:[1,0,0] neg_hi:[1,0,0]
	v_pk_fma_f32 v[250:251], v[80:81], v[72:73], v[250:251] op_sel_hi:[0,1,1] neg_lo:[1,0,0] neg_hi:[1,0,0]
	v_pk_fma_f32 v[252:253], v[80:81], v[74:75], v[252:253] op_sel_hi:[0,1,1] neg_lo:[1,0,0] neg_hi:[1,0,0]
	v_pk_fma_f32 v[254:255], v[80:81], v[76:77], v[254:255] op_sel_hi:[0,1,1] neg_lo:[1,0,0] neg_hi:[1,0,0]
	v_pk_fma_f32 v[106:107], v[80:81], v[78:79], v[106:107] op_sel_hi:[0,1,1] neg_lo:[1,0,0] neg_hi:[1,0,0]
	ds_read_b128 v[64:67], v1 offset:9920
	ds_read_b128 v[68:71], v1 offset:9936
	ds_read_b128 v[72:75], v1 offset:9952
	ds_read_b128 v[76:79], v1 offset:9968
	s_waitcnt lgkmcnt(8)
	v_pk_fma_f32 v[238:239], v[226:227], v[32:33], v[238:239] op_sel_hi:[0,1,1] neg_lo:[1,0,0] neg_hi:[1,0,0]
	v_pk_fma_f32 v[240:241], v[226:227], v[34:35], v[240:241] op_sel_hi:[0,1,1] neg_lo:[1,0,0] neg_hi:[1,0,0]
	v_pk_fma_f32 v[242:243], v[226:227], v[36:37], v[242:243] op_sel_hi:[0,1,1] neg_lo:[1,0,0] neg_hi:[1,0,0]
	v_pk_fma_f32 v[248:249], v[226:227], v[38:39], v[248:249] op_sel_hi:[0,1,1] neg_lo:[1,0,0] neg_hi:[1,0,0]
	v_pk_fma_f32 v[250:251], v[226:227], v[40:41], v[250:251] op_sel_hi:[0,1,1] neg_lo:[1,0,0] neg_hi:[1,0,0]
	v_pk_fma_f32 v[252:253], v[226:227], v[42:43], v[252:253] op_sel_hi:[0,1,1] neg_lo:[1,0,0] neg_hi:[1,0,0]
	v_pk_fma_f32 v[254:255], v[226:227], v[44:45], v[254:255] op_sel_hi:[0,1,1] neg_lo:[1,0,0] neg_hi:[1,0,0]
	v_pk_fma_f32 v[106:107], v[226:227], v[46:47], v[106:107] op_sel_hi:[0,1,1] neg_lo:[1,0,0] neg_hi:[1,0,0]
	ds_read_b128 v[32:35], v1 offset:10176
	ds_read_b128 v[36:39], v1 offset:10192
	ds_read_b128 v[40:43], v1 offset:10208
	ds_read_b128 v[44:47], v1 offset:10224
	s_waitcnt lgkmcnt(8)
	v_mov_b32_e32 v80, v227
	v_pk_fma_f32 v[238:239], v[80:81], v[48:49], v[238:239] op_sel_hi:[0,1,1] neg_lo:[1,0,0] neg_hi:[1,0,0]
	v_pk_fma_f32 v[240:241], v[80:81], v[50:51], v[240:241] op_sel_hi:[0,1,1] neg_lo:[1,0,0] neg_hi:[1,0,0]
	v_pk_fma_f32 v[242:243], v[80:81], v[52:53], v[242:243] op_sel_hi:[0,1,1] neg_lo:[1,0,0] neg_hi:[1,0,0]
	v_pk_fma_f32 v[248:249], v[80:81], v[54:55], v[248:249] op_sel_hi:[0,1,1] neg_lo:[1,0,0] neg_hi:[1,0,0]
	v_pk_fma_f32 v[250:251], v[80:81], v[56:57], v[250:251] op_sel_hi:[0,1,1] neg_lo:[1,0,0] neg_hi:[1,0,0]
	v_pk_fma_f32 v[252:253], v[80:81], v[58:59], v[252:253] op_sel_hi:[0,1,1] neg_lo:[1,0,0] neg_hi:[1,0,0]
	v_pk_fma_f32 v[254:255], v[80:81], v[60:61], v[254:255] op_sel_hi:[0,1,1] neg_lo:[1,0,0] neg_hi:[1,0,0]
	v_pk_fma_f32 v[106:107], v[80:81], v[62:63], v[106:107] op_sel_hi:[0,1,1] neg_lo:[1,0,0] neg_hi:[1,0,0]
	ds_read_b128 v[48:51], v1 offset:10432
	ds_read_b128 v[52:55], v1 offset:10448
	ds_read_b128 v[56:59], v1 offset:10464
	ds_read_b128 v[60:63], v1 offset:10480
	s_waitcnt lgkmcnt(8)
	v_pk_fma_f32 v[238:239], v[228:229], v[64:65], v[238:239] op_sel_hi:[0,1,1] neg_lo:[1,0,0] neg_hi:[1,0,0]
	v_pk_fma_f32 v[240:241], v[228:229], v[66:67], v[240:241] op_sel_hi:[0,1,1] neg_lo:[1,0,0] neg_hi:[1,0,0]
	v_pk_fma_f32 v[242:243], v[228:229], v[68:69], v[242:243] op_sel_hi:[0,1,1] neg_lo:[1,0,0] neg_hi:[1,0,0]
	v_pk_fma_f32 v[248:249], v[228:229], v[70:71], v[248:249] op_sel_hi:[0,1,1] neg_lo:[1,0,0] neg_hi:[1,0,0]
	v_pk_fma_f32 v[250:251], v[228:229], v[72:73], v[250:251] op_sel_hi:[0,1,1] neg_lo:[1,0,0] neg_hi:[1,0,0]
	v_pk_fma_f32 v[252:253], v[228:229], v[74:75], v[252:253] op_sel_hi:[0,1,1] neg_lo:[1,0,0] neg_hi:[1,0,0]
	v_pk_fma_f32 v[254:255], v[228:229], v[76:77], v[254:255] op_sel_hi:[0,1,1] neg_lo:[1,0,0] neg_hi:[1,0,0]
	v_pk_fma_f32 v[106:107], v[228:229], v[78:79], v[106:107] op_sel_hi:[0,1,1] neg_lo:[1,0,0] neg_hi:[1,0,0]
	ds_read_b128 v[64:67], v1 offset:10688
	ds_read_b128 v[68:71], v1 offset:10704
	ds_read_b128 v[72:75], v1 offset:10720
	ds_read_b128 v[76:79], v1 offset:10736
	s_waitcnt lgkmcnt(8)
	v_mov_b32_e32 v80, v229
	v_pk_fma_f32 v[238:239], v[80:81], v[32:33], v[238:239] op_sel_hi:[0,1,1] neg_lo:[1,0,0] neg_hi:[1,0,0]
	v_pk_fma_f32 v[240:241], v[80:81], v[34:35], v[240:241] op_sel_hi:[0,1,1] neg_lo:[1,0,0] neg_hi:[1,0,0]
	v_pk_fma_f32 v[242:243], v[80:81], v[36:37], v[242:243] op_sel_hi:[0,1,1] neg_lo:[1,0,0] neg_hi:[1,0,0]
	v_pk_fma_f32 v[248:249], v[80:81], v[38:39], v[248:249] op_sel_hi:[0,1,1] neg_lo:[1,0,0] neg_hi:[1,0,0]
	v_pk_fma_f32 v[250:251], v[80:81], v[40:41], v[250:251] op_sel_hi:[0,1,1] neg_lo:[1,0,0] neg_hi:[1,0,0]
	v_pk_fma_f32 v[252:253], v[80:81], v[42:43], v[252:253] op_sel_hi:[0,1,1] neg_lo:[1,0,0] neg_hi:[1,0,0]
	v_pk_fma_f32 v[254:255], v[80:81], v[44:45], v[254:255] op_sel_hi:[0,1,1] neg_lo:[1,0,0] neg_hi:[1,0,0]
	v_pk_fma_f32 v[106:107], v[80:81], v[46:47], v[106:107] op_sel_hi:[0,1,1] neg_lo:[1,0,0] neg_hi:[1,0,0]
	ds_read_b128 v[32:35], v1 offset:10944
	ds_read_b128 v[36:39], v1 offset:10960
	ds_read_b128 v[40:43], v1 offset:10976
	ds_read_b128 v[44:47], v1 offset:10992
	s_waitcnt lgkmcnt(8)
	v_pk_fma_f32 v[238:239], v[230:231], v[48:49], v[238:239] op_sel_hi:[0,1,1] neg_lo:[1,0,0] neg_hi:[1,0,0]
	v_pk_fma_f32 v[240:241], v[230:231], v[50:51], v[240:241] op_sel_hi:[0,1,1] neg_lo:[1,0,0] neg_hi:[1,0,0]
	v_pk_fma_f32 v[242:243], v[230:231], v[52:53], v[242:243] op_sel_hi:[0,1,1] neg_lo:[1,0,0] neg_hi:[1,0,0]
	v_pk_fma_f32 v[248:249], v[230:231], v[54:55], v[248:249] op_sel_hi:[0,1,1] neg_lo:[1,0,0] neg_hi:[1,0,0]
	v_pk_fma_f32 v[250:251], v[230:231], v[56:57], v[250:251] op_sel_hi:[0,1,1] neg_lo:[1,0,0] neg_hi:[1,0,0]
	v_pk_fma_f32 v[252:253], v[230:231], v[58:59], v[252:253] op_sel_hi:[0,1,1] neg_lo:[1,0,0] neg_hi:[1,0,0]
	v_pk_fma_f32 v[254:255], v[230:231], v[60:61], v[254:255] op_sel_hi:[0,1,1] neg_lo:[1,0,0] neg_hi:[1,0,0]
	v_pk_fma_f32 v[106:107], v[230:231], v[62:63], v[106:107] op_sel_hi:[0,1,1] neg_lo:[1,0,0] neg_hi:[1,0,0]
	ds_read_b128 v[48:51], v1 offset:11200
	ds_read_b128 v[52:55], v1 offset:11216
	ds_read_b128 v[56:59], v1 offset:11232
	ds_read_b128 v[60:63], v1 offset:11248
	s_waitcnt lgkmcnt(8)
	v_mov_b32_e32 v80, v231
	v_pk_fma_f32 v[238:239], v[80:81], v[64:65], v[238:239] op_sel_hi:[0,1,1] neg_lo:[1,0,0] neg_hi:[1,0,0]
	v_pk_fma_f32 v[240:241], v[80:81], v[66:67], v[240:241] op_sel_hi:[0,1,1] neg_lo:[1,0,0] neg_hi:[1,0,0]
	v_pk_fma_f32 v[242:243], v[80:81], v[68:69], v[242:243] op_sel_hi:[0,1,1] neg_lo:[1,0,0] neg_hi:[1,0,0]
	v_pk_fma_f32 v[248:249], v[80:81], v[70:71], v[248:249] op_sel_hi:[0,1,1] neg_lo:[1,0,0] neg_hi:[1,0,0]
	v_pk_fma_f32 v[250:251], v[80:81], v[72:73], v[250:251] op_sel_hi:[0,1,1] neg_lo:[1,0,0] neg_hi:[1,0,0]
	v_pk_fma_f32 v[252:253], v[80:81], v[74:75], v[252:253] op_sel_hi:[0,1,1] neg_lo:[1,0,0] neg_hi:[1,0,0]
	v_pk_fma_f32 v[254:255], v[80:81], v[76:77], v[254:255] op_sel_hi:[0,1,1] neg_lo:[1,0,0] neg_hi:[1,0,0]
	v_pk_fma_f32 v[106:107], v[80:81], v[78:79], v[106:107] op_sel_hi:[0,1,1] neg_lo:[1,0,0] neg_hi:[1,0,0]
	ds_read_b128 v[64:67], v1 offset:11456
	ds_read_b128 v[68:71], v1 offset:11472
	ds_read_b128 v[72:75], v1 offset:11488
	ds_read_b128 v[76:79], v1 offset:11504
	s_waitcnt lgkmcnt(8)
	v_pk_fma_f32 v[238:239], v[232:233], v[32:33], v[238:239] op_sel_hi:[0,1,1] neg_lo:[1,0,0] neg_hi:[1,0,0]
	v_pk_fma_f32 v[240:241], v[232:233], v[34:35], v[240:241] op_sel_hi:[0,1,1] neg_lo:[1,0,0] neg_hi:[1,0,0]
	v_pk_fma_f32 v[242:243], v[232:233], v[36:37], v[242:243] op_sel_hi:[0,1,1] neg_lo:[1,0,0] neg_hi:[1,0,0]
	v_pk_fma_f32 v[248:249], v[232:233], v[38:39], v[248:249] op_sel_hi:[0,1,1] neg_lo:[1,0,0] neg_hi:[1,0,0]
	v_pk_fma_f32 v[250:251], v[232:233], v[40:41], v[250:251] op_sel_hi:[0,1,1] neg_lo:[1,0,0] neg_hi:[1,0,0]
	v_pk_fma_f32 v[252:253], v[232:233], v[42:43], v[252:253] op_sel_hi:[0,1,1] neg_lo:[1,0,0] neg_hi:[1,0,0]
	v_pk_fma_f32 v[254:255], v[232:233], v[44:45], v[254:255] op_sel_hi:[0,1,1] neg_lo:[1,0,0] neg_hi:[1,0,0]
	v_pk_fma_f32 v[106:107], v[232:233], v[46:47], v[106:107] op_sel_hi:[0,1,1] neg_lo:[1,0,0] neg_hi:[1,0,0]
	ds_read_b128 v[32:35], v1 offset:11712
	ds_read_b128 v[36:39], v1 offset:11728
	ds_read_b128 v[40:43], v1 offset:11744
	ds_read_b128 v[44:47], v1 offset:11760
	s_waitcnt lgkmcnt(8)
	v_mov_b32_e32 v80, v233
	v_pk_fma_f32 v[238:239], v[80:81], v[48:49], v[238:239] op_sel_hi:[0,1,1] neg_lo:[1,0,0] neg_hi:[1,0,0]
	v_pk_fma_f32 v[240:241], v[80:81], v[50:51], v[240:241] op_sel_hi:[0,1,1] neg_lo:[1,0,0] neg_hi:[1,0,0]
	v_pk_fma_f32 v[242:243], v[80:81], v[52:53], v[242:243] op_sel_hi:[0,1,1] neg_lo:[1,0,0] neg_hi:[1,0,0]
	v_pk_fma_f32 v[248:249], v[80:81], v[54:55], v[248:249] op_sel_hi:[0,1,1] neg_lo:[1,0,0] neg_hi:[1,0,0]
	v_pk_fma_f32 v[250:251], v[80:81], v[56:57], v[250:251] op_sel_hi:[0,1,1] neg_lo:[1,0,0] neg_hi:[1,0,0]
	v_pk_fma_f32 v[252:253], v[80:81], v[58:59], v[252:253] op_sel_hi:[0,1,1] neg_lo:[1,0,0] neg_hi:[1,0,0]
	v_pk_fma_f32 v[254:255], v[80:81], v[60:61], v[254:255] op_sel_hi:[0,1,1] neg_lo:[1,0,0] neg_hi:[1,0,0]
	v_pk_fma_f32 v[106:107], v[80:81], v[62:63], v[106:107] op_sel_hi:[0,1,1] neg_lo:[1,0,0] neg_hi:[1,0,0]
	ds_read_b128 v[48:51], v1 offset:11968
	ds_read_b128 v[52:55], v1 offset:11984
	ds_read_b128 v[56:59], v1 offset:12000
	ds_read_b128 v[60:63], v1 offset:12016
	s_waitcnt lgkmcnt(8)
	v_pk_fma_f32 v[238:239], v[234:235], v[64:65], v[238:239] op_sel_hi:[0,1,1] neg_lo:[1,0,0] neg_hi:[1,0,0]
	v_pk_fma_f32 v[240:241], v[234:235], v[66:67], v[240:241] op_sel_hi:[0,1,1] neg_lo:[1,0,0] neg_hi:[1,0,0]
	v_pk_fma_f32 v[242:243], v[234:235], v[68:69], v[242:243] op_sel_hi:[0,1,1] neg_lo:[1,0,0] neg_hi:[1,0,0]
	v_pk_fma_f32 v[248:249], v[234:235], v[70:71], v[248:249] op_sel_hi:[0,1,1] neg_lo:[1,0,0] neg_hi:[1,0,0]
	v_pk_fma_f32 v[250:251], v[234:235], v[72:73], v[250:251] op_sel_hi:[0,1,1] neg_lo:[1,0,0] neg_hi:[1,0,0]
	v_pk_fma_f32 v[252:253], v[234:235], v[74:75], v[252:253] op_sel_hi:[0,1,1] neg_lo:[1,0,0] neg_hi:[1,0,0]
	v_pk_fma_f32 v[254:255], v[234:235], v[76:77], v[254:255] op_sel_hi:[0,1,1] neg_lo:[1,0,0] neg_hi:[1,0,0]
	v_pk_fma_f32 v[106:107], v[234:235], v[78:79], v[106:107] op_sel_hi:[0,1,1] neg_lo:[1,0,0] neg_hi:[1,0,0]
	ds_read_b128 v[64:67], v1 offset:12224
	ds_read_b128 v[68:71], v1 offset:12240
	ds_read_b128 v[72:75], v1 offset:12256
	ds_read_b128 v[76:79], v1 offset:12272
	s_waitcnt lgkmcnt(8)
	v_mov_b32_e32 v80, v235
	v_pk_fma_f32 v[238:239], v[80:81], v[32:33], v[238:239] op_sel_hi:[0,1,1] neg_lo:[1,0,0] neg_hi:[1,0,0]
	v_pk_fma_f32 v[240:241], v[80:81], v[34:35], v[240:241] op_sel_hi:[0,1,1] neg_lo:[1,0,0] neg_hi:[1,0,0]
	v_pk_fma_f32 v[242:243], v[80:81], v[36:37], v[242:243] op_sel_hi:[0,1,1] neg_lo:[1,0,0] neg_hi:[1,0,0]
	v_pk_fma_f32 v[248:249], v[80:81], v[38:39], v[248:249] op_sel_hi:[0,1,1] neg_lo:[1,0,0] neg_hi:[1,0,0]
	v_pk_fma_f32 v[250:251], v[80:81], v[40:41], v[250:251] op_sel_hi:[0,1,1] neg_lo:[1,0,0] neg_hi:[1,0,0]
	v_pk_fma_f32 v[252:253], v[80:81], v[42:43], v[252:253] op_sel_hi:[0,1,1] neg_lo:[1,0,0] neg_hi:[1,0,0]
	v_pk_fma_f32 v[254:255], v[80:81], v[44:45], v[254:255] op_sel_hi:[0,1,1] neg_lo:[1,0,0] neg_hi:[1,0,0]
	v_pk_fma_f32 v[106:107], v[80:81], v[46:47], v[106:107] op_sel_hi:[0,1,1] neg_lo:[1,0,0] neg_hi:[1,0,0]
	ds_read_b128 v[32:35], v1 offset:12480
	ds_read_b128 v[36:39], v1 offset:12496
	ds_read_b128 v[40:43], v1 offset:12512
	ds_read_b128 v[44:47], v1 offset:12528
	s_waitcnt lgkmcnt(8)
	v_pk_fma_f32 v[238:239], v[236:237], v[48:49], v[238:239] op_sel_hi:[0,1,1] neg_lo:[1,0,0] neg_hi:[1,0,0]
	v_pk_fma_f32 v[240:241], v[236:237], v[50:51], v[240:241] op_sel_hi:[0,1,1] neg_lo:[1,0,0] neg_hi:[1,0,0]
	v_pk_fma_f32 v[242:243], v[236:237], v[52:53], v[242:243] op_sel_hi:[0,1,1] neg_lo:[1,0,0] neg_hi:[1,0,0]
	v_pk_fma_f32 v[248:249], v[236:237], v[54:55], v[248:249] op_sel_hi:[0,1,1] neg_lo:[1,0,0] neg_hi:[1,0,0]
	v_pk_fma_f32 v[250:251], v[236:237], v[56:57], v[250:251] op_sel_hi:[0,1,1] neg_lo:[1,0,0] neg_hi:[1,0,0]
	v_pk_fma_f32 v[252:253], v[236:237], v[58:59], v[252:253] op_sel_hi:[0,1,1] neg_lo:[1,0,0] neg_hi:[1,0,0]
	v_pk_fma_f32 v[254:255], v[236:237], v[60:61], v[254:255] op_sel_hi:[0,1,1] neg_lo:[1,0,0] neg_hi:[1,0,0]
	v_pk_fma_f32 v[106:107], v[236:237], v[62:63], v[106:107] op_sel_hi:[0,1,1] neg_lo:[1,0,0] neg_hi:[1,0,0]
	ds_read_b128 v[48:51], v1 offset:12736
	ds_read_b128 v[52:55], v1 offset:12752
	ds_read_b128 v[56:59], v1 offset:12768
	ds_read_b128 v[60:63], v1 offset:12784
	s_waitcnt lgkmcnt(8)
	v_mov_b32_e32 v80, v237
	v_pk_fma_f32 v[238:239], v[80:81], v[64:65], v[238:239] op_sel_hi:[0,1,1] neg_lo:[1,0,0] neg_hi:[1,0,0]
	v_pk_fma_f32 v[240:241], v[80:81], v[66:67], v[240:241] op_sel_hi:[0,1,1] neg_lo:[1,0,0] neg_hi:[1,0,0]
	v_pk_fma_f32 v[242:243], v[80:81], v[68:69], v[242:243] op_sel_hi:[0,1,1] neg_lo:[1,0,0] neg_hi:[1,0,0]
	v_pk_fma_f32 v[248:249], v[80:81], v[70:71], v[248:249] op_sel_hi:[0,1,1] neg_lo:[1,0,0] neg_hi:[1,0,0]
	v_pk_fma_f32 v[250:251], v[80:81], v[72:73], v[250:251] op_sel_hi:[0,1,1] neg_lo:[1,0,0] neg_hi:[1,0,0]
	v_pk_fma_f32 v[252:253], v[80:81], v[74:75], v[252:253] op_sel_hi:[0,1,1] neg_lo:[1,0,0] neg_hi:[1,0,0]
	v_pk_fma_f32 v[254:255], v[80:81], v[76:77], v[254:255] op_sel_hi:[0,1,1] neg_lo:[1,0,0] neg_hi:[1,0,0]
	v_pk_fma_f32 v[106:107], v[80:81], v[78:79], v[106:107] op_sel_hi:[0,1,1] neg_lo:[1,0,0] neg_hi:[1,0,0]
	ds_read_b128 v[64:67], v1 offset:12992
	ds_read_b128 v[68:71], v1 offset:13008
	ds_read_b128 v[72:75], v1 offset:13024
	ds_read_b128 v[76:79], v1 offset:13040
	s_waitcnt lgkmcnt(8)
	v_fma_f32 v239, -v238, v33, v239
	v_pk_fma_f32 v[240:241], v[238:239], v[34:35], v[240:241] op_sel_hi:[0,1,1] neg_lo:[1,0,0] neg_hi:[1,0,0]
	v_pk_fma_f32 v[242:243], v[238:239], v[36:37], v[242:243] op_sel_hi:[0,1,1] neg_lo:[1,0,0] neg_hi:[1,0,0]
	v_pk_fma_f32 v[248:249], v[238:239], v[38:39], v[248:249] op_sel_hi:[0,1,1] neg_lo:[1,0,0] neg_hi:[1,0,0]
	v_pk_fma_f32 v[250:251], v[238:239], v[40:41], v[250:251] op_sel_hi:[0,1,1] neg_lo:[1,0,0] neg_hi:[1,0,0]
	v_pk_fma_f32 v[252:253], v[238:239], v[42:43], v[252:253] op_sel_hi:[0,1,1] neg_lo:[1,0,0] neg_hi:[1,0,0]
	v_pk_fma_f32 v[254:255], v[238:239], v[44:45], v[254:255] op_sel_hi:[0,1,1] neg_lo:[1,0,0] neg_hi:[1,0,0]
	v_pk_fma_f32 v[106:107], v[238:239], v[46:47], v[106:107] op_sel_hi:[0,1,1] neg_lo:[1,0,0] neg_hi:[1,0,0]
	ds_read_b128 v[36:39], v1 offset:13264
	ds_read_b128 v[40:43], v1 offset:13280
	ds_read_b128 v[44:47], v1 offset:13296
	s_waitcnt lgkmcnt(7)
	v_mov_b32_e32 v80, v239
	v_pk_fma_f32 v[240:241], v[80:81], v[50:51], v[240:241] op_sel_hi:[0,1,1] neg_lo:[1,0,0] neg_hi:[1,0,0]
	v_pk_fma_f32 v[242:243], v[80:81], v[52:53], v[242:243] op_sel_hi:[0,1,1] neg_lo:[1,0,0] neg_hi:[1,0,0]
	v_pk_fma_f32 v[248:249], v[80:81], v[54:55], v[248:249] op_sel_hi:[0,1,1] neg_lo:[1,0,0] neg_hi:[1,0,0]
	v_pk_fma_f32 v[250:251], v[80:81], v[56:57], v[250:251] op_sel_hi:[0,1,1] neg_lo:[1,0,0] neg_hi:[1,0,0]
	v_pk_fma_f32 v[252:253], v[80:81], v[58:59], v[252:253] op_sel_hi:[0,1,1] neg_lo:[1,0,0] neg_hi:[1,0,0]
	v_pk_fma_f32 v[254:255], v[80:81], v[60:61], v[254:255] op_sel_hi:[0,1,1] neg_lo:[1,0,0] neg_hi:[1,0,0]
	v_pk_fma_f32 v[106:107], v[80:81], v[62:63], v[106:107] op_sel_hi:[0,1,1] neg_lo:[1,0,0] neg_hi:[1,0,0]
	ds_read_b128 v[52:55], v1 offset:13520
	ds_read_b128 v[56:59], v1 offset:13536
	ds_read_b128 v[60:63], v1 offset:13552
	s_waitcnt lgkmcnt(6)
	v_fma_f32 v241, -v240, v67, v241
	v_pk_fma_f32 v[242:243], v[240:241], v[68:69], v[242:243] op_sel_hi:[0,1,1] neg_lo:[1,0,0] neg_hi:[1,0,0]
	v_pk_fma_f32 v[248:249], v[240:241], v[70:71], v[248:249] op_sel_hi:[0,1,1] neg_lo:[1,0,0] neg_hi:[1,0,0]
	v_pk_fma_f32 v[250:251], v[240:241], v[72:73], v[250:251] op_sel_hi:[0,1,1] neg_lo:[1,0,0] neg_hi:[1,0,0]
	v_pk_fma_f32 v[252:253], v[240:241], v[74:75], v[252:253] op_sel_hi:[0,1,1] neg_lo:[1,0,0] neg_hi:[1,0,0]
	v_pk_fma_f32 v[254:255], v[240:241], v[76:77], v[254:255] op_sel_hi:[0,1,1] neg_lo:[1,0,0] neg_hi:[1,0,0]
	v_pk_fma_f32 v[106:107], v[240:241], v[78:79], v[106:107] op_sel_hi:[0,1,1] neg_lo:[1,0,0] neg_hi:[1,0,0]
	ds_read_b128 v[68:71], v1 offset:13776
	ds_read_b128 v[72:75], v1 offset:13792
	ds_read_b128 v[76:79], v1 offset:13808
	s_waitcnt lgkmcnt(6)
	v_mov_b32_e32 v80, v241
	v_pk_fma_f32 v[242:243], v[80:81], v[36:37], v[242:243] op_sel_hi:[0,1,1] neg_lo:[1,0,0] neg_hi:[1,0,0]
	v_pk_fma_f32 v[248:249], v[80:81], v[38:39], v[248:249] op_sel_hi:[0,1,1] neg_lo:[1,0,0] neg_hi:[1,0,0]
	v_pk_fma_f32 v[250:251], v[80:81], v[40:41], v[250:251] op_sel_hi:[0,1,1] neg_lo:[1,0,0] neg_hi:[1,0,0]
	v_pk_fma_f32 v[252:253], v[80:81], v[42:43], v[252:253] op_sel_hi:[0,1,1] neg_lo:[1,0,0] neg_hi:[1,0,0]
	v_pk_fma_f32 v[254:255], v[80:81], v[44:45], v[254:255] op_sel_hi:[0,1,1] neg_lo:[1,0,0] neg_hi:[1,0,0]
	v_pk_fma_f32 v[106:107], v[80:81], v[46:47], v[106:107] op_sel_hi:[0,1,1] neg_lo:[1,0,0] neg_hi:[1,0,0]
	ds_read_b128 v[36:39], v1 offset:14032
	ds_read_b128 v[40:43], v1 offset:14048
	ds_read_b128 v[44:47], v1 offset:14064
	s_waitcnt lgkmcnt(6)
	v_fma_f32 v243, -v242, v53, v243
	v_pk_fma_f32 v[248:249], v[242:243], v[54:55], v[248:249] op_sel_hi:[0,1,1] neg_lo:[1,0,0] neg_hi:[1,0,0]
	v_pk_fma_f32 v[250:251], v[242:243], v[56:57], v[250:251] op_sel_hi:[0,1,1] neg_lo:[1,0,0] neg_hi:[1,0,0]
	v_pk_fma_f32 v[252:253], v[242:243], v[58:59], v[252:253] op_sel_hi:[0,1,1] neg_lo:[1,0,0] neg_hi:[1,0,0]
	v_pk_fma_f32 v[254:255], v[242:243], v[60:61], v[254:255] op_sel_hi:[0,1,1] neg_lo:[1,0,0] neg_hi:[1,0,0]
	v_pk_fma_f32 v[106:107], v[242:243], v[62:63], v[106:107] op_sel_hi:[0,1,1] neg_lo:[1,0,0] neg_hi:[1,0,0]
	ds_read_b128 v[56:59], v1 offset:14304
	ds_read_b128 v[60:63], v1 offset:14320
	s_waitcnt lgkmcnt(5)
	v_mov_b32_e32 v80, v243
	v_pk_fma_f32 v[248:249], v[80:81], v[70:71], v[248:249] op_sel_hi:[0,1,1] neg_lo:[1,0,0] neg_hi:[1,0,0]
	v_pk_fma_f32 v[250:251], v[80:81], v[72:73], v[250:251] op_sel_hi:[0,1,1] neg_lo:[1,0,0] neg_hi:[1,0,0]
	v_pk_fma_f32 v[252:253], v[80:81], v[74:75], v[252:253] op_sel_hi:[0,1,1] neg_lo:[1,0,0] neg_hi:[1,0,0]
	v_pk_fma_f32 v[254:255], v[80:81], v[76:77], v[254:255] op_sel_hi:[0,1,1] neg_lo:[1,0,0] neg_hi:[1,0,0]
	v_pk_fma_f32 v[106:107], v[80:81], v[78:79], v[106:107] op_sel_hi:[0,1,1] neg_lo:[1,0,0] neg_hi:[1,0,0]
	ds_read_b128 v[72:75], v1 offset:14560
	ds_read_b128 v[76:79], v1 offset:14576
	s_waitcnt lgkmcnt(4)
	v_fma_f32 v249, -v248, v39, v249
	v_pk_fma_f32 v[250:251], v[248:249], v[40:41], v[250:251] op_sel_hi:[0,1,1] neg_lo:[1,0,0] neg_hi:[1,0,0]
	v_pk_fma_f32 v[252:253], v[248:249], v[42:43], v[252:253] op_sel_hi:[0,1,1] neg_lo:[1,0,0] neg_hi:[1,0,0]
	v_pk_fma_f32 v[254:255], v[248:249], v[44:45], v[254:255] op_sel_hi:[0,1,1] neg_lo:[1,0,0] neg_hi:[1,0,0]
	v_pk_fma_f32 v[106:107], v[248:249], v[46:47], v[106:107] op_sel_hi:[0,1,1] neg_lo:[1,0,0] neg_hi:[1,0,0]
	ds_read_b128 v[40:43], v1 offset:14816
	ds_read_b128 v[44:47], v1 offset:14832
	s_waitcnt lgkmcnt(4)
	v_mov_b32_e32 v80, v249
	v_pk_fma_f32 v[250:251], v[80:81], v[56:57], v[250:251] op_sel_hi:[0,1,1] neg_lo:[1,0,0] neg_hi:[1,0,0]
	v_pk_fma_f32 v[252:253], v[80:81], v[58:59], v[252:253] op_sel_hi:[0,1,1] neg_lo:[1,0,0] neg_hi:[1,0,0]
	v_pk_fma_f32 v[254:255], v[80:81], v[60:61], v[254:255] op_sel_hi:[0,1,1] neg_lo:[1,0,0] neg_hi:[1,0,0]
	v_pk_fma_f32 v[106:107], v[80:81], v[62:63], v[106:107] op_sel_hi:[0,1,1] neg_lo:[1,0,0] neg_hi:[1,0,0]
	ds_read_b128 v[56:59], v1 offset:15072
	ds_read_b128 v[60:63], v1 offset:15088
	s_waitcnt lgkmcnt(4)
	v_fma_f32 v251, -v250, v73, v251
	v_pk_fma_f32 v[252:253], v[250:251], v[74:75], v[252:253] op_sel_hi:[0,1,1] neg_lo:[1,0,0] neg_hi:[1,0,0]
	v_pk_fma_f32 v[254:255], v[250:251], v[76:77], v[254:255] op_sel_hi:[0,1,1] neg_lo:[1,0,0] neg_hi:[1,0,0]
	v_pk_fma_f32 v[106:107], v[250:251], v[78:79], v[106:107] op_sel_hi:[0,1,1] neg_lo:[1,0,0] neg_hi:[1,0,0]
	ds_read_b128 v[76:79], v1 offset:15344
	s_waitcnt lgkmcnt(3)
	v_mov_b32_e32 v80, v251
	v_pk_fma_f32 v[252:253], v[80:81], v[42:43], v[252:253] op_sel_hi:[0,1,1] neg_lo:[1,0,0] neg_hi:[1,0,0]
	v_pk_fma_f32 v[254:255], v[80:81], v[44:45], v[254:255] op_sel_hi:[0,1,1] neg_lo:[1,0,0] neg_hi:[1,0,0]
	v_pk_fma_f32 v[106:107], v[80:81], v[46:47], v[106:107] op_sel_hi:[0,1,1] neg_lo:[1,0,0] neg_hi:[1,0,0]
	ds_read_b128 v[44:47], v1 offset:15600
	s_waitcnt lgkmcnt(2)
	v_fma_f32 v253, -v252, v59, v253
	v_pk_fma_f32 v[254:255], v[252:253], v[60:61], v[254:255] op_sel_hi:[0,1,1] neg_lo:[1,0,0] neg_hi:[1,0,0]
	v_pk_fma_f32 v[106:107], v[252:253], v[62:63], v[106:107] op_sel_hi:[0,1,1] neg_lo:[1,0,0] neg_hi:[1,0,0]
	ds_read_b128 v[60:63], v1 offset:15856
	s_waitcnt lgkmcnt(2)
	v_mov_b32_e32 v80, v253
	v_pk_fma_f32 v[254:255], v[80:81], v[76:77], v[254:255] op_sel_hi:[0,1,1] neg_lo:[1,0,0] neg_hi:[1,0,0]
	v_pk_fma_f32 v[106:107], v[80:81], v[78:79], v[106:107] op_sel_hi:[0,1,1] neg_lo:[1,0,0] neg_hi:[1,0,0]
	ds_read_b128 v[76:79], v1 offset:16112
	s_waitcnt lgkmcnt(2)
	v_fma_f32 v255, -v254, v45, v255
	v_pk_fma_f32 v[106:107], v[254:255], v[46:47], v[106:107] op_sel_hi:[0,1,1] neg_lo:[1,0,0] neg_hi:[1,0,0]
	s_waitcnt lgkmcnt(1)
	v_mov_b32_e32 v80, v255
	v_pk_fma_f32 v[106:107], v[80:81], v[62:63], v[106:107] op_sel_hi:[0,1,1] neg_lo:[1,0,0] neg_hi:[1,0,0]
	s_waitcnt lgkmcnt(0)
	v_fma_f32 v107, -v106, v79, v107
	ds_write_b32 v0, v190 offset:0
	ds_write_b32 v0, v191 offset:528
	ds_write_b32 v0, v192 offset:1056
	ds_write_b32 v0, v193 offset:1584
	ds_write_b32 v0, v194 offset:2112
	ds_write_b32 v0, v195 offset:2640
	ds_write_b32 v0, v196 offset:3168
	ds_write_b32 v0, v197 offset:3696
	ds_write_b32 v0, v198 offset:4224
	ds_write_b32 v0, v199 offset:4752
	ds_write_b32 v0, v200 offset:5280
	ds_write_b32 v0, v201 offset:5808
	ds_write_b32 v0, v202 offset:6336
	ds_write_b32 v0, v203 offset:6864
	ds_write_b32 v0, v204 offset:7392
	ds_write_b32 v0, v205 offset:7920
	ds_write_b32 v0, v206 offset:8448
	ds_write_b32 v0, v207 offset:8976
	ds_write_b32 v0, v208 offset:9504
	ds_write_b32 v0, v209 offset:10032
	ds_write_b32 v0, v210 offset:10560
	ds_write_b32 v0, v211 offset:11088
	ds_write_b32 v0, v212 offset:11616
	ds_write_b32 v0, v213 offset:12144
	ds_write_b32 v0, v214 offset:12672
	ds_write_b32 v0, v215 offset:13200
	ds_write_b32 v0, v216 offset:13728
	ds_write_b32 v0, v217 offset:14256
	ds_write_b32 v0, v218 offset:14784
	ds_write_b32 v0, v219 offset:15312
	ds_write_b32 v0, v220 offset:15840
	ds_write_b32 v0, v221 offset:16368
	ds_write_b32 v0, v222 offset:16896
	ds_write_b32 v0, v223 offset:17424
	ds_write_b32 v0, v224 offset:17952
	ds_write_b32 v0, v225 offset:18480
	ds_write_b32 v0, v226 offset:19008
	ds_write_b32 v0, v227 offset:19536
	ds_write_b32 v0, v228 offset:20064
	ds_write_b32 v0, v229 offset:20592
	ds_write_b32 v0, v230 offset:21120
	ds_write_b32 v0, v231 offset:21648
	ds_write_b32 v0, v232 offset:22176
	ds_write_b32 v0, v233 offset:22704
	ds_write_b32 v0, v234 offset:23232
	ds_write_b32 v0, v235 offset:23760
	ds_write_b32 v0, v236 offset:24288
	ds_write_b32 v0, v237 offset:24816
	ds_write_b32 v0, v238 offset:25344
	ds_write_b32 v0, v239 offset:25872
	ds_write_b32 v0, v240 offset:26400
	ds_write_b32 v0, v241 offset:26928
	ds_write_b32 v0, v242 offset:27456
	ds_write_b32 v0, v243 offset:27984
	ds_write_b32 v0, v248 offset:28512
	ds_write_b32 v0, v249 offset:29040
	ds_write_b32 v0, v250 offset:29568
	ds_write_b32 v0, v251 offset:30096
	ds_write_b32 v0, v252 offset:30624
	ds_write_b32 v0, v253 offset:31152
	ds_write_b32 v0, v254 offset:31680
	ds_write_b32 v0, v255 offset:32208
	ds_write_b32 v0, v106 offset:32736
	ds_write_b32 v0, v107 offset:33264

.LBB0_970:
	s_cmp_le_i32 s46, s6
	s_cselect_b64 s[2:3], -1, 0
	s_and_b64 s[26:27], s[2:3], s[0:1]
	v_readlane_b32 s0, v244, 12
	s_lshl_b32 s38, s0, 8
	s_mov_b32 s39, s67
	s_lshl_b32 s24, s0, 7
	s_andn2_b64 vcc, exec, s[26:27]
	s_mov_b32 s25, s67
	s_cbranch_vccnz .LBB0_1081
	v_readlane_b32 s0, v244, 12
	s_lshl_b32 s9, s0, 4
	s_lshl_b32 s8, s0, 5
	v_readlane_b32 s0, v246, 62
	v_readlane_b32 s2, v246, 6
	v_readlane_b32 s3, v246, 7
	v_readlane_b32 s0, v246, 63
	v_readlane_b32 s84, v246, 0
	s_and_b64 vcc, exec, s[2:3]
	s_waitcnt lgkmcnt(0)
	v_readlane_b32 s0, v245, 0
	s_waitcnt lgkmcnt(0)
	s_nop 0
	v_readlane_b32 s0, v245, 1
	s_waitcnt lgkmcnt(0)
	s_nop 0
	v_readlane_b32 s0, v245, 2
	s_waitcnt lgkmcnt(0)
	s_nop 0
	v_mov_b32_e32 v0, s0
	ds_read_b32 v0, v0
	v_readlane_b32 s0, v245, 3
	s_waitcnt lgkmcnt(0)
	v_readfirstlane_b32 s28, v0
	v_mov_b32_e32 v0, s0
	ds_read_b32 v0, v0
	v_readlane_b32 s0, v245, 4
	s_waitcnt lgkmcnt(0)
	v_readfirstlane_b32 s29, v0
	v_mov_b32_e32 v0, s0
	ds_read_b32 v0, v0
	v_readlane_b32 s0, v245, 5
	s_waitcnt lgkmcnt(0)
	v_readfirstlane_b32 s30, v0
	v_mov_b32_e32 v0, s0
	ds_read_b32 v0, v0
	v_readlane_b32 s0, v245, 6
	s_waitcnt lgkmcnt(0)
	v_readfirstlane_b32 s31, v0
	v_mov_b32_e32 v0, s0
	ds_read_b32 v0, v0
	v_readlane_b32 s0, v245, 7
	s_waitcnt lgkmcnt(0)
	v_readfirstlane_b32 s34, v0
	v_mov_b32_e32 v0, s0
	ds_read_b32 v0, v0
	v_readlane_b32 s0, v245, 8
	s_waitcnt lgkmcnt(0)
	v_readfirstlane_b32 s35, v0
	v_readlane_b32 s0, v245, 9
	s_waitcnt lgkmcnt(0)
	s_nop 0
	v_readlane_b32 s0, v245, 10
	s_waitcnt lgkmcnt(0)
	s_nop 0
	v_readlane_b32 s0, v245, 11
	s_waitcnt lgkmcnt(0)
	s_nop 0
	v_readlane_b32 s0, v245, 12
	s_waitcnt lgkmcnt(0)
	s_nop 0
	v_readlane_b32 s0, v245, 13
	s_waitcnt lgkmcnt(0)
	s_nop 0
	v_readlane_b32 s0, v245, 14
	s_waitcnt lgkmcnt(0)
	s_nop 0
	v_readlane_b32 s0, v245, 15
	s_waitcnt lgkmcnt(0)
	s_nop 0
	v_readlane_b32 s0, v245, 16
	s_waitcnt lgkmcnt(0)
	s_nop 0
	v_mov_b32_e32 v0, s0
	ds_read_b32 v0, v0
	v_readlane_b32 s0, v245, 17
	s_waitcnt lgkmcnt(0)
	v_readfirstlane_b32 s14, v0
	v_mov_b32_e32 v0, s0
	ds_read_b32 v0, v0
	v_readlane_b32 s0, v245, 18
	s_waitcnt lgkmcnt(0)
	v_readfirstlane_b32 s15, v0
	v_mov_b32_e32 v0, s0
	ds_read_b32 v0, v0
	v_readlane_b32 s0, v245, 19
	s_waitcnt lgkmcnt(0)
	v_readfirstlane_b32 s75, v0
	v_mov_b32_e32 v0, s0
	ds_read_b32 v0, v0
	v_readlane_b32 s0, v245, 20
	s_waitcnt lgkmcnt(0)
	v_readfirstlane_b32 s82, v0
	v_mov_b32_e32 v0, s0
	ds_read_b32 v0, v0
	v_readlane_b32 s0, v245, 21
	s_waitcnt lgkmcnt(0)
	v_readfirstlane_b32 s83, v0
	v_mov_b32_e32 v0, s0
	ds_read_b32 v0, v0
	v_readlane_b32 s0, v245, 22
	s_waitcnt lgkmcnt(0)
	v_readfirstlane_b32 s18, v0
	v_mov_b32_e32 v0, s0
	ds_read_b32 v0, v0
	v_readlane_b32 s0, v245, 23
	s_waitcnt lgkmcnt(0)
	v_readfirstlane_b32 s33, v0
	v_mov_b32_e32 v0, s0
	ds_read_b32 v0, v0
	v_readlane_b32 s0, v245, 24
	s_waitcnt lgkmcnt(0)
	v_readfirstlane_b32 s49, v0
	v_mov_b32_e32 v0, s0
	ds_read_b32 v0, v0
	v_readlane_b32 s0, v245, 25
	s_waitcnt lgkmcnt(0)
	v_readfirstlane_b32 s19, v0
	v_mov_b32_e32 v0, s0
	ds_read_b32 v0, v0
	v_readlane_b32 s0, v245, 26
	s_waitcnt lgkmcnt(0)
	v_readfirstlane_b32 s20, v0
	v_mov_b32_e32 v0, s0
	ds_read_b32 v0, v0
	v_readlane_b32 s0, v245, 27
	s_waitcnt lgkmcnt(0)
	v_readfirstlane_b32 s54, v0
	v_mov_b32_e32 v0, s0
	ds_read_b32 v0, v0
	v_readlane_b32 s0, v245, 28
	s_waitcnt lgkmcnt(0)
	v_readfirstlane_b32 s55, v0
	v_mov_b32_e32 v0, s0
	ds_read_b32 v0, v0
	v_readlane_b32 s0, v245, 29
	s_waitcnt lgkmcnt(0)
	v_readfirstlane_b32 s16, v0
	v_mov_b32_e32 v0, s0
	ds_read_b32 v0, v0
	v_readlane_b32 s0, v245, 30
	s_waitcnt lgkmcnt(0)
	v_readfirstlane_b32 s17, v0
	v_readlane_b32 s0, v245, 31
	s_waitcnt lgkmcnt(0)
	s_nop 0
	v_readlane_b32 s0, v245, 32
	s_waitcnt lgkmcnt(0)
	s_nop 0
	v_readlane_b32 s0, v245, 33
	s_waitcnt lgkmcnt(0)
	s_nop 0
	v_readlane_b32 s0, v245, 34
	s_waitcnt lgkmcnt(0)
	s_nop 0
	v_readlane_b32 s0, v245, 35
	s_waitcnt lgkmcnt(0)
	s_nop 0
	v_readlane_b32 s0, v245, 36
	s_waitcnt lgkmcnt(0)
	s_nop 0
	v_readlane_b32 s0, v245, 37
	s_waitcnt lgkmcnt(0)
	s_nop 0
	v_readlane_b32 s0, v245, 38
	s_waitcnt lgkmcnt(0)
	s_nop 0
	v_readlane_b32 s0, v245, 39
	s_waitcnt lgkmcnt(0)
	s_nop 0
	v_readlane_b32 s0, v245, 40
	s_waitcnt lgkmcnt(0)
	s_nop 0
	v_readlane_b32 s0, v245, 41
	s_waitcnt lgkmcnt(0)
	s_nop 0
	v_readlane_b32 s0, v245, 42
	s_waitcnt lgkmcnt(0)
	s_nop 0
	v_readlane_b32 s0, v245, 43
	s_waitcnt lgkmcnt(0)
	s_nop 0
	v_readlane_b32 s0, v245, 44
	s_waitcnt lgkmcnt(0)
	s_nop 0
	v_readlane_b32 s0, v245, 45
	s_waitcnt lgkmcnt(0)
	s_nop 0
	v_readlane_b32 s0, v245, 46
	s_waitcnt lgkmcnt(0)
	s_nop 0
	v_readlane_b32 s0, v245, 47
	s_waitcnt lgkmcnt(0)
	s_nop 0
	v_readlane_b32 s0, v245, 48
	s_waitcnt lgkmcnt(0)
	s_nop 0
	v_readlane_b32 s0, v245, 49
	s_waitcnt lgkmcnt(0)
	s_nop 0
	v_readlane_b32 s0, v245, 50
	s_waitcnt lgkmcnt(0)
	s_nop 0
	v_readlane_b32 s0, v245, 51
	s_waitcnt lgkmcnt(0)
	s_nop 0
	v_readlane_b32 s0, v245, 52
	s_waitcnt lgkmcnt(0)
	s_nop 0
	v_readlane_b32 s0, v245, 53
	s_waitcnt lgkmcnt(0)
	s_nop 0
	v_readlane_b32 s0, v245, 54
	s_waitcnt lgkmcnt(0)
	s_nop 0
	v_mov_b32_e32 v0, s0
	ds_read_b32 v0, v0
	v_readlane_b32 s0, v245, 55
	s_waitcnt lgkmcnt(0)
	v_readfirstlane_b32 s40, v0
	v_mov_b32_e32 v0, s0
	ds_read_b32 v0, v0
	v_readlane_b32 s0, v245, 56
	s_waitcnt lgkmcnt(0)
	v_readfirstlane_b32 s41, v0
	v_mov_b32_e32 v0, s0
	ds_read_b32 v0, v0
	v_readlane_b32 s0, v245, 57
	s_waitcnt lgkmcnt(0)
	v_readfirstlane_b32 s12, v0
	v_mov_b32_e32 v0, s0
	ds_read_b32 v0, v0
	s_mov_b64 s[0:1], -1
	s_waitcnt lgkmcnt(0)
	v_readfirstlane_b32 s13, v0
	s_cbranch_vccnz .LBB0_974
	s_andn2_b64 vcc, exec, s[0:1]
	s_cbranch_vccz .LBB0_992

.LBB0_1131:
	s_cmp_le_i32 s46, s6
	s_cselect_b64 s[2:3], -1, 0
	s_and_b64 s[22:23], s[2:3], s[0:1]
	v_readlane_b32 s0, v244, 12
	s_lshl_b32 s30, s0, 22
	s_lshl_b32 s66, s0, 11
	v_readlane_b32 s0, v244, 17
	v_readlane_b32 s1, v244, 18
	s_mov_b32 s1, s67
	v_writelane_b32 v244, s0, 17
	s_andn2_b64 vcc, exec, s[22:23]
	s_nop 0
	v_writelane_b32 v244, s1, 18
	s_cbranch_vccnz .LBB0_1205
	v_readlane_b32 s0, v246, 62
	v_readlane_b32 s6, v246, 6
	v_readlane_b32 s7, v246, 7
	v_readlane_b32 s0, v246, 63
	s_and_b64 vcc, exec, s[6:7]
	s_waitcnt lgkmcnt(0)
	v_readlane_b32 s0, v245, 0
	s_waitcnt lgkmcnt(0)
	s_nop 0
	v_mov_b32_e32 v0, s0
	ds_read_b32 v0, v0
	v_readlane_b32 s0, v245, 1
	s_waitcnt lgkmcnt(0)
	v_readfirstlane_b32 s16, v0
	v_mov_b32_e32 v0, s0
	ds_read_b32 v0, v0
	v_readlane_b32 s0, v245, 2
	s_waitcnt lgkmcnt(0)
	v_readfirstlane_b32 s17, v0
	v_readlane_b32 s0, v245, 3
	s_waitcnt lgkmcnt(0)
	s_nop 0
	v_readlane_b32 s0, v245, 4
	s_waitcnt lgkmcnt(0)
	s_nop 0
	v_readlane_b32 s0, v245, 5
	s_waitcnt lgkmcnt(0)
	s_nop 0
	v_readlane_b32 s0, v245, 6
	s_waitcnt lgkmcnt(0)
	s_nop 0
	v_readlane_b32 s0, v245, 7
	s_waitcnt lgkmcnt(0)
	s_nop 0
	v_readlane_b32 s0, v245, 8
	s_waitcnt lgkmcnt(0)
	s_nop 0
	v_readlane_b32 s0, v245, 9
	s_waitcnt lgkmcnt(0)
	s_nop 0
	v_readlane_b32 s0, v245, 10
	s_waitcnt lgkmcnt(0)
	s_nop 0
	v_readlane_b32 s0, v245, 11
	s_waitcnt lgkmcnt(0)
	s_nop 0
	v_readlane_b32 s0, v245, 12
	s_waitcnt lgkmcnt(0)
	s_nop 0
	v_readlane_b32 s0, v245, 13
	s_waitcnt lgkmcnt(0)
	s_nop 0
	v_readlane_b32 s0, v245, 14
	s_waitcnt lgkmcnt(0)
	s_nop 0
	v_mov_b32_e32 v0, s0
	ds_read_b32 v0, v0
	v_readlane_b32 s0, v245, 15
	s_waitcnt lgkmcnt(0)
	v_readfirstlane_b32 s28, v0
	v_mov_b32_e32 v0, s0
	ds_read_b32 v0, v0
	v_readlane_b32 s0, v245, 16
	s_waitcnt lgkmcnt(0)
	v_readfirstlane_b32 s29, v0
	v_readlane_b32 s0, v245, 17
	s_waitcnt lgkmcnt(0)
	s_nop 0
	v_readlane_b32 s0, v245, 18
	s_waitcnt lgkmcnt(0)
	s_nop 0
	v_readlane_b32 s0, v245, 19
	s_waitcnt lgkmcnt(0)
	s_nop 0
	v_readlane_b32 s0, v245, 20
	s_waitcnt lgkmcnt(0)
	s_nop 0
	v_readlane_b32 s0, v245, 21
	s_waitcnt lgkmcnt(0)
	s_nop 0
	v_readlane_b32 s0, v245, 22
	s_waitcnt lgkmcnt(0)
	s_nop 0
	v_mov_b32_e32 v0, s0
	ds_read_b32 v0, v0
	v_readlane_b32 s0, v245, 23
	s_waitcnt lgkmcnt(0)
	v_readfirstlane_b32 s2, v0
	v_mov_b32_e32 v0, s0
	ds_read_b32 v0, v0
	v_readlane_b32 s0, v245, 24
	s_waitcnt lgkmcnt(0)
	v_readfirstlane_b32 s4, v0
	v_readlane_b32 s0, v245, 25
	s_waitcnt lgkmcnt(0)
	s_nop 0
	v_readlane_b32 s0, v245, 26
	s_waitcnt lgkmcnt(0)
	s_nop 0
	v_readlane_b32 s0, v245, 27
	s_waitcnt lgkmcnt(0)
	s_nop 0
	v_readlane_b32 s0, v245, 28
	s_waitcnt lgkmcnt(0)
	s_nop 0
	v_mov_b32_e32 v0, s0
	ds_read_b32 v0, v0
	v_readlane_b32 s0, v245, 29
	s_waitcnt lgkmcnt(0)
	v_readfirstlane_b32 s5, v0
	v_mov_b32_e32 v0, s0
	ds_read_b32 v0, v0
	v_readlane_b32 s0, v245, 30
	s_waitcnt lgkmcnt(0)
	v_readfirstlane_b32 s14, v0
	v_readlane_b32 s0, v245, 31
	s_waitcnt lgkmcnt(0)
	s_nop 0
	v_readlane_b32 s0, v245, 32
	s_waitcnt lgkmcnt(0)
	s_nop 0
	v_mov_b32_e32 v0, s0
	ds_read_b32 v0, v0
	v_readlane_b32 s0, v245, 33
	s_waitcnt lgkmcnt(0)
	v_readfirstlane_b32 s18, v0
	v_mov_b32_e32 v0, s0
	ds_read_b32 v0, v0
	v_readlane_b32 s0, v245, 34
	s_waitcnt lgkmcnt(0)
	v_readfirstlane_b32 s19, v0
	v_readlane_b32 s0, v245, 35
	s_waitcnt lgkmcnt(0)
	s_nop 0
	v_readlane_b32 s0, v245, 36
	s_waitcnt lgkmcnt(0)
	s_nop 0
	v_readlane_b32 s0, v245, 37
	s_waitcnt lgkmcnt(0)
	s_nop 0
	v_readlane_b32 s0, v245, 38
	s_waitcnt lgkmcnt(0)
	s_nop 0
	v_readlane_b32 s0, v245, 39
	s_waitcnt lgkmcnt(0)
	s_nop 0
	v_readlane_b32 s0, v245, 40
	s_waitcnt lgkmcnt(0)
	s_nop 0
	v_readlane_b32 s0, v245, 41
	s_waitcnt lgkmcnt(0)
	s_nop 0
	v_readlane_b32 s0, v245, 42
	s_waitcnt lgkmcnt(0)
	s_nop 0
	v_readlane_b32 s0, v245, 43
	s_waitcnt lgkmcnt(0)
	s_nop 0
	v_readlane_b32 s0, v245, 44
	s_waitcnt lgkmcnt(0)
	s_nop 0
	v_readlane_b32 s0, v245, 45
	s_waitcnt lgkmcnt(0)
	s_nop 0
	v_readlane_b32 s0, v245, 46
	s_waitcnt lgkmcnt(0)
	s_nop 0
	v_readlane_b32 s0, v245, 47
	s_waitcnt lgkmcnt(0)
	s_nop 0
	v_readlane_b32 s0, v245, 48
	s_waitcnt lgkmcnt(0)
	s_nop 0
	v_readlane_b32 s0, v245, 49
	s_waitcnt lgkmcnt(0)
	s_nop 0
	v_readlane_b32 s0, v245, 50
	s_waitcnt lgkmcnt(0)
	s_nop 0
	v_readlane_b32 s0, v245, 51
	s_waitcnt lgkmcnt(0)
	s_nop 0
	v_readlane_b32 s0, v245, 52
	s_waitcnt lgkmcnt(0)
	s_nop 0
	v_readlane_b32 s0, v245, 53
	s_waitcnt lgkmcnt(0)
	s_nop 0
	v_readlane_b32 s0, v245, 54
	s_waitcnt lgkmcnt(0)
	s_nop 0
	v_readlane_b32 s0, v245, 55
	s_waitcnt lgkmcnt(0)
	s_nop 0
	v_readlane_b32 s0, v245, 56
	s_waitcnt lgkmcnt(0)
	s_nop 0
	v_mov_b32_e32 v0, s0
	ds_read_b32 v0, v0
	v_readlane_b32 s0, v245, 57
	s_waitcnt lgkmcnt(0)
	v_readfirstlane_b32 s26, v0
	v_mov_b32_e32 v0, s0
	ds_read_b32 v0, v0
	s_mov_b64 s[0:1], -1
	s_waitcnt lgkmcnt(0)
	v_readfirstlane_b32 s27, v0
	s_cbranch_vccz .LBB0_1137
	v_mov_b32_e32 v1, v180
	v_readlane_b32 s0, v246, 0
	s_lshl_b32 s0, s0, 3
	v_ashrrev_i32_e32 v0, 6, v1
	v_add_u32_e32 v88, s0, v0
	v_cmp_gt_i32_e32 vcc, s87, v88
	s_and_saveexec_b64 s[8:9], vcc
	v_readlane_b32 s34, v244, 1
	s_mov_b32 s3, 0xe900000
	s_mov_b32 s15, 0x10d03000
	v_readlane_b32 s35, v244, 2
	s_mov_b32 s36, 0x358637bd
	s_mov_b32 s40, 0x3b800000
	s_brev_b32 s52, 60
	s_cbranch_execz .LBB0_1136
	v_and_b32_e32 v3, 64, v182
	v_xor_b32_e32 v2, 1, v182
	v_add_u32_e32 v3, 64, v3
	v_cmp_lt_i32_e32 vcc, v2, v3
	s_lshl_b64 s[6:7], s[24:25], 2
	s_add_u32 s6, s2, s6
	v_cndmask_b32_e32 v2, v182, v2, vcc
	v_lshlrev_b32_e32 v89, 2, v2
	v_xor_b32_e32 v2, 2, v182
	v_cmp_lt_i32_e32 vcc, v2, v3
	s_addc_u32 s7, s4, s7
	s_mov_b64 s[12:13], 0
	v_cndmask_b32_e32 v2, v182, v2, vcc
	v_lshlrev_b32_e32 v90, 2, v2
	v_xor_b32_e32 v2, 4, v182
	v_cmp_lt_i32_e32 vcc, v2, v3
	s_nop 1
	v_cndmask_b32_e32 v2, v182, v2, vcc
	v_lshlrev_b32_e32 v91, 2, v2
	v_xor_b32_e32 v2, 8, v182
	v_cmp_lt_i32_e32 vcc, v2, v3
	s_nop 1
	v_cndmask_b32_e32 v2, v182, v2, vcc
	v_lshlrev_b32_e32 v92, 2, v2
	v_xor_b32_e32 v2, 16, v182
	v_cmp_lt_i32_e32 vcc, v2, v3
	s_nop 1
	v_cndmask_b32_e32 v2, v182, v2, vcc
	v_lshlrev_b32_e32 v93, 2, v2
	v_lshlrev_b32_e32 v2, 5, v1
	v_and_b32_e32 v144, 0x1e0, v2
	v_lshl_add_u64 v[8:9], s[6:7], 0, v[144:145]
	s_lshl_b64 s[6:7], s[38:39], 2
	s_add_u32 s6, s5, s6
	s_addc_u32 s7, s14, s7
	v_and_b32_e32 v144, 0x3e0, v2
	v_and_b32_e32 v1, 63, v1
	v_lshl_add_u64 v[10:11], s[6:7], 0, v[144:145]
	v_lshlrev_b32_e32 v144, 4, v1
	v_ashrrev_i32_e32 v1, 31, v0
	s_ashr_i32 s1, s0, 31
	v_lshl_add_u64 v[0:1], v[0:1], 0, s[0:1]
	v_mov_b64_e32 v[2:3], s[26:27]
	v_mad_u64_u32 v[12:13], s[0:1], v0, s86, v[2:3]
	v_mad_i32_i24 v13, v1, s86, v13
	v_lshlrev_b64 v[0:1], 12, v[0:1]
	v_lshl_add_u64 v[14:15], s[26:27], 0, v[0:1]

.LBB0_1152:
	v_bfe_u32 v146, v14, 4, 2
	s_lshl_b32 s14, s14, 5
	v_and_b32_e32 v15, 15, v14
	v_lshlrev_b32_e32 v16, 4, v146
	v_lshlrev_b32_e32 v14, 2, v14
	s_and_b32 s28, s14, 0x60
	v_lshl_or_b32 v160, s3, 6, v15
	v_lshl_or_b32 v15, v15, 6, v16
	v_and_b32_e32 v14, 32, v14
	s_lshl_b32 s14, s28, 7
	v_bitop3_b32 v38, v15, s14, v14 bitop3:0xde
	s_lshl_b64 s[14:15], s[90:91], 22
	s_add_i32 m0, s1, 0x18000
	v_lshl_add_u64 v[6:7], v[6:7], 0, s[94:95]
	s_lshl_b32 s3, s3, 13
	s_and_b32 s14, s14, 0xff800000
	s_waitcnt vmcnt(2)
	s_barrier
	global_load_lds_dwordx4 v[6:7], off
	v_lshl_add_u64 v[4:5], v[4:5], 0, s[94:95]
	s_add_i32 m0, s1, 0x1a000
	s_add_i32 s29, s1, 0x8000
	s_add_i32 s31, s1, 0xa000
	global_load_lds_dwordx4 v[4:5], off
	v_lshl_add_u64 v[2:3], v[2:3], 0, s[94:95]
	s_mov_b32 m0, s29
	s_add_u32 s34, s4, 0x80080
	global_load_lds_dwordx4 v[2:3], off
	v_lshl_add_u64 v[0:1], v[0:1], 0, s[94:95]
	s_mov_b32 m0, s31
	s_addc_u32 s35, s5, 0
	global_load_lds_dwordx4 v[0:1], off
	s_add_i32 m0, s1, 0x1c000
	v_lshl_add_u64 v[0:1], s[34:35], 0, v[144:145]
	global_load_lds_dwordx4 v[0:1], off
	v_lshl_add_u64 v[0:1], s[34:35], 0, v[28:29]
	s_add_i32 m0, s1, 0x1e000
	s_or_b64 s[12:13], s[14:15], s[12:13]
	global_load_lds_dwordx4 v[0:1], off
	v_bitop3_b32 v14, v15, s3, v14 bitop3:0xde
	s_add_u32 s3, s26, s12
	s_addc_u32 s12, s27, s13
	s_add_u32 s33, s3, 0x3b00100
	s_addc_u32 s34, s12, 0
	s_ashr_i32 s3, s2, 31
	s_lshl_b64 s[2:3], s[2:3], 20
	v_lshlrev_b32_e32 v0, 15, v11
	v_and_b32_e32 v0, 0xffff0000, v0
	s_add_u32 s35, s26, s2
	v_lshl_add_u32 v0, v12, 12, v0
	v_and_b32_e32 v1, 1, v11
	s_addc_u32 s36, s27, s3
	v_lshl_or_b32 v0, v1, 6, v0
	s_add_u32 s2, s35, 0x10980080
	v_lshl_add_u32 v0, v13, 1, v0
	v_mov_b32_e32 v1, v145
	s_addc_u32 s3, s36, 0
	v_lshl_add_u64 v[30:31], s[2:3], 0, v[0:1]
	v_lshlrev_b32_e32 v0, 15, v8
	v_and_b32_e32 v0, 0xffff0000, v0
	v_lshl_add_u32 v0, v9, 12, v0
	v_and_b32_e32 v1, 1, v8
	v_lshl_or_b32 v0, v1, 6, v0
	s_waitcnt vmcnt(6)
	v_lshl_add_u32 v0, v10, 1, v0
	v_mov_b32_e32 v1, v145
	v_lshl_add_u64 v[36:37], s[2:3], 0, v[0:1]
	v_mov_b32_e32 v0, 0
	s_mov_b32 s37, -2
	s_mov_b64 s[12:13], 0
	v_add_u32_e32 v39, 0, v14
	v_lshrrev_b32_e32 v0, 8, v180
	v_and_b32_e32 v0, 1, v0
	v_lshlrev_b32_e32 v0, 6, v0
	v_and_b32_e32 v1, 15, v180
	v_or_b32_e32 v0, v0, v1
	v_lshlrev_b32_e32 v0, 13, v0
	v_lshrrev_b32_e32 v1, 6, v180
	v_and_b32_e32 v1, 3, v1
	v_lshl_or_b32 v0, v1, 7, v0
	v_lshrrev_b32_e32 v1, 4, v180
	v_and_b32_e32 v1, 3, v1
	v_lshl_or_b32 v0, v1, 4, v0
	v_readlane_b32 s32, v246, 0
	s_lshr_b32 s100, s32, 3
	s_and_b32 s32, s32, 7
	s_lshl_b32 s32, s32, 10
	s_lshl_b32 s100, s100, 21
	s_add_u32 s32, s32, s100
	s_cmp_eq_u32 s90, 0
	s_cbranch_scc1 .Lpre_smp_in1
	s_add_u32 s100, s44, 0xbd00000
	s_addc_u32 s101, s45, 0
	s_branch .Lpre_smp_go
.Lpre_smp_in1:
	v_mov_b32_e32 v1, 0x23008
	ds_read_b64 v[140:141], v1
	s_waitcnt lgkmcnt(0)
	v_readfirstlane_b32 s100, v140
	v_readfirstlane_b32 s101, v141
.Lpre_smp_go:
	s_add_u32 s100, s100, s32
	s_addc_u32 s101, s101, 0
	global_load_dwordx4 v[140:143], v0, s[100:101]
	global_load_dwordx4 v[136:139], v0, s[100:101] offset:64
	global_load_dwordx4 v[132:135], v0, s[100:101] offset:512
	global_load_dwordx4 v[128:131], v0, s[100:101] offset:576
	s_add_u32 s100, s100, 0x20000
	s_addc_u32 s101, s101, 0
	global_load_dwordx4 v[124:127], v0, s[100:101]
	global_load_dwordx4 v[120:123], v0, s[100:101] offset:64
	global_load_dwordx4 v[116:119], v0, s[100:101] offset:512
	global_load_dwordx4 v[112:115], v0, s[100:101] offset:576
	s_add_u32 s100, s100, 0x20000
	s_addc_u32 s101, s101, 0
	global_load_dwordx4 v[108:111], v0, s[100:101]
	global_load_dwordx4 v[104:107], v0, s[100:101] offset:64
	global_load_dwordx4 v[100:103], v0, s[100:101] offset:512
	global_load_dwordx4 v[96:99], v0, s[100:101] offset:576
	s_add_u32 s100, s100, 0x20000
	s_addc_u32 s101, s101, 0
	global_load_dwordx4 v[92:95], v0, s[100:101]
	global_load_dwordx4 v[88:91], v0, s[100:101] offset:64
	global_load_dwordx4 v[84:87], v0, s[100:101] offset:512
	global_load_dwordx4 v[80:83], v0, s[100:101] offset:576
	s_add_u32 s100, s100, 0xa0000
	s_addc_u32 s101, s101, 0
	global_load_dwordx4 v[76:79], v0, s[100:101]
	global_load_dwordx4 v[72:75], v0, s[100:101] offset:64
	global_load_dwordx4 v[68:71], v0, s[100:101] offset:512
	global_load_dwordx4 v[64:67], v0, s[100:101] offset:576
	s_add_u32 s100, s100, 0x20000
	s_addc_u32 s101, s101, 0
	global_load_dwordx4 v[60:63], v0, s[100:101]
	global_load_dwordx4 v[56:59], v0, s[100:101] offset:64
	global_load_dwordx4 v[52:55], v0, s[100:101] offset:512
	global_load_dwordx4 v[44:47], v0, s[100:101] offset:576
	s_add_u32 s100, s100, 0x20000
	s_addc_u32 s101, s101, 0
	global_load_dwordx4 v[32:35], v0, s[100:101]
	global_load_dwordx4 v[24:27], v0, s[100:101] offset:64
	global_load_dwordx4 v[20:23], v0, s[100:101] offset:512
	global_load_dwordx4 v[16:19], v0, s[100:101] offset:576
	s_add_u32 s100, s100, 0x20000
	s_addc_u32 s101, s101, 0
	global_load_dwordx4 v[12:15], v0, s[100:101]
	global_load_dwordx4 v[8:11], v0, s[100:101] offset:64
	global_load_dwordx4 v[4:7], v0, s[100:101] offset:512
	global_load_dwordx4 v[0:3], v0, s[100:101] offset:576
	s_waitcnt vmcnt(0)
	s_barrier

.LBB0_1156:
	s_add_u32 s1, s26, 0xbd00000
	v_readlane_b32 s2, v244, 13
	s_addc_u32 s4, s27, 0
	v_readlane_b32 s3, v244, 14
	s_and_b64 s[2:3], s[2:3], exec
	s_cselect_b32 s17, s17, s4
	s_cselect_b32 s16, s16, s1
	s_lshl_b64 s[2:3], s[66:67], 2
	s_add_u32 s2, s18, s2
	s_addc_u32 s3, s19, s3
	s_add_u32 s14, s26, 0x7d00000
	s_addc_u32 s15, s27, 0
	s_lshl_b32 s1, s6, 8
	v_lshl_or_b32 v28, v146, 2, s1
	v_or_b32_e32 v168, s28, v28
	v_lshlrev_b32_e32 v144, 2, v168
	v_lshl_add_u64 v[28:29], s[2:3], 0, v[144:145]
	global_load_dwordx4 v[48:51], v[28:29], off
	global_load_dwordx4 v[40:43], v[28:29], off offset:64
	global_load_dwordx4 v[36:39], v[28:29], off offset:512
	s_nop 0
	global_load_dwordx4 v[28:31], v[28:29], off offset:576
	v_lshl_add_u32 v160, s0, 8, v160
	v_cmp_lt_i32_e32 vcc, s70, v160
	s_and_saveexec_b64 s[0:1], vcc
	s_xor_b64 s[0:1], exec, s[0:1]
	v_add_u32_e32 v162, 0xffffe000, v160
	v_mov_b32_e32 v163, v145
	v_lshlrev_b64 v[162:163], 13, v[162:163]
	v_mov_b32_e32 v161, v145
	v_lshl_add_u64 v[162:163], s[16:17], 0, v[162:163]
	v_lshlrev_b64 v[166:167], 11, v[160:161]
	s_andn2_saveexec_b64 s[0:1], s[0:1]
	v_ashrrev_i32_e32 v161, 31, v160
	v_lshlrev_b64 v[162:163], 13, v[160:161]
	v_lshlrev_b64 v[166:167], 11, v[160:161]
	v_lshl_add_u64 v[162:163], s[14:15], 0, v[162:163]
	s_or_b64 exec, exec, s[0:1]
	v_lshl_add_u64 v[164:165], v[162:163], 0, v[144:145]
	v_readlane_b32 s0, v244, 17
	v_readlane_b32 s1, v244, 18
	s_lshl_b64 s[0:1], s[0:1], 2
	s_add_u32 s0, s26, s0
	s_addc_u32 s1, s27, s1
	v_lshl_add_u64 v[162:163], v[166:167], 2, s[14:15]
	v_cmp_eq_u32_e32 vcc, 0, v146
	s_add_u32 s8, s0, 0x10000
	v_lshl_add_u64 v[162:163], v[162:163], 0, v[144:145]
	s_addc_u32 s9, s1, 0
	s_add_u32 s12, s26, 0xc500000
	s_addc_u32 s13, s27, 0
	s_waitcnt vmcnt(0) lgkmcnt(0)
	v_mul_f32_e32 v166, v143, v143
	v_mul_f32_e32 v146, v141, v141
	global_store_dwordx4 v[162:163], v[140:143], off
	v_fmac_f32_e32 v146, v140, v140
	v_fmac_f32_e32 v166, v142, v142
	v_mul_f32_e32 v140, v48, v140
	v_mul_f32_e32 v141, v49, v141
	v_add_f32_e32 v146, v146, v166
	v_cvt_pk_bf16_f32 v166, v140, v141
	v_mul_f32_e32 v140, v50, v142
	v_mul_f32_e32 v141, v51, v143
	v_cvt_pk_bf16_f32 v167, v140, v141
	v_lshlrev_b64 v[140:141], 12, v[160:161]
	v_lshl_add_u64 v[142:143], s[12:13], 0, v[140:141]
	v_lshlrev_b32_e32 v140, 1, v168
	v_mov_b32_e32 v141, v145
	v_lshl_add_u64 v[142:143], v[142:143], 0, v[140:141]
	global_store_dwordx2 v[142:143], v[166:167], off
	s_waitcnt lgkmcnt(0)
	v_mul_f32_e32 v141, v137, v137
	global_store_dwordx4 v[162:163], v[136:139], off offset:64
	v_fmac_f32_e32 v141, v136, v136
	v_mul_f32_e32 v166, v139, v139
	v_mul_f32_e32 v136, v40, v136
	v_mul_f32_e32 v137, v41, v137
	v_cvt_pk_bf16_f32 v136, v136, v137
	v_mul_f32_e32 v137, v42, v138
	v_fmac_f32_e32 v166, v138, v138
	v_mul_f32_e32 v138, v43, v139
	v_cvt_pk_bf16_f32 v137, v137, v138
	global_store_dwordx2 v[142:143], v[136:137], off offset:32
	v_add_f32_e32 v141, v141, v166
	v_add_f32_e32 v141, v146, v141
	s_waitcnt lgkmcnt(0)
	v_mul_f32_e32 v136, v133, v133
	global_store_dwordx4 v[162:163], v[132:135], off offset:512
	v_fmac_f32_e32 v136, v132, v132
	v_mul_f32_e32 v137, v135, v135
	v_mul_f32_e32 v132, v36, v132
	v_mul_f32_e32 v133, v37, v133
	v_cvt_pk_bf16_f32 v132, v132, v133
	v_mul_f32_e32 v133, v38, v134
	v_fmac_f32_e32 v137, v134, v134
	v_mul_f32_e32 v134, v39, v135
	v_cvt_pk_bf16_f32 v133, v133, v134
	global_store_dwordx2 v[142:143], v[132:133], off offset:256
	v_add_f32_e32 v136, v136, v137
	v_add_f32_e32 v136, v141, v136
	s_waitcnt lgkmcnt(0)
	global_store_dwordx4 v[162:163], v[128:131], off offset:576
	v_mul_f32_e32 v133, v29, v129
	v_mul_f32_e32 v132, v28, v128
	v_mul_f32_e32 v129, v129, v129
	v_fmac_f32_e32 v129, v128, v128
	v_mul_f32_e32 v128, v131, v131
	v_cvt_pk_bf16_f32 v132, v132, v133
	v_mul_f32_e32 v133, v30, v130
	v_fmac_f32_e32 v128, v130, v130
	v_and_b32_e32 v130, 64, v182
	v_add_f32_e32 v128, v129, v128
	v_xor_b32_e32 v129, 16, v182
	v_add_u32_e32 v130, 64, v130
	v_cmp_lt_i32_e64 s[0:1], v129, v130
	v_add_f32_e32 v128, v136, v128
	v_mul_f32_e32 v134, v31, v131
	v_cndmask_b32_e64 v129, v182, v129, s[0:1]
	v_lshlrev_b32_e32 v136, 2, v129
	ds_bpermute_b32 v129, v136, v128
	v_cvt_pk_bf16_f32 v133, v133, v134
	global_store_dwordx2 v[142:143], v[132:133], off offset:288
	s_waitcnt lgkmcnt(0)
	v_add_f32_e32 v128, v128, v129
	v_xor_b32_e32 v129, 32, v182
	v_cmp_lt_i32_e64 s[0:1], v129, v130
	s_nop 1
	v_cndmask_b32_e64 v129, v182, v129, s[0:1]
	v_lshlrev_b32_e32 v137, 2, v129
	ds_bpermute_b32 v129, v137, v128
	s_and_saveexec_b64 s[0:1], vcc
	s_cbranch_execz .LBB0_1162
	v_lshl_add_u64 v[130:131], v[160:161], 2, s[8:9]
	s_waitcnt lgkmcnt(0)
	v_add_f32_e32 v128, v128, v129
	global_atomic_add_f32 v[130:131], v128, off
.LBB0_1162:
	s_or_b64 exec, exec, s[0:1]
	s_waitcnt lgkmcnt(0)
	v_or_b32_e32 v128, 16, v160
	v_cmp_lt_i32_e64 s[0:1], s70, v128
	s_and_saveexec_b64 s[2:3], s[0:1]
	s_xor_b64 s[0:1], exec, s[2:3]
	v_add_u32_e32 v130, 0xffffe010, v160
	v_mov_b32_e32 v131, v145
	v_lshlrev_b64 v[130:131], 13, v[130:131]
	v_mov_b32_e32 v129, v145
	v_lshl_add_u64 v[130:131], s[16:17], 0, v[130:131]
	v_lshlrev_b64 v[134:135], 11, v[128:129]
	s_andn2_saveexec_b64 s[0:1], s[0:1]
	v_ashrrev_i32_e32 v129, 31, v128
	v_lshlrev_b64 v[130:131], 13, v[128:129]
	v_lshlrev_b64 v[134:135], 11, v[128:129]
	v_lshl_add_u64 v[130:131], s[14:15], 0, v[130:131]
	s_or_b64 exec, exec, s[0:1]
	v_lshl_add_u64 v[132:133], v[130:131], 0, v[144:145]
	v_lshl_add_u64 v[130:131], v[134:135], 2, s[14:15]
	v_lshl_add_u64 v[130:131], v[130:131], 0, v[144:145]
	v_mov_b32_e32 v141, v145
	s_waitcnt lgkmcnt(0)
	v_mul_f32_e32 v134, v125, v125
	global_store_dwordx4 v[130:131], v[124:127], off
	v_fmac_f32_e32 v134, v124, v124
	v_mul_f32_e32 v135, v127, v127
	v_mul_f32_e32 v124, v48, v124
	v_mul_f32_e32 v125, v49, v125
	v_fmac_f32_e32 v135, v126, v126
	v_cvt_pk_bf16_f32 v124, v124, v125
	v_mul_f32_e32 v125, v50, v126
	v_mul_f32_e32 v126, v51, v127
	v_cvt_pk_bf16_f32 v125, v125, v126
	v_lshlrev_b64 v[126:127], 12, v[128:129]
	v_lshl_add_u64 v[126:127], s[12:13], 0, v[126:127]
	v_add_f32_e32 v138, v134, v135
	v_lshl_add_u64 v[134:135], v[126:127], 0, v[140:141]
	global_store_dwordx2 v[134:135], v[124:125], off
	s_waitcnt lgkmcnt(0)
	v_mul_f32_e32 v124, v121, v121
	global_store_dwordx4 v[130:131], v[120:123], off offset:64
	v_fmac_f32_e32 v124, v120, v120
	v_mul_f32_e32 v125, v123, v123
	v_mul_f32_e32 v120, v40, v120
	v_mul_f32_e32 v121, v41, v121
	v_cvt_pk_bf16_f32 v120, v120, v121
	v_mul_f32_e32 v121, v42, v122
	v_fmac_f32_e32 v125, v122, v122
	v_mul_f32_e32 v122, v43, v123
	v_cvt_pk_bf16_f32 v121, v121, v122
	global_store_dwordx2 v[134:135], v[120:121], off offset:32
	v_add_f32_e32 v124, v124, v125
	v_add_f32_e32 v124, v138, v124
	s_waitcnt lgkmcnt(0)
	v_mul_f32_e32 v120, v117, v117
	global_store_dwordx4 v[130:131], v[116:119], off offset:512
	v_fmac_f32_e32 v120, v116, v116
	v_mul_f32_e32 v121, v119, v119
	v_mul_f32_e32 v116, v36, v116
	v_mul_f32_e32 v117, v37, v117
	v_cvt_pk_bf16_f32 v116, v116, v117
	v_mul_f32_e32 v117, v38, v118
	v_fmac_f32_e32 v121, v118, v118
	v_mul_f32_e32 v118, v39, v119
	v_cvt_pk_bf16_f32 v117, v117, v118
	global_store_dwordx2 v[134:135], v[116:117], off offset:256
	v_add_f32_e32 v120, v120, v121
	v_add_f32_e32 v120, v124, v120
	s_waitcnt lgkmcnt(0)
	global_store_dwordx4 v[130:131], v[112:115], off offset:576
	v_mul_f32_e32 v117, v29, v113
	v_mul_f32_e32 v116, v28, v112
	v_mul_f32_e32 v113, v113, v113
	v_fmac_f32_e32 v113, v112, v112
	v_mul_f32_e32 v112, v115, v115
	v_fmac_f32_e32 v112, v114, v114
	v_add_f32_e32 v112, v113, v112
	v_add_f32_e32 v112, v120, v112
	ds_bpermute_b32 v113, v136, v112
	v_cvt_pk_bf16_f32 v116, v116, v117
	v_mul_f32_e32 v117, v30, v114
	v_mul_f32_e32 v118, v31, v115
	v_cvt_pk_bf16_f32 v117, v117, v118
	s_waitcnt lgkmcnt(0)
	v_add_f32_e32 v112, v112, v113
	ds_bpermute_b32 v113, v137, v112
	global_store_dwordx2 v[134:135], v[116:117], off offset:288
	s_and_saveexec_b64 s[0:1], vcc
	s_cbranch_execz .LBB0_1168
	v_lshl_add_u64 v[114:115], v[128:129], 2, s[8:9]
	s_waitcnt lgkmcnt(0)
	v_add_f32_e32 v112, v112, v113
	global_atomic_add_f32 v[114:115], v112, off
.LBB0_1168:
	s_or_b64 exec, exec, s[0:1]
	s_waitcnt lgkmcnt(0)
	v_or_b32_e32 v112, 32, v160
	v_cmp_lt_i32_e64 s[0:1], s70, v112
	s_and_saveexec_b64 s[2:3], s[0:1]
	s_xor_b64 s[0:1], exec, s[2:3]
	v_add_u32_e32 v114, 0xffffe020, v160
	v_mov_b32_e32 v115, v145
	v_lshlrev_b64 v[114:115], 13, v[114:115]
	v_mov_b32_e32 v113, v145
	v_lshl_add_u64 v[114:115], s[16:17], 0, v[114:115]
	v_lshlrev_b64 v[118:119], 11, v[112:113]
	s_andn2_saveexec_b64 s[0:1], s[0:1]
	v_ashrrev_i32_e32 v113, 31, v112
	v_lshlrev_b64 v[114:115], 13, v[112:113]
	v_lshlrev_b64 v[118:119], 11, v[112:113]
	v_lshl_add_u64 v[114:115], s[14:15], 0, v[114:115]
	s_or_b64 exec, exec, s[0:1]
	v_lshl_add_u64 v[116:117], v[114:115], 0, v[144:145]
	v_lshl_add_u64 v[114:115], v[118:119], 2, s[14:15]
	v_lshl_add_u64 v[114:115], v[114:115], 0, v[144:145]
	v_mov_b32_e32 v141, v145
	s_waitcnt lgkmcnt(0)
	v_mul_f32_e32 v118, v109, v109
	global_store_dwordx4 v[114:115], v[108:111], off
	v_fmac_f32_e32 v118, v108, v108
	v_mul_f32_e32 v119, v111, v111
	v_mul_f32_e32 v108, v48, v108
	v_mul_f32_e32 v109, v49, v109
	v_fmac_f32_e32 v119, v110, v110
	v_cvt_pk_bf16_f32 v108, v108, v109
	v_mul_f32_e32 v109, v50, v110
	v_mul_f32_e32 v110, v51, v111
	v_cvt_pk_bf16_f32 v109, v109, v110
	v_lshlrev_b64 v[110:111], 12, v[112:113]
	v_lshl_add_u64 v[110:111], s[12:13], 0, v[110:111]
	v_add_f32_e32 v120, v118, v119
	v_lshl_add_u64 v[118:119], v[110:111], 0, v[140:141]
	global_store_dwordx2 v[118:119], v[108:109], off
	s_waitcnt lgkmcnt(0)
	v_mul_f32_e32 v108, v105, v105
	global_store_dwordx4 v[114:115], v[104:107], off offset:64
	v_fmac_f32_e32 v108, v104, v104
	v_mul_f32_e32 v109, v107, v107
	v_mul_f32_e32 v104, v40, v104
	v_mul_f32_e32 v105, v41, v105
	v_cvt_pk_bf16_f32 v104, v104, v105
	v_mul_f32_e32 v105, v42, v106
	v_fmac_f32_e32 v109, v106, v106
	v_mul_f32_e32 v106, v43, v107
	v_cvt_pk_bf16_f32 v105, v105, v106
	global_store_dwordx2 v[118:119], v[104:105], off offset:32
	v_add_f32_e32 v108, v108, v109
	v_add_f32_e32 v108, v120, v108
	s_waitcnt lgkmcnt(0)
	v_mul_f32_e32 v104, v101, v101
	global_store_dwordx4 v[114:115], v[100:103], off offset:512
	v_fmac_f32_e32 v104, v100, v100
	v_mul_f32_e32 v105, v103, v103
	v_mul_f32_e32 v100, v36, v100
	v_mul_f32_e32 v101, v37, v101
	v_cvt_pk_bf16_f32 v100, v100, v101
	v_mul_f32_e32 v101, v38, v102
	v_fmac_f32_e32 v105, v102, v102
	v_mul_f32_e32 v102, v39, v103
	v_cvt_pk_bf16_f32 v101, v101, v102
	global_store_dwordx2 v[118:119], v[100:101], off offset:256
	v_add_f32_e32 v104, v104, v105
	v_add_f32_e32 v104, v108, v104
	s_waitcnt lgkmcnt(0)
	global_store_dwordx4 v[114:115], v[96:99], off offset:576
	v_mul_f32_e32 v101, v29, v97
	v_mul_f32_e32 v100, v28, v96
	v_mul_f32_e32 v97, v97, v97
	v_fmac_f32_e32 v97, v96, v96
	v_mul_f32_e32 v96, v99, v99
	v_fmac_f32_e32 v96, v98, v98
	v_add_f32_e32 v96, v97, v96
	v_add_f32_e32 v96, v104, v96
	ds_bpermute_b32 v97, v136, v96
	v_cvt_pk_bf16_f32 v100, v100, v101
	v_mul_f32_e32 v101, v30, v98
	v_mul_f32_e32 v102, v31, v99
	v_cvt_pk_bf16_f32 v101, v101, v102
	s_waitcnt lgkmcnt(0)
	v_add_f32_e32 v96, v96, v97
	ds_bpermute_b32 v97, v137, v96
	global_store_dwordx2 v[118:119], v[100:101], off offset:288
	s_and_saveexec_b64 s[0:1], vcc
	s_cbranch_execz .LBB0_1174
	v_lshl_add_u64 v[98:99], v[112:113], 2, s[8:9]
	s_waitcnt lgkmcnt(0)
	v_add_f32_e32 v96, v96, v97
	global_atomic_add_f32 v[98:99], v96, off
.LBB0_1174:
	s_or_b64 exec, exec, s[0:1]
	s_waitcnt lgkmcnt(0)
	v_or_b32_e32 v96, 48, v160
	v_cmp_lt_i32_e64 s[0:1], s70, v96
	s_and_saveexec_b64 s[2:3], s[0:1]
	s_xor_b64 s[0:1], exec, s[2:3]
	v_add_u32_e32 v98, 0xffffe030, v160
	v_mov_b32_e32 v99, v145
	v_lshlrev_b64 v[98:99], 13, v[98:99]
	v_mov_b32_e32 v97, v145
	v_lshl_add_u64 v[98:99], s[16:17], 0, v[98:99]
	v_lshlrev_b64 v[102:103], 11, v[96:97]
	s_andn2_saveexec_b64 s[0:1], s[0:1]
	v_ashrrev_i32_e32 v97, 31, v96
	v_lshlrev_b64 v[98:99], 13, v[96:97]
	v_lshlrev_b64 v[102:103], 11, v[96:97]
	v_lshl_add_u64 v[98:99], s[14:15], 0, v[98:99]
	s_or_b64 exec, exec, s[0:1]
	v_lshl_add_u64 v[100:101], v[98:99], 0, v[144:145]
	v_lshl_add_u64 v[98:99], v[102:103], 2, s[14:15]
	v_lshl_add_u64 v[98:99], v[98:99], 0, v[144:145]
	v_mov_b32_e32 v141, v145
	s_waitcnt lgkmcnt(0)
	v_mul_f32_e32 v102, v93, v93
	global_store_dwordx4 v[98:99], v[92:95], off
	v_fmac_f32_e32 v102, v92, v92
	v_mul_f32_e32 v103, v95, v95
	v_mul_f32_e32 v92, v48, v92
	v_mul_f32_e32 v93, v49, v93
	v_fmac_f32_e32 v103, v94, v94
	v_cvt_pk_bf16_f32 v92, v92, v93
	v_mul_f32_e32 v93, v50, v94
	v_mul_f32_e32 v94, v51, v95
	v_cvt_pk_bf16_f32 v93, v93, v94
	v_lshlrev_b64 v[94:95], 12, v[96:97]
	v_lshl_add_u64 v[94:95], s[12:13], 0, v[94:95]
	v_add_f32_e32 v104, v102, v103
	v_lshl_add_u64 v[102:103], v[94:95], 0, v[140:141]
	global_store_dwordx2 v[102:103], v[92:93], off
	s_waitcnt lgkmcnt(0)
	v_mul_f32_e32 v92, v89, v89
	global_store_dwordx4 v[98:99], v[88:91], off offset:64
	v_fmac_f32_e32 v92, v88, v88
	v_mul_f32_e32 v93, v91, v91
	v_mul_f32_e32 v88, v40, v88
	v_mul_f32_e32 v89, v41, v89
	v_cvt_pk_bf16_f32 v88, v88, v89
	v_mul_f32_e32 v89, v42, v90
	v_fmac_f32_e32 v93, v90, v90
	v_mul_f32_e32 v90, v43, v91
	v_cvt_pk_bf16_f32 v89, v89, v90
	global_store_dwordx2 v[102:103], v[88:89], off offset:32
	v_add_f32_e32 v92, v92, v93
	v_add_f32_e32 v92, v104, v92
	s_waitcnt lgkmcnt(0)
	v_mul_f32_e32 v88, v85, v85
	global_store_dwordx4 v[98:99], v[84:87], off offset:512
	v_fmac_f32_e32 v88, v84, v84
	v_mul_f32_e32 v89, v87, v87
	v_mul_f32_e32 v84, v36, v84
	v_mul_f32_e32 v85, v37, v85
	v_cvt_pk_bf16_f32 v84, v84, v85
	v_mul_f32_e32 v85, v38, v86
	v_fmac_f32_e32 v89, v86, v86
	v_mul_f32_e32 v86, v39, v87
	v_cvt_pk_bf16_f32 v85, v85, v86
	global_store_dwordx2 v[102:103], v[84:85], off offset:256
	v_add_f32_e32 v88, v88, v89
	v_add_f32_e32 v88, v92, v88
	s_waitcnt lgkmcnt(0)
	global_store_dwordx4 v[98:99], v[80:83], off offset:576
	v_mul_f32_e32 v85, v29, v81
	v_mul_f32_e32 v84, v28, v80
	v_mul_f32_e32 v81, v81, v81
	v_fmac_f32_e32 v81, v80, v80
	v_mul_f32_e32 v80, v83, v83
	v_fmac_f32_e32 v80, v82, v82
	v_add_f32_e32 v80, v81, v80
	v_add_f32_e32 v80, v88, v80
	ds_bpermute_b32 v81, v136, v80
	v_cvt_pk_bf16_f32 v84, v84, v85
	v_mul_f32_e32 v85, v30, v82
	v_mul_f32_e32 v86, v31, v83
	v_cvt_pk_bf16_f32 v85, v85, v86
	s_waitcnt lgkmcnt(0)
	v_add_f32_e32 v80, v80, v81
	ds_bpermute_b32 v81, v137, v80
	global_store_dwordx2 v[102:103], v[84:85], off offset:288
	s_and_saveexec_b64 s[0:1], vcc
	s_cbranch_execz .LBB0_1180
	v_lshl_add_u64 v[82:83], v[96:97], 2, s[8:9]
	s_waitcnt lgkmcnt(0)
	v_add_f32_e32 v80, v80, v81
	global_atomic_add_f32 v[82:83], v80, off
.LBB0_1180:
	s_or_b64 exec, exec, s[0:1]
	s_movk_i32 s0, 0x1f7f
	s_waitcnt lgkmcnt(0)
	v_add_u32_e32 v80, 0x80, v160
	v_cmp_lt_i32_e64 s[0:1], s0, v160
	s_and_saveexec_b64 s[2:3], s[0:1]
	s_xor_b64 s[0:1], exec, s[2:3]
	v_add_u32_e32 v82, 0xffffe080, v160
	v_mov_b32_e32 v83, v145
	v_lshlrev_b64 v[82:83], 13, v[82:83]
	v_mov_b32_e32 v81, v145
	v_lshl_add_u64 v[82:83], s[16:17], 0, v[82:83]
	v_lshlrev_b64 v[86:87], 11, v[80:81]
	s_andn2_saveexec_b64 s[0:1], s[0:1]
	v_ashrrev_i32_e32 v81, 31, v80
	v_lshlrev_b64 v[82:83], 13, v[80:81]
	v_lshlrev_b64 v[86:87], 11, v[80:81]
	v_lshl_add_u64 v[82:83], s[14:15], 0, v[82:83]
	s_or_b64 exec, exec, s[0:1]
	v_lshl_add_u64 v[84:85], v[82:83], 0, v[144:145]
	v_lshl_add_u64 v[82:83], v[86:87], 2, s[14:15]
	v_lshl_add_u64 v[82:83], v[82:83], 0, v[144:145]
	v_mov_b32_e32 v141, v145
	s_waitcnt lgkmcnt(0)
	v_mul_f32_e32 v86, v77, v77
	global_store_dwordx4 v[82:83], v[76:79], off
	v_fmac_f32_e32 v86, v76, v76
	v_mul_f32_e32 v87, v79, v79
	v_mul_f32_e32 v76, v48, v76
	v_mul_f32_e32 v77, v49, v77
	v_fmac_f32_e32 v87, v78, v78
	v_cvt_pk_bf16_f32 v76, v76, v77
	v_mul_f32_e32 v77, v50, v78
	v_mul_f32_e32 v78, v51, v79
	v_cvt_pk_bf16_f32 v77, v77, v78
	v_lshlrev_b64 v[78:79], 12, v[80:81]
	v_lshl_add_u64 v[78:79], s[12:13], 0, v[78:79]
	v_add_f32_e32 v88, v86, v87
	v_lshl_add_u64 v[86:87], v[78:79], 0, v[140:141]
	global_store_dwordx2 v[86:87], v[76:77], off
	s_waitcnt lgkmcnt(0)
	v_mul_f32_e32 v76, v73, v73
	global_store_dwordx4 v[82:83], v[72:75], off offset:64
	v_fmac_f32_e32 v76, v72, v72
	v_mul_f32_e32 v77, v75, v75
	v_mul_f32_e32 v72, v40, v72
	v_mul_f32_e32 v73, v41, v73
	v_cvt_pk_bf16_f32 v72, v72, v73
	v_mul_f32_e32 v73, v42, v74
	v_fmac_f32_e32 v77, v74, v74
	v_mul_f32_e32 v74, v43, v75
	v_cvt_pk_bf16_f32 v73, v73, v74
	global_store_dwordx2 v[86:87], v[72:73], off offset:32
	v_add_f32_e32 v76, v76, v77
	v_add_f32_e32 v76, v88, v76
	s_waitcnt lgkmcnt(0)
	v_mul_f32_e32 v72, v69, v69
	global_store_dwordx4 v[82:83], v[68:71], off offset:512
	v_fmac_f32_e32 v72, v68, v68
	v_mul_f32_e32 v73, v71, v71
	v_mul_f32_e32 v68, v36, v68
	v_mul_f32_e32 v69, v37, v69
	v_cvt_pk_bf16_f32 v68, v68, v69
	v_mul_f32_e32 v69, v38, v70
	v_fmac_f32_e32 v73, v70, v70
	v_mul_f32_e32 v70, v39, v71
	v_cvt_pk_bf16_f32 v69, v69, v70
	global_store_dwordx2 v[86:87], v[68:69], off offset:256
	v_add_f32_e32 v72, v72, v73
	v_add_f32_e32 v72, v76, v72
	s_waitcnt lgkmcnt(0)
	global_store_dwordx4 v[82:83], v[64:67], off offset:576
	v_mul_f32_e32 v69, v29, v65
	v_mul_f32_e32 v68, v28, v64
	v_mul_f32_e32 v65, v65, v65
	v_fmac_f32_e32 v65, v64, v64
	v_mul_f32_e32 v64, v67, v67
	v_fmac_f32_e32 v64, v66, v66
	v_add_f32_e32 v64, v65, v64
	v_add_f32_e32 v64, v72, v64
	ds_bpermute_b32 v65, v136, v64
	v_cvt_pk_bf16_f32 v68, v68, v69
	v_mul_f32_e32 v69, v30, v66
	v_mul_f32_e32 v70, v31, v67
	v_cvt_pk_bf16_f32 v69, v69, v70
	s_waitcnt lgkmcnt(0)
	v_add_f32_e32 v64, v64, v65
	ds_bpermute_b32 v65, v137, v64
	global_store_dwordx2 v[86:87], v[68:69], off offset:288
	s_and_saveexec_b64 s[0:1], vcc
	s_cbranch_execz .LBB0_1186
	v_lshl_add_u64 v[66:67], v[80:81], 2, s[8:9]
	s_waitcnt lgkmcnt(0)
	v_add_f32_e32 v64, v64, v65
	global_atomic_add_f32 v[66:67], v64, off
.LBB0_1186:
	s_or_b64 exec, exec, s[0:1]
	s_movk_i32 s0, 0x1f6f
	s_waitcnt lgkmcnt(0)
	v_add_u32_e32 v64, 0x90, v160
	v_cmp_lt_i32_e64 s[0:1], s0, v160
	s_and_saveexec_b64 s[2:3], s[0:1]
	s_xor_b64 s[0:1], exec, s[2:3]
	v_add_u32_e32 v66, 0xffffe090, v160
	v_mov_b32_e32 v67, v145
	v_lshlrev_b64 v[66:67], 13, v[66:67]
	v_mov_b32_e32 v65, v145
	v_lshl_add_u64 v[66:67], s[16:17], 0, v[66:67]
	v_lshlrev_b64 v[70:71], 11, v[64:65]
	s_andn2_saveexec_b64 s[0:1], s[0:1]
	v_ashrrev_i32_e32 v65, 31, v64
	v_lshlrev_b64 v[66:67], 13, v[64:65]
	v_lshlrev_b64 v[70:71], 11, v[64:65]
	v_lshl_add_u64 v[66:67], s[14:15], 0, v[66:67]
	s_or_b64 exec, exec, s[0:1]
	v_lshl_add_u64 v[68:69], v[66:67], 0, v[144:145]
	v_lshl_add_u64 v[66:67], v[70:71], 2, s[14:15]
	v_lshl_add_u64 v[66:67], v[66:67], 0, v[144:145]
	v_mov_b32_e32 v141, v145
	s_waitcnt lgkmcnt(0)
	v_mul_f32_e32 v70, v61, v61
	global_store_dwordx4 v[66:67], v[60:63], off
	v_fmac_f32_e32 v70, v60, v60
	v_mul_f32_e32 v71, v63, v63
	v_mul_f32_e32 v60, v48, v60
	v_mul_f32_e32 v61, v49, v61
	v_fmac_f32_e32 v71, v62, v62
	v_cvt_pk_bf16_f32 v60, v60, v61
	v_mul_f32_e32 v61, v50, v62
	v_mul_f32_e32 v62, v51, v63
	v_cvt_pk_bf16_f32 v61, v61, v62
	v_lshlrev_b64 v[62:63], 12, v[64:65]
	v_lshl_add_u64 v[62:63], s[12:13], 0, v[62:63]
	v_add_f32_e32 v72, v70, v71
	v_lshl_add_u64 v[70:71], v[62:63], 0, v[140:141]
	global_store_dwordx2 v[70:71], v[60:61], off
	s_waitcnt lgkmcnt(0)
	v_mul_f32_e32 v60, v57, v57
	global_store_dwordx4 v[66:67], v[56:59], off offset:64
	v_fmac_f32_e32 v60, v56, v56
	v_mul_f32_e32 v61, v59, v59
	v_mul_f32_e32 v56, v40, v56
	v_mul_f32_e32 v57, v41, v57
	v_cvt_pk_bf16_f32 v56, v56, v57
	v_mul_f32_e32 v57, v42, v58
	v_fmac_f32_e32 v61, v58, v58
	v_mul_f32_e32 v58, v43, v59
	v_cvt_pk_bf16_f32 v57, v57, v58
	global_store_dwordx2 v[70:71], v[56:57], off offset:32
	v_add_f32_e32 v60, v60, v61
	v_add_f32_e32 v60, v72, v60
	s_waitcnt lgkmcnt(0)
	v_mul_f32_e32 v56, v53, v53
	global_store_dwordx4 v[66:67], v[52:55], off offset:512
	v_fmac_f32_e32 v56, v52, v52
	v_mul_f32_e32 v57, v55, v55
	v_mul_f32_e32 v52, v36, v52
	v_mul_f32_e32 v53, v37, v53
	v_cvt_pk_bf16_f32 v52, v52, v53
	v_mul_f32_e32 v53, v38, v54
	v_fmac_f32_e32 v57, v54, v54
	v_mul_f32_e32 v54, v39, v55
	v_cvt_pk_bf16_f32 v53, v53, v54
	global_store_dwordx2 v[70:71], v[52:53], off offset:256
	v_add_f32_e32 v56, v56, v57
	v_add_f32_e32 v56, v60, v56
	s_waitcnt lgkmcnt(0)
	global_store_dwordx4 v[66:67], v[44:47], off offset:576
	v_mul_f32_e32 v53, v29, v45
	v_mul_f32_e32 v52, v28, v44
	v_mul_f32_e32 v45, v45, v45
	v_fmac_f32_e32 v45, v44, v44
	v_mul_f32_e32 v44, v47, v47
	v_fmac_f32_e32 v44, v46, v46
	v_add_f32_e32 v44, v45, v44
	v_add_f32_e32 v44, v56, v44
	ds_bpermute_b32 v45, v136, v44
	v_cvt_pk_bf16_f32 v52, v52, v53
	v_mul_f32_e32 v53, v30, v46
	v_mul_f32_e32 v54, v31, v47
	v_cvt_pk_bf16_f32 v53, v53, v54
	s_waitcnt lgkmcnt(0)
	v_add_f32_e32 v44, v44, v45
	ds_bpermute_b32 v45, v137, v44
	global_store_dwordx2 v[70:71], v[52:53], off offset:288
	s_and_saveexec_b64 s[0:1], vcc
	s_cbranch_execz .LBB0_1192
	v_lshl_add_u64 v[46:47], v[64:65], 2, s[8:9]
	s_waitcnt lgkmcnt(0)
	v_add_f32_e32 v44, v44, v45
	global_atomic_add_f32 v[46:47], v44, off
.LBB0_1192:
	s_or_b64 exec, exec, s[0:1]
	s_movk_i32 s0, 0x1f5f
	s_waitcnt lgkmcnt(0)
	v_add_u32_e32 v44, 0xa0, v160
	v_cmp_lt_i32_e64 s[0:1], s0, v160
	s_and_saveexec_b64 s[2:3], s[0:1]
	s_xor_b64 s[0:1], exec, s[2:3]
	v_add_u32_e32 v46, 0xffffe0a0, v160
	v_mov_b32_e32 v47, v145
	v_lshlrev_b64 v[46:47], 13, v[46:47]
	v_mov_b32_e32 v45, v145
	v_lshl_add_u64 v[46:47], s[16:17], 0, v[46:47]
	v_lshlrev_b64 v[54:55], 11, v[44:45]
	s_andn2_saveexec_b64 s[0:1], s[0:1]
	v_ashrrev_i32_e32 v45, 31, v44
	v_lshlrev_b64 v[46:47], 13, v[44:45]
	v_lshlrev_b64 v[54:55], 11, v[44:45]
	v_lshl_add_u64 v[46:47], s[14:15], 0, v[46:47]
	s_or_b64 exec, exec, s[0:1]
	v_lshl_add_u64 v[52:53], v[46:47], 0, v[144:145]
	v_lshl_add_u64 v[46:47], v[54:55], 2, s[14:15]
	v_lshl_add_u64 v[46:47], v[46:47], 0, v[144:145]
	v_mov_b32_e32 v141, v145
	s_waitcnt lgkmcnt(0)
	v_mul_f32_e32 v54, v33, v33
	global_store_dwordx4 v[46:47], v[32:35], off
	v_fmac_f32_e32 v54, v32, v32
	v_mul_f32_e32 v55, v35, v35
	v_mul_f32_e32 v32, v48, v32
	v_mul_f32_e32 v33, v49, v33
	v_fmac_f32_e32 v55, v34, v34
	v_cvt_pk_bf16_f32 v32, v32, v33
	v_mul_f32_e32 v33, v50, v34
	v_mul_f32_e32 v34, v51, v35
	v_cvt_pk_bf16_f32 v33, v33, v34
	v_lshlrev_b64 v[34:35], 12, v[44:45]
	v_lshl_add_u64 v[34:35], s[12:13], 0, v[34:35]
	v_add_f32_e32 v56, v54, v55
	v_lshl_add_u64 v[54:55], v[34:35], 0, v[140:141]
	global_store_dwordx2 v[54:55], v[32:33], off
	s_waitcnt lgkmcnt(0)
	v_mul_f32_e32 v32, v25, v25
	global_store_dwordx4 v[46:47], v[24:27], off offset:64
	v_fmac_f32_e32 v32, v24, v24
	v_mul_f32_e32 v33, v27, v27
	v_mul_f32_e32 v24, v40, v24
	v_mul_f32_e32 v25, v41, v25
	v_cvt_pk_bf16_f32 v24, v24, v25
	v_mul_f32_e32 v25, v42, v26
	v_fmac_f32_e32 v33, v26, v26
	v_mul_f32_e32 v26, v43, v27
	v_cvt_pk_bf16_f32 v25, v25, v26
	global_store_dwordx2 v[54:55], v[24:25], off offset:32
	v_add_f32_e32 v32, v32, v33
	v_add_f32_e32 v32, v56, v32
	s_waitcnt lgkmcnt(0)
	v_mul_f32_e32 v24, v21, v21
	global_store_dwordx4 v[46:47], v[20:23], off offset:512
	v_fmac_f32_e32 v24, v20, v20
	v_mul_f32_e32 v25, v23, v23
	v_mul_f32_e32 v20, v36, v20
	v_mul_f32_e32 v21, v37, v21
	v_cvt_pk_bf16_f32 v20, v20, v21
	v_mul_f32_e32 v21, v38, v22
	v_fmac_f32_e32 v25, v22, v22
	v_mul_f32_e32 v22, v39, v23
	v_cvt_pk_bf16_f32 v21, v21, v22
	global_store_dwordx2 v[54:55], v[20:21], off offset:256
	v_add_f32_e32 v24, v24, v25
	v_add_f32_e32 v24, v32, v24
	s_waitcnt lgkmcnt(0)
	global_store_dwordx4 v[46:47], v[16:19], off offset:576
	v_mul_f32_e32 v21, v29, v17
	v_mul_f32_e32 v20, v28, v16
	v_mul_f32_e32 v17, v17, v17
	v_fmac_f32_e32 v17, v16, v16
	v_mul_f32_e32 v16, v19, v19
	v_fmac_f32_e32 v16, v18, v18
	v_add_f32_e32 v16, v17, v16
	v_add_f32_e32 v16, v24, v16
	ds_bpermute_b32 v17, v136, v16
	v_cvt_pk_bf16_f32 v20, v20, v21
	v_mul_f32_e32 v21, v30, v18
	v_mul_f32_e32 v22, v31, v19
	v_cvt_pk_bf16_f32 v21, v21, v22
	s_waitcnt lgkmcnt(0)
	v_add_f32_e32 v16, v16, v17
	ds_bpermute_b32 v17, v137, v16
	global_store_dwordx2 v[54:55], v[20:21], off offset:288
	s_and_saveexec_b64 s[0:1], vcc
	s_cbranch_execz .LBB0_1198
	v_lshl_add_u64 v[18:19], v[44:45], 2, s[8:9]
	s_waitcnt lgkmcnt(0)
	v_add_f32_e32 v16, v16, v17
	global_atomic_add_f32 v[18:19], v16, off
.LBB0_1198:
	s_or_b64 exec, exec, s[0:1]
	s_movk_i32 s0, 0x1f4f
	s_waitcnt lgkmcnt(0)
	v_add_u32_e32 v16, 0xb0, v160
	v_cmp_lt_i32_e64 s[0:1], s0, v160
	s_and_saveexec_b64 s[2:3], s[0:1]
	s_xor_b64 s[0:1], exec, s[2:3]
	v_add_u32_e32 v18, 0xffffe0b0, v160
	v_mov_b32_e32 v19, v145
	v_lshlrev_b64 v[18:19], 13, v[18:19]
	v_mov_b32_e32 v17, v145
	v_lshl_add_u64 v[18:19], s[16:17], 0, v[18:19]
	v_lshlrev_b64 v[22:23], 11, v[16:17]
	s_andn2_saveexec_b64 s[0:1], s[0:1]
	v_ashrrev_i32_e32 v17, 31, v16
	v_lshlrev_b64 v[18:19], 13, v[16:17]
	v_lshlrev_b64 v[22:23], 11, v[16:17]
	v_lshl_add_u64 v[18:19], s[14:15], 0, v[18:19]
	s_or_b64 exec, exec, s[0:1]
	v_lshl_add_u64 v[20:21], v[18:19], 0, v[144:145]
	v_lshl_add_u64 v[18:19], v[22:23], 2, s[14:15]
	v_lshl_add_u64 v[18:19], v[18:19], 0, v[144:145]
	v_mov_b32_e32 v141, v145
	s_waitcnt lgkmcnt(0)
	v_mul_f32_e32 v22, v13, v13
	global_store_dwordx4 v[18:19], v[12:15], off
	v_fmac_f32_e32 v22, v12, v12
	v_mul_f32_e32 v23, v15, v15
	v_mul_f32_e32 v12, v48, v12
	v_mul_f32_e32 v13, v49, v13
	v_fmac_f32_e32 v23, v14, v14
	v_cvt_pk_bf16_f32 v12, v12, v13
	v_mul_f32_e32 v13, v50, v14
	v_mul_f32_e32 v14, v51, v15
	v_cvt_pk_bf16_f32 v13, v13, v14
	v_lshlrev_b64 v[14:15], 12, v[16:17]
	v_lshl_add_u64 v[14:15], s[12:13], 0, v[14:15]
	v_add_f32_e32 v24, v22, v23
	v_lshl_add_u64 v[22:23], v[14:15], 0, v[140:141]
	global_store_dwordx2 v[22:23], v[12:13], off
	s_waitcnt lgkmcnt(0)
	v_mul_f32_e32 v12, v9, v9
	global_store_dwordx4 v[18:19], v[8:11], off offset:64
	v_fmac_f32_e32 v12, v8, v8
	v_mul_f32_e32 v13, v11, v11
	v_mul_f32_e32 v8, v40, v8
	v_mul_f32_e32 v9, v41, v9
	v_cvt_pk_bf16_f32 v8, v8, v9
	v_mul_f32_e32 v9, v42, v10
	v_fmac_f32_e32 v13, v10, v10
	v_mul_f32_e32 v10, v43, v11
	v_cvt_pk_bf16_f32 v9, v9, v10
	global_store_dwordx2 v[22:23], v[8:9], off offset:32
	v_add_f32_e32 v12, v12, v13
	v_add_f32_e32 v12, v24, v12
	s_waitcnt lgkmcnt(0)
	v_mul_f32_e32 v8, v5, v5
	global_store_dwordx4 v[18:19], v[4:7], off offset:512
	v_fmac_f32_e32 v8, v4, v4
	v_mul_f32_e32 v9, v7, v7
	v_mul_f32_e32 v4, v36, v4
	v_mul_f32_e32 v5, v37, v5
	v_cvt_pk_bf16_f32 v4, v4, v5
	v_mul_f32_e32 v5, v38, v6
	v_fmac_f32_e32 v9, v6, v6
	v_mul_f32_e32 v6, v39, v7
	v_cvt_pk_bf16_f32 v5, v5, v6
	global_store_dwordx2 v[22:23], v[4:5], off offset:256
	v_add_f32_e32 v8, v8, v9
	v_add_f32_e32 v8, v12, v8
	s_waitcnt lgkmcnt(0)
	global_store_dwordx4 v[18:19], v[0:3], off offset:576
	v_mul_f32_e32 v5, v29, v1
	v_mul_f32_e32 v4, v28, v0
	v_mul_f32_e32 v1, v1, v1
	v_fmac_f32_e32 v1, v0, v0
	v_mul_f32_e32 v0, v3, v3
	v_fmac_f32_e32 v0, v2, v2
	v_add_f32_e32 v0, v1, v0
	v_add_f32_e32 v0, v8, v0
	ds_bpermute_b32 v1, v136, v0
	v_cvt_pk_bf16_f32 v4, v4, v5
	v_mul_f32_e32 v5, v30, v2
	v_mul_f32_e32 v6, v31, v3
	v_cvt_pk_bf16_f32 v5, v5, v6
	s_waitcnt lgkmcnt(0)
	v_add_f32_e32 v0, v0, v1
	ds_bpermute_b32 v1, v137, v0
	flat_store_dwordx2 v[22:23], v[4:5] offset:288
	s_and_saveexec_b64 s[0:1], vcc
	s_cbranch_execz .LBB0_1204
	v_lshl_add_u64 v[2:3], v[16:17], 2, s[8:9]
	s_waitcnt lgkmcnt(0)
	v_add_f32_e32 v0, v0, v1
	flat_atomic_add_f32 v[2:3], v0

.LBB0_1255:
	s_cmp_le_i32 s46, s6
	s_cselect_b64 s[2:3], -1, 0
	s_and_b64 s[0:1], s[2:3], s[0:1]
	s_andn2_b64 vcc, exec, s[0:1]
	s_cbranch_vccnz .LBB0_1322
	v_readlane_b32 s2, v246, 62
	v_readlane_b32 s64, v246, 0
	v_readlane_b32 s4, v246, 58
	v_mov_b32_e32 v0, s2
	ds_read_b32 v0, v0
	v_readlane_b32 s2, v246, 63
	v_mov_b32_e32 v10, v180
	v_readlane_b32 s5, v246, 59
	s_waitcnt lgkmcnt(0)
	v_readfirstlane_b32 s6, v0
	v_mov_b32_e32 v0, s2
	ds_read_b32 v0, v0
	v_readlane_b32 s2, v245, 0
	s_waitcnt lgkmcnt(0)
	v_readfirstlane_b32 s7, v0
	v_mov_b32_e32 v0, s2
	ds_read_b32 v0, v0
	v_readlane_b32 s2, v245, 1
	s_waitcnt lgkmcnt(0)
	v_readfirstlane_b32 s18, v0
	v_mov_b32_e32 v0, s2
	ds_read_b32 v0, v0
	v_readlane_b32 s2, v245, 2
	s_waitcnt lgkmcnt(0)
	v_readfirstlane_b32 s19, v0
	v_readlane_b32 s2, v245, 3
	s_waitcnt lgkmcnt(0)
	s_nop 0
	v_readlane_b32 s2, v245, 4
	s_waitcnt lgkmcnt(0)
	s_nop 0
	v_readlane_b32 s2, v245, 5
	s_waitcnt lgkmcnt(0)
	s_nop 0
	v_readlane_b32 s2, v245, 6
	s_waitcnt lgkmcnt(0)
	s_nop 0
	v_readlane_b32 s2, v245, 7
	s_waitcnt lgkmcnt(0)
	s_nop 0
	v_readlane_b32 s2, v245, 8
	s_waitcnt lgkmcnt(0)
	s_nop 0
	v_readlane_b32 s2, v245, 9
	s_waitcnt lgkmcnt(0)
	s_nop 0
	v_readlane_b32 s2, v245, 10
	s_waitcnt lgkmcnt(0)
	s_nop 0
	v_readlane_b32 s2, v245, 11
	s_waitcnt lgkmcnt(0)
	s_nop 0
	v_readlane_b32 s2, v245, 12
	s_waitcnt lgkmcnt(0)
	s_nop 0
	v_readlane_b32 s2, v245, 13
	s_waitcnt lgkmcnt(0)
	s_nop 0
	v_readlane_b32 s2, v245, 14
	s_waitcnt lgkmcnt(0)
	s_nop 0
	v_readlane_b32 s2, v245, 15
	s_waitcnt lgkmcnt(0)
	s_nop 0
	v_readlane_b32 s2, v245, 16
	s_waitcnt lgkmcnt(0)
	s_nop 0
	v_readlane_b32 s2, v245, 17
	s_waitcnt lgkmcnt(0)
	s_nop 0
	v_readlane_b32 s2, v245, 18
	s_waitcnt lgkmcnt(0)
	s_nop 0
	v_readlane_b32 s2, v245, 19
	s_waitcnt lgkmcnt(0)
	s_nop 0
	v_readlane_b32 s2, v245, 20
	s_waitcnt lgkmcnt(0)
	s_nop 0
	v_readlane_b32 s2, v245, 21
	s_waitcnt lgkmcnt(0)
	s_nop 0
	v_readlane_b32 s2, v245, 22
	s_waitcnt lgkmcnt(0)
	s_nop 0
	v_readlane_b32 s2, v245, 23
	s_waitcnt lgkmcnt(0)
	s_nop 0
	v_readlane_b32 s2, v245, 24
	s_waitcnt lgkmcnt(0)
	s_nop 0
	v_readlane_b32 s2, v245, 25
	s_waitcnt lgkmcnt(0)
	s_nop 0
	v_readlane_b32 s2, v245, 26
	s_waitcnt lgkmcnt(0)
	s_nop 0
	v_readlane_b32 s2, v245, 27
	s_waitcnt lgkmcnt(0)
	s_nop 0
	v_readlane_b32 s2, v245, 28
	s_waitcnt lgkmcnt(0)
	s_nop 0
	v_readlane_b32 s2, v245, 29
	s_waitcnt lgkmcnt(0)
	s_nop 0
	v_readlane_b32 s2, v245, 30
	s_waitcnt lgkmcnt(0)
	s_nop 0
	v_readlane_b32 s2, v245, 31
	s_waitcnt lgkmcnt(0)
	s_nop 0
	v_readlane_b32 s2, v245, 32
	s_waitcnt lgkmcnt(0)
	s_nop 0
	v_mov_b32_e32 v0, s2
	ds_read_b32 v0, v0
	v_readlane_b32 s2, v245, 33
	s_waitcnt lgkmcnt(0)
	v_readfirstlane_b32 s20, v0
	v_mov_b32_e32 v0, s2
	ds_read_b32 v0, v0
	v_readlane_b32 s2, v245, 34
	s_waitcnt lgkmcnt(0)
	v_readfirstlane_b32 s21, v0
	v_readlane_b32 s2, v245, 35
	s_waitcnt lgkmcnt(0)
	s_nop 0
	v_readlane_b32 s2, v245, 36
	s_waitcnt lgkmcnt(0)
	s_nop 0
	v_readlane_b32 s2, v245, 37
	s_waitcnt lgkmcnt(0)
	s_nop 0
	v_readlane_b32 s2, v245, 38
	s_waitcnt lgkmcnt(0)
	s_nop 0
	v_readlane_b32 s2, v245, 39
	s_waitcnt lgkmcnt(0)
	s_nop 0
	v_readlane_b32 s2, v245, 40
	s_waitcnt lgkmcnt(0)
	s_nop 0
	v_readlane_b32 s2, v245, 41
	s_waitcnt lgkmcnt(0)
	s_nop 0
	v_readlane_b32 s2, v245, 42
	s_waitcnt lgkmcnt(0)
	s_nop 0
	v_readlane_b32 s2, v245, 43
	s_waitcnt lgkmcnt(0)
	s_nop 0
	v_readlane_b32 s2, v245, 44
	s_waitcnt lgkmcnt(0)
	s_nop 0
	v_readlane_b32 s2, v245, 45
	s_waitcnt lgkmcnt(0)
	s_nop 0
	v_readlane_b32 s2, v245, 46
	s_waitcnt lgkmcnt(0)
	s_nop 0
	v_readlane_b32 s2, v245, 47
	s_waitcnt lgkmcnt(0)
	s_nop 0
	v_readlane_b32 s2, v245, 48
	s_waitcnt lgkmcnt(0)
	s_nop 0
	v_readlane_b32 s2, v245, 49
	s_waitcnt lgkmcnt(0)
	s_nop 0
	v_readlane_b32 s2, v245, 50
	s_waitcnt lgkmcnt(0)
	s_nop 0
	v_readlane_b32 s2, v245, 51
	s_waitcnt lgkmcnt(0)
	s_nop 0
	v_readlane_b32 s2, v245, 52
	s_waitcnt lgkmcnt(0)
	s_nop 0
	v_readlane_b32 s2, v245, 53
	s_waitcnt lgkmcnt(0)
	s_nop 0
	v_readlane_b32 s2, v245, 54
	s_waitcnt lgkmcnt(0)
	s_nop 0
	v_readlane_b32 s2, v245, 55
	s_waitcnt lgkmcnt(0)
	s_nop 0
	v_readlane_b32 s2, v245, 56
	s_waitcnt lgkmcnt(0)
	s_nop 0
	v_mov_b32_e32 v0, s2
	ds_read_b32 v0, v0
	v_readlane_b32 s2, v245, 57
	s_waitcnt lgkmcnt(0)
	v_readfirstlane_b32 s25, v0
	v_mov_b32_e32 v0, s2
	ds_read_b32 v0, v0
	s_cmp_lt_i32 s64, s4
	s_cselect_b64 s[2:3], -1, 0
	s_waitcnt lgkmcnt(0)
	v_readfirstlane_b32 s26, v0
	v_readfirstlane_b32 s24, v10
	s_cmp_ge_i32 s64, s4
	s_cbranch_scc1 .LBB0_1258
	s_ashr_i32 s4, s64, 31
	s_lshr_b32 s4, s4, 29
	s_add_i32 s4, s64, s4
	s_ashr_i32 s5, s4, 3
	s_and_b32 s4, s4, -8
	s_sub_i32 s4, s64, s4
	s_lshr_b32 s8, s4, 31
	v_readlane_b32 s9, v246, 57
	s_or_b32 s8, s9, s8
	s_mul_i32 s4, s4, s8
	s_add_i32 s4, s4, s5
	s_ashr_i32 s5, s4, 31
	s_lshr_b32 s5, s5, 26
	s_add_i32 s5, s4, s5
	s_ashr_i32 s8, s5, 6
	s_lshl_b32 s8, s8, 3
	s_sub_i32 s9, s9, s8
	s_min_u32 s9, s9, 8
	s_andn2_b32 s5, s5, 63
	s_sub_i32 s12, s4, s5
	v_cvt_f32_ubyte0_e32 v1, s9
	v_cvt_f32_i32_e32 v0, s12
	v_rcp_iflag_f32_e32 v2, v1
	s_ashr_i32 s4, s12, 30
	s_or_b32 s13, s4, 1
	v_mul_f32_e32 v2, v0, v2
	v_trunc_f32_e32 v2, v2
	v_fma_f32 v0, -v2, v1, v0
	v_cvt_i32_f32_e32 v2, v2
	v_cmp_ge_f32_e64 s[4:5], |v0|, v1
	s_and_b64 s[4:5], s[4:5], exec
	s_cselect_b32 s4, s13, 0
	v_readfirstlane_b32 s5, v2
	s_add_i32 s5, s5, s4
	s_sext_i32_i8 s4, s5
	s_mul_i32 s5, s5, s9
	s_sub_i32 s5, s12, s5
	s_sext_i32_i8 s5, s5
	s_add_i32 s40, s8, s5

.LBB0_1266:
	s_ashr_i32 s29, s28, 31
	s_lshl_b64 s[2:3], s[28:29], 20
	s_add_u32 s30, s65, s2
	s_addc_u32 s31, s68, s3
	s_and_b64 s[2:3], s[38:39], exec
	s_cselect_b32 s6, s31, s55
	s_cselect_b32 s7, s30, s54
	s_ashr_i32 s27, s26, 31
	s_lshl_b64 s[2:3], s[26:27], 20
	s_add_u32 s34, s69, s2
	s_addc_u32 s35, s72, s3
	s_and_b64 s[2:3], s[38:39], exec
	s_cselect_b32 s27, s35, s53
	s_cselect_b32 s29, s34, s52
	s_add_u32 s33, s52, 0x100
	s_addc_u32 s49, s53, 0
	s_add_u32 s52, s54, 0x80080
	v_mov_b32_e32 v0, 0
	s_addc_u32 s53, s55, 0
	s_mov_b32 s51, -2
	v_lshrrev_b32_e32 v0, 8, v180
	v_and_b32_e32 v0, 1, v0
	v_lshlrev_b32_e32 v0, 6, v0
	v_and_b32_e32 v1, 15, v180
	v_or_b32_e32 v0, v0, v1
	v_lshlrev_b32_e32 v0, 13, v0
	v_lshrrev_b32_e32 v1, 6, v180
	v_and_b32_e32 v1, 3, v1
	v_lshl_or_b32 v0, v1, 7, v0
	v_lshrrev_b32_e32 v1, 4, v180
	v_and_b32_e32 v1, 3, v1
	v_lshl_or_b32 v0, v1, 4, v0
	s_cmp_gt_u32 s40, 31
	s_cbranch_scc1 .Lpre_abo_s
	s_lshl_b32 s32, s40, 21
	s_add_u32 s100, s16, s32
	s_addc_u32 s101, s17, 0
	s_branch .Lpre_abo_go
.Lpre_abo_s:
	s_sub_u32 s32, s40, 32
	s_lshl_b32 s32, s32, 21
	s_add_u32 s100, s18, s32
	s_addc_u32 s101, s19, 0
.Lpre_abo_go:
	s_lshl_b32 s32, s4, 10
	s_add_u32 s100, s100, s32
	s_addc_u32 s101, s101, 0
	global_load_dwordx4 v[140:143], v0, s[100:101]
	global_load_dwordx4 v[136:139], v0, s[100:101] offset:64
	global_load_dwordx4 v[132:135], v0, s[100:101] offset:512
	global_load_dwordx4 v[128:131], v0, s[100:101] offset:576
	s_add_u32 s100, s100, 0x20000
	s_addc_u32 s101, s101, 0
	global_load_dwordx4 v[124:127], v0, s[100:101]
	global_load_dwordx4 v[120:123], v0, s[100:101] offset:64
	global_load_dwordx4 v[116:119], v0, s[100:101] offset:512
	global_load_dwordx4 v[112:115], v0, s[100:101] offset:576
	s_add_u32 s100, s100, 0x20000
	s_addc_u32 s101, s101, 0
	global_load_dwordx4 v[108:111], v0, s[100:101]
	global_load_dwordx4 v[104:107], v0, s[100:101] offset:64
	global_load_dwordx4 v[100:103], v0, s[100:101] offset:512
	global_load_dwordx4 v[96:99], v0, s[100:101] offset:576
	s_add_u32 s100, s100, 0x20000
	s_addc_u32 s101, s101, 0
	global_load_dwordx4 v[92:95], v0, s[100:101]
	global_load_dwordx4 v[88:91], v0, s[100:101] offset:64
	global_load_dwordx4 v[84:87], v0, s[100:101] offset:512
	global_load_dwordx4 v[80:83], v0, s[100:101] offset:576
	s_add_u32 s100, s100, 0xa0000
	s_addc_u32 s101, s101, 0
	global_load_dwordx4 v[76:79], v0, s[100:101]
	global_load_dwordx4 v[72:75], v0, s[100:101] offset:64
	global_load_dwordx4 v[68:71], v0, s[100:101] offset:512
	global_load_dwordx4 v[64:67], v0, s[100:101] offset:576
	s_add_u32 s100, s100, 0x20000
	s_addc_u32 s101, s101, 0
	global_load_dwordx4 v[60:63], v0, s[100:101]
	global_load_dwordx4 v[56:59], v0, s[100:101] offset:64
	global_load_dwordx4 v[52:55], v0, s[100:101] offset:512
	global_load_dwordx4 v[44:47], v0, s[100:101] offset:576
	s_add_u32 s100, s100, 0x20000
	s_addc_u32 s101, s101, 0
	global_load_dwordx4 v[32:35], v0, s[100:101]
	global_load_dwordx4 v[24:27], v0, s[100:101] offset:64
	global_load_dwordx4 v[20:23], v0, s[100:101] offset:512
	global_load_dwordx4 v[16:19], v0, s[100:101] offset:576
	s_add_u32 s100, s100, 0x20000
	s_addc_u32 s101, s101, 0
	global_load_dwordx4 v[12:15], v0, s[100:101]
	global_load_dwordx4 v[8:11], v0, s[100:101] offset:64
	global_load_dwordx4 v[4:7], v0, s[100:101] offset:512
	global_load_dwordx4 v[0:3], v0, s[100:101] offset:576
	s_waitcnt vmcnt(0)

.LBB0_1270:
	v_lshl_or_b32 v168, s4, 8, v191
	v_ashrrev_i32_e32 v169, 31, v168
	v_lshl_add_u64 v[28:29], v[168:169], 2, s[22:23]
	global_load_dwordx4 v[48:51], v[28:29], off
	global_load_dwordx4 v[40:43], v[28:29], off offset:64
	global_load_dwordx4 v[36:39], v[28:29], off offset:512
	s_nop 0
	global_load_dwordx4 v[28:31], v[28:29], off offset:576
	v_lshl_add_u32 v170, s40, 8, v146
	v_cmp_lt_i32_e32 vcc, s70, v170
	s_and_saveexec_b64 s[2:3], vcc
	s_xor_b64 s[2:3], exec, s[2:3]
	v_add_u32_e32 v144, 0xffffe000, v170
	v_lshlrev_b64 v[172:173], 13, v[144:145]
	v_mov_b32_e32 v171, v145
	v_lshl_add_u64 v[174:175], s[18:19], 0, v[172:173]
	v_lshlrev_b64 v[178:179], 11, v[170:171]
	s_andn2_saveexec_b64 s[2:3], s[2:3]
	v_ashrrev_i32_e32 v171, 31, v170
	v_lshlrev_b64 v[172:173], 13, v[170:171]
	v_lshlrev_b64 v[178:179], 11, v[170:171]
	v_lshl_add_u64 v[174:175], s[16:17], 0, v[172:173]
	s_or_b64 exec, exec, s[2:3]
	v_lshlrev_b64 v[172:173], 2, v[168:169]
	v_lshl_add_u64 v[176:177], v[174:175], 0, v[172:173]
	v_lshl_add_u64 v[174:175], v[178:179], 2, s[12:13]
	v_lshl_add_u64 v[174:175], v[174:175], 0, v[172:173]
	s_waitcnt vmcnt(0) lgkmcnt(0)
	v_mul_f32_e32 v144, v141, v141
	global_store_dwordx4 v[174:175], v[140:143], off
	v_fmac_f32_e32 v144, v140, v140
	v_mul_f32_e32 v178, v143, v143
	v_mul_f32_e32 v140, v48, v140
	v_mul_f32_e32 v141, v49, v141
	v_fmac_f32_e32 v178, v142, v142
	v_cvt_pk_bf16_f32 v140, v140, v141
	v_mul_f32_e32 v141, v50, v142
	v_mul_f32_e32 v142, v51, v143
	v_cvt_pk_bf16_f32 v141, v141, v142
	v_lshlrev_b64 v[142:143], 12, v[170:171]
	v_lshl_add_u64 v[142:143], s[14:15], 0, v[142:143]
	v_add_f32_e32 v144, v144, v178
	v_lshl_add_u64 v[178:179], v[168:169], 1, v[142:143]
	global_store_dwordx2 v[178:179], v[140:141], off
	s_waitcnt lgkmcnt(0)
	v_mul_f32_e32 v140, v137, v137
	global_store_dwordx4 v[174:175], v[136:139], off offset:64
	v_fmac_f32_e32 v140, v136, v136
	v_mul_f32_e32 v141, v139, v139
	v_mul_f32_e32 v136, v40, v136
	v_mul_f32_e32 v137, v41, v137
	v_cvt_pk_bf16_f32 v136, v136, v137
	v_mul_f32_e32 v137, v42, v138
	v_fmac_f32_e32 v141, v138, v138
	v_mul_f32_e32 v138, v43, v139
	v_cvt_pk_bf16_f32 v137, v137, v138
	global_store_dwordx2 v[178:179], v[136:137], off offset:32
	v_add_f32_e32 v140, v140, v141
	v_add_f32_e32 v140, v144, v140
	s_waitcnt lgkmcnt(0)
	v_mul_f32_e32 v136, v133, v133
	global_store_dwordx4 v[174:175], v[132:135], off offset:512
	v_fmac_f32_e32 v136, v132, v132
	v_mul_f32_e32 v137, v135, v135
	v_mul_f32_e32 v132, v36, v132
	v_mul_f32_e32 v133, v37, v133
	v_cvt_pk_bf16_f32 v132, v132, v133
	v_mul_f32_e32 v133, v38, v134
	v_fmac_f32_e32 v137, v134, v134
	v_mul_f32_e32 v134, v39, v135
	v_cvt_pk_bf16_f32 v133, v133, v134
	global_store_dwordx2 v[178:179], v[132:133], off offset:256
	v_add_f32_e32 v136, v136, v137
	v_add_f32_e32 v136, v140, v136
	s_waitcnt lgkmcnt(0)
	global_store_dwordx4 v[174:175], v[128:131], off offset:576
	v_mul_f32_e32 v133, v29, v129
	v_mul_f32_e32 v132, v28, v128
	v_mul_f32_e32 v129, v129, v129
	v_fmac_f32_e32 v129, v128, v128
	v_mul_f32_e32 v128, v131, v131
	v_cvt_pk_bf16_f32 v132, v132, v133
	v_mul_f32_e32 v133, v30, v130
	v_fmac_f32_e32 v128, v130, v130
	v_and_b32_e32 v130, 64, v182
	v_add_f32_e32 v128, v129, v128
	v_xor_b32_e32 v129, 16, v182
	v_add_u32_e32 v130, 64, v130
	v_cmp_lt_i32_e32 vcc, v129, v130
	v_add_f32_e32 v128, v136, v128
	v_mul_f32_e32 v134, v31, v131
	v_cndmask_b32_e32 v129, v182, v129, vcc
	v_lshlrev_b32_e32 v136, 2, v129
	ds_bpermute_b32 v129, v136, v128
	v_cvt_pk_bf16_f32 v133, v133, v134
	global_store_dwordx2 v[178:179], v[132:133], off offset:288
	s_waitcnt lgkmcnt(0)
	v_add_f32_e32 v128, v128, v129
	v_xor_b32_e32 v129, 32, v182
	v_cmp_lt_i32_e32 vcc, v129, v130
	s_nop 1
	v_cndmask_b32_e32 v129, v182, v129, vcc
	v_lshlrev_b32_e32 v137, 2, v129
	ds_bpermute_b32 v129, v137, v128
	s_and_saveexec_b64 s[2:3], s[36:37]
	s_mov_b32 s88, 0x91a2b3c5
	s_cbranch_execz .LBB0_1276
	v_lshl_add_u64 v[130:131], v[170:171], 2, s[20:21]
	s_waitcnt lgkmcnt(0)
	v_add_f32_e32 v128, v128, v129
	global_atomic_add_f32 v[130:131], v128, off
.LBB0_1276:
	s_or_b64 exec, exec, s[2:3]
	s_waitcnt lgkmcnt(0)
	v_or_b32_e32 v128, 16, v170
	v_cmp_lt_i32_e32 vcc, s70, v128
	s_and_saveexec_b64 s[2:3], vcc
	s_xor_b64 s[2:3], exec, s[2:3]
	v_add_u32_e32 v144, 0xffffe010, v170
	v_lshlrev_b64 v[130:131], 13, v[144:145]
	v_mov_b32_e32 v129, v145
	v_lshl_add_u64 v[130:131], s[18:19], 0, v[130:131]
	v_lshlrev_b64 v[134:135], 11, v[128:129]
	s_andn2_saveexec_b64 s[2:3], s[2:3]
	v_ashrrev_i32_e32 v129, 31, v128
	v_lshlrev_b64 v[130:131], 13, v[128:129]
	v_lshlrev_b64 v[134:135], 11, v[128:129]
	v_lshl_add_u64 v[130:131], s[16:17], 0, v[130:131]
	s_or_b64 exec, exec, s[2:3]
	v_lshl_add_u64 v[132:133], v[130:131], 0, v[172:173]
	v_lshl_add_u64 v[130:131], v[134:135], 2, s[12:13]
	v_lshl_add_u64 v[130:131], v[130:131], 0, v[172:173]
	s_waitcnt lgkmcnt(0)
	v_mul_f32_e32 v134, v125, v125
	global_store_dwordx4 v[130:131], v[124:127], off
	v_fmac_f32_e32 v134, v124, v124
	v_mul_f32_e32 v135, v127, v127
	v_mul_f32_e32 v124, v48, v124
	v_mul_f32_e32 v125, v49, v125
	v_fmac_f32_e32 v135, v126, v126
	v_cvt_pk_bf16_f32 v124, v124, v125
	v_mul_f32_e32 v125, v50, v126
	v_mul_f32_e32 v126, v51, v127
	v_cvt_pk_bf16_f32 v125, v125, v126
	v_lshlrev_b64 v[126:127], 12, v[128:129]
	v_lshl_add_u64 v[126:127], s[14:15], 0, v[126:127]
	v_add_f32_e32 v138, v134, v135
	v_lshl_add_u64 v[134:135], v[168:169], 1, v[126:127]
	global_store_dwordx2 v[134:135], v[124:125], off
	s_waitcnt lgkmcnt(0)
	v_mul_f32_e32 v124, v121, v121
	global_store_dwordx4 v[130:131], v[120:123], off offset:64
	v_fmac_f32_e32 v124, v120, v120
	v_mul_f32_e32 v125, v123, v123
	v_mul_f32_e32 v120, v40, v120
	v_mul_f32_e32 v121, v41, v121
	v_cvt_pk_bf16_f32 v120, v120, v121
	v_mul_f32_e32 v121, v42, v122
	v_fmac_f32_e32 v125, v122, v122
	v_mul_f32_e32 v122, v43, v123
	v_cvt_pk_bf16_f32 v121, v121, v122
	global_store_dwordx2 v[134:135], v[120:121], off offset:32
	v_add_f32_e32 v124, v124, v125
	v_add_f32_e32 v124, v138, v124
	s_waitcnt lgkmcnt(0)
	v_mul_f32_e32 v120, v117, v117
	global_store_dwordx4 v[130:131], v[116:119], off offset:512
	v_fmac_f32_e32 v120, v116, v116
	v_mul_f32_e32 v121, v119, v119
	v_mul_f32_e32 v116, v36, v116
	v_mul_f32_e32 v117, v37, v117
	v_cvt_pk_bf16_f32 v116, v116, v117
	v_mul_f32_e32 v117, v38, v118
	v_fmac_f32_e32 v121, v118, v118
	v_mul_f32_e32 v118, v39, v119
	v_cvt_pk_bf16_f32 v117, v117, v118
	global_store_dwordx2 v[134:135], v[116:117], off offset:256
	v_add_f32_e32 v120, v120, v121
	v_add_f32_e32 v120, v124, v120
	s_waitcnt lgkmcnt(0)
	global_store_dwordx4 v[130:131], v[112:115], off offset:576
	v_mul_f32_e32 v117, v29, v113
	v_mul_f32_e32 v116, v28, v112
	v_mul_f32_e32 v113, v113, v113
	v_fmac_f32_e32 v113, v112, v112
	v_mul_f32_e32 v112, v115, v115
	v_fmac_f32_e32 v112, v114, v114
	v_add_f32_e32 v112, v113, v112
	v_add_f32_e32 v112, v120, v112
	ds_bpermute_b32 v113, v136, v112
	v_cvt_pk_bf16_f32 v116, v116, v117
	v_mul_f32_e32 v117, v30, v114
	v_mul_f32_e32 v118, v31, v115
	v_cvt_pk_bf16_f32 v117, v117, v118
	s_waitcnt lgkmcnt(0)
	v_add_f32_e32 v112, v112, v113
	ds_bpermute_b32 v113, v137, v112
	global_store_dwordx2 v[134:135], v[116:117], off offset:288
	s_and_saveexec_b64 s[2:3], s[36:37]
	s_cbranch_execz .LBB0_1282
	v_lshl_add_u64 v[114:115], v[128:129], 2, s[20:21]
	s_waitcnt lgkmcnt(0)
	v_add_f32_e32 v112, v112, v113
	global_atomic_add_f32 v[114:115], v112, off
.LBB0_1282:
	s_or_b64 exec, exec, s[2:3]
	s_waitcnt lgkmcnt(0)
	v_or_b32_e32 v112, 32, v170
	v_cmp_lt_i32_e32 vcc, s70, v112
	s_and_saveexec_b64 s[2:3], vcc
	s_xor_b64 s[2:3], exec, s[2:3]
	v_add_u32_e32 v144, 0xffffe020, v170
	v_lshlrev_b64 v[114:115], 13, v[144:145]
	v_mov_b32_e32 v113, v145
	v_lshl_add_u64 v[114:115], s[18:19], 0, v[114:115]
	v_lshlrev_b64 v[118:119], 11, v[112:113]
	s_andn2_saveexec_b64 s[2:3], s[2:3]
	v_ashrrev_i32_e32 v113, 31, v112
	v_lshlrev_b64 v[114:115], 13, v[112:113]
	v_lshlrev_b64 v[118:119], 11, v[112:113]
	v_lshl_add_u64 v[114:115], s[16:17], 0, v[114:115]
	s_or_b64 exec, exec, s[2:3]
	v_lshl_add_u64 v[116:117], v[114:115], 0, v[172:173]
	v_lshl_add_u64 v[114:115], v[118:119], 2, s[12:13]
	v_lshl_add_u64 v[114:115], v[114:115], 0, v[172:173]
	s_waitcnt lgkmcnt(0)
	v_mul_f32_e32 v118, v109, v109
	global_store_dwordx4 v[114:115], v[108:111], off
	v_fmac_f32_e32 v118, v108, v108
	v_mul_f32_e32 v119, v111, v111
	v_mul_f32_e32 v108, v48, v108
	v_mul_f32_e32 v109, v49, v109
	v_fmac_f32_e32 v119, v110, v110
	v_cvt_pk_bf16_f32 v108, v108, v109
	v_mul_f32_e32 v109, v50, v110
	v_mul_f32_e32 v110, v51, v111
	v_cvt_pk_bf16_f32 v109, v109, v110
	v_lshlrev_b64 v[110:111], 12, v[112:113]
	v_lshl_add_u64 v[110:111], s[14:15], 0, v[110:111]
	v_add_f32_e32 v120, v118, v119
	v_lshl_add_u64 v[118:119], v[168:169], 1, v[110:111]
	global_store_dwordx2 v[118:119], v[108:109], off
	s_waitcnt lgkmcnt(0)
	v_mul_f32_e32 v108, v105, v105
	global_store_dwordx4 v[114:115], v[104:107], off offset:64
	v_fmac_f32_e32 v108, v104, v104
	v_mul_f32_e32 v109, v107, v107
	v_mul_f32_e32 v104, v40, v104
	v_mul_f32_e32 v105, v41, v105
	v_cvt_pk_bf16_f32 v104, v104, v105
	v_mul_f32_e32 v105, v42, v106
	v_fmac_f32_e32 v109, v106, v106
	v_mul_f32_e32 v106, v43, v107
	v_cvt_pk_bf16_f32 v105, v105, v106
	global_store_dwordx2 v[118:119], v[104:105], off offset:32
	v_add_f32_e32 v108, v108, v109
	v_add_f32_e32 v108, v120, v108
	s_waitcnt lgkmcnt(0)
	v_mul_f32_e32 v104, v101, v101
	global_store_dwordx4 v[114:115], v[100:103], off offset:512
	v_fmac_f32_e32 v104, v100, v100
	v_mul_f32_e32 v105, v103, v103
	v_mul_f32_e32 v100, v36, v100
	v_mul_f32_e32 v101, v37, v101
	v_cvt_pk_bf16_f32 v100, v100, v101
	v_mul_f32_e32 v101, v38, v102
	v_fmac_f32_e32 v105, v102, v102
	v_mul_f32_e32 v102, v39, v103
	v_cvt_pk_bf16_f32 v101, v101, v102
	global_store_dwordx2 v[118:119], v[100:101], off offset:256
	v_add_f32_e32 v104, v104, v105
	v_add_f32_e32 v104, v108, v104
	s_waitcnt lgkmcnt(0)
	global_store_dwordx4 v[114:115], v[96:99], off offset:576
	v_mul_f32_e32 v101, v29, v97
	v_mul_f32_e32 v100, v28, v96
	v_mul_f32_e32 v97, v97, v97
	v_fmac_f32_e32 v97, v96, v96
	v_mul_f32_e32 v96, v99, v99
	v_fmac_f32_e32 v96, v98, v98
	v_add_f32_e32 v96, v97, v96
	v_add_f32_e32 v96, v104, v96
	ds_bpermute_b32 v97, v136, v96
	v_cvt_pk_bf16_f32 v100, v100, v101
	v_mul_f32_e32 v101, v30, v98
	v_mul_f32_e32 v102, v31, v99
	v_cvt_pk_bf16_f32 v101, v101, v102
	s_waitcnt lgkmcnt(0)
	v_add_f32_e32 v96, v96, v97
	ds_bpermute_b32 v97, v137, v96
	global_store_dwordx2 v[118:119], v[100:101], off offset:288
	s_and_saveexec_b64 s[2:3], s[36:37]
	s_cbranch_execz .LBB0_1288
	v_lshl_add_u64 v[98:99], v[112:113], 2, s[20:21]
	s_waitcnt lgkmcnt(0)
	v_add_f32_e32 v96, v96, v97
	global_atomic_add_f32 v[98:99], v96, off
.LBB0_1288:
	s_or_b64 exec, exec, s[2:3]
	s_waitcnt lgkmcnt(0)
	v_or_b32_e32 v96, 48, v170
	v_cmp_lt_i32_e32 vcc, s70, v96
	s_and_saveexec_b64 s[2:3], vcc
	s_xor_b64 s[2:3], exec, s[2:3]
	v_add_u32_e32 v144, 0xffffe030, v170
	v_lshlrev_b64 v[98:99], 13, v[144:145]
	v_mov_b32_e32 v97, v145
	v_lshl_add_u64 v[98:99], s[18:19], 0, v[98:99]
	v_lshlrev_b64 v[102:103], 11, v[96:97]
	s_andn2_saveexec_b64 s[2:3], s[2:3]
	v_ashrrev_i32_e32 v97, 31, v96
	v_lshlrev_b64 v[98:99], 13, v[96:97]
	v_lshlrev_b64 v[102:103], 11, v[96:97]
	v_lshl_add_u64 v[98:99], s[16:17], 0, v[98:99]
	s_or_b64 exec, exec, s[2:3]
	v_lshl_add_u64 v[100:101], v[98:99], 0, v[172:173]
	v_lshl_add_u64 v[98:99], v[102:103], 2, s[12:13]
	v_lshl_add_u64 v[98:99], v[98:99], 0, v[172:173]
	s_waitcnt lgkmcnt(0)
	v_mul_f32_e32 v102, v93, v93
	global_store_dwordx4 v[98:99], v[92:95], off
	v_fmac_f32_e32 v102, v92, v92
	v_mul_f32_e32 v103, v95, v95
	v_mul_f32_e32 v92, v48, v92
	v_mul_f32_e32 v93, v49, v93
	v_fmac_f32_e32 v103, v94, v94
	v_cvt_pk_bf16_f32 v92, v92, v93
	v_mul_f32_e32 v93, v50, v94
	v_mul_f32_e32 v94, v51, v95
	v_cvt_pk_bf16_f32 v93, v93, v94
	v_lshlrev_b64 v[94:95], 12, v[96:97]
	v_lshl_add_u64 v[94:95], s[14:15], 0, v[94:95]
	v_add_f32_e32 v104, v102, v103
	v_lshl_add_u64 v[102:103], v[168:169], 1, v[94:95]
	global_store_dwordx2 v[102:103], v[92:93], off
	s_waitcnt lgkmcnt(0)
	v_mul_f32_e32 v92, v89, v89
	global_store_dwordx4 v[98:99], v[88:91], off offset:64
	v_fmac_f32_e32 v92, v88, v88
	v_mul_f32_e32 v93, v91, v91
	v_mul_f32_e32 v88, v40, v88
	v_mul_f32_e32 v89, v41, v89
	v_cvt_pk_bf16_f32 v88, v88, v89
	v_mul_f32_e32 v89, v42, v90
	v_fmac_f32_e32 v93, v90, v90
	v_mul_f32_e32 v90, v43, v91
	v_cvt_pk_bf16_f32 v89, v89, v90
	global_store_dwordx2 v[102:103], v[88:89], off offset:32
	v_add_f32_e32 v92, v92, v93
	v_add_f32_e32 v92, v104, v92
	s_waitcnt lgkmcnt(0)
	v_mul_f32_e32 v88, v85, v85
	global_store_dwordx4 v[98:99], v[84:87], off offset:512
	v_fmac_f32_e32 v88, v84, v84
	v_mul_f32_e32 v89, v87, v87
	v_mul_f32_e32 v84, v36, v84
	v_mul_f32_e32 v85, v37, v85
	v_cvt_pk_bf16_f32 v84, v84, v85
	v_mul_f32_e32 v85, v38, v86
	v_fmac_f32_e32 v89, v86, v86
	v_mul_f32_e32 v86, v39, v87
	v_cvt_pk_bf16_f32 v85, v85, v86
	global_store_dwordx2 v[102:103], v[84:85], off offset:256
	v_add_f32_e32 v88, v88, v89
	v_add_f32_e32 v88, v92, v88
	s_waitcnt lgkmcnt(0)
	global_store_dwordx4 v[98:99], v[80:83], off offset:576
	v_mul_f32_e32 v85, v29, v81
	v_mul_f32_e32 v84, v28, v80
	v_mul_f32_e32 v81, v81, v81
	v_fmac_f32_e32 v81, v80, v80
	v_mul_f32_e32 v80, v83, v83
	v_fmac_f32_e32 v80, v82, v82
	v_add_f32_e32 v80, v81, v80
	v_add_f32_e32 v80, v88, v80
	ds_bpermute_b32 v81, v136, v80
	v_cvt_pk_bf16_f32 v84, v84, v85
	v_mul_f32_e32 v85, v30, v82
	v_mul_f32_e32 v86, v31, v83
	v_cvt_pk_bf16_f32 v85, v85, v86
	s_waitcnt lgkmcnt(0)
	v_add_f32_e32 v80, v80, v81
	ds_bpermute_b32 v81, v137, v80
	global_store_dwordx2 v[102:103], v[84:85], off offset:288
	s_and_saveexec_b64 s[2:3], s[36:37]
	s_cbranch_execz .LBB0_1294
	v_lshl_add_u64 v[82:83], v[96:97], 2, s[20:21]
	s_waitcnt lgkmcnt(0)
	v_add_f32_e32 v80, v80, v81
	global_atomic_add_f32 v[82:83], v80, off
.LBB0_1294:
	s_or_b64 exec, exec, s[2:3]
	s_movk_i32 s2, 0x1f7f
	s_waitcnt lgkmcnt(0)
	v_add_u32_e32 v80, 0x80, v170
	v_cmp_lt_i32_e32 vcc, s2, v170
	s_and_saveexec_b64 s[2:3], vcc
	s_xor_b64 s[2:3], exec, s[2:3]
	v_add_u32_e32 v144, 0xffffe080, v170
	v_lshlrev_b64 v[82:83], 13, v[144:145]
	v_mov_b32_e32 v81, v145
	v_lshl_add_u64 v[82:83], s[18:19], 0, v[82:83]
	v_lshlrev_b64 v[86:87], 11, v[80:81]
	s_andn2_saveexec_b64 s[2:3], s[2:3]
	v_ashrrev_i32_e32 v81, 31, v80
	v_lshlrev_b64 v[82:83], 13, v[80:81]
	v_lshlrev_b64 v[86:87], 11, v[80:81]
	v_lshl_add_u64 v[82:83], s[16:17], 0, v[82:83]
	s_or_b64 exec, exec, s[2:3]
	v_lshl_add_u64 v[84:85], v[82:83], 0, v[172:173]
	v_lshl_add_u64 v[82:83], v[86:87], 2, s[12:13]
	v_lshl_add_u64 v[82:83], v[82:83], 0, v[172:173]
	s_waitcnt lgkmcnt(0)
	v_mul_f32_e32 v86, v77, v77
	global_store_dwordx4 v[82:83], v[76:79], off
	v_fmac_f32_e32 v86, v76, v76
	v_mul_f32_e32 v87, v79, v79
	v_mul_f32_e32 v76, v48, v76
	v_mul_f32_e32 v77, v49, v77
	v_fmac_f32_e32 v87, v78, v78
	v_cvt_pk_bf16_f32 v76, v76, v77
	v_mul_f32_e32 v77, v50, v78
	v_mul_f32_e32 v78, v51, v79
	v_cvt_pk_bf16_f32 v77, v77, v78
	v_lshlrev_b64 v[78:79], 12, v[80:81]
	v_lshl_add_u64 v[78:79], s[14:15], 0, v[78:79]
	v_add_f32_e32 v88, v86, v87
	v_lshl_add_u64 v[86:87], v[168:169], 1, v[78:79]
	global_store_dwordx2 v[86:87], v[76:77], off
	s_waitcnt lgkmcnt(0)
	v_mul_f32_e32 v76, v73, v73
	global_store_dwordx4 v[82:83], v[72:75], off offset:64
	v_fmac_f32_e32 v76, v72, v72
	v_mul_f32_e32 v77, v75, v75
	v_mul_f32_e32 v72, v40, v72
	v_mul_f32_e32 v73, v41, v73
	v_cvt_pk_bf16_f32 v72, v72, v73
	v_mul_f32_e32 v73, v42, v74
	v_fmac_f32_e32 v77, v74, v74
	v_mul_f32_e32 v74, v43, v75
	v_cvt_pk_bf16_f32 v73, v73, v74
	global_store_dwordx2 v[86:87], v[72:73], off offset:32
	v_add_f32_e32 v76, v76, v77
	v_add_f32_e32 v76, v88, v76
	s_waitcnt lgkmcnt(0)
	v_mul_f32_e32 v72, v69, v69
	global_store_dwordx4 v[82:83], v[68:71], off offset:512
	v_fmac_f32_e32 v72, v68, v68
	v_mul_f32_e32 v73, v71, v71
	v_mul_f32_e32 v68, v36, v68
	v_mul_f32_e32 v69, v37, v69
	v_cvt_pk_bf16_f32 v68, v68, v69
	v_mul_f32_e32 v69, v38, v70
	v_fmac_f32_e32 v73, v70, v70
	v_mul_f32_e32 v70, v39, v71
	v_cvt_pk_bf16_f32 v69, v69, v70
	global_store_dwordx2 v[86:87], v[68:69], off offset:256
	v_add_f32_e32 v72, v72, v73
	v_add_f32_e32 v72, v76, v72
	s_waitcnt lgkmcnt(0)
	global_store_dwordx4 v[82:83], v[64:67], off offset:576
	v_mul_f32_e32 v69, v29, v65
	v_mul_f32_e32 v68, v28, v64
	v_mul_f32_e32 v65, v65, v65
	v_fmac_f32_e32 v65, v64, v64
	v_mul_f32_e32 v64, v67, v67
	v_fmac_f32_e32 v64, v66, v66
	v_add_f32_e32 v64, v65, v64
	v_add_f32_e32 v64, v72, v64
	ds_bpermute_b32 v65, v136, v64
	v_cvt_pk_bf16_f32 v68, v68, v69
	v_mul_f32_e32 v69, v30, v66
	v_mul_f32_e32 v70, v31, v67
	v_cvt_pk_bf16_f32 v69, v69, v70
	s_waitcnt lgkmcnt(0)
	v_add_f32_e32 v64, v64, v65
	ds_bpermute_b32 v65, v137, v64
	global_store_dwordx2 v[86:87], v[68:69], off offset:288
	s_and_saveexec_b64 s[2:3], s[36:37]
	s_cbranch_execz .LBB0_1300
	v_lshl_add_u64 v[66:67], v[80:81], 2, s[20:21]
	s_waitcnt lgkmcnt(0)
	v_add_f32_e32 v64, v64, v65
	global_atomic_add_f32 v[66:67], v64, off
.LBB0_1300:
	s_or_b64 exec, exec, s[2:3]
	s_movk_i32 s2, 0x1f6f
	s_waitcnt lgkmcnt(0)
	v_add_u32_e32 v64, 0x90, v170
	v_cmp_lt_i32_e32 vcc, s2, v170
	s_and_saveexec_b64 s[2:3], vcc
	s_xor_b64 s[2:3], exec, s[2:3]
	v_add_u32_e32 v144, 0xffffe090, v170
	v_lshlrev_b64 v[66:67], 13, v[144:145]
	v_mov_b32_e32 v65, v145
	v_lshl_add_u64 v[66:67], s[18:19], 0, v[66:67]
	v_lshlrev_b64 v[70:71], 11, v[64:65]
	s_andn2_saveexec_b64 s[2:3], s[2:3]
	v_ashrrev_i32_e32 v65, 31, v64
	v_lshlrev_b64 v[66:67], 13, v[64:65]
	v_lshlrev_b64 v[70:71], 11, v[64:65]
	v_lshl_add_u64 v[66:67], s[16:17], 0, v[66:67]
	s_or_b64 exec, exec, s[2:3]
	v_lshl_add_u64 v[68:69], v[66:67], 0, v[172:173]
	v_lshl_add_u64 v[66:67], v[70:71], 2, s[12:13]
	v_lshl_add_u64 v[66:67], v[66:67], 0, v[172:173]
	s_waitcnt lgkmcnt(0)
	v_mul_f32_e32 v70, v61, v61
	global_store_dwordx4 v[66:67], v[60:63], off
	v_fmac_f32_e32 v70, v60, v60
	v_mul_f32_e32 v71, v63, v63
	v_mul_f32_e32 v60, v48, v60
	v_mul_f32_e32 v61, v49, v61
	v_fmac_f32_e32 v71, v62, v62
	v_cvt_pk_bf16_f32 v60, v60, v61
	v_mul_f32_e32 v61, v50, v62
	v_mul_f32_e32 v62, v51, v63
	v_cvt_pk_bf16_f32 v61, v61, v62
	v_lshlrev_b64 v[62:63], 12, v[64:65]
	v_lshl_add_u64 v[62:63], s[14:15], 0, v[62:63]
	v_add_f32_e32 v72, v70, v71
	v_lshl_add_u64 v[70:71], v[168:169], 1, v[62:63]
	global_store_dwordx2 v[70:71], v[60:61], off
	s_waitcnt lgkmcnt(0)
	v_mul_f32_e32 v60, v57, v57
	global_store_dwordx4 v[66:67], v[56:59], off offset:64
	v_fmac_f32_e32 v60, v56, v56
	v_mul_f32_e32 v61, v59, v59
	v_mul_f32_e32 v56, v40, v56
	v_mul_f32_e32 v57, v41, v57
	v_cvt_pk_bf16_f32 v56, v56, v57
	v_mul_f32_e32 v57, v42, v58
	v_fmac_f32_e32 v61, v58, v58
	v_mul_f32_e32 v58, v43, v59
	v_cvt_pk_bf16_f32 v57, v57, v58
	global_store_dwordx2 v[70:71], v[56:57], off offset:32
	v_add_f32_e32 v60, v60, v61
	v_add_f32_e32 v60, v72, v60
	s_waitcnt lgkmcnt(0)
	v_mul_f32_e32 v56, v53, v53
	global_store_dwordx4 v[66:67], v[52:55], off offset:512
	v_fmac_f32_e32 v56, v52, v52
	v_mul_f32_e32 v57, v55, v55
	v_mul_f32_e32 v52, v36, v52
	v_mul_f32_e32 v53, v37, v53
	v_cvt_pk_bf16_f32 v52, v52, v53
	v_mul_f32_e32 v53, v38, v54
	v_fmac_f32_e32 v57, v54, v54
	v_mul_f32_e32 v54, v39, v55
	v_cvt_pk_bf16_f32 v53, v53, v54
	global_store_dwordx2 v[70:71], v[52:53], off offset:256
	v_add_f32_e32 v56, v56, v57
	v_add_f32_e32 v56, v60, v56
	s_waitcnt lgkmcnt(0)
	global_store_dwordx4 v[66:67], v[44:47], off offset:576
	v_mul_f32_e32 v53, v29, v45
	v_mul_f32_e32 v52, v28, v44
	v_mul_f32_e32 v45, v45, v45
	v_fmac_f32_e32 v45, v44, v44
	v_mul_f32_e32 v44, v47, v47
	v_fmac_f32_e32 v44, v46, v46
	v_add_f32_e32 v44, v45, v44
	v_add_f32_e32 v44, v56, v44
	ds_bpermute_b32 v45, v136, v44
	v_cvt_pk_bf16_f32 v52, v52, v53
	v_mul_f32_e32 v53, v30, v46
	v_mul_f32_e32 v54, v31, v47
	v_cvt_pk_bf16_f32 v53, v53, v54
	s_waitcnt lgkmcnt(0)
	v_add_f32_e32 v44, v44, v45
	ds_bpermute_b32 v45, v137, v44
	global_store_dwordx2 v[70:71], v[52:53], off offset:288
	s_and_saveexec_b64 s[2:3], s[36:37]
	s_cbranch_execz .LBB0_1306
	v_lshl_add_u64 v[46:47], v[64:65], 2, s[20:21]
	s_waitcnt lgkmcnt(0)
	v_add_f32_e32 v44, v44, v45
	global_atomic_add_f32 v[46:47], v44, off
.LBB0_1306:
	s_or_b64 exec, exec, s[2:3]
	s_movk_i32 s2, 0x1f5f
	s_waitcnt lgkmcnt(0)
	v_add_u32_e32 v44, 0xa0, v170
	v_cmp_lt_i32_e32 vcc, s2, v170
	s_and_saveexec_b64 s[2:3], vcc
	s_xor_b64 s[2:3], exec, s[2:3]
	v_add_u32_e32 v144, 0xffffe0a0, v170
	v_lshlrev_b64 v[46:47], 13, v[144:145]
	v_mov_b32_e32 v45, v145
	v_lshl_add_u64 v[46:47], s[18:19], 0, v[46:47]
	v_lshlrev_b64 v[54:55], 11, v[44:45]
	s_andn2_saveexec_b64 s[2:3], s[2:3]
	v_ashrrev_i32_e32 v45, 31, v44
	v_lshlrev_b64 v[46:47], 13, v[44:45]
	v_lshlrev_b64 v[54:55], 11, v[44:45]
	v_lshl_add_u64 v[46:47], s[16:17], 0, v[46:47]
	s_or_b64 exec, exec, s[2:3]
	v_lshl_add_u64 v[52:53], v[46:47], 0, v[172:173]
	v_lshl_add_u64 v[46:47], v[54:55], 2, s[12:13]
	v_lshl_add_u64 v[46:47], v[46:47], 0, v[172:173]
	s_waitcnt lgkmcnt(0)
	v_mul_f32_e32 v54, v33, v33
	global_store_dwordx4 v[46:47], v[32:35], off
	v_fmac_f32_e32 v54, v32, v32
	v_mul_f32_e32 v55, v35, v35
	v_mul_f32_e32 v32, v48, v32
	v_mul_f32_e32 v33, v49, v33
	v_fmac_f32_e32 v55, v34, v34
	v_cvt_pk_bf16_f32 v32, v32, v33
	v_mul_f32_e32 v33, v50, v34
	v_mul_f32_e32 v34, v51, v35
	v_cvt_pk_bf16_f32 v33, v33, v34
	v_lshlrev_b64 v[34:35], 12, v[44:45]
	v_lshl_add_u64 v[34:35], s[14:15], 0, v[34:35]
	v_add_f32_e32 v56, v54, v55
	v_lshl_add_u64 v[54:55], v[168:169], 1, v[34:35]
	global_store_dwordx2 v[54:55], v[32:33], off
	s_waitcnt lgkmcnt(0)
	v_mul_f32_e32 v32, v25, v25
	global_store_dwordx4 v[46:47], v[24:27], off offset:64
	v_fmac_f32_e32 v32, v24, v24
	v_mul_f32_e32 v33, v27, v27
	v_mul_f32_e32 v24, v40, v24
	v_mul_f32_e32 v25, v41, v25
	v_cvt_pk_bf16_f32 v24, v24, v25
	v_mul_f32_e32 v25, v42, v26
	v_fmac_f32_e32 v33, v26, v26
	v_mul_f32_e32 v26, v43, v27
	v_cvt_pk_bf16_f32 v25, v25, v26
	global_store_dwordx2 v[54:55], v[24:25], off offset:32
	v_add_f32_e32 v32, v32, v33
	v_add_f32_e32 v32, v56, v32
	s_waitcnt lgkmcnt(0)
	v_mul_f32_e32 v24, v21, v21
	global_store_dwordx4 v[46:47], v[20:23], off offset:512
	v_fmac_f32_e32 v24, v20, v20
	v_mul_f32_e32 v25, v23, v23
	v_mul_f32_e32 v20, v36, v20
	v_mul_f32_e32 v21, v37, v21
	v_cvt_pk_bf16_f32 v20, v20, v21
	v_mul_f32_e32 v21, v38, v22
	v_fmac_f32_e32 v25, v22, v22
	v_mul_f32_e32 v22, v39, v23
	v_cvt_pk_bf16_f32 v21, v21, v22
	global_store_dwordx2 v[54:55], v[20:21], off offset:256
	v_add_f32_e32 v24, v24, v25
	v_add_f32_e32 v24, v32, v24
	s_waitcnt lgkmcnt(0)
	global_store_dwordx4 v[46:47], v[16:19], off offset:576
	v_mul_f32_e32 v21, v29, v17
	v_mul_f32_e32 v20, v28, v16
	v_mul_f32_e32 v17, v17, v17
	v_fmac_f32_e32 v17, v16, v16
	v_mul_f32_e32 v16, v19, v19
	v_fmac_f32_e32 v16, v18, v18
	v_add_f32_e32 v16, v17, v16
	v_add_f32_e32 v16, v24, v16
	ds_bpermute_b32 v17, v136, v16
	v_cvt_pk_bf16_f32 v20, v20, v21
	v_mul_f32_e32 v21, v30, v18
	v_mul_f32_e32 v22, v31, v19
	v_cvt_pk_bf16_f32 v21, v21, v22
	s_waitcnt lgkmcnt(0)
	v_add_f32_e32 v16, v16, v17
	ds_bpermute_b32 v17, v137, v16
	global_store_dwordx2 v[54:55], v[20:21], off offset:288
	s_and_saveexec_b64 s[2:3], s[36:37]
	s_cbranch_execz .LBB0_1312
	v_lshl_add_u64 v[18:19], v[44:45], 2, s[20:21]
	s_waitcnt lgkmcnt(0)
	v_add_f32_e32 v16, v16, v17
	global_atomic_add_f32 v[18:19], v16, off
.LBB0_1312:
	s_or_b64 exec, exec, s[2:3]
	s_movk_i32 s2, 0x1f4f
	s_waitcnt lgkmcnt(0)
	v_add_u32_e32 v16, 0xb0, v170
	v_cmp_lt_i32_e32 vcc, s2, v170
	s_and_saveexec_b64 s[2:3], vcc
	s_xor_b64 s[2:3], exec, s[2:3]
	v_add_u32_e32 v144, 0xffffe0b0, v170
	v_lshlrev_b64 v[18:19], 13, v[144:145]
	v_mov_b32_e32 v17, v145
	v_lshl_add_u64 v[18:19], s[18:19], 0, v[18:19]
	v_lshlrev_b64 v[22:23], 11, v[16:17]
	s_andn2_saveexec_b64 s[2:3], s[2:3]
	v_ashrrev_i32_e32 v17, 31, v16
	v_lshlrev_b64 v[18:19], 13, v[16:17]
	v_lshlrev_b64 v[22:23], 11, v[16:17]
	v_lshl_add_u64 v[18:19], s[16:17], 0, v[18:19]
	s_or_b64 exec, exec, s[2:3]
	v_lshl_add_u64 v[20:21], v[18:19], 0, v[172:173]
	v_lshl_add_u64 v[18:19], v[22:23], 2, s[12:13]
	v_lshl_add_u64 v[18:19], v[18:19], 0, v[172:173]
	s_waitcnt lgkmcnt(0)
	v_mul_f32_e32 v22, v13, v13
	global_store_dwordx4 v[18:19], v[12:15], off
	v_fmac_f32_e32 v22, v12, v12
	v_mul_f32_e32 v23, v15, v15
	v_mul_f32_e32 v12, v48, v12
	v_mul_f32_e32 v13, v49, v13
	v_fmac_f32_e32 v23, v14, v14
	v_cvt_pk_bf16_f32 v12, v12, v13
	v_mul_f32_e32 v13, v50, v14
	v_mul_f32_e32 v14, v51, v15
	v_cvt_pk_bf16_f32 v13, v13, v14
	v_lshlrev_b64 v[14:15], 12, v[16:17]
	v_lshl_add_u64 v[14:15], s[14:15], 0, v[14:15]
	v_add_f32_e32 v24, v22, v23
	v_lshl_add_u64 v[22:23], v[168:169], 1, v[14:15]
	global_store_dwordx2 v[22:23], v[12:13], off
	s_waitcnt lgkmcnt(0)
	v_mul_f32_e32 v12, v9, v9
	global_store_dwordx4 v[18:19], v[8:11], off offset:64
	v_fmac_f32_e32 v12, v8, v8
	v_mul_f32_e32 v13, v11, v11
	v_mul_f32_e32 v8, v40, v8
	v_mul_f32_e32 v9, v41, v9
	v_cvt_pk_bf16_f32 v8, v8, v9
	v_mul_f32_e32 v9, v42, v10
	v_fmac_f32_e32 v13, v10, v10
	v_mul_f32_e32 v10, v43, v11
	v_cvt_pk_bf16_f32 v9, v9, v10
	global_store_dwordx2 v[22:23], v[8:9], off offset:32
	v_add_f32_e32 v12, v12, v13
	v_add_f32_e32 v12, v24, v12
	s_waitcnt lgkmcnt(0)
	v_mul_f32_e32 v8, v5, v5
	global_store_dwordx4 v[18:19], v[4:7], off offset:512
	v_fmac_f32_e32 v8, v4, v4
	v_mul_f32_e32 v9, v7, v7
	v_mul_f32_e32 v4, v36, v4
	v_mul_f32_e32 v5, v37, v5
	v_cvt_pk_bf16_f32 v4, v4, v5
	v_mul_f32_e32 v5, v38, v6
	v_fmac_f32_e32 v9, v6, v6
	v_mul_f32_e32 v6, v39, v7
	v_cvt_pk_bf16_f32 v5, v5, v6
	global_store_dwordx2 v[22:23], v[4:5], off offset:256
	v_add_f32_e32 v8, v8, v9
	v_add_f32_e32 v8, v12, v8
	s_waitcnt lgkmcnt(0)
	global_store_dwordx4 v[18:19], v[0:3], off offset:576
	v_mul_f32_e32 v5, v29, v1
	v_mul_f32_e32 v4, v28, v0
	v_mul_f32_e32 v1, v1, v1
	v_fmac_f32_e32 v1, v0, v0
	v_mul_f32_e32 v0, v3, v3
	v_fmac_f32_e32 v0, v2, v2
	v_add_f32_e32 v0, v1, v0
	v_add_f32_e32 v0, v8, v0
	ds_bpermute_b32 v1, v136, v0
	v_cvt_pk_bf16_f32 v4, v4, v5
	v_mul_f32_e32 v5, v30, v2
	v_mul_f32_e32 v6, v31, v3
	v_cvt_pk_bf16_f32 v5, v5, v6
	s_waitcnt lgkmcnt(0)
	v_add_f32_e32 v0, v0, v1
	ds_bpermute_b32 v1, v137, v0
	flat_store_dwordx2 v[22:23], v[4:5] offset:288
	s_and_saveexec_b64 s[2:3], s[36:37]
	s_cbranch_execz .LBB0_1318
	v_lshl_add_u64 v[2:3], v[16:17], 2, s[20:21]
	s_waitcnt lgkmcnt(0)
	v_add_f32_e32 v0, v0, v1
	flat_atomic_add_f32 v[2:3], v0

	.amdhsa_kernel _Z6mk_fwd6Params
		.amdhsa_group_segment_fixed_size 0
		.amdhsa_private_segment_fixed_size 0
		.amdhsa_kernarg_size 504
		.amdhsa_user_sgpr_count 2
		.amdhsa_user_sgpr_dispatch_ptr 0
		.amdhsa_user_sgpr_queue_ptr 0
		.amdhsa_user_sgpr_kernarg_segment_ptr 1
		.amdhsa_user_sgpr_dispatch_id 0
		.amdhsa_user_sgpr_kernarg_preload_length 0
		.amdhsa_user_sgpr_kernarg_preload_offset 0
		.amdhsa_user_sgpr_private_segment_size 0
		.amdhsa_uses_dynamic_stack 0
		.amdhsa_enable_private_segment 0
		.amdhsa_system_sgpr_workgroup_id_x 1
		.amdhsa_system_sgpr_workgroup_id_y 0
		.amdhsa_system_sgpr_workgroup_id_z 0
		.amdhsa_system_sgpr_workgroup_info 0
		.amdhsa_system_vgpr_workitem_id 2
		.amdhsa_next_free_vgpr 256
		.amdhsa_next_free_sgpr 102
		.amdhsa_accum_offset 256
		.amdhsa_reserve_vcc 1
		.amdhsa_float_round_mode_32 0
		.amdhsa_float_round_mode_16_64 0
		.amdhsa_float_denorm_mode_32 3
		.amdhsa_float_denorm_mode_16_64 3
		.amdhsa_dx10_clamp 1
		.amdhsa_ieee_mode 1
		.amdhsa_fp16_overflow 0
		.amdhsa_tg_split 0
		.amdhsa_exception_fp_ieee_invalid_op 0
		.amdhsa_exception_fp_denorm_src 0
		.amdhsa_exception_fp_ieee_div_zero 0
		.amdhsa_exception_fp_ieee_overflow 0
		.amdhsa_exception_fp_ieee_underflow 0
		.amdhsa_exception_fp_ieee_inexact 0
		.amdhsa_exception_int_div_zero 0
	.end_amdhsa_kernel

amdhsa.kernels:
  - .agpr_count:     0
    .args:
      - .offset:         0
        .size:           248
        .value_kind:     by_value
      - .offset:         248
        .size:           4
        .value_kind:     hidden_block_count_x
      - .offset:         252
        .size:           4
        .value_kind:     hidden_block_count_y
      - .offset:         256
        .size:           4
        .value_kind:     hidden_block_count_z
      - .offset:         260
        .size:           2
        .value_kind:     hidden_group_size_x
      - .offset:         262
        .size:           2
        .value_kind:     hidden_group_size_y
      - .offset:         264
        .size:           2
        .value_kind:     hidden_group_size_z
      - .offset:         266
        .size:           2
        .value_kind:     hidden_remainder_x
      - .offset:         268
        .size:           2
        .value_kind:     hidden_remainder_y
      - .offset:         270
        .size:           2
        .value_kind:     hidden_remainder_z
      - .offset:         288
        .size:           8
        .value_kind:     hidden_global_offset_x
      - .offset:         296
        .size:           8
        .value_kind:     hidden_global_offset_y
      - .offset:         304
        .size:           8
        .value_kind:     hidden_global_offset_z
      - .offset:         312
        .size:           2
        .value_kind:     hidden_grid_dims
      - .offset:         336
        .size:           8
        .value_kind:     hidden_multigrid_sync_arg
      - .offset:         368
        .size:           4
        .value_kind:     hidden_dynamic_lds_size
    .group_segment_fixed_size: 0
    .kernarg_segment_align: 8
    .kernarg_segment_size: 504
    .language:       OpenCL C
    .language_version:
      - 2
      - 0
    .max_flat_workgroup_size: 512
    .name:           _Z6mk_fwd6Params
    .private_segment_fixed_size: 0
    .sgpr_count:     108
    .sgpr_spill_count: 193
    .symbol:         _Z6mk_fwd6Params.kd
    .uniform_work_group_size: 1
    .uses_dynamic_stack: false
    .vgpr_count:     256
    .vgpr_spill_count: 0
    .wavefront_size: 64
